# attn_stage
# speedup vs baseline: 1.0152x; 1.0152x over previous
; DEVI f32x4 ozero() { float z = 0.f; asm volatile("" : "+v"(z)); return f32x4{z, z, z, z}; }
; #define LDA(dst, b, h)                                                                                    \
;   _Pragma("unroll") for (int m = 0; m < 4; ++m) _Pragma("unroll") for (int k = 0; k < 2; ++k)             \
;       dst[m][k] = *reinterpret_cast<const bf16x8*>((char*)SA(b, h) + lds_byte(wr * 64 + m * 16 + fr, k * 32 + fq * 8))
; #define LDB(dst, b, h)                                                                                    \
;   _Pragma("unroll") for (int n = 0; n < 2; ++n) _Pragma("unroll") for (int k = 0; k < 2; ++k)             \
;       dst[n][k] = *reinterpret_cast<const bf16x8*>((char*)SB(b, h) + lds_byte(wc * 32 + n * 16 + fr, k * 32 + fq * 8))
; #define WAIT_V(n) asm volatile("s_waitcnt vmcnt(" #n ")" ::: "memory")
; #define WAIT_L(n) asm volatile("s_waitcnt lgkmcnt(" #n ")" ::: "memory")
; #define BAR __builtin_amdgcn_s_barrier()
; #define SCHED __builtin_amdgcn_sched_barrier(0)
; template <int EPI> ...
;     ...
;   const int brow = m0, bcol = n0;
;   const int wid = __builtin_amdgcn_readfirstlane(tid >> 6), lane = tid & 63, wr = wid >> 2, wc = wid & 3, fr = lane & 15, fq = lane >> 4;
;   f32x4 acc[2][2][4][2];
;   {
;     const f32x4 zq = ozero();
; #pragma unroll
;     for (int a_ = 0; a_ < 2; ++a_)
; #pragma unroll
;       for (int b_ = 0; b_ < 2; ++b_)
; #pragma unroll
;         for (int m = 0; m < 4; ++m) { acc[a_][b_][m][0] = zq; acc[a_][b_][m][1] = zq; }
;   }
;   bf16x8 At[4][2], B0[2][2], B1[2][2];
;   const int nt = K / BK;
;     ...
;   if (first) {
;     WAIT_V(0);
;     ISSUE_PRO(brow, bcol);
;   }
;   if (wr == 1) BAR;
;   WAIT_V(10); BAR;
;   WAIT_V(6); BAR;
;   for (int t = 0; t < nt - 2; t += 2) {
;     LDB(B0, 0, 0); SCHED; LDA(At, 0, 0); STAGE(SA(1, 1), A, brow + HALF, t + 1);
;     WAIT_L(8); BAR; WAIT_L(0); MMA(0, 0, At, B0); BAR; SCHED;
.LBB0_140:
	v_and_b32_e32 v132, 15, v134
	v_and_b32_e32 v1, 48, v134
	v_lshlrev_b32_e32 v2, 6, v132
	v_lshlrev_b32_e32 v4, 2, v134
	v_or_b32_e32 v3, v2, v1
	v_and_b32_e32 v4, 32, v4
	s_mov_b32 s14, 0x10000
	v_bitop3_b32 v5, v3, s14, v4 bitop3:0xde
	s_mov_b32 s14, 0x14000
	s_ashr_i32 s7, s34, 6
	v_bitop3_b32 v6, v3, s14, v4 bitop3:0xde
	s_mov_b32 s14, 0x18000
	v_lshlrev_b32_e32 v8, 6, v134
	s_and_b32 s35, s7, 3
	s_waitcnt vmcnt(10)
	s_barrier
	s_waitcnt vmcnt(6)
	s_lshl_b32 s44, s16, 6
	v_bitop3_b32 v7, v3, s14, v4 bitop3:0xde
	s_mov_b32 s14, 0x1c000
	s_lshl_b32 s16, s16, 13
	v_and_b32_e32 v8, 0x3c0, v8
	s_lshl_b32 s17, s35, 12
	v_bitop3_b32 v2, v2, v4, v1 bitop3:0x36
	v_bitop3_b32 v3, v3, s14, v4 bitop3:0xde
	v_bitop3_b32 v1, v8, v4, v1 bitop3:0x36
	s_or_b32 s18, s16, 0x800
	s_or_b32 s19, s16, 0x1000
	s_or_b32 s63, s16, 0x1800
	s_mov_b32 s62, -2
	s_mov_b64 s[14:15], 0
	v_add_u32_e32 v159, s17, v5
	v_add_u32_e32 v138, s16, v2
	v_add_u32_e32 v137, s18, v1
	v_add_u32_e32 v136, s19, v1
	v_add_u32_e32 v135, s63, v1
	v_add_u32_e32 v158, 0xc000, v133
	v_add_u32_e32 v157, 0xe000, v133
	v_add_u32_e32 v155, s17, v6
	v_add_u32_e32 v143, s17, v7
	v_add_u32_e32 v140, s17, v3
	v_mov_b32_e32 v1, v0
	v_mov_b32_e32 v2, v0
	v_mov_b32_e32 v3, v0
	v_mov_b32_e32 v4, v0
	v_mov_b32_e32 v5, v0
	v_mov_b32_e32 v6, v0
	v_mov_b32_e32 v7, v0
	v_mov_b32_e32 v8, v0
	v_mov_b32_e32 v9, v0
	v_mov_b32_e32 v10, v0
	v_mov_b32_e32 v11, v0
	v_mov_b32_e32 v12, v0
	v_mov_b32_e32 v13, v0
	v_mov_b32_e32 v14, v0
	v_mov_b32_e32 v15, v0
	v_mov_b32_e32 v16, v0
	v_mov_b32_e32 v17, v0
	v_mov_b32_e32 v18, v0
	v_mov_b32_e32 v19, v0
	v_mov_b32_e32 v20, v0
	v_mov_b32_e32 v21, v0
	v_mov_b32_e32 v22, v0
	v_mov_b32_e32 v23, v0
	v_mov_b32_e32 v24, v0
	v_mov_b32_e32 v25, v0
	v_mov_b32_e32 v26, v0
	v_mov_b32_e32 v27, v0
	v_mov_b32_e32 v28, v0
	v_mov_b32_e32 v29, v0
	v_mov_b32_e32 v30, v0
	v_mov_b32_e32 v31, v0
	v_mov_b32_e32 v32, v0
	v_mov_b32_e32 v33, v0
	v_mov_b32_e32 v34, v0
	v_mov_b32_e32 v35, v0
	v_mov_b32_e32 v36, v0
	v_mov_b32_e32 v37, v0
	v_mov_b32_e32 v38, v0
	v_mov_b32_e32 v39, v0
	v_mov_b32_e32 v40, v0
	v_mov_b32_e32 v41, v0
	v_mov_b32_e32 v42, v0
	v_mov_b32_e32 v43, v0
	v_mov_b32_e32 v44, v0
	v_mov_b32_e32 v45, v0
	v_mov_b32_e32 v46, v0
	v_mov_b32_e32 v47, v0
	v_mov_b32_e32 v48, v0
	v_mov_b32_e32 v49, v0
	v_mov_b32_e32 v50, v0
	v_mov_b32_e32 v51, v0
	v_mov_b32_e32 v52, v0
	v_mov_b32_e32 v53, v0
	v_mov_b32_e32 v54, v0
	v_mov_b32_e32 v55, v0
	v_mov_b32_e32 v56, v0
	v_mov_b32_e32 v57, v0
	v_mov_b32_e32 v58, v0
	v_mov_b32_e32 v59, v0
	v_mov_b32_e32 v60, v0
	v_mov_b32_e32 v61, v0
	v_mov_b32_e32 v62, v0
	v_mov_b32_e32 v63, v0
	v_mov_b32_e32 v64, v0
	v_mov_b32_e32 v65, v0
	v_mov_b32_e32 v66, v0
	v_mov_b32_e32 v67, v0
	v_mov_b32_e32 v68, v0
	v_mov_b32_e32 v69, v0
	v_mov_b32_e32 v70, v0
	v_mov_b32_e32 v71, v0
	v_mov_b32_e32 v72, v0
	v_mov_b32_e32 v73, v0
	v_mov_b32_e32 v74, v0
	v_mov_b32_e32 v75, v0
	v_mov_b32_e32 v76, v0
	v_mov_b32_e32 v77, v0
	v_mov_b32_e32 v78, v0
	v_mov_b32_e32 v79, v0
	v_mov_b32_e32 v80, v0
	v_mov_b32_e32 v81, v0
	v_mov_b32_e32 v82, v0
	v_mov_b32_e32 v83, v0
	v_mov_b32_e32 v84, v0
	v_mov_b32_e32 v85, v0
	v_mov_b32_e32 v86, v0
	v_mov_b32_e32 v87, v0
	v_mov_b32_e32 v88, v0
	v_mov_b32_e32 v89, v0
	v_mov_b32_e32 v90, v0
	v_mov_b32_e32 v91, v0
	v_mov_b32_e32 v92, v0
	v_mov_b32_e32 v93, v0
	v_mov_b32_e32 v94, v0
	v_mov_b32_e32 v95, v0
	v_mov_b32_e32 v96, v0
	v_mov_b32_e32 v97, v0
	v_mov_b32_e32 v98, v0
	v_mov_b32_e32 v99, v0
	v_mov_b32_e32 v100, v0
	v_mov_b32_e32 v101, v0
	v_mov_b32_e32 v102, v0
	v_mov_b32_e32 v103, v0
	v_mov_b32_e32 v104, v0
	v_mov_b32_e32 v105, v0
	v_mov_b32_e32 v106, v0
	v_mov_b32_e32 v107, v0
	v_mov_b32_e32 v108, v0
	v_mov_b32_e32 v109, v0
	v_mov_b32_e32 v110, v0
	v_mov_b32_e32 v111, v0
	v_mov_b32_e32 v112, v0
	v_mov_b32_e32 v113, v0
	v_mov_b32_e32 v114, v0
	v_mov_b32_e32 v115, v0
	v_mov_b32_e32 v116, v0
	v_mov_b32_e32 v117, v0
	v_mov_b32_e32 v118, v0
	v_mov_b32_e32 v119, v0
	v_mov_b32_e32 v120, v0
	v_mov_b32_e32 v121, v0
	v_mov_b32_e32 v122, v0
	v_mov_b32_e32 v123, v0
	v_mov_b32_e32 v124, v0
	v_mov_b32_e32 v125, v0
	v_mov_b32_e32 v126, v0
	v_mov_b32_e32 v127, v0
	s_barrier
	v_lshlrev_b32_e32 v253, 1, v128
	v_lshlrev_b32_e32 v252, 1, v130
	v_readfirstlane_b32 s32, v133
.LBB0_141:
	ds_read_b128 v[160:163], v159
	ds_read_b128 v[164:167], v159 offset:1024
	ds_read_b128 v[178:181], v159 offset:2048
	ds_read_b128 v[182:185], v159 offset:3072
	s_add_u32 s16, s10, s14
	s_addc_u32 s17, s11, s15
	ds_read_b128 v[186:189], v138
	ds_read_b128 v[190:193], v138 offset:1024
	ds_read_b128 v[194:197], v137
	ds_read_b128 v[198:201], v137 offset:1024
	ds_read_b128 v[202:205], v136
	ds_read_b128 v[206:209], v136 offset:1024
	ds_read_b128 v[210:213], v135
	ds_read_b128 v[214:217], v135 offset:1024
	s_add_u32 m0, s32, 0xc000
	s_add_u32 s98, s16, 0x40080
	s_addc_u32 s99, s17, 0
	global_load_lds_dwordx4 v253, s[98:99]
	s_add_u32 m0, s32, 0xe000
	s_nop 0
	global_load_lds_dwordx4 v252, s[98:99]
	s_waitcnt lgkmcnt(8)
	s_barrier
	s_waitcnt lgkmcnt(0)
	s_setprio 1
	s_waitcnt lgkmcnt(0)
	v_mfma_f32_16x16x32_bf16 v[124:127], v[186:189], v[160:163], v[124:127]
	v_mfma_f32_16x16x32_bf16 v[120:123], v[186:189], v[178:181], v[120:123]
	v_mfma_f32_16x16x32_bf16 v[116:119], v[194:197], v[160:163], v[116:119]
	v_mfma_f32_16x16x32_bf16 v[112:115], v[194:197], v[178:181], v[112:115]
	v_mfma_f32_16x16x32_bf16 v[108:111], v[202:205], v[160:163], v[108:111]
	v_mfma_f32_16x16x32_bf16 v[104:107], v[202:205], v[178:181], v[104:107]
	v_mfma_f32_16x16x32_bf16 v[100:103], v[210:213], v[160:163], v[100:103]
	v_mfma_f32_16x16x32_bf16 v[96:99], v[210:213], v[178:181], v[96:99]
	v_mfma_f32_16x16x32_bf16 v[124:127], v[190:193], v[164:167], v[124:127]
	v_mfma_f32_16x16x32_bf16 v[120:123], v[190:193], v[182:185], v[120:123]
	v_mfma_f32_16x16x32_bf16 v[116:119], v[198:201], v[164:167], v[116:119]
	v_mfma_f32_16x16x32_bf16 v[112:115], v[198:201], v[182:185], v[112:115]
	v_mfma_f32_16x16x32_bf16 v[108:111], v[206:209], v[164:167], v[108:111]
	v_mfma_f32_16x16x32_bf16 v[104:107], v[206:209], v[182:185], v[104:107]
	v_mfma_f32_16x16x32_bf16 v[100:103], v[214:217], v[164:167], v[100:103]
	v_mfma_f32_16x16x32_bf16 v[96:99], v[214:217], v[182:185], v[96:99]
	s_setprio 0
	s_barrier
; #define LDA(dst, b, h)                                                                                    \
;   _Pragma("unroll") for (int m = 0; m < 4; ++m) _Pragma("unroll") for (int k = 0; k < 2; ++k)             \
;       dst[m][k] = *reinterpret_cast<const bf16x8*>((char*)SA(b, h) + lds_byte(wr * 64 + m * 16 + fr, k * 32 + fq * 8))
; #define LDB(dst, b, h)                                                                                    \
;   _Pragma("unroll") for (int n = 0; n < 2; ++n) _Pragma("unroll") for (int k = 0; k < 2; ++k)             \
;       dst[n][k] = *reinterpret_cast<const bf16x8*>((char*)SB(b, h) + lds_byte(wc * 32 + n * 16 + fr, k * 32 + fq * 8))
; #define WAIT_V(n) asm volatile("s_waitcnt vmcnt(" #n ")" ::: "memory")
; #define WAIT_L(n) asm volatile("s_waitcnt lgkmcnt(" #n ")" ::: "memory")
; #define BAR __builtin_amdgcn_s_barrier()
; #define SCHED __builtin_amdgcn_sched_barrier(0)
; template <int EPI> ...
;     ...
;     LDB(B1, 0, 1); STAGE(SB(0, 0), Bt, bcol, t + 2);
;     BAR; WAIT_L(0); MMA(0, 1, At, B1); BAR;
;     LDA(At, 0, 1); STAGE(SA(0, 0), A, brow, t + 2);
;     BAR; WAIT_L(0); MMA(1, 0, At, B0); BAR; SCHED;
;     STAGE(SB(0, 1), Bt, bcol + HALF, t + 2);
;     WAIT_V(6); BAR; MMA(1, 1, At, B1); BAR;
;     LDB(B0, 1, 0); SCHED; LDA(At, 1, 0); STAGE(SA(0, 1), A, brow + HALF, t + 2);
;     WAIT_L(8); BAR; WAIT_L(0); MMA(0, 0, At, B0); BAR; SCHED;
	s_add_u32 s18, s8, s14
	s_addc_u32 s19, s9, s15
	ds_read_b128 v[218:221], v155
	ds_read_b128 v[222:225], v155 offset:1024
	ds_read_b128 v[226:229], v155 offset:2048
	ds_read_b128 v[230:233], v155 offset:3072
	s_add_u32 m0, s32, 0x10000
	s_add_u32 s98, s18, 0x100
	s_addc_u32 s99, s19, 0
	global_load_lds_dwordx4 v253, s[98:99]
	s_add_u32 m0, s32, 0x12000
	s_nop 0
	global_load_lds_dwordx4 v252, s[98:99]
	s_barrier
	s_waitcnt lgkmcnt(0)
	s_setprio 1
	s_waitcnt lgkmcnt(0)
	v_mfma_f32_16x16x32_bf16 v[92:95], v[186:189], v[218:221], v[92:95]
	v_mfma_f32_16x16x32_bf16 v[88:91], v[186:189], v[226:229], v[88:91]
	v_mfma_f32_16x16x32_bf16 v[84:87], v[194:197], v[218:221], v[84:87]
	v_mfma_f32_16x16x32_bf16 v[80:83], v[194:197], v[226:229], v[80:83]
	v_mfma_f32_16x16x32_bf16 v[76:79], v[202:205], v[218:221], v[76:79]
	v_mfma_f32_16x16x32_bf16 v[72:75], v[202:205], v[226:229], v[72:75]
	v_mfma_f32_16x16x32_bf16 v[68:71], v[210:213], v[218:221], v[68:71]
	v_mfma_f32_16x16x32_bf16 v[64:67], v[210:213], v[226:229], v[64:67]
	v_mfma_f32_16x16x32_bf16 v[92:95], v[190:193], v[222:225], v[92:95]
	v_mfma_f32_16x16x32_bf16 v[88:91], v[190:193], v[230:233], v[88:91]
	v_mfma_f32_16x16x32_bf16 v[84:87], v[198:201], v[222:225], v[84:87]
	v_mfma_f32_16x16x32_bf16 v[80:83], v[198:201], v[230:233], v[80:83]
	v_mfma_f32_16x16x32_bf16 v[76:79], v[206:209], v[222:225], v[76:79]
	v_mfma_f32_16x16x32_bf16 v[72:75], v[206:209], v[230:233], v[72:75]
	v_mfma_f32_16x16x32_bf16 v[68:71], v[214:217], v[222:225], v[68:71]
	v_mfma_f32_16x16x32_bf16 v[64:67], v[214:217], v[230:233], v[64:67]
	s_setprio 0
	s_barrier
	ds_read_b128 v[186:189], v138 offset:16384
	ds_read_b128 v[190:193], v138 offset:17408
	ds_read_b128 v[194:197], v137 offset:16384
	ds_read_b128 v[198:201], v137 offset:17408
	ds_read_b128 v[202:205], v136 offset:16384
	ds_read_b128 v[206:209], v136 offset:17408
	ds_read_b128 v[210:213], v135 offset:16384
	ds_read_b128 v[214:217], v135 offset:17408
	s_mov_b32 m0, s32
	s_add_u32 s98, s16, 0x100
	s_addc_u32 s99, s17, 0
	global_load_lds_dwordx4 v253, s[98:99]
	s_add_u32 m0, s32, 0x2000
	s_nop 0
	global_load_lds_dwordx4 v252, s[98:99]
	s_barrier
	s_waitcnt lgkmcnt(0)
	s_setprio 1
	s_waitcnt lgkmcnt(0)
	v_mfma_f32_16x16x32_bf16 v[60:63], v[186:189], v[160:163], v[60:63]
	v_mfma_f32_16x16x32_bf16 v[56:59], v[186:189], v[178:181], v[56:59]
	v_mfma_f32_16x16x32_bf16 v[52:55], v[194:197], v[160:163], v[52:55]
	v_mfma_f32_16x16x32_bf16 v[48:51], v[194:197], v[178:181], v[48:51]
	v_mfma_f32_16x16x32_bf16 v[44:47], v[202:205], v[160:163], v[44:47]
	v_mfma_f32_16x16x32_bf16 v[40:43], v[202:205], v[178:181], v[40:43]
	v_mfma_f32_16x16x32_bf16 v[36:39], v[210:213], v[160:163], v[36:39]
	v_mfma_f32_16x16x32_bf16 v[32:35], v[210:213], v[178:181], v[32:35]
	v_mfma_f32_16x16x32_bf16 v[60:63], v[190:193], v[164:167], v[60:63]
	v_mfma_f32_16x16x32_bf16 v[56:59], v[190:193], v[182:185], v[56:59]
	v_mfma_f32_16x16x32_bf16 v[52:55], v[198:201], v[164:167], v[52:55]
	v_mfma_f32_16x16x32_bf16 v[48:51], v[198:201], v[182:185], v[48:51]
	v_mfma_f32_16x16x32_bf16 v[44:47], v[206:209], v[164:167], v[44:47]
	v_mfma_f32_16x16x32_bf16 v[40:43], v[206:209], v[182:185], v[40:43]
	v_mfma_f32_16x16x32_bf16 v[36:39], v[214:217], v[164:167], v[36:39]
	v_mfma_f32_16x16x32_bf16 v[32:35], v[214:217], v[182:185], v[32:35]
	s_setprio 0
	s_barrier
	s_add_u32 m0, s32, 0x14000
	s_add_u32 s98, s18, 0x40100
	s_addc_u32 s99, s19, 0
	global_load_lds_dwordx4 v253, s[98:99]
	s_add_u32 m0, s32, 0x16000
	s_nop 0
	global_load_lds_dwordx4 v252, s[98:99]
	s_waitcnt vmcnt(6)
	s_barrier
	s_setprio 1
	v_mfma_f32_16x16x32_bf16 v[28:31], v[186:189], v[218:221], v[28:31]
	v_mfma_f32_16x16x32_bf16 v[24:27], v[186:189], v[226:229], v[24:27]
	v_mfma_f32_16x16x32_bf16 v[20:23], v[194:197], v[218:221], v[20:23]
	v_mfma_f32_16x16x32_bf16 v[16:19], v[194:197], v[226:229], v[16:19]
	v_mfma_f32_16x16x32_bf16 v[12:15], v[202:205], v[218:221], v[12:15]
	v_mfma_f32_16x16x32_bf16 v[8:11], v[202:205], v[226:229], v[8:11]
	v_mfma_f32_16x16x32_bf16 v[4:7], v[210:213], v[218:221], v[4:7]
	v_mfma_f32_16x16x32_bf16 v[0:3], v[210:213], v[226:229], v[0:3]
	v_mfma_f32_16x16x32_bf16 v[28:31], v[190:193], v[222:225], v[28:31]
	v_mfma_f32_16x16x32_bf16 v[24:27], v[190:193], v[230:233], v[24:27]
	v_mfma_f32_16x16x32_bf16 v[20:23], v[198:201], v[222:225], v[20:23]
	v_mfma_f32_16x16x32_bf16 v[16:19], v[198:201], v[230:233], v[16:19]
	v_mfma_f32_16x16x32_bf16 v[12:15], v[206:209], v[222:225], v[12:15]
	v_mfma_f32_16x16x32_bf16 v[8:11], v[206:209], v[230:233], v[8:11]
	v_mfma_f32_16x16x32_bf16 v[4:7], v[214:217], v[222:225], v[4:7]
	v_mfma_f32_16x16x32_bf16 v[0:3], v[214:217], v[230:233], v[0:3]
	s_setprio 0
	s_barrier
	ds_read_b128 v[160:163], v143
	ds_read_b128 v[164:167], v143 offset:1024
	ds_read_b128 v[178:181], v143 offset:2048
	ds_read_b128 v[182:185], v143 offset:3072
	ds_read_b128 v[186:189], v138 offset:32768
	ds_read_b128 v[190:193], v138 offset:33792
	ds_read_b128 v[194:197], v137 offset:32768
	ds_read_b128 v[198:201], v137 offset:33792
	ds_read_b128 v[202:205], v136 offset:32768
	ds_read_b128 v[206:209], v136 offset:33792
	ds_read_b128 v[210:213], v135 offset:32768
	ds_read_b128 v[214:217], v135 offset:33792
	s_add_u32 m0, s32, 0x4000
	s_add_u32 s98, s16, 0x40100
	s_addc_u32 s99, s17, 0
	global_load_lds_dwordx4 v253, s[98:99]
	s_add_u32 m0, s32, 0x6000
	s_nop 0
	global_load_lds_dwordx4 v252, s[98:99]
	s_waitcnt lgkmcnt(8)
	s_barrier
; #define LDA(dst, b, h)                                                                                    \
;   _Pragma("unroll") for (int m = 0; m < 4; ++m) _Pragma("unroll") for (int k = 0; k < 2; ++k)             \
;       dst[m][k] = *reinterpret_cast<const bf16x8*>((char*)SA(b, h) + lds_byte(wr * 64 + m * 16 + fr, k * 32 + fq * 8))
; #define LDB(dst, b, h)                                                                                    \
;   _Pragma("unroll") for (int n = 0; n < 2; ++n) _Pragma("unroll") for (int k = 0; k < 2; ++k)             \
;       dst[n][k] = *reinterpret_cast<const bf16x8*>((char*)SB(b, h) + lds_byte(wc * 32 + n * 16 + fr, k * 32 + fq * 8))
; #define WAIT_V(n) asm volatile("s_waitcnt vmcnt(" #n ")" ::: "memory")
; #define WAIT_L(n) asm volatile("s_waitcnt lgkmcnt(" #n ")" ::: "memory")
; #define BAR __builtin_amdgcn_s_barrier()
; #define SCHED __builtin_amdgcn_sched_barrier(0)
; template <int EPI> ...
;     ...
;     WAIT_L(8); BAR; WAIT_L(0); MMA(0, 0, At, B0); BAR; SCHED;
;     LDB(B1, 1, 1); STAGE(SB(1, 0), Bt, bcol, t + 3);
;     BAR; WAIT_L(0); MMA(0, 1, At, B1); BAR;
;     LDA(At, 1, 1); STAGE(SA(1, 0), A, brow, t + 3);
;     BAR; WAIT_L(0); MMA(1, 0, At, B0); BAR; SCHED;
;     STAGE(SB(1, 1), Bt, bcol + HALF, t + 3);
;     WAIT_V(6); BAR; MMA(1, 1, At, B1); BAR;
;   }
	s_waitcnt lgkmcnt(0)
	s_setprio 1
	s_waitcnt lgkmcnt(0)
	v_mfma_f32_16x16x32_bf16 v[124:127], v[186:189], v[160:163], v[124:127]
	v_mfma_f32_16x16x32_bf16 v[120:123], v[186:189], v[178:181], v[120:123]
	v_mfma_f32_16x16x32_bf16 v[116:119], v[194:197], v[160:163], v[116:119]
	v_mfma_f32_16x16x32_bf16 v[112:115], v[194:197], v[178:181], v[112:115]
	v_mfma_f32_16x16x32_bf16 v[108:111], v[202:205], v[160:163], v[108:111]
	v_mfma_f32_16x16x32_bf16 v[104:107], v[202:205], v[178:181], v[104:107]
	v_mfma_f32_16x16x32_bf16 v[100:103], v[210:213], v[160:163], v[100:103]
	v_mfma_f32_16x16x32_bf16 v[96:99], v[210:213], v[178:181], v[96:99]
	v_mfma_f32_16x16x32_bf16 v[124:127], v[190:193], v[164:167], v[124:127]
	v_mfma_f32_16x16x32_bf16 v[120:123], v[190:193], v[182:185], v[120:123]
	v_mfma_f32_16x16x32_bf16 v[116:119], v[198:201], v[164:167], v[116:119]
	v_mfma_f32_16x16x32_bf16 v[112:115], v[198:201], v[182:185], v[112:115]
	v_mfma_f32_16x16x32_bf16 v[108:111], v[206:209], v[164:167], v[108:111]
	v_mfma_f32_16x16x32_bf16 v[104:107], v[206:209], v[182:185], v[104:107]
	v_mfma_f32_16x16x32_bf16 v[100:103], v[214:217], v[164:167], v[100:103]
	v_mfma_f32_16x16x32_bf16 v[96:99], v[214:217], v[182:185], v[96:99]
	s_setprio 0
	s_barrier
	ds_read_b128 v[218:221], v140
	ds_read_b128 v[222:225], v140 offset:1024
	ds_read_b128 v[226:229], v140 offset:2048
	ds_read_b128 v[230:233], v140 offset:3072
	s_add_u32 m0, s32, 0x18000
	s_add_u32 s98, s18, 0x180
	s_addc_u32 s99, s19, 0
	global_load_lds_dwordx4 v253, s[98:99]
	s_add_u32 m0, s32, 0x1a000
	s_nop 0
	global_load_lds_dwordx4 v252, s[98:99]
	s_barrier
	s_waitcnt lgkmcnt(0)
	s_setprio 1
	s_waitcnt lgkmcnt(0)
	v_mfma_f32_16x16x32_bf16 v[92:95], v[186:189], v[218:221], v[92:95]
	v_mfma_f32_16x16x32_bf16 v[88:91], v[186:189], v[226:229], v[88:91]
	v_mfma_f32_16x16x32_bf16 v[84:87], v[194:197], v[218:221], v[84:87]
	v_mfma_f32_16x16x32_bf16 v[80:83], v[194:197], v[226:229], v[80:83]
	v_mfma_f32_16x16x32_bf16 v[76:79], v[202:205], v[218:221], v[76:79]
	v_mfma_f32_16x16x32_bf16 v[72:75], v[202:205], v[226:229], v[72:75]
	v_mfma_f32_16x16x32_bf16 v[68:71], v[210:213], v[218:221], v[68:71]
	v_mfma_f32_16x16x32_bf16 v[64:67], v[210:213], v[226:229], v[64:67]
	v_mfma_f32_16x16x32_bf16 v[92:95], v[190:193], v[222:225], v[92:95]
	v_mfma_f32_16x16x32_bf16 v[88:91], v[190:193], v[230:233], v[88:91]
	v_mfma_f32_16x16x32_bf16 v[84:87], v[198:201], v[222:225], v[84:87]
	v_mfma_f32_16x16x32_bf16 v[80:83], v[198:201], v[230:233], v[80:83]
	v_mfma_f32_16x16x32_bf16 v[76:79], v[206:209], v[222:225], v[76:79]
	v_mfma_f32_16x16x32_bf16 v[72:75], v[206:209], v[230:233], v[72:75]
	v_mfma_f32_16x16x32_bf16 v[68:71], v[214:217], v[222:225], v[68:71]
	v_mfma_f32_16x16x32_bf16 v[64:67], v[214:217], v[230:233], v[64:67]
	s_setprio 0
	s_barrier
	ds_read_b128 v[186:189], v138 offset:49152
	ds_read_b128 v[190:193], v138 offset:50176
	ds_read_b128 v[194:197], v137 offset:49152
	ds_read_b128 v[198:201], v137 offset:50176
	ds_read_b128 v[202:205], v136 offset:49152
	ds_read_b128 v[206:209], v136 offset:50176
	ds_read_b128 v[210:213], v135 offset:49152
	ds_read_b128 v[214:217], v135 offset:50176
	s_add_u32 m0, s32, 0x8000
	s_add_u32 s98, s16, 0x180
	s_addc_u32 s99, s17, 0
	global_load_lds_dwordx4 v253, s[98:99]
	s_nop 0
	s_add_u32 m0, s32, 0xa000
	s_nop 0
	global_load_lds_dwordx4 v252, s[98:99]
	s_barrier
	s_waitcnt lgkmcnt(0)
	s_setprio 1
	s_waitcnt lgkmcnt(0)
	v_mfma_f32_16x16x32_bf16 v[60:63], v[186:189], v[160:163], v[60:63]
	v_mfma_f32_16x16x32_bf16 v[56:59], v[186:189], v[178:181], v[56:59]
	v_mfma_f32_16x16x32_bf16 v[52:55], v[194:197], v[160:163], v[52:55]
	v_mfma_f32_16x16x32_bf16 v[48:51], v[194:197], v[178:181], v[48:51]
	v_mfma_f32_16x16x32_bf16 v[44:47], v[202:205], v[160:163], v[44:47]
	v_mfma_f32_16x16x32_bf16 v[40:43], v[202:205], v[178:181], v[40:43]
	v_mfma_f32_16x16x32_bf16 v[36:39], v[210:213], v[160:163], v[36:39]
	v_mfma_f32_16x16x32_bf16 v[32:35], v[210:213], v[178:181], v[32:35]
	v_mfma_f32_16x16x32_bf16 v[60:63], v[190:193], v[164:167], v[60:63]
	v_mfma_f32_16x16x32_bf16 v[56:59], v[190:193], v[182:185], v[56:59]
	v_mfma_f32_16x16x32_bf16 v[52:55], v[198:201], v[164:167], v[52:55]
	v_mfma_f32_16x16x32_bf16 v[48:51], v[198:201], v[182:185], v[48:51]
	v_mfma_f32_16x16x32_bf16 v[44:47], v[206:209], v[164:167], v[44:47]
	v_mfma_f32_16x16x32_bf16 v[40:43], v[206:209], v[182:185], v[40:43]
	v_mfma_f32_16x16x32_bf16 v[36:39], v[214:217], v[164:167], v[36:39]
	v_mfma_f32_16x16x32_bf16 v[32:35], v[214:217], v[182:185], v[32:35]
	s_setprio 0
	s_barrier
	s_add_u32 m0, s32, 0x1c000
	s_add_u32 s98, s18, 0x40180
	s_addc_u32 s99, s19, 0
	global_load_lds_dwordx4 v253, s[98:99]
	s_add_u32 m0, s32, 0x1e000
	s_nop 0
	global_load_lds_dwordx4 v252, s[98:99]
	s_waitcnt vmcnt(6)
	s_barrier
	s_setprio 1
	v_mfma_f32_16x16x32_bf16 v[28:31], v[186:189], v[218:221], v[28:31]
	v_mfma_f32_16x16x32_bf16 v[24:27], v[186:189], v[226:229], v[24:27]
	v_mfma_f32_16x16x32_bf16 v[20:23], v[194:197], v[218:221], v[20:23]
	v_mfma_f32_16x16x32_bf16 v[16:19], v[194:197], v[226:229], v[16:19]
	v_mfma_f32_16x16x32_bf16 v[12:15], v[202:205], v[218:221], v[12:15]
	v_mfma_f32_16x16x32_bf16 v[8:11], v[202:205], v[226:229], v[8:11]
	v_mfma_f32_16x16x32_bf16 v[4:7], v[210:213], v[218:221], v[4:7]
	v_mfma_f32_16x16x32_bf16 v[0:3], v[210:213], v[226:229], v[0:3]
	v_mfma_f32_16x16x32_bf16 v[28:31], v[190:193], v[222:225], v[28:31]
	v_mfma_f32_16x16x32_bf16 v[24:27], v[190:193], v[230:233], v[24:27]
	v_mfma_f32_16x16x32_bf16 v[20:23], v[198:201], v[222:225], v[20:23]
	v_mfma_f32_16x16x32_bf16 v[16:19], v[198:201], v[230:233], v[16:19]
	v_mfma_f32_16x16x32_bf16 v[12:15], v[206:209], v[222:225], v[12:15]
	v_mfma_f32_16x16x32_bf16 v[8:11], v[206:209], v[230:233], v[8:11]
	v_mfma_f32_16x16x32_bf16 v[4:7], v[214:217], v[222:225], v[4:7]
	v_mfma_f32_16x16x32_bf16 v[0:3], v[214:217], v[230:233], v[0:3]
	s_setprio 0
	s_add_i32 s62, s62, 2
	s_add_u32 s14, s14, 0x100
	s_addc_u32 s15, s15, 0
	s_cmp_lt_u32 s62, 12
	s_barrier
; #define LDA(dst, b, h)                                                                                    \
;   _Pragma("unroll") for (int m = 0; m < 4; ++m) _Pragma("unroll") for (int k = 0; k < 2; ++k)             \
;       dst[m][k] = *reinterpret_cast<const bf16x8*>((char*)SA(b, h) + lds_byte(wr * 64 + m * 16 + fr, k * 32 + fq * 8))
; #define LDB(dst, b, h)                                                                                    \
;   _Pragma("unroll") for (int n = 0; n < 2; ++n) _Pragma("unroll") for (int k = 0; k < 2; ++k)             \
;       dst[n][k] = *reinterpret_cast<const bf16x8*>((char*)SB(b, h) + lds_byte(wc * 32 + n * 16 + fr, k * 32 + fq * 8))
; #define WAIT_V(n) asm volatile("s_waitcnt vmcnt(" #n ")" ::: "memory")
; #define WAIT_L(n) asm volatile("s_waitcnt lgkmcnt(" #n ")" ::: "memory")
; #define BAR __builtin_amdgcn_s_barrier()
; template <int EPI> ...
;     ...
;   }
;   {
;     LDB(B0, 0, 0); LDA(At, 0, 0); STAGE(SA(1, 1), A, brow + HALF, nt - 1);
;     BAR; WAIT_L(0); MMA(0, 0, At, B0); BAR;
;     LDB(B1, 0, 1); BAR; WAIT_L(0); MMA(0, 1, At, B1); BAR;
;     LDA(At, 0, 1); WAIT_V(4); BAR; WAIT_L(0); MMA(1, 0, At, B0); MMA(1, 1, At, B1); BAR;
;   }
;   {
;     LDB(B0, 1, 0); LDA(At, 1, 0); WAIT_V(2); BAR; WAIT_L(0); MMA(0, 0, At, B0); BAR;
	s_cbranch_scc1 .LBB0_141
	ds_read_b128 v[144:147], v159
	ds_read_b128 v[160:163], v159 offset:1024
	ds_read_b128 v[164:167], v159 offset:2048
	ds_read_b128 v[178:181], v159 offset:3072
	ds_read_b128 v[182:185], v138
	ds_read_b128 v[186:189], v138 offset:1024
	ds_read_b128 v[190:193], v137
	ds_read_b128 v[194:197], v137 offset:1024
	ds_read_b128 v[198:201], v136
	ds_read_b128 v[202:205], v136 offset:1024
	ds_read_b128 v[206:209], v135
	ds_read_b128 v[210:213], v135 offset:1024
	v_mov_b32_e32 v129, v149
	v_lshl_add_u64 v[128:129], v[128:129], 1, s[12:13]
	s_mov_b64 s[10:11], 0x780
	v_readfirstlane_b32 s8, v158
	v_lshl_add_u64 v[128:129], v[128:129], 0, s[10:11]
	s_mov_b32 m0, s8
	v_mov_b32_e32 v131, v149
	global_load_lds_dwordx4 v[128:129], off
	v_readfirstlane_b32 s8, v157
	v_lshl_add_u64 v[128:129], v[130:131], 1, s[12:13]
	v_lshl_add_u64 v[128:129], v[128:129], 0, s[10:11]
	s_mov_b32 m0, s8
	s_nop 0
	global_load_lds_dwordx4 v[128:129], off
	s_barrier
	s_waitcnt lgkmcnt(0)
	s_setprio 1
	s_waitcnt lgkmcnt(0)
	v_mfma_f32_16x16x32_bf16 v[124:127], v[182:185], v[144:147], v[124:127]
	v_mfma_f32_16x16x32_bf16 v[120:123], v[182:185], v[164:167], v[120:123]
	v_mfma_f32_16x16x32_bf16 v[116:119], v[190:193], v[144:147], v[116:119]
	v_mfma_f32_16x16x32_bf16 v[112:115], v[190:193], v[164:167], v[112:115]
	v_mfma_f32_16x16x32_bf16 v[108:111], v[198:201], v[144:147], v[108:111]
	v_mfma_f32_16x16x32_bf16 v[104:107], v[198:201], v[164:167], v[104:107]
	v_mfma_f32_16x16x32_bf16 v[96:99], v[206:209], v[164:167], v[96:99]
	v_mfma_f32_16x16x32_bf16 v[124:127], v[186:189], v[160:163], v[124:127]
	v_mfma_f32_16x16x32_bf16 v[120:123], v[186:189], v[178:181], v[120:123]
	v_mfma_f32_16x16x32_bf16 v[116:119], v[194:197], v[160:163], v[116:119]
	v_mfma_f32_16x16x32_bf16 v[112:115], v[194:197], v[178:181], v[112:115]
	v_mfma_f32_16x16x32_bf16 v[108:111], v[202:205], v[160:163], v[108:111]
	v_mfma_f32_16x16x32_bf16 v[104:107], v[202:205], v[178:181], v[104:107]
	v_mfma_f32_16x16x32_bf16 v[100:103], v[206:209], v[144:147], v[100:103]
	v_mfma_f32_16x16x32_bf16 v[96:99], v[210:213], v[178:181], v[96:99]
	v_mfma_f32_16x16x32_bf16 v[128:131], v[210:213], v[160:163], v[100:103]
	s_setprio 0
	s_barrier
	s_nop 3
	ds_read_b128 v[100:103], v155
	ds_read_b128 v[156:159], v155 offset:1024
	ds_read_b128 v[214:217], v155 offset:2048
	ds_read_b128 v[152:155], v155 offset:3072
	s_barrier
	s_waitcnt lgkmcnt(0)
	s_setprio 1
	s_waitcnt lgkmcnt(0)
	v_mfma_f32_16x16x32_bf16 v[88:91], v[182:185], v[214:217], v[88:91]
	v_mfma_f32_16x16x32_bf16 v[92:95], v[182:185], v[100:103], v[92:95]
	v_mfma_f32_16x16x32_bf16 v[88:91], v[186:189], v[152:155], v[88:91]
	v_mfma_f32_16x16x32_bf16 v[84:87], v[190:193], v[100:103], v[84:87]
	v_mfma_f32_16x16x32_bf16 v[80:83], v[190:193], v[214:217], v[80:83]
	v_mfma_f32_16x16x32_bf16 v[76:79], v[198:201], v[100:103], v[76:79]
	v_mfma_f32_16x16x32_bf16 v[72:75], v[198:201], v[214:217], v[72:75]
	v_mfma_f32_16x16x32_bf16 v[68:71], v[206:209], v[100:103], v[68:71]
	v_mfma_f32_16x16x32_bf16 v[64:67], v[206:209], v[214:217], v[64:67]
	v_mfma_f32_16x16x32_bf16 v[218:221], v[186:189], v[156:159], v[92:95]
	v_mfma_f32_16x16x32_bf16 v[182:185], v[194:197], v[156:159], v[84:87]
	v_mfma_f32_16x16x32_bf16 v[186:189], v[194:197], v[152:155], v[80:83]
	v_mfma_f32_16x16x32_bf16 v[190:193], v[202:205], v[156:159], v[76:79]
	v_mfma_f32_16x16x32_bf16 v[194:197], v[202:205], v[152:155], v[72:75]
	v_mfma_f32_16x16x32_bf16 v[198:201], v[210:213], v[156:159], v[68:71]
	v_mfma_f32_16x16x32_bf16 v[202:205], v[210:213], v[152:155], v[64:67]
	s_setprio 0
	s_barrier
	s_nop 0
	ds_read_b128 v[64:67], v138 offset:16384
	ds_read_b128 v[68:71], v138 offset:17408
	ds_read_b128 v[72:75], v137 offset:16384
	ds_read_b128 v[76:79], v137 offset:17408
	ds_read_b128 v[80:83], v136 offset:16384
	ds_read_b128 v[84:87], v136 offset:17408
	ds_read_b128 v[92:95], v135 offset:16384
	ds_read_b128 v[206:209], v135 offset:17408
	s_waitcnt vmcnt(4)
	s_barrier
	s_waitcnt lgkmcnt(0)
	s_setprio 1
	s_waitcnt lgkmcnt(0)
	v_mfma_f32_16x16x32_bf16 v[60:63], v[64:67], v[144:147], v[60:63]
	v_mfma_f32_16x16x32_bf16 v[56:59], v[64:67], v[164:167], v[56:59]
	v_mfma_f32_16x16x32_bf16 v[52:55], v[72:75], v[144:147], v[52:55]
	v_mfma_f32_16x16x32_bf16 v[48:51], v[72:75], v[164:167], v[48:51]
	v_mfma_f32_16x16x32_bf16 v[44:47], v[80:83], v[144:147], v[44:47]
	v_mfma_f32_16x16x32_bf16 v[40:43], v[80:83], v[164:167], v[40:43]
	v_mfma_f32_16x16x32_bf16 v[36:39], v[92:95], v[144:147], v[36:39]
	v_mfma_f32_16x16x32_bf16 v[32:35], v[92:95], v[164:167], v[32:35]
	v_mfma_f32_16x16x32_bf16 v[60:63], v[68:71], v[160:163], v[60:63]
	v_mfma_f32_16x16x32_bf16 v[56:59], v[68:71], v[178:181], v[56:59]
	v_mfma_f32_16x16x32_bf16 v[52:55], v[76:79], v[160:163], v[52:55]
	v_mfma_f32_16x16x32_bf16 v[48:51], v[76:79], v[178:181], v[48:51]
	v_mfma_f32_16x16x32_bf16 v[44:47], v[84:87], v[160:163], v[44:47]
	v_mfma_f32_16x16x32_bf16 v[40:43], v[84:87], v[178:181], v[40:43]
	v_mfma_f32_16x16x32_bf16 v[36:39], v[206:209], v[160:163], v[36:39]
	v_mfma_f32_16x16x32_bf16 v[32:35], v[206:209], v[178:181], v[32:35]
	s_setprio 0
	s_setprio 1
	v_mfma_f32_16x16x32_bf16 v[28:31], v[64:67], v[100:103], v[28:31]
	v_mfma_f32_16x16x32_bf16 v[24:27], v[64:67], v[214:217], v[24:27]
	v_mfma_f32_16x16x32_bf16 v[20:23], v[72:75], v[100:103], v[20:23]
	v_mfma_f32_16x16x32_bf16 v[16:19], v[72:75], v[214:217], v[16:19]
	v_mfma_f32_16x16x32_bf16 v[12:15], v[80:83], v[100:103], v[12:15]
	v_mfma_f32_16x16x32_bf16 v[8:11], v[80:83], v[214:217], v[8:11]
	v_mfma_f32_16x16x32_bf16 v[4:7], v[92:95], v[100:103], v[4:7]
	v_mfma_f32_16x16x32_bf16 v[0:3], v[92:95], v[214:217], v[0:3]
	v_mfma_f32_16x16x32_bf16 v[144:147], v[68:71], v[156:159], v[28:31]
	v_mfma_f32_16x16x32_bf16 v[160:163], v[68:71], v[152:155], v[24:27]
	v_mfma_f32_16x16x32_bf16 v[164:167], v[76:79], v[156:159], v[20:23]
	v_mfma_f32_16x16x32_bf16 v[178:181], v[76:79], v[152:155], v[16:19]
	v_mfma_f32_16x16x32_bf16 v[210:213], v[84:87], v[156:159], v[12:15]
	v_mfma_f32_16x16x32_bf16 v[222:225], v[84:87], v[152:155], v[8:11]
	v_mfma_f32_16x16x32_bf16 v[156:159], v[206:209], v[156:159], v[4:7]
	v_mfma_f32_16x16x32_bf16 v[152:155], v[206:209], v[152:155], v[0:3]
	s_setprio 0
	s_barrier
; #define LDA(dst, b, h)                                                                                    \
;   _Pragma("unroll") for (int m = 0; m < 4; ++m) _Pragma("unroll") for (int k = 0; k < 2; ++k)             \
;       dst[m][k] = *reinterpret_cast<const bf16x8*>((char*)SA(b, h) + lds_byte(wr * 64 + m * 16 + fr, k * 32 + fq * 8))
; #define LDB(dst, b, h)                                                                                    \
;   _Pragma("unroll") for (int n = 0; n < 2; ++n) _Pragma("unroll") for (int k = 0; k < 2; ++k)             \
;       dst[n][k] = *reinterpret_cast<const bf16x8*>((char*)SB(b, h) + lds_byte(wc * 32 + n * 16 + fr, k * 32 + fq * 8))
; #define WAIT_V(n) asm volatile("s_waitcnt vmcnt(" #n ")" ::: "memory")
; #define WAIT_L(n) asm volatile("s_waitcnt lgkmcnt(" #n ")" ::: "memory")
; #define BAR __builtin_amdgcn_s_barrier()
; template <int EPI> ...
;     ...
;     LDB(B0, 1, 0); LDA(At, 1, 0); WAIT_V(2); BAR; WAIT_L(0); MMA(0, 0, At, B0); BAR;
;     LDB(B1, 1, 1); WAIT_V(0); BAR; WAIT_L(0); MMA(0, 1, At, B1); BAR;
;     LDA(At, 1, 1); BAR; WAIT_L(0); MMA(1, 0, At, B0); MMA(1, 1, At, B1); BAR;
;   }
;   if (wr == 0) BAR;
;   if (has_next) ISSUE_PRO(nm0, nn0);
	s_nop 0
	ds_read_b128 v[0:3], v143
	ds_read_b128 v[4:7], v143 offset:1024
	ds_read_b128 v[206:209], v143 offset:2048
	ds_read_b128 v[214:217], v143 offset:3072
	ds_read_b128 v[8:11], v138 offset:32768
	ds_read_b128 v[12:15], v138 offset:33792
	ds_read_b128 v[16:19], v137 offset:32768
	ds_read_b128 v[20:23], v137 offset:33792
	ds_read_b128 v[24:27], v136 offset:32768
	ds_read_b128 v[28:31], v136 offset:33792
	ds_read_b128 v[226:229], v135 offset:32768
	ds_read_b128 v[230:233], v135 offset:33792
	s_waitcnt vmcnt(2)
	s_barrier
	s_waitcnt lgkmcnt(0)
	s_setprio 1
	s_waitcnt lgkmcnt(0)
	v_mfma_f32_16x16x32_bf16 v[64:67], v[8:11], v[0:3], v[124:127]
	v_mfma_f32_16x16x32_bf16 v[92:95], v[12:15], v[4:7], v[64:67]
	v_mfma_f32_16x16x32_bf16 v[64:67], v[8:11], v[206:209], v[120:123]
	v_mfma_f32_16x16x32_bf16 v[100:103], v[12:15], v[214:217], v[64:67]
	v_mfma_f32_16x16x32_bf16 v[64:67], v[16:19], v[0:3], v[116:119]
	v_mfma_f32_16x16x32_bf16 v[80:83], v[20:23], v[4:7], v[64:67]
	v_mfma_f32_16x16x32_bf16 v[64:67], v[16:19], v[206:209], v[112:115]
	v_mfma_f32_16x16x32_bf16 v[84:87], v[20:23], v[214:217], v[64:67]
	v_mfma_f32_16x16x32_bf16 v[64:67], v[24:27], v[0:3], v[108:111]
	v_mfma_f32_16x16x32_bf16 v[72:75], v[28:31], v[4:7], v[64:67]
	v_mfma_f32_16x16x32_bf16 v[64:67], v[24:27], v[206:209], v[104:107]
	v_mfma_f32_16x16x32_bf16 v[76:79], v[28:31], v[214:217], v[64:67]
	v_mfma_f32_16x16x32_bf16 v[64:67], v[226:229], v[0:3], v[128:131]
	v_mfma_f32_16x16x32_bf16 v[68:71], v[226:229], v[206:209], v[96:99]
	v_mfma_f32_16x16x32_bf16 v[64:67], v[230:233], v[4:7], v[64:67]
	v_mfma_f32_16x16x32_bf16 v[68:71], v[230:233], v[214:217], v[68:71]
	s_setprio 0
	s_barrier
	ds_read_b128 v[128:131], v140
	ds_read_b128 v[234:237], v140 offset:1024
	ds_read_b128 v[238:241], v140 offset:2048
	ds_read_b128 v[140:143], v140 offset:3072
	s_waitcnt vmcnt(0)
	s_barrier
	s_waitcnt lgkmcnt(0)
	s_setprio 1
	s_waitcnt lgkmcnt(0)
	v_mfma_f32_16x16x32_bf16 v[96:99], v[8:11], v[128:131], v[218:221]
	v_mfma_f32_16x16x32_bf16 v[8:11], v[8:11], v[238:241], v[88:91]
	v_mfma_f32_16x16x32_bf16 v[124:127], v[12:15], v[140:143], v[8:11]
	v_mfma_f32_16x16x32_bf16 v[8:11], v[16:19], v[128:131], v[182:185]
	v_mfma_f32_16x16x32_bf16 v[112:115], v[20:23], v[234:237], v[8:11]
	v_mfma_f32_16x16x32_bf16 v[8:11], v[16:19], v[238:241], v[186:189]
	v_mfma_f32_16x16x32_bf16 v[116:119], v[20:23], v[140:143], v[8:11]
	v_mfma_f32_16x16x32_bf16 v[8:11], v[24:27], v[128:131], v[190:193]
	v_mfma_f32_16x16x32_bf16 v[104:107], v[28:31], v[234:237], v[8:11]
	v_mfma_f32_16x16x32_bf16 v[8:11], v[24:27], v[238:241], v[194:197]
	v_mfma_f32_16x16x32_bf16 v[108:111], v[28:31], v[140:143], v[8:11]
	v_mfma_f32_16x16x32_bf16 v[8:11], v[226:229], v[128:131], v[198:201]
	v_mfma_f32_16x16x32_bf16 v[88:91], v[230:233], v[234:237], v[8:11]
	v_mfma_f32_16x16x32_bf16 v[8:11], v[226:229], v[238:241], v[202:205]
	v_mfma_f32_16x16x32_bf16 v[120:123], v[12:15], v[234:237], v[96:99]
	v_mfma_f32_16x16x32_bf16 v[96:99], v[230:233], v[140:143], v[8:11]
	s_setprio 0
	s_barrier
	ds_read_b128 v[182:185], v138 offset:49152
	ds_read_b128 v[186:189], v138 offset:50176
	ds_read_b128 v[190:193], v137 offset:49152
	ds_read_b128 v[194:197], v137 offset:50176
	ds_read_b128 v[198:201], v136 offset:49152
	ds_read_b128 v[136:139], v136 offset:50176
	ds_read_b128 v[202:205], v135 offset:49152
	ds_read_b128 v[218:221], v135 offset:50176
	s_barrier
	s_waitcnt lgkmcnt(0)
	s_setprio 1
	s_waitcnt lgkmcnt(0)
	v_mfma_f32_16x16x32_bf16 v[8:11], v[182:185], v[0:3], v[60:63]
	v_mfma_f32_16x16x32_bf16 v[24:27], v[186:189], v[4:7], v[8:11]
	v_mfma_f32_16x16x32_bf16 v[8:11], v[182:185], v[206:209], v[56:59]
	v_mfma_f32_16x16x32_bf16 v[28:31], v[186:189], v[214:217], v[8:11]
	v_mfma_f32_16x16x32_bf16 v[8:11], v[190:193], v[0:3], v[52:55]
	v_mfma_f32_16x16x32_bf16 v[16:19], v[194:197], v[4:7], v[8:11]
	v_mfma_f32_16x16x32_bf16 v[8:11], v[190:193], v[206:209], v[48:51]
	v_mfma_f32_16x16x32_bf16 v[20:23], v[194:197], v[214:217], v[8:11]
	v_mfma_f32_16x16x32_bf16 v[8:11], v[198:201], v[0:3], v[44:47]
	v_mfma_f32_16x16x32_bf16 v[0:3], v[202:205], v[0:3], v[36:39]
	v_mfma_f32_16x16x32_bf16 v[8:11], v[136:139], v[4:7], v[8:11]
	v_mfma_f32_16x16x32_bf16 v[12:15], v[198:201], v[206:209], v[40:43]
	v_mfma_f32_16x16x32_bf16 v[0:3], v[218:221], v[4:7], v[0:3]
	v_mfma_f32_16x16x32_bf16 v[4:7], v[202:205], v[206:209], v[32:35]
	v_mfma_f32_16x16x32_bf16 v[12:15], v[136:139], v[214:217], v[12:15]
	v_mfma_f32_16x16x32_bf16 v[4:7], v[218:221], v[214:217], v[4:7]
	s_setprio 0
	s_setprio 1
	v_mfma_f32_16x16x32_bf16 v[32:35], v[182:185], v[128:131], v[144:147]
	v_mfma_f32_16x16x32_bf16 v[56:59], v[186:189], v[234:237], v[32:35]
	v_mfma_f32_16x16x32_bf16 v[32:35], v[182:185], v[238:241], v[160:163]
	v_mfma_f32_16x16x32_bf16 v[60:63], v[186:189], v[140:143], v[32:35]
	v_mfma_f32_16x16x32_bf16 v[32:35], v[190:193], v[128:131], v[164:167]
	v_mfma_f32_16x16x32_bf16 v[48:51], v[194:197], v[234:237], v[32:35]
	v_mfma_f32_16x16x32_bf16 v[32:35], v[190:193], v[238:241], v[178:181]
	v_mfma_f32_16x16x32_bf16 v[52:55], v[194:197], v[140:143], v[32:35]
	v_mfma_f32_16x16x32_bf16 v[32:35], v[198:201], v[128:131], v[210:213]
	v_mfma_f32_16x16x32_bf16 v[40:43], v[136:139], v[234:237], v[32:35]
	v_mfma_f32_16x16x32_bf16 v[32:35], v[198:201], v[238:241], v[222:225]
	v_mfma_f32_16x16x32_bf16 v[44:47], v[136:139], v[140:143], v[32:35]
	v_mfma_f32_16x16x32_bf16 v[32:35], v[202:205], v[128:131], v[156:159]
	v_mfma_f32_16x16x32_bf16 v[36:39], v[202:205], v[238:241], v[152:155]
	v_mfma_f32_16x16x32_bf16 v[32:35], v[218:221], v[234:237], v[32:35]
	v_mfma_f32_16x16x32_bf16 v[36:39], v[218:221], v[140:143], v[36:39]
	s_setprio 0
	s_cmpk_gt_u32 s34, 0xff
	s_barrier
	s_cbranch_scc1 .LBB0_135
	s_barrier
	s_branch .LBB0_135

; DEVI f32x4 ozero() { float z = 0.f; asm volatile("" : "+v"(z)); return f32x4{z, z, z, z}; }
; #define LDA(dst, b, h)                                                                                    \
;   _Pragma("unroll") for (int m = 0; m < 4; ++m) _Pragma("unroll") for (int k = 0; k < 2; ++k)             \
;       dst[m][k] = *reinterpret_cast<const bf16x8*>((char*)SA(b, h) + lds_byte(wr * 64 + m * 16 + fr, k * 32 + fq * 8))
; #define LDB(dst, b, h)                                                                                    \
;   _Pragma("unroll") for (int n = 0; n < 2; ++n) _Pragma("unroll") for (int k = 0; k < 2; ++k)             \
;       dst[n][k] = *reinterpret_cast<const bf16x8*>((char*)SB(b, h) + lds_byte(wc * 32 + n * 16 + fr, k * 32 + fq * 8))
; #define WAIT_V(n) asm volatile("s_waitcnt vmcnt(" #n ")" ::: "memory")
; #define WAIT_L(n) asm volatile("s_waitcnt lgkmcnt(" #n ")" ::: "memory")
; #define BAR __builtin_amdgcn_s_barrier()
; #define SCHED __builtin_amdgcn_sched_barrier(0)
; template <int EPI> ...
;     ...
;   const int brow = m0, bcol = n0;
;   const int wid = __builtin_amdgcn_readfirstlane(tid >> 6), lane = tid & 63, wr = wid >> 2, wc = wid & 3, fr = lane & 15, fq = lane >> 4;
;   f32x4 acc[2][2][4][2];
;   {
;     const f32x4 zq = ozero();
; #pragma unroll
;     for (int a_ = 0; a_ < 2; ++a_)
; #pragma unroll
;       for (int b_ = 0; b_ < 2; ++b_)
; #pragma unroll
;         for (int m = 0; m < 4; ++m) { acc[a_][b_][m][0] = zq; acc[a_][b_][m][1] = zq; }
;   }
;   bf16x8 At[4][2], B0[2][2], B1[2][2];
;   const int nt = K / BK;
;     ...
;   if (first) {
;     WAIT_V(0);
;     ISSUE_PRO(brow, bcol);
;   }
;   if (wr == 1) BAR;
;   WAIT_V(10); BAR;
;   WAIT_V(6); BAR;
;   for (int t = 0; t < nt - 2; t += 2) {
;     LDB(B0, 0, 0); SCHED; LDA(At, 0, 0); STAGE(SA(1, 1), A, brow + HALF, t + 1);
;     WAIT_L(8); BAR; WAIT_L(0); MMA(0, 0, At, B0); BAR; SCHED;
.LBB0_165:
	v_and_b32_e32 v133, 15, v132
	v_and_b32_e32 v1, 48, v132
	v_lshlrev_b32_e32 v2, 6, v133
	v_lshlrev_b32_e32 v4, 2, v132
	v_or_b32_e32 v3, v2, v1
	v_and_b32_e32 v4, 32, v4
	s_mov_b32 s20, 0x10000
	v_bitop3_b32 v5, v3, s20, v4 bitop3:0xde
	s_mov_b32 s20, 0x14000
	s_ashr_i32 s68, s62, 6
	v_bitop3_b32 v6, v3, s20, v4 bitop3:0xde
	s_mov_b32 s20, 0x18000
	s_and_b32 s64, s68, 3
	s_waitcnt vmcnt(10)
	s_barrier
	s_waitcnt vmcnt(6)
	v_bitop3_b32 v7, v3, s20, v4 bitop3:0xde
	s_mov_b32 s20, 0x1c000
	v_lshlrev_b32_e32 v8, 6, v132
	s_lshl_b32 s23, s64, 12
	v_bitop3_b32 v2, v2, v4, v1 bitop3:0x36
	s_lshl_b32 s65, s22, 6
	v_bitop3_b32 v3, v3, s20, v4 bitop3:0xde
	s_lshl_b32 s22, s22, 13
	v_and_b32_e32 v8, 0x3c0, v8
	s_ashr_i32 s63, s34, 31
	v_bitop3_b32 v154, v8, v4, v1 bitop3:0x36
	s_or_b32 s66, s22, 0x800
	s_or_b32 s67, s22, 0x1000
	s_or_b32 s69, s22, 0x1800
	s_mov_b32 s70, -2
	s_mov_b64 s[20:21], 0
	v_add_u32_e32 v155, s23, v5
	v_add_u32_e32 v135, s22, v2
	v_add_u32_e32 v152, s23, v6
	v_add_u32_e32 v140, s23, v7
	v_add_u32_e32 v137, s23, v3
	v_mov_b32_e32 v1, v0
	v_mov_b32_e32 v2, v0
	v_mov_b32_e32 v3, v0
	v_mov_b32_e32 v4, v0
	v_mov_b32_e32 v5, v0
	v_mov_b32_e32 v6, v0
	v_mov_b32_e32 v7, v0
	v_mov_b32_e32 v8, v0
	v_mov_b32_e32 v9, v0
	v_mov_b32_e32 v10, v0
	v_mov_b32_e32 v11, v0
	v_mov_b32_e32 v12, v0
	v_mov_b32_e32 v13, v0
	v_mov_b32_e32 v14, v0
	v_mov_b32_e32 v15, v0
	v_mov_b32_e32 v16, v0
	v_mov_b32_e32 v17, v0
	v_mov_b32_e32 v18, v0
	v_mov_b32_e32 v19, v0
	v_mov_b32_e32 v20, v0
	v_mov_b32_e32 v21, v0
	v_mov_b32_e32 v22, v0
	v_mov_b32_e32 v23, v0
	v_mov_b32_e32 v24, v0
	v_mov_b32_e32 v25, v0
	v_mov_b32_e32 v26, v0
	v_mov_b32_e32 v27, v0
	v_mov_b32_e32 v28, v0
	v_mov_b32_e32 v29, v0
	v_mov_b32_e32 v30, v0
	v_mov_b32_e32 v31, v0
	v_mov_b32_e32 v32, v0
	v_mov_b32_e32 v33, v0
	v_mov_b32_e32 v34, v0
	v_mov_b32_e32 v35, v0
	v_mov_b32_e32 v36, v0
	v_mov_b32_e32 v37, v0
	v_mov_b32_e32 v38, v0
	v_mov_b32_e32 v39, v0
	v_mov_b32_e32 v40, v0
	v_mov_b32_e32 v41, v0
	v_mov_b32_e32 v42, v0
	v_mov_b32_e32 v43, v0
	v_mov_b32_e32 v44, v0
	v_mov_b32_e32 v45, v0
	v_mov_b32_e32 v46, v0
	v_mov_b32_e32 v47, v0
	v_mov_b32_e32 v48, v0
	v_mov_b32_e32 v49, v0
	v_mov_b32_e32 v50, v0
	v_mov_b32_e32 v51, v0
	v_mov_b32_e32 v52, v0
	v_mov_b32_e32 v53, v0
	v_mov_b32_e32 v54, v0
	v_mov_b32_e32 v55, v0
	v_mov_b32_e32 v56, v0
	v_mov_b32_e32 v57, v0
	v_mov_b32_e32 v58, v0
	v_mov_b32_e32 v59, v0
	v_mov_b32_e32 v60, v0
	v_mov_b32_e32 v61, v0
	v_mov_b32_e32 v62, v0
	v_mov_b32_e32 v63, v0
	v_mov_b32_e32 v64, v0
	v_mov_b32_e32 v65, v0
	v_mov_b32_e32 v66, v0
	v_mov_b32_e32 v67, v0
	v_mov_b32_e32 v68, v0
	v_mov_b32_e32 v69, v0
	v_mov_b32_e32 v70, v0
	v_mov_b32_e32 v71, v0
	v_mov_b32_e32 v72, v0
	v_mov_b32_e32 v73, v0
	v_mov_b32_e32 v74, v0
	v_mov_b32_e32 v75, v0
	v_mov_b32_e32 v76, v0
	v_mov_b32_e32 v77, v0
	v_mov_b32_e32 v78, v0
	v_mov_b32_e32 v79, v0
	v_mov_b32_e32 v80, v0
	v_mov_b32_e32 v81, v0
	v_mov_b32_e32 v82, v0
	v_mov_b32_e32 v83, v0
	v_mov_b32_e32 v84, v0
	v_mov_b32_e32 v85, v0
	v_mov_b32_e32 v86, v0
	v_mov_b32_e32 v87, v0
	v_mov_b32_e32 v88, v0
	v_mov_b32_e32 v89, v0
	v_mov_b32_e32 v90, v0
	v_mov_b32_e32 v91, v0
	v_mov_b32_e32 v92, v0
	v_mov_b32_e32 v93, v0
	v_mov_b32_e32 v94, v0
	v_mov_b32_e32 v95, v0
	v_mov_b32_e32 v96, v0
	v_mov_b32_e32 v97, v0
	v_mov_b32_e32 v98, v0
	v_mov_b32_e32 v99, v0
	v_mov_b32_e32 v100, v0
	v_mov_b32_e32 v101, v0
	v_mov_b32_e32 v102, v0
	v_mov_b32_e32 v103, v0
	v_mov_b32_e32 v104, v0
	v_mov_b32_e32 v105, v0
	v_mov_b32_e32 v106, v0
	v_mov_b32_e32 v107, v0
	v_mov_b32_e32 v108, v0
	v_mov_b32_e32 v109, v0
	v_mov_b32_e32 v110, v0
	v_mov_b32_e32 v111, v0
	v_mov_b32_e32 v112, v0
	v_mov_b32_e32 v113, v0
	v_mov_b32_e32 v114, v0
	v_mov_b32_e32 v115, v0
	v_mov_b32_e32 v116, v0
	v_mov_b32_e32 v117, v0
	v_mov_b32_e32 v118, v0
	v_mov_b32_e32 v119, v0
	v_mov_b32_e32 v120, v0
	v_mov_b32_e32 v121, v0
	v_mov_b32_e32 v122, v0
	v_mov_b32_e32 v123, v0
	v_mov_b32_e32 v124, v0
	v_mov_b32_e32 v125, v0
	v_mov_b32_e32 v126, v0
	v_mov_b32_e32 v127, v0
	s_barrier
	v_lshlrev_b32_e32 v253, 1, v128
	v_lshlrev_b32_e32 v252, 1, v130
	v_readfirstlane_b32 s32, v129
.LBB0_166:
	ds_read_b128 v[162:165], v155
	ds_read_b128 v[178:181], v155 offset:1024
	ds_read_b128 v[182:185], v155 offset:2048
	ds_read_b128 v[186:189], v155 offset:3072
	s_add_u32 s22, s4, s20
	v_add_u32_e32 v156, s66, v154
	v_add_u32_e32 v157, s67, v154
	v_add_u32_e32 v158, s69, v154
	s_addc_u32 s23, s5, s21
	v_add_u32_e32 v159, 0xc000, v129
	ds_read_b128 v[190:193], v135
	ds_read_b128 v[194:197], v135 offset:1024
	ds_read_b128 v[198:201], v156
	ds_read_b128 v[202:205], v156 offset:1024
	ds_read_b128 v[206:209], v157
	ds_read_b128 v[210:213], v157 offset:1024
	ds_read_b128 v[214:217], v158
	ds_read_b128 v[218:221], v158 offset:1024
	s_add_u32 m0, s32, 0xc000
	s_add_u32 s98, s22, 0xb0080
	s_addc_u32 s99, s23, 0
	global_load_lds_dwordx4 v253, s[98:99]
	s_nop 0
	v_add_u32_e32 v160, 0xe000, v129
	s_nop 0
	s_add_u32 m0, s32, 0xe000
	s_nop 0
	global_load_lds_dwordx4 v252, s[98:99]
	s_waitcnt lgkmcnt(8)
	s_barrier
; #define LDA(dst, b, h)                                                                                    \
;   _Pragma("unroll") for (int m = 0; m < 4; ++m) _Pragma("unroll") for (int k = 0; k < 2; ++k)             \
;       dst[m][k] = *reinterpret_cast<const bf16x8*>((char*)SA(b, h) + lds_byte(wr * 64 + m * 16 + fr, k * 32 + fq * 8))
; #define LDB(dst, b, h)                                                                                    \
;   _Pragma("unroll") for (int n = 0; n < 2; ++n) _Pragma("unroll") for (int k = 0; k < 2; ++k)             \
;       dst[n][k] = *reinterpret_cast<const bf16x8*>((char*)SB(b, h) + lds_byte(wc * 32 + n * 16 + fr, k * 32 + fq * 8))
; #define WAIT_V(n) asm volatile("s_waitcnt vmcnt(" #n ")" ::: "memory")
; #define WAIT_L(n) asm volatile("s_waitcnt lgkmcnt(" #n ")" ::: "memory")
; #define BAR __builtin_amdgcn_s_barrier()
; #define SCHED __builtin_amdgcn_sched_barrier(0)
; template <int EPI> ...
;     ...
;     LDB(B1, 0, 1); STAGE(SB(0, 0), Bt, bcol, t + 2);
;     BAR; WAIT_L(0); MMA(0, 1, At, B1); BAR;
;     LDA(At, 0, 1); STAGE(SA(0, 0), A, brow, t + 2);
;     BAR; WAIT_L(0); MMA(1, 0, At, B0); BAR; SCHED;
;     STAGE(SB(0, 1), Bt, bcol + HALF, t + 2);
;     WAIT_V(6); BAR; MMA(1, 1, At, B1); BAR;
;     LDB(B0, 1, 0); SCHED; LDA(At, 1, 0); STAGE(SA(0, 1), A, brow + HALF, t + 2);
;     WAIT_L(8); BAR; WAIT_L(0); MMA(0, 0, At, B0); BAR; SCHED;
	s_waitcnt lgkmcnt(0)
	s_setprio 1
	s_waitcnt lgkmcnt(0)
	v_mfma_f32_16x16x32_bf16 v[124:127], v[190:193], v[162:165], v[124:127]
	v_mfma_f32_16x16x32_bf16 v[120:123], v[190:193], v[182:185], v[120:123]
	v_mfma_f32_16x16x32_bf16 v[116:119], v[198:201], v[162:165], v[116:119]
	v_mfma_f32_16x16x32_bf16 v[112:115], v[198:201], v[182:185], v[112:115]
	v_mfma_f32_16x16x32_bf16 v[108:111], v[206:209], v[162:165], v[108:111]
	v_mfma_f32_16x16x32_bf16 v[104:107], v[206:209], v[182:185], v[104:107]
	v_mfma_f32_16x16x32_bf16 v[100:103], v[214:217], v[162:165], v[100:103]
	v_mfma_f32_16x16x32_bf16 v[96:99], v[214:217], v[182:185], v[96:99]
	v_mfma_f32_16x16x32_bf16 v[124:127], v[194:197], v[178:181], v[124:127]
	v_mfma_f32_16x16x32_bf16 v[120:123], v[194:197], v[186:189], v[120:123]
	v_mfma_f32_16x16x32_bf16 v[116:119], v[202:205], v[178:181], v[116:119]
	v_mfma_f32_16x16x32_bf16 v[112:115], v[202:205], v[186:189], v[112:115]
	v_mfma_f32_16x16x32_bf16 v[108:111], v[210:213], v[178:181], v[108:111]
	v_mfma_f32_16x16x32_bf16 v[104:107], v[210:213], v[186:189], v[104:107]
	v_mfma_f32_16x16x32_bf16 v[100:103], v[218:221], v[178:181], v[100:103]
	v_mfma_f32_16x16x32_bf16 v[96:99], v[218:221], v[186:189], v[96:99]
	s_setprio 0
	s_barrier
	s_add_u32 s30, s0, s20
	s_addc_u32 s31, s1, s21
	ds_read_b128 v[222:225], v152
	ds_read_b128 v[226:229], v152 offset:1024
	ds_read_b128 v[230:233], v152 offset:2048
	ds_read_b128 v[234:237], v152 offset:3072
	s_add_u32 m0, s32, 0x10000
	s_add_u32 s98, s30, 0x100
	s_addc_u32 s99, s31, 0
	global_load_lds_dwordx4 v253, s[98:99]
	s_add_u32 m0, s32, 0x12000
	s_nop 0
	global_load_lds_dwordx4 v252, s[98:99]
	s_barrier
	s_waitcnt lgkmcnt(0)
	s_setprio 1
	s_waitcnt lgkmcnt(0)
	v_mfma_f32_16x16x32_bf16 v[92:95], v[190:193], v[222:225], v[92:95]
	v_mfma_f32_16x16x32_bf16 v[88:91], v[190:193], v[230:233], v[88:91]
	v_mfma_f32_16x16x32_bf16 v[84:87], v[198:201], v[222:225], v[84:87]
	v_mfma_f32_16x16x32_bf16 v[80:83], v[198:201], v[230:233], v[80:83]
	v_mfma_f32_16x16x32_bf16 v[76:79], v[206:209], v[222:225], v[76:79]
	v_mfma_f32_16x16x32_bf16 v[72:75], v[206:209], v[230:233], v[72:75]
	v_mfma_f32_16x16x32_bf16 v[68:71], v[214:217], v[222:225], v[68:71]
	v_mfma_f32_16x16x32_bf16 v[64:67], v[214:217], v[230:233], v[64:67]
	v_mfma_f32_16x16x32_bf16 v[92:95], v[194:197], v[226:229], v[92:95]
	v_mfma_f32_16x16x32_bf16 v[88:91], v[194:197], v[234:237], v[88:91]
	v_mfma_f32_16x16x32_bf16 v[84:87], v[202:205], v[226:229], v[84:87]
	v_mfma_f32_16x16x32_bf16 v[80:83], v[202:205], v[234:237], v[80:83]
	v_mfma_f32_16x16x32_bf16 v[76:79], v[210:213], v[226:229], v[76:79]
	v_mfma_f32_16x16x32_bf16 v[72:75], v[210:213], v[234:237], v[72:75]
	v_mfma_f32_16x16x32_bf16 v[68:71], v[218:221], v[226:229], v[68:71]
	v_mfma_f32_16x16x32_bf16 v[64:67], v[218:221], v[234:237], v[64:67]
	s_setprio 0
	s_barrier
	ds_read_b128 v[190:193], v135 offset:16384
	ds_read_b128 v[194:197], v135 offset:17408
	ds_read_b128 v[198:201], v156 offset:16384
	ds_read_b128 v[202:205], v156 offset:17408
	ds_read_b128 v[206:209], v157 offset:16384
	ds_read_b128 v[210:213], v157 offset:17408
	ds_read_b128 v[214:217], v158 offset:16384
	ds_read_b128 v[218:221], v158 offset:17408
	s_mov_b32 m0, s32
	s_add_u32 s98, s22, 0x100
	s_addc_u32 s99, s23, 0
	global_load_lds_dwordx4 v253, s[98:99]
	s_add_u32 m0, s32, 0x2000
	s_nop 0
	global_load_lds_dwordx4 v252, s[98:99]
	s_barrier
	s_waitcnt lgkmcnt(0)
	s_setprio 1
	s_waitcnt lgkmcnt(0)
	v_mfma_f32_16x16x32_bf16 v[60:63], v[190:193], v[162:165], v[60:63]
	v_mfma_f32_16x16x32_bf16 v[56:59], v[190:193], v[182:185], v[56:59]
	v_mfma_f32_16x16x32_bf16 v[52:55], v[198:201], v[162:165], v[52:55]
	v_mfma_f32_16x16x32_bf16 v[48:51], v[198:201], v[182:185], v[48:51]
	v_mfma_f32_16x16x32_bf16 v[44:47], v[206:209], v[162:165], v[44:47]
	v_mfma_f32_16x16x32_bf16 v[40:43], v[206:209], v[182:185], v[40:43]
	v_mfma_f32_16x16x32_bf16 v[36:39], v[214:217], v[162:165], v[36:39]
	v_mfma_f32_16x16x32_bf16 v[32:35], v[214:217], v[182:185], v[32:35]
	v_mfma_f32_16x16x32_bf16 v[60:63], v[194:197], v[178:181], v[60:63]
	v_mfma_f32_16x16x32_bf16 v[56:59], v[194:197], v[186:189], v[56:59]
	v_mfma_f32_16x16x32_bf16 v[52:55], v[202:205], v[178:181], v[52:55]
	v_mfma_f32_16x16x32_bf16 v[48:51], v[202:205], v[186:189], v[48:51]
	v_mfma_f32_16x16x32_bf16 v[44:47], v[210:213], v[178:181], v[44:47]
	v_mfma_f32_16x16x32_bf16 v[40:43], v[210:213], v[186:189], v[40:43]
	v_mfma_f32_16x16x32_bf16 v[36:39], v[218:221], v[178:181], v[36:39]
	v_mfma_f32_16x16x32_bf16 v[32:35], v[218:221], v[186:189], v[32:35]
	s_setprio 0
	s_barrier
	s_add_u32 m0, s32, 0x14000
	s_add_u32 s98, s30, 0xb0100
	s_addc_u32 s99, s31, 0
	global_load_lds_dwordx4 v253, s[98:99]
	s_add_u32 m0, s32, 0x16000
	s_nop 0
	global_load_lds_dwordx4 v252, s[98:99]
	s_waitcnt vmcnt(6)
	s_barrier
	s_setprio 1
	v_mfma_f32_16x16x32_bf16 v[28:31], v[190:193], v[222:225], v[28:31]
	v_mfma_f32_16x16x32_bf16 v[24:27], v[190:193], v[230:233], v[24:27]
	v_mfma_f32_16x16x32_bf16 v[20:23], v[198:201], v[222:225], v[20:23]
	v_mfma_f32_16x16x32_bf16 v[16:19], v[198:201], v[230:233], v[16:19]
	v_mfma_f32_16x16x32_bf16 v[12:15], v[206:209], v[222:225], v[12:15]
	v_mfma_f32_16x16x32_bf16 v[8:11], v[206:209], v[230:233], v[8:11]
	v_mfma_f32_16x16x32_bf16 v[4:7], v[214:217], v[222:225], v[4:7]
	v_mfma_f32_16x16x32_bf16 v[0:3], v[214:217], v[230:233], v[0:3]
	v_mfma_f32_16x16x32_bf16 v[28:31], v[194:197], v[226:229], v[28:31]
	v_mfma_f32_16x16x32_bf16 v[24:27], v[194:197], v[234:237], v[24:27]
	v_mfma_f32_16x16x32_bf16 v[20:23], v[202:205], v[226:229], v[20:23]
	v_mfma_f32_16x16x32_bf16 v[16:19], v[202:205], v[234:237], v[16:19]
	v_mfma_f32_16x16x32_bf16 v[12:15], v[210:213], v[226:229], v[12:15]
	v_mfma_f32_16x16x32_bf16 v[8:11], v[210:213], v[234:237], v[8:11]
	v_mfma_f32_16x16x32_bf16 v[4:7], v[218:221], v[226:229], v[4:7]
	v_mfma_f32_16x16x32_bf16 v[0:3], v[218:221], v[234:237], v[0:3]
	s_setprio 0
	s_barrier
; #define LDA(dst, b, h)                                                                                    \
;   _Pragma("unroll") for (int m = 0; m < 4; ++m) _Pragma("unroll") for (int k = 0; k < 2; ++k)             \
;       dst[m][k] = *reinterpret_cast<const bf16x8*>((char*)SA(b, h) + lds_byte(wr * 64 + m * 16 + fr, k * 32 + fq * 8))
; #define LDB(dst, b, h)                                                                                    \
;   _Pragma("unroll") for (int n = 0; n < 2; ++n) _Pragma("unroll") for (int k = 0; k < 2; ++k)             \
;       dst[n][k] = *reinterpret_cast<const bf16x8*>((char*)SB(b, h) + lds_byte(wc * 32 + n * 16 + fr, k * 32 + fq * 8))
; #define WAIT_V(n) asm volatile("s_waitcnt vmcnt(" #n ")" ::: "memory")
; #define WAIT_L(n) asm volatile("s_waitcnt lgkmcnt(" #n ")" ::: "memory")
; #define BAR __builtin_amdgcn_s_barrier()
; #define SCHED __builtin_amdgcn_sched_barrier(0)
; template <int EPI> ...
;     ...
;     WAIT_L(8); BAR; WAIT_L(0); MMA(0, 0, At, B0); BAR; SCHED;
;     LDB(B1, 1, 1); STAGE(SB(1, 0), Bt, bcol, t + 3);
;     BAR; WAIT_L(0); MMA(0, 1, At, B1); BAR;
;     LDA(At, 1, 1); STAGE(SA(1, 0), A, brow, t + 3);
;     BAR; WAIT_L(0); MMA(1, 0, At, B0); BAR; SCHED;
;     STAGE(SB(1, 1), Bt, bcol + HALF, t + 3);
;     WAIT_V(6); BAR; MMA(1, 1, At, B1); BAR;
;   }
	ds_read_b128 v[162:165], v140
	ds_read_b128 v[178:181], v140 offset:1024
	ds_read_b128 v[182:185], v140 offset:2048
	ds_read_b128 v[186:189], v140 offset:3072
	ds_read_b128 v[190:193], v135 offset:32768
	ds_read_b128 v[194:197], v135 offset:33792
	ds_read_b128 v[198:201], v156 offset:32768
	ds_read_b128 v[202:205], v156 offset:33792
	ds_read_b128 v[206:209], v157 offset:32768
	ds_read_b128 v[210:213], v157 offset:33792
	ds_read_b128 v[214:217], v158 offset:32768
	ds_read_b128 v[218:221], v158 offset:33792
	s_add_u32 m0, s32, 0x4000
	s_add_u32 s98, s22, 0xb0100
	s_addc_u32 s99, s23, 0
	global_load_lds_dwordx4 v253, s[98:99]
	s_add_u32 m0, s32, 0x6000
	s_nop 0
	global_load_lds_dwordx4 v252, s[98:99]
	s_waitcnt lgkmcnt(8)
	s_barrier
	s_waitcnt lgkmcnt(0)
	s_setprio 1
	s_waitcnt lgkmcnt(0)
	v_mfma_f32_16x16x32_bf16 v[124:127], v[190:193], v[162:165], v[124:127]
	v_mfma_f32_16x16x32_bf16 v[120:123], v[190:193], v[182:185], v[120:123]
	v_mfma_f32_16x16x32_bf16 v[116:119], v[198:201], v[162:165], v[116:119]
	v_mfma_f32_16x16x32_bf16 v[112:115], v[198:201], v[182:185], v[112:115]
	v_mfma_f32_16x16x32_bf16 v[108:111], v[206:209], v[162:165], v[108:111]
	v_mfma_f32_16x16x32_bf16 v[104:107], v[206:209], v[182:185], v[104:107]
	v_mfma_f32_16x16x32_bf16 v[100:103], v[214:217], v[162:165], v[100:103]
	v_mfma_f32_16x16x32_bf16 v[96:99], v[214:217], v[182:185], v[96:99]
	v_mfma_f32_16x16x32_bf16 v[124:127], v[194:197], v[178:181], v[124:127]
	v_mfma_f32_16x16x32_bf16 v[120:123], v[194:197], v[186:189], v[120:123]
	v_mfma_f32_16x16x32_bf16 v[116:119], v[202:205], v[178:181], v[116:119]
	v_mfma_f32_16x16x32_bf16 v[112:115], v[202:205], v[186:189], v[112:115]
	v_mfma_f32_16x16x32_bf16 v[108:111], v[210:213], v[178:181], v[108:111]
	v_mfma_f32_16x16x32_bf16 v[104:107], v[210:213], v[186:189], v[104:107]
	v_mfma_f32_16x16x32_bf16 v[100:103], v[218:221], v[178:181], v[100:103]
	v_mfma_f32_16x16x32_bf16 v[96:99], v[218:221], v[186:189], v[96:99]
	s_setprio 0
	s_barrier
	ds_read_b128 v[222:225], v137
	ds_read_b128 v[226:229], v137 offset:1024
	ds_read_b128 v[230:233], v137 offset:2048
	ds_read_b128 v[234:237], v137 offset:3072
	s_add_u32 m0, s32, 0x18000
	s_add_u32 s98, s30, 0x180
	s_addc_u32 s99, s31, 0
	global_load_lds_dwordx4 v253, s[98:99]
	s_add_u32 m0, s32, 0x1a000
	s_nop 0
	global_load_lds_dwordx4 v252, s[98:99]
	s_barrier
	s_waitcnt lgkmcnt(0)
	s_setprio 1
	s_waitcnt lgkmcnt(0)
	v_mfma_f32_16x16x32_bf16 v[92:95], v[190:193], v[222:225], v[92:95]
	v_mfma_f32_16x16x32_bf16 v[88:91], v[190:193], v[230:233], v[88:91]
	v_mfma_f32_16x16x32_bf16 v[84:87], v[198:201], v[222:225], v[84:87]
	v_mfma_f32_16x16x32_bf16 v[80:83], v[198:201], v[230:233], v[80:83]
	v_mfma_f32_16x16x32_bf16 v[76:79], v[206:209], v[222:225], v[76:79]
	v_mfma_f32_16x16x32_bf16 v[72:75], v[206:209], v[230:233], v[72:75]
	v_mfma_f32_16x16x32_bf16 v[68:71], v[214:217], v[222:225], v[68:71]
	v_mfma_f32_16x16x32_bf16 v[64:67], v[214:217], v[230:233], v[64:67]
	v_mfma_f32_16x16x32_bf16 v[92:95], v[194:197], v[226:229], v[92:95]
	v_mfma_f32_16x16x32_bf16 v[88:91], v[194:197], v[234:237], v[88:91]
	v_mfma_f32_16x16x32_bf16 v[84:87], v[202:205], v[226:229], v[84:87]
	v_mfma_f32_16x16x32_bf16 v[80:83], v[202:205], v[234:237], v[80:83]
	v_mfma_f32_16x16x32_bf16 v[76:79], v[210:213], v[226:229], v[76:79]
	v_mfma_f32_16x16x32_bf16 v[72:75], v[210:213], v[234:237], v[72:75]
	v_mfma_f32_16x16x32_bf16 v[68:71], v[218:221], v[226:229], v[68:71]
	v_mfma_f32_16x16x32_bf16 v[64:67], v[218:221], v[234:237], v[64:67]
	s_setprio 0
	s_barrier
	ds_read_b128 v[190:193], v135 offset:49152
	ds_read_b128 v[194:197], v135 offset:50176
	ds_read_b128 v[198:201], v156 offset:49152
	ds_read_b128 v[202:205], v156 offset:50176
	ds_read_b128 v[206:209], v157 offset:49152
	ds_read_b128 v[210:213], v157 offset:50176
	ds_read_b128 v[214:217], v158 offset:49152
	ds_read_b128 v[218:221], v158 offset:50176
	s_add_u32 m0, s32, 0x8000
	s_add_u32 s98, s22, 0x180
	s_addc_u32 s99, s23, 0
	global_load_lds_dwordx4 v253, s[98:99]
	s_nop 0
	s_add_u32 m0, s32, 0xa000
	s_nop 0
	global_load_lds_dwordx4 v252, s[98:99]
	s_barrier
	s_waitcnt lgkmcnt(0)
	s_setprio 1
	s_waitcnt lgkmcnt(0)
	v_mfma_f32_16x16x32_bf16 v[60:63], v[190:193], v[162:165], v[60:63]
	v_mfma_f32_16x16x32_bf16 v[56:59], v[190:193], v[182:185], v[56:59]
	v_mfma_f32_16x16x32_bf16 v[52:55], v[198:201], v[162:165], v[52:55]
	v_mfma_f32_16x16x32_bf16 v[48:51], v[198:201], v[182:185], v[48:51]
	v_mfma_f32_16x16x32_bf16 v[44:47], v[206:209], v[162:165], v[44:47]
	v_mfma_f32_16x16x32_bf16 v[40:43], v[206:209], v[182:185], v[40:43]
	v_mfma_f32_16x16x32_bf16 v[36:39], v[214:217], v[162:165], v[36:39]
	v_mfma_f32_16x16x32_bf16 v[32:35], v[214:217], v[182:185], v[32:35]
	v_mfma_f32_16x16x32_bf16 v[60:63], v[194:197], v[178:181], v[60:63]
	v_mfma_f32_16x16x32_bf16 v[56:59], v[194:197], v[186:189], v[56:59]
	v_mfma_f32_16x16x32_bf16 v[52:55], v[202:205], v[178:181], v[52:55]
	v_mfma_f32_16x16x32_bf16 v[48:51], v[202:205], v[186:189], v[48:51]
	v_mfma_f32_16x16x32_bf16 v[44:47], v[210:213], v[178:181], v[44:47]
	v_mfma_f32_16x16x32_bf16 v[40:43], v[210:213], v[186:189], v[40:43]
	v_mfma_f32_16x16x32_bf16 v[36:39], v[218:221], v[178:181], v[36:39]
	v_mfma_f32_16x16x32_bf16 v[32:35], v[218:221], v[186:189], v[32:35]
	s_setprio 0
	s_barrier
	s_add_u32 m0, s32, 0x1c000
	s_add_u32 s98, s30, 0xb0180
	s_addc_u32 s99, s31, 0
	global_load_lds_dwordx4 v253, s[98:99]
	s_add_u32 m0, s32, 0x1e000
	s_nop 0
	global_load_lds_dwordx4 v252, s[98:99]
	s_waitcnt vmcnt(6)
	s_barrier
; #define LDA(dst, b, h)                                                                                    \
;   _Pragma("unroll") for (int m = 0; m < 4; ++m) _Pragma("unroll") for (int k = 0; k < 2; ++k)             \
;       dst[m][k] = *reinterpret_cast<const bf16x8*>((char*)SA(b, h) + lds_byte(wr * 64 + m * 16 + fr, k * 32 + fq * 8))
; #define LDB(dst, b, h)                                                                                    \
;   _Pragma("unroll") for (int n = 0; n < 2; ++n) _Pragma("unroll") for (int k = 0; k < 2; ++k)             \
;       dst[n][k] = *reinterpret_cast<const bf16x8*>((char*)SB(b, h) + lds_byte(wc * 32 + n * 16 + fr, k * 32 + fq * 8))
; #define WAIT_V(n) asm volatile("s_waitcnt vmcnt(" #n ")" ::: "memory")
; #define WAIT_L(n) asm volatile("s_waitcnt lgkmcnt(" #n ")" ::: "memory")
; #define BAR __builtin_amdgcn_s_barrier()
; template <int EPI> ...
;     ...
;     WAIT_V(6); BAR; MMA(1, 1, At, B1); BAR;
;   }
;   {
;     LDB(B0, 0, 0); LDA(At, 0, 0); STAGE(SA(1, 1), A, brow + HALF, nt - 1);
;     BAR; WAIT_L(0); MMA(0, 0, At, B0); BAR;
;     LDB(B1, 0, 1); BAR; WAIT_L(0); MMA(0, 1, At, B1); BAR;
;     LDA(At, 0, 1); WAIT_V(4); BAR; WAIT_L(0); MMA(1, 0, At, B0); MMA(1, 1, At, B1); BAR;
;   }
;   {
;     LDB(B0, 1, 0); LDA(At, 1, 0); WAIT_V(2); BAR; WAIT_L(0); MMA(0, 0, At, B0); BAR;
	s_setprio 1
	v_mfma_f32_16x16x32_bf16 v[28:31], v[190:193], v[222:225], v[28:31]
	v_mfma_f32_16x16x32_bf16 v[24:27], v[190:193], v[230:233], v[24:27]
	v_mfma_f32_16x16x32_bf16 v[20:23], v[198:201], v[222:225], v[20:23]
	v_mfma_f32_16x16x32_bf16 v[16:19], v[198:201], v[230:233], v[16:19]
	v_mfma_f32_16x16x32_bf16 v[12:15], v[206:209], v[222:225], v[12:15]
	v_mfma_f32_16x16x32_bf16 v[8:11], v[206:209], v[230:233], v[8:11]
	v_mfma_f32_16x16x32_bf16 v[4:7], v[214:217], v[222:225], v[4:7]
	v_mfma_f32_16x16x32_bf16 v[0:3], v[214:217], v[230:233], v[0:3]
	v_mfma_f32_16x16x32_bf16 v[28:31], v[194:197], v[226:229], v[28:31]
	v_mfma_f32_16x16x32_bf16 v[24:27], v[194:197], v[234:237], v[24:27]
	v_mfma_f32_16x16x32_bf16 v[20:23], v[202:205], v[226:229], v[20:23]
	v_mfma_f32_16x16x32_bf16 v[16:19], v[202:205], v[234:237], v[16:19]
	v_mfma_f32_16x16x32_bf16 v[12:15], v[210:213], v[226:229], v[12:15]
	v_mfma_f32_16x16x32_bf16 v[8:11], v[210:213], v[234:237], v[8:11]
	v_mfma_f32_16x16x32_bf16 v[4:7], v[218:221], v[226:229], v[4:7]
	v_mfma_f32_16x16x32_bf16 v[0:3], v[218:221], v[234:237], v[0:3]
	s_setprio 0
	s_add_i32 s70, s70, 2
	s_add_u32 s20, s20, 0x100
	s_addc_u32 s21, s21, 0
	s_cmp_lt_u32 s70, 40
	s_barrier
	s_cbranch_scc1 .LBB0_166
	s_add_u32 s0, s18, 0x1580
	ds_read_b128 v[142:145], v155
	ds_read_b128 v[162:165], v155 offset:1024
	ds_read_b128 v[178:181], v155 offset:2048
	ds_read_b128 v[182:185], v155 offset:3072
	ds_read_b128 v[186:189], v135
	ds_read_b128 v[190:193], v135 offset:1024
	ds_read_b128 v[194:197], v156
	ds_read_b128 v[198:201], v156 offset:1024
	ds_read_b128 v[202:205], v157
	ds_read_b128 v[206:209], v157 offset:1024
	ds_read_b128 v[210:213], v158
	ds_read_b128 v[214:217], v158 offset:1024
	s_addc_u32 s1, s19, 0
	v_mov_b32_e32 v129, v149
	v_readfirstlane_b32 s4, v159
	v_lshl_add_u64 v[128:129], v[128:129], 1, s[0:1]
	s_mov_b32 m0, s4
	v_mov_b32_e32 v131, v149
	global_load_lds_dwordx4 v[128:129], off
	s_nop 0
	v_lshl_add_u64 v[128:129], v[130:131], 1, s[0:1]
	v_readfirstlane_b32 s0, v160
	s_mov_b32 m0, s0
	s_nop 0
	global_load_lds_dwordx4 v[128:129], off
	s_barrier
	s_waitcnt lgkmcnt(0)
	s_setprio 1
	s_waitcnt lgkmcnt(0)
	v_mfma_f32_16x16x32_bf16 v[124:127], v[186:189], v[142:145], v[124:127]
	v_mfma_f32_16x16x32_bf16 v[120:123], v[186:189], v[178:181], v[120:123]
	v_mfma_f32_16x16x32_bf16 v[116:119], v[194:197], v[142:145], v[116:119]
	v_mfma_f32_16x16x32_bf16 v[112:115], v[194:197], v[178:181], v[112:115]
	v_mfma_f32_16x16x32_bf16 v[108:111], v[202:205], v[142:145], v[108:111]
	v_mfma_f32_16x16x32_bf16 v[104:107], v[202:205], v[178:181], v[104:107]
	v_mfma_f32_16x16x32_bf16 v[96:99], v[210:213], v[178:181], v[96:99]
	v_mfma_f32_16x16x32_bf16 v[124:127], v[190:193], v[162:165], v[124:127]
	v_mfma_f32_16x16x32_bf16 v[120:123], v[190:193], v[182:185], v[120:123]
	v_mfma_f32_16x16x32_bf16 v[116:119], v[198:201], v[162:165], v[116:119]
	v_mfma_f32_16x16x32_bf16 v[112:115], v[198:201], v[182:185], v[112:115]
	v_mfma_f32_16x16x32_bf16 v[108:111], v[206:209], v[162:165], v[108:111]
	v_mfma_f32_16x16x32_bf16 v[104:107], v[206:209], v[182:185], v[104:107]
	v_mfma_f32_16x16x32_bf16 v[100:103], v[210:213], v[142:145], v[100:103]
	v_mfma_f32_16x16x32_bf16 v[96:99], v[214:217], v[182:185], v[96:99]
	v_mfma_f32_16x16x32_bf16 v[128:131], v[214:217], v[162:165], v[100:103]
	s_setprio 0
	s_barrier
	s_nop 3
	ds_read_b128 v[100:103], v152
	ds_read_b128 v[218:221], v152 offset:1024
	ds_read_b128 v[222:225], v152 offset:2048
	ds_read_b128 v[152:155], v152 offset:3072
	s_barrier
	s_waitcnt lgkmcnt(0)
	s_setprio 1
	s_waitcnt lgkmcnt(0)
	v_mfma_f32_16x16x32_bf16 v[88:91], v[186:189], v[222:225], v[88:91]
	v_mfma_f32_16x16x32_bf16 v[92:95], v[186:189], v[100:103], v[92:95]
	v_mfma_f32_16x16x32_bf16 v[88:91], v[190:193], v[152:155], v[88:91]
	v_mfma_f32_16x16x32_bf16 v[84:87], v[194:197], v[100:103], v[84:87]
	v_mfma_f32_16x16x32_bf16 v[80:83], v[194:197], v[222:225], v[80:83]
	v_mfma_f32_16x16x32_bf16 v[76:79], v[202:205], v[100:103], v[76:79]
	v_mfma_f32_16x16x32_bf16 v[72:75], v[202:205], v[222:225], v[72:75]
	v_mfma_f32_16x16x32_bf16 v[68:71], v[210:213], v[100:103], v[68:71]
	v_mfma_f32_16x16x32_bf16 v[64:67], v[210:213], v[222:225], v[64:67]
	v_mfma_f32_16x16x32_bf16 v[226:229], v[190:193], v[218:221], v[92:95]
	v_mfma_f32_16x16x32_bf16 v[186:189], v[198:201], v[218:221], v[84:87]
	v_mfma_f32_16x16x32_bf16 v[190:193], v[198:201], v[152:155], v[80:83]
	v_mfma_f32_16x16x32_bf16 v[194:197], v[206:209], v[218:221], v[76:79]
	v_mfma_f32_16x16x32_bf16 v[198:201], v[206:209], v[152:155], v[72:75]
	v_mfma_f32_16x16x32_bf16 v[202:205], v[214:217], v[218:221], v[68:71]
	v_mfma_f32_16x16x32_bf16 v[206:209], v[214:217], v[152:155], v[64:67]
	s_setprio 0
	s_barrier
	s_nop 0
	ds_read_b128 v[64:67], v135 offset:16384
	ds_read_b128 v[68:71], v135 offset:17408
	ds_read_b128 v[72:75], v156 offset:16384
	ds_read_b128 v[76:79], v156 offset:17408
	ds_read_b128 v[80:83], v157 offset:16384
	ds_read_b128 v[84:87], v157 offset:17408
	ds_read_b128 v[92:95], v158 offset:16384
	ds_read_b128 v[210:213], v158 offset:17408
	s_waitcnt vmcnt(4)
	s_barrier
; #define LDA(dst, b, h)                                                                                    \
;   _Pragma("unroll") for (int m = 0; m < 4; ++m) _Pragma("unroll") for (int k = 0; k < 2; ++k)             \
;       dst[m][k] = *reinterpret_cast<const bf16x8*>((char*)SA(b, h) + lds_byte(wr * 64 + m * 16 + fr, k * 32 + fq * 8))
; #define LDB(dst, b, h)                                                                                    \
;   _Pragma("unroll") for (int n = 0; n < 2; ++n) _Pragma("unroll") for (int k = 0; k < 2; ++k)             \
;       dst[n][k] = *reinterpret_cast<const bf16x8*>((char*)SB(b, h) + lds_byte(wc * 32 + n * 16 + fr, k * 32 + fq * 8))
; #define WAIT_V(n) asm volatile("s_waitcnt vmcnt(" #n ")" ::: "memory")
; #define WAIT_L(n) asm volatile("s_waitcnt lgkmcnt(" #n ")" ::: "memory")
; #define BAR __builtin_amdgcn_s_barrier()
; template <int EPI> ...
;     ...
;     LDB(B0, 1, 0); LDA(At, 1, 0); WAIT_V(2); BAR; WAIT_L(0); MMA(0, 0, At, B0); BAR;
;     LDB(B1, 1, 1); WAIT_V(0); BAR; WAIT_L(0); MMA(0, 1, At, B1); BAR;
;     LDA(At, 1, 1); BAR; WAIT_L(0); MMA(1, 0, At, B0); MMA(1, 1, At, B1); BAR;
	s_waitcnt lgkmcnt(0)
	s_setprio 1
	s_waitcnt lgkmcnt(0)
	v_mfma_f32_16x16x32_bf16 v[60:63], v[64:67], v[142:145], v[60:63]
	v_mfma_f32_16x16x32_bf16 v[56:59], v[64:67], v[178:181], v[56:59]
	v_mfma_f32_16x16x32_bf16 v[52:55], v[72:75], v[142:145], v[52:55]
	v_mfma_f32_16x16x32_bf16 v[48:51], v[72:75], v[178:181], v[48:51]
	v_mfma_f32_16x16x32_bf16 v[44:47], v[80:83], v[142:145], v[44:47]
	v_mfma_f32_16x16x32_bf16 v[40:43], v[80:83], v[178:181], v[40:43]
	v_mfma_f32_16x16x32_bf16 v[36:39], v[92:95], v[142:145], v[36:39]
	v_mfma_f32_16x16x32_bf16 v[32:35], v[92:95], v[178:181], v[32:35]
	v_mfma_f32_16x16x32_bf16 v[60:63], v[68:71], v[162:165], v[60:63]
	v_mfma_f32_16x16x32_bf16 v[56:59], v[68:71], v[182:185], v[56:59]
	v_mfma_f32_16x16x32_bf16 v[52:55], v[76:79], v[162:165], v[52:55]
	v_mfma_f32_16x16x32_bf16 v[48:51], v[76:79], v[182:185], v[48:51]
	v_mfma_f32_16x16x32_bf16 v[44:47], v[84:87], v[162:165], v[44:47]
	v_mfma_f32_16x16x32_bf16 v[40:43], v[84:87], v[182:185], v[40:43]
	v_mfma_f32_16x16x32_bf16 v[36:39], v[210:213], v[162:165], v[36:39]
	v_mfma_f32_16x16x32_bf16 v[32:35], v[210:213], v[182:185], v[32:35]
	s_setprio 0
	s_setprio 1
	v_mfma_f32_16x16x32_bf16 v[28:31], v[64:67], v[100:103], v[28:31]
	v_mfma_f32_16x16x32_bf16 v[24:27], v[64:67], v[222:225], v[24:27]
	v_mfma_f32_16x16x32_bf16 v[20:23], v[72:75], v[100:103], v[20:23]
	v_mfma_f32_16x16x32_bf16 v[16:19], v[72:75], v[222:225], v[16:19]
	v_mfma_f32_16x16x32_bf16 v[12:15], v[80:83], v[100:103], v[12:15]
	v_mfma_f32_16x16x32_bf16 v[8:11], v[80:83], v[222:225], v[8:11]
	v_mfma_f32_16x16x32_bf16 v[4:7], v[92:95], v[100:103], v[4:7]
	v_mfma_f32_16x16x32_bf16 v[0:3], v[92:95], v[222:225], v[0:3]
	v_mfma_f32_16x16x32_bf16 v[142:145], v[68:71], v[218:221], v[28:31]
	v_mfma_f32_16x16x32_bf16 v[160:163], v[68:71], v[152:155], v[24:27]
	v_mfma_f32_16x16x32_bf16 v[164:167], v[76:79], v[218:221], v[20:23]
	v_mfma_f32_16x16x32_bf16 v[178:181], v[76:79], v[152:155], v[16:19]
	v_mfma_f32_16x16x32_bf16 v[182:185], v[84:87], v[218:221], v[12:15]
	v_mfma_f32_16x16x32_bf16 v[214:217], v[84:87], v[152:155], v[8:11]
	v_mfma_f32_16x16x32_bf16 v[218:221], v[210:213], v[218:221], v[4:7]
	v_mfma_f32_16x16x32_bf16 v[152:155], v[210:213], v[152:155], v[0:3]
	s_setprio 0
	s_barrier
	s_nop 0
	ds_read_b128 v[0:3], v140
	ds_read_b128 v[4:7], v140 offset:1024
	ds_read_b128 v[210:213], v140 offset:2048
	ds_read_b128 v[138:141], v140 offset:3072
	ds_read_b128 v[8:11], v135 offset:32768
	ds_read_b128 v[12:15], v135 offset:33792
	ds_read_b128 v[16:19], v156 offset:32768
	ds_read_b128 v[20:23], v156 offset:33792
	ds_read_b128 v[24:27], v157 offset:32768
	ds_read_b128 v[28:31], v157 offset:33792
	ds_read_b128 v[222:225], v158 offset:32768
	ds_read_b128 v[230:233], v158 offset:33792
	s_waitcnt vmcnt(2)
	s_barrier
	s_waitcnt lgkmcnt(0)
	s_setprio 1
	s_waitcnt lgkmcnt(0)
	v_mfma_f32_16x16x32_bf16 v[64:67], v[8:11], v[0:3], v[124:127]
	v_mfma_f32_16x16x32_bf16 v[92:95], v[12:15], v[4:7], v[64:67]
	v_mfma_f32_16x16x32_bf16 v[64:67], v[8:11], v[210:213], v[120:123]
	v_mfma_f32_16x16x32_bf16 v[100:103], v[12:15], v[138:141], v[64:67]
	v_mfma_f32_16x16x32_bf16 v[64:67], v[16:19], v[0:3], v[116:119]
	v_mfma_f32_16x16x32_bf16 v[80:83], v[20:23], v[4:7], v[64:67]
	v_mfma_f32_16x16x32_bf16 v[64:67], v[16:19], v[210:213], v[112:115]
	v_mfma_f32_16x16x32_bf16 v[84:87], v[20:23], v[138:141], v[64:67]
	v_mfma_f32_16x16x32_bf16 v[64:67], v[24:27], v[0:3], v[108:111]
	v_mfma_f32_16x16x32_bf16 v[72:75], v[28:31], v[4:7], v[64:67]
	v_mfma_f32_16x16x32_bf16 v[64:67], v[24:27], v[210:213], v[104:107]
	v_mfma_f32_16x16x32_bf16 v[76:79], v[28:31], v[138:141], v[64:67]
	v_mfma_f32_16x16x32_bf16 v[64:67], v[222:225], v[0:3], v[128:131]
	v_mfma_f32_16x16x32_bf16 v[68:71], v[222:225], v[210:213], v[96:99]
	v_mfma_f32_16x16x32_bf16 v[64:67], v[230:233], v[4:7], v[64:67]
	v_mfma_f32_16x16x32_bf16 v[68:71], v[230:233], v[138:141], v[68:71]
	s_setprio 0
	s_barrier
; #define LDA(dst, b, h)                                                                                    \
;   _Pragma("unroll") for (int m = 0; m < 4; ++m) _Pragma("unroll") for (int k = 0; k < 2; ++k)             \
;       dst[m][k] = *reinterpret_cast<const bf16x8*>((char*)SA(b, h) + lds_byte(wr * 64 + m * 16 + fr, k * 32 + fq * 8))
; #define LDB(dst, b, h)                                                                                    \
;   _Pragma("unroll") for (int n = 0; n < 2; ++n) _Pragma("unroll") for (int k = 0; k < 2; ++k)             \
;       dst[n][k] = *reinterpret_cast<const bf16x8*>((char*)SB(b, h) + lds_byte(wc * 32 + n * 16 + fr, k * 32 + fq * 8))
; #define WAIT_V(n) asm volatile("s_waitcnt vmcnt(" #n ")" ::: "memory")
; #define WAIT_L(n) asm volatile("s_waitcnt lgkmcnt(" #n ")" ::: "memory")
; #define BAR __builtin_amdgcn_s_barrier()
; template <int EPI> ...
;     ...
;     LDB(B1, 1, 1); WAIT_V(0); BAR; WAIT_L(0); MMA(0, 1, At, B1); BAR;
;     LDA(At, 1, 1); BAR; WAIT_L(0); MMA(1, 0, At, B0); MMA(1, 1, At, B1); BAR;
;   }
;   if (wr == 0) BAR;
;   if (has_next) ISSUE_PRO(nm0, nn0);
	ds_read_b128 v[128:131], v137
	ds_read_b128 v[234:237], v137 offset:1024
	ds_read_b128 v[238:241], v137 offset:2048
	ds_read_b128 v[242:245], v137 offset:3072
	s_waitcnt vmcnt(0)
	s_barrier
	s_waitcnt lgkmcnt(0)
	s_setprio 1
	s_waitcnt lgkmcnt(0)
	v_mfma_f32_16x16x32_bf16 v[96:99], v[8:11], v[128:131], v[226:229]
	v_mfma_f32_16x16x32_bf16 v[8:11], v[8:11], v[238:241], v[88:91]
	v_mfma_f32_16x16x32_bf16 v[124:127], v[12:15], v[242:245], v[8:11]
	v_mfma_f32_16x16x32_bf16 v[8:11], v[16:19], v[128:131], v[186:189]
	v_mfma_f32_16x16x32_bf16 v[112:115], v[20:23], v[234:237], v[8:11]
	v_mfma_f32_16x16x32_bf16 v[8:11], v[16:19], v[238:241], v[190:193]
	v_mfma_f32_16x16x32_bf16 v[116:119], v[20:23], v[242:245], v[8:11]
	v_mfma_f32_16x16x32_bf16 v[8:11], v[24:27], v[128:131], v[194:197]
	v_mfma_f32_16x16x32_bf16 v[104:107], v[28:31], v[234:237], v[8:11]
	v_mfma_f32_16x16x32_bf16 v[8:11], v[24:27], v[238:241], v[198:201]
	v_mfma_f32_16x16x32_bf16 v[108:111], v[28:31], v[242:245], v[8:11]
	v_mfma_f32_16x16x32_bf16 v[8:11], v[222:225], v[128:131], v[202:205]
	v_mfma_f32_16x16x32_bf16 v[88:91], v[230:233], v[234:237], v[8:11]
	v_mfma_f32_16x16x32_bf16 v[8:11], v[222:225], v[238:241], v[206:209]
	v_mfma_f32_16x16x32_bf16 v[120:123], v[12:15], v[234:237], v[96:99]
	v_mfma_f32_16x16x32_bf16 v[96:99], v[230:233], v[242:245], v[8:11]
	s_setprio 0
	s_barrier
	ds_read_b128 v[186:189], v135 offset:49152
	ds_read_b128 v[134:137], v135 offset:50176
	ds_read_b128 v[190:193], v156 offset:49152
	ds_read_b128 v[194:197], v156 offset:50176
	ds_read_b128 v[198:201], v157 offset:49152
	ds_read_b128 v[202:205], v157 offset:50176
	ds_read_b128 v[206:209], v158 offset:49152
	ds_read_b128 v[156:159], v158 offset:50176
	s_barrier
	s_waitcnt lgkmcnt(0)
	s_setprio 1
	s_waitcnt lgkmcnt(0)
	v_mfma_f32_16x16x32_bf16 v[8:11], v[186:189], v[0:3], v[60:63]
	v_mfma_f32_16x16x32_bf16 v[24:27], v[134:137], v[4:7], v[8:11]
	v_mfma_f32_16x16x32_bf16 v[8:11], v[186:189], v[210:213], v[56:59]
	v_mfma_f32_16x16x32_bf16 v[28:31], v[134:137], v[138:141], v[8:11]
	v_mfma_f32_16x16x32_bf16 v[8:11], v[190:193], v[0:3], v[52:55]
	v_mfma_f32_16x16x32_bf16 v[16:19], v[194:197], v[4:7], v[8:11]
	v_mfma_f32_16x16x32_bf16 v[8:11], v[190:193], v[210:213], v[48:51]
	v_mfma_f32_16x16x32_bf16 v[20:23], v[194:197], v[138:141], v[8:11]
	v_mfma_f32_16x16x32_bf16 v[8:11], v[198:201], v[0:3], v[44:47]
	v_mfma_f32_16x16x32_bf16 v[0:3], v[206:209], v[0:3], v[36:39]
	v_mfma_f32_16x16x32_bf16 v[8:11], v[202:205], v[4:7], v[8:11]
	v_mfma_f32_16x16x32_bf16 v[12:15], v[198:201], v[210:213], v[40:43]
	v_mfma_f32_16x16x32_bf16 v[0:3], v[156:159], v[4:7], v[0:3]
	v_mfma_f32_16x16x32_bf16 v[4:7], v[206:209], v[210:213], v[32:35]
	v_mfma_f32_16x16x32_bf16 v[12:15], v[202:205], v[138:141], v[12:15]
	v_mfma_f32_16x16x32_bf16 v[4:7], v[156:159], v[138:141], v[4:7]
	s_setprio 0
	s_setprio 1
	v_mfma_f32_16x16x32_bf16 v[32:35], v[186:189], v[128:131], v[142:145]
	v_mfma_f32_16x16x32_bf16 v[56:59], v[134:137], v[234:237], v[32:35]
	v_mfma_f32_16x16x32_bf16 v[32:35], v[186:189], v[238:241], v[160:163]
	v_mfma_f32_16x16x32_bf16 v[60:63], v[134:137], v[242:245], v[32:35]
	v_mfma_f32_16x16x32_bf16 v[32:35], v[190:193], v[128:131], v[164:167]
	v_mfma_f32_16x16x32_bf16 v[48:51], v[194:197], v[234:237], v[32:35]
	v_mfma_f32_16x16x32_bf16 v[32:35], v[190:193], v[238:241], v[178:181]
	v_mfma_f32_16x16x32_bf16 v[52:55], v[194:197], v[242:245], v[32:35]
	v_mfma_f32_16x16x32_bf16 v[32:35], v[198:201], v[128:131], v[182:185]
	v_mfma_f32_16x16x32_bf16 v[40:43], v[202:205], v[234:237], v[32:35]
	v_mfma_f32_16x16x32_bf16 v[32:35], v[198:201], v[238:241], v[214:217]
	v_mfma_f32_16x16x32_bf16 v[44:47], v[202:205], v[242:245], v[32:35]
	v_mfma_f32_16x16x32_bf16 v[32:35], v[206:209], v[128:131], v[218:221]
	v_mfma_f32_16x16x32_bf16 v[36:39], v[206:209], v[238:241], v[152:155]
	v_mfma_f32_16x16x32_bf16 v[32:35], v[156:159], v[234:237], v[32:35]
	v_mfma_f32_16x16x32_bf16 v[36:39], v[156:159], v[242:245], v[36:39]
	s_setprio 0
	s_cmpk_gt_u32 s62, 0xff
	s_barrier
	s_cbranch_scc1 .LBB0_169
	s_barrier

; DEVI f32x4 ozero() { float z = 0.f; asm volatile("" : "+v"(z)); return f32x4{z, z, z, z}; }
; #define LDA(dst, b, h)                                                                                    \
;   _Pragma("unroll") for (int m = 0; m < 4; ++m) _Pragma("unroll") for (int k = 0; k < 2; ++k)             \
;       dst[m][k] = *reinterpret_cast<const bf16x8*>((char*)SA(b, h) + lds_byte(wr * 64 + m * 16 + fr, k * 32 + fq * 8))
; #define LDB(dst, b, h)                                                                                    \
;   _Pragma("unroll") for (int n = 0; n < 2; ++n) _Pragma("unroll") for (int k = 0; k < 2; ++k)             \
;       dst[n][k] = *reinterpret_cast<const bf16x8*>((char*)SB(b, h) + lds_byte(wc * 32 + n * 16 + fr, k * 32 + fq * 8))
; #define WAIT_V(n) asm volatile("s_waitcnt vmcnt(" #n ")" ::: "memory")
; #define WAIT_L(n) asm volatile("s_waitcnt lgkmcnt(" #n ")" ::: "memory")
; #define BAR __builtin_amdgcn_s_barrier()
; #define SCHED __builtin_amdgcn_sched_barrier(0)
; template <int EPI> ...
;     ...
;   const int brow = m0, bcol = n0;
;   const int wid = __builtin_amdgcn_readfirstlane(tid >> 6), lane = tid & 63, wr = wid >> 2, wc = wid & 3, fr = lane & 15, fq = lane >> 4;
;   f32x4 acc[2][2][4][2];
;   {
;     const f32x4 zq = ozero();
; #pragma unroll
;     for (int a_ = 0; a_ < 2; ++a_)
; #pragma unroll
;       for (int b_ = 0; b_ < 2; ++b_)
; #pragma unroll
;         for (int m = 0; m < 4; ++m) { acc[a_][b_][m][0] = zq; acc[a_][b_][m][1] = zq; }
;   }
;   bf16x8 At[4][2], B0[2][2], B1[2][2];
;   const int nt = K / BK;
;     ...
;   if (first) {
;     WAIT_V(0);
;     ISSUE_PRO(brow, bcol);
;   }
;   if (wr == 1) BAR;
;   WAIT_V(10); BAR;
;   WAIT_V(6); BAR;
;   for (int t = 0; t < nt - 2; t += 2) {
;     LDB(B0, 0, 0); SCHED; LDA(At, 0, 0); STAGE(SA(1, 1), A, brow + HALF, t + 1);
;     WAIT_L(8); BAR; WAIT_L(0); MMA(0, 0, At, B0); BAR; SCHED;
.LBB0_415:
	v_and_b32_e32 v132, 15, v133
	v_and_b32_e32 v1, 48, v133
	v_lshlrev_b32_e32 v2, 6, v132
	v_lshlrev_b32_e32 v4, 2, v133
	v_or_b32_e32 v3, v2, v1
	v_and_b32_e32 v4, 32, v4
	s_mov_b32 s12, 0x10000
	v_bitop3_b32 v5, v3, s12, v4 bitop3:0xde
	s_mov_b32 s12, 0x14000
	s_ashr_i32 s1, s62, 6
	v_bitop3_b32 v6, v3, s12, v4 bitop3:0xde
	s_mov_b32 s12, 0x18000
	s_and_b32 s5, s1, 3
	s_waitcnt vmcnt(10)
	s_barrier
	s_waitcnt vmcnt(6)
	v_bitop3_b32 v7, v3, s12, v4 bitop3:0xde
	s_mov_b32 s12, 0x1c000
	v_lshlrev_b32_e32 v8, 6, v133
	s_lshl_b32 s15, s5, 12
	v_bitop3_b32 v2, v2, v4, v1 bitop3:0x36
	s_lshl_b32 s63, s14, 6
	v_bitop3_b32 v3, v3, s12, v4 bitop3:0xde
	s_lshl_b32 s14, s14, 13
	v_and_b32_e32 v8, 0x3c0, v8
	v_bitop3_b32 v154, v8, v4, v1 bitop3:0x36
	s_or_b32 s64, s14, 0x800
	s_or_b32 s65, s14, 0x1000
	s_or_b32 s66, s14, 0x1800
	s_mov_b32 s67, -2
	s_mov_b64 s[12:13], 0
	v_add_u32_e32 v155, s15, v5
	v_add_u32_e32 v135, s14, v2
	v_add_u32_e32 v152, s15, v6
	v_add_u32_e32 v140, s15, v7
	v_add_u32_e32 v137, s15, v3
	v_mov_b32_e32 v1, v0
	v_mov_b32_e32 v2, v0
	v_mov_b32_e32 v3, v0
	v_mov_b32_e32 v4, v0
	v_mov_b32_e32 v5, v0
	v_mov_b32_e32 v6, v0
	v_mov_b32_e32 v7, v0
	v_mov_b32_e32 v8, v0
	v_mov_b32_e32 v9, v0
	v_mov_b32_e32 v10, v0
	v_mov_b32_e32 v11, v0
	v_mov_b32_e32 v12, v0
	v_mov_b32_e32 v13, v0
	v_mov_b32_e32 v14, v0
	v_mov_b32_e32 v15, v0
	v_mov_b32_e32 v16, v0
	v_mov_b32_e32 v17, v0
	v_mov_b32_e32 v18, v0
	v_mov_b32_e32 v19, v0
	v_mov_b32_e32 v20, v0
	v_mov_b32_e32 v21, v0
	v_mov_b32_e32 v22, v0
	v_mov_b32_e32 v23, v0
	v_mov_b32_e32 v24, v0
	v_mov_b32_e32 v25, v0
	v_mov_b32_e32 v26, v0
	v_mov_b32_e32 v27, v0
	v_mov_b32_e32 v28, v0
	v_mov_b32_e32 v29, v0
	v_mov_b32_e32 v30, v0
	v_mov_b32_e32 v31, v0
	v_mov_b32_e32 v32, v0
	v_mov_b32_e32 v33, v0
	v_mov_b32_e32 v34, v0
	v_mov_b32_e32 v35, v0
	v_mov_b32_e32 v36, v0
	v_mov_b32_e32 v37, v0
	v_mov_b32_e32 v38, v0
	v_mov_b32_e32 v39, v0
	v_mov_b32_e32 v40, v0
	v_mov_b32_e32 v41, v0
	v_mov_b32_e32 v42, v0
	v_mov_b32_e32 v43, v0
	v_mov_b32_e32 v44, v0
	v_mov_b32_e32 v45, v0
	v_mov_b32_e32 v46, v0
	v_mov_b32_e32 v47, v0
	v_mov_b32_e32 v48, v0
	v_mov_b32_e32 v49, v0
	v_mov_b32_e32 v50, v0
	v_mov_b32_e32 v51, v0
	v_mov_b32_e32 v52, v0
	v_mov_b32_e32 v53, v0
	v_mov_b32_e32 v54, v0
	v_mov_b32_e32 v55, v0
	v_mov_b32_e32 v56, v0
	v_mov_b32_e32 v57, v0
	v_mov_b32_e32 v58, v0
	v_mov_b32_e32 v59, v0
	v_mov_b32_e32 v60, v0
	v_mov_b32_e32 v61, v0
	v_mov_b32_e32 v62, v0
	v_mov_b32_e32 v63, v0
	v_mov_b32_e32 v64, v0
	v_mov_b32_e32 v65, v0
	v_mov_b32_e32 v66, v0
	v_mov_b32_e32 v67, v0
	v_mov_b32_e32 v68, v0
	v_mov_b32_e32 v69, v0
	v_mov_b32_e32 v70, v0
	v_mov_b32_e32 v71, v0
	v_mov_b32_e32 v72, v0
	v_mov_b32_e32 v73, v0
	v_mov_b32_e32 v74, v0
	v_mov_b32_e32 v75, v0
	v_mov_b32_e32 v76, v0
	v_mov_b32_e32 v77, v0
	v_mov_b32_e32 v78, v0
	v_mov_b32_e32 v79, v0
	v_mov_b32_e32 v80, v0
	v_mov_b32_e32 v81, v0
	v_mov_b32_e32 v82, v0
	v_mov_b32_e32 v83, v0
	v_mov_b32_e32 v84, v0
	v_mov_b32_e32 v85, v0
	v_mov_b32_e32 v86, v0
	v_mov_b32_e32 v87, v0
	v_mov_b32_e32 v88, v0
	v_mov_b32_e32 v89, v0
	v_mov_b32_e32 v90, v0
	v_mov_b32_e32 v91, v0
	v_mov_b32_e32 v92, v0
	v_mov_b32_e32 v93, v0
	v_mov_b32_e32 v94, v0
	v_mov_b32_e32 v95, v0
	v_mov_b32_e32 v96, v0
	v_mov_b32_e32 v97, v0
	v_mov_b32_e32 v98, v0
	v_mov_b32_e32 v99, v0
	v_mov_b32_e32 v100, v0
	v_mov_b32_e32 v101, v0
	v_mov_b32_e32 v102, v0
	v_mov_b32_e32 v103, v0
	v_mov_b32_e32 v104, v0
	v_mov_b32_e32 v105, v0
	v_mov_b32_e32 v106, v0
	v_mov_b32_e32 v107, v0
	v_mov_b32_e32 v108, v0
	v_mov_b32_e32 v109, v0
	v_mov_b32_e32 v110, v0
	v_mov_b32_e32 v111, v0
	v_mov_b32_e32 v112, v0
	v_mov_b32_e32 v113, v0
	v_mov_b32_e32 v114, v0
	v_mov_b32_e32 v115, v0
	v_mov_b32_e32 v116, v0
	v_mov_b32_e32 v117, v0
	v_mov_b32_e32 v118, v0
	v_mov_b32_e32 v119, v0
	v_mov_b32_e32 v120, v0
	v_mov_b32_e32 v121, v0
	v_mov_b32_e32 v122, v0
	v_mov_b32_e32 v123, v0
	v_mov_b32_e32 v124, v0
	v_mov_b32_e32 v125, v0
	v_mov_b32_e32 v126, v0
	v_mov_b32_e32 v127, v0
	s_barrier
	v_lshlrev_b32_e32 v253, 1, v128
	v_lshlrev_b32_e32 v252, 1, v130
	v_readfirstlane_b32 s32, v129
.LBB0_416:
	ds_read_b128 v[162:165], v155
	ds_read_b128 v[178:181], v155 offset:1024
	ds_read_b128 v[182:185], v155 offset:2048
	ds_read_b128 v[186:189], v155 offset:3072
	s_add_u32 s14, s8, s12
	v_add_u32_e32 v156, s64, v154
	v_add_u32_e32 v157, s65, v154
	v_add_u32_e32 v158, s66, v154
	s_addc_u32 s15, s9, s13
	ds_read_b128 v[190:193], v135
	ds_read_b128 v[194:197], v135 offset:1024
	ds_read_b128 v[198:201], v156
	ds_read_b128 v[202:205], v156 offset:1024
	ds_read_b128 v[206:209], v157
	ds_read_b128 v[210:213], v157 offset:1024
	ds_read_b128 v[214:217], v158
	ds_read_b128 v[218:221], v158 offset:1024
	v_add_u32_e32 v159, 0xe000, v129
	v_add_u32_e32 v160, 0xc000, v129
	s_add_u32 m0, s32, 0xc000
	s_add_u32 s98, s14, 0x40080
	s_addc_u32 s99, s15, 0
	global_load_lds_dwordx4 v253, s[98:99]
	s_add_u32 m0, s32, 0xe000
	s_nop 0
	global_load_lds_dwordx4 v252, s[98:99]
	s_waitcnt lgkmcnt(8)
	s_barrier
	s_waitcnt lgkmcnt(0)
	s_setprio 1
	s_waitcnt lgkmcnt(0)
	v_mfma_f32_16x16x32_bf16 v[124:127], v[190:193], v[162:165], v[124:127]
	v_mfma_f32_16x16x32_bf16 v[120:123], v[190:193], v[182:185], v[120:123]
	v_mfma_f32_16x16x32_bf16 v[116:119], v[198:201], v[162:165], v[116:119]
	v_mfma_f32_16x16x32_bf16 v[112:115], v[198:201], v[182:185], v[112:115]
	v_mfma_f32_16x16x32_bf16 v[108:111], v[206:209], v[162:165], v[108:111]
	v_mfma_f32_16x16x32_bf16 v[104:107], v[206:209], v[182:185], v[104:107]
	v_mfma_f32_16x16x32_bf16 v[100:103], v[214:217], v[162:165], v[100:103]
	v_mfma_f32_16x16x32_bf16 v[96:99], v[214:217], v[182:185], v[96:99]
	v_mfma_f32_16x16x32_bf16 v[124:127], v[194:197], v[178:181], v[124:127]
	v_mfma_f32_16x16x32_bf16 v[120:123], v[194:197], v[186:189], v[120:123]
	v_mfma_f32_16x16x32_bf16 v[116:119], v[202:205], v[178:181], v[116:119]
	v_mfma_f32_16x16x32_bf16 v[112:115], v[202:205], v[186:189], v[112:115]
	v_mfma_f32_16x16x32_bf16 v[108:111], v[210:213], v[178:181], v[108:111]
	v_mfma_f32_16x16x32_bf16 v[104:107], v[210:213], v[186:189], v[104:107]
	v_mfma_f32_16x16x32_bf16 v[100:103], v[218:221], v[178:181], v[100:103]
	v_mfma_f32_16x16x32_bf16 v[96:99], v[218:221], v[186:189], v[96:99]
	s_setprio 0
	s_barrier
; #define LDA(dst, b, h)                                                                                    \
;   _Pragma("unroll") for (int m = 0; m < 4; ++m) _Pragma("unroll") for (int k = 0; k < 2; ++k)             \
;       dst[m][k] = *reinterpret_cast<const bf16x8*>((char*)SA(b, h) + lds_byte(wr * 64 + m * 16 + fr, k * 32 + fq * 8))
; #define LDB(dst, b, h)                                                                                    \
;   _Pragma("unroll") for (int n = 0; n < 2; ++n) _Pragma("unroll") for (int k = 0; k < 2; ++k)             \
;       dst[n][k] = *reinterpret_cast<const bf16x8*>((char*)SB(b, h) + lds_byte(wc * 32 + n * 16 + fr, k * 32 + fq * 8))
; #define WAIT_V(n) asm volatile("s_waitcnt vmcnt(" #n ")" ::: "memory")
; #define WAIT_L(n) asm volatile("s_waitcnt lgkmcnt(" #n ")" ::: "memory")
; #define BAR __builtin_amdgcn_s_barrier()
; #define SCHED __builtin_amdgcn_sched_barrier(0)
; template <int EPI> ...
;     ...
;     LDB(B1, 0, 1); STAGE(SB(0, 0), Bt, bcol, t + 2);
;     BAR; WAIT_L(0); MMA(0, 1, At, B1); BAR;
;     LDA(At, 0, 1); STAGE(SA(0, 0), A, brow, t + 2);
;     BAR; WAIT_L(0); MMA(1, 0, At, B0); BAR; SCHED;
;     STAGE(SB(0, 1), Bt, bcol + HALF, t + 2);
;     WAIT_V(6); BAR; MMA(1, 1, At, B1); BAR;
;     LDB(B0, 1, 0); SCHED; LDA(At, 1, 0); STAGE(SA(0, 1), A, brow + HALF, t + 2);
;     WAIT_L(8); BAR; WAIT_L(0); MMA(0, 0, At, B0); BAR; SCHED;
	s_add_u32 s34, s6, s12
	s_addc_u32 s35, s7, s13
	ds_read_b128 v[222:225], v152
	ds_read_b128 v[226:229], v152 offset:1024
	ds_read_b128 v[230:233], v152 offset:2048
	ds_read_b128 v[234:237], v152 offset:3072
	s_add_u32 m0, s32, 0x10000
	s_add_u32 s98, s34, 0x100
	s_addc_u32 s99, s35, 0
	global_load_lds_dwordx4 v253, s[98:99]
	s_add_u32 m0, s32, 0x12000
	s_nop 0
	global_load_lds_dwordx4 v252, s[98:99]
	s_barrier
	s_waitcnt lgkmcnt(0)
	s_setprio 1
	s_waitcnt lgkmcnt(0)
	v_mfma_f32_16x16x32_bf16 v[92:95], v[190:193], v[222:225], v[92:95]
	v_mfma_f32_16x16x32_bf16 v[88:91], v[190:193], v[230:233], v[88:91]
	v_mfma_f32_16x16x32_bf16 v[84:87], v[198:201], v[222:225], v[84:87]
	v_mfma_f32_16x16x32_bf16 v[80:83], v[198:201], v[230:233], v[80:83]
	v_mfma_f32_16x16x32_bf16 v[76:79], v[206:209], v[222:225], v[76:79]
	v_mfma_f32_16x16x32_bf16 v[72:75], v[206:209], v[230:233], v[72:75]
	v_mfma_f32_16x16x32_bf16 v[68:71], v[214:217], v[222:225], v[68:71]
	v_mfma_f32_16x16x32_bf16 v[64:67], v[214:217], v[230:233], v[64:67]
	v_mfma_f32_16x16x32_bf16 v[92:95], v[194:197], v[226:229], v[92:95]
	v_mfma_f32_16x16x32_bf16 v[88:91], v[194:197], v[234:237], v[88:91]
	v_mfma_f32_16x16x32_bf16 v[84:87], v[202:205], v[226:229], v[84:87]
	v_mfma_f32_16x16x32_bf16 v[80:83], v[202:205], v[234:237], v[80:83]
	v_mfma_f32_16x16x32_bf16 v[76:79], v[210:213], v[226:229], v[76:79]
	v_mfma_f32_16x16x32_bf16 v[72:75], v[210:213], v[234:237], v[72:75]
	v_mfma_f32_16x16x32_bf16 v[68:71], v[218:221], v[226:229], v[68:71]
	v_mfma_f32_16x16x32_bf16 v[64:67], v[218:221], v[234:237], v[64:67]
	s_setprio 0
	s_barrier
	ds_read_b128 v[190:193], v135 offset:16384
	ds_read_b128 v[194:197], v135 offset:17408
	ds_read_b128 v[198:201], v156 offset:16384
	ds_read_b128 v[202:205], v156 offset:17408
	ds_read_b128 v[206:209], v157 offset:16384
	ds_read_b128 v[210:213], v157 offset:17408
	ds_read_b128 v[214:217], v158 offset:16384
	ds_read_b128 v[218:221], v158 offset:17408
	s_mov_b32 m0, s32
	s_add_u32 s98, s14, 0x100
	s_addc_u32 s99, s15, 0
	global_load_lds_dwordx4 v253, s[98:99]
	s_add_u32 m0, s32, 0x2000
	s_nop 0
	global_load_lds_dwordx4 v252, s[98:99]
	s_barrier
	s_waitcnt lgkmcnt(0)
	s_setprio 1
	s_waitcnt lgkmcnt(0)
	v_mfma_f32_16x16x32_bf16 v[60:63], v[190:193], v[162:165], v[60:63]
	v_mfma_f32_16x16x32_bf16 v[56:59], v[190:193], v[182:185], v[56:59]
	v_mfma_f32_16x16x32_bf16 v[52:55], v[198:201], v[162:165], v[52:55]
	v_mfma_f32_16x16x32_bf16 v[48:51], v[198:201], v[182:185], v[48:51]
	v_mfma_f32_16x16x32_bf16 v[44:47], v[206:209], v[162:165], v[44:47]
	v_mfma_f32_16x16x32_bf16 v[40:43], v[206:209], v[182:185], v[40:43]
	v_mfma_f32_16x16x32_bf16 v[36:39], v[214:217], v[162:165], v[36:39]
	v_mfma_f32_16x16x32_bf16 v[32:35], v[214:217], v[182:185], v[32:35]
	v_mfma_f32_16x16x32_bf16 v[60:63], v[194:197], v[178:181], v[60:63]
	v_mfma_f32_16x16x32_bf16 v[56:59], v[194:197], v[186:189], v[56:59]
	v_mfma_f32_16x16x32_bf16 v[52:55], v[202:205], v[178:181], v[52:55]
	v_mfma_f32_16x16x32_bf16 v[48:51], v[202:205], v[186:189], v[48:51]
	v_mfma_f32_16x16x32_bf16 v[44:47], v[210:213], v[178:181], v[44:47]
	v_mfma_f32_16x16x32_bf16 v[40:43], v[210:213], v[186:189], v[40:43]
	v_mfma_f32_16x16x32_bf16 v[36:39], v[218:221], v[178:181], v[36:39]
	v_mfma_f32_16x16x32_bf16 v[32:35], v[218:221], v[186:189], v[32:35]
	s_setprio 0
	s_barrier
	s_add_u32 m0, s32, 0x14000
	s_add_u32 s98, s34, 0x40100
	s_addc_u32 s99, s35, 0
	global_load_lds_dwordx4 v253, s[98:99]
	s_add_u32 m0, s32, 0x16000
	s_nop 0
	global_load_lds_dwordx4 v252, s[98:99]
	s_waitcnt vmcnt(6)
	s_barrier
	s_setprio 1
	v_mfma_f32_16x16x32_bf16 v[28:31], v[190:193], v[222:225], v[28:31]
	v_mfma_f32_16x16x32_bf16 v[24:27], v[190:193], v[230:233], v[24:27]
	v_mfma_f32_16x16x32_bf16 v[20:23], v[198:201], v[222:225], v[20:23]
	v_mfma_f32_16x16x32_bf16 v[16:19], v[198:201], v[230:233], v[16:19]
	v_mfma_f32_16x16x32_bf16 v[12:15], v[206:209], v[222:225], v[12:15]
	v_mfma_f32_16x16x32_bf16 v[8:11], v[206:209], v[230:233], v[8:11]
	v_mfma_f32_16x16x32_bf16 v[4:7], v[214:217], v[222:225], v[4:7]
	v_mfma_f32_16x16x32_bf16 v[0:3], v[214:217], v[230:233], v[0:3]
	v_mfma_f32_16x16x32_bf16 v[28:31], v[194:197], v[226:229], v[28:31]
	v_mfma_f32_16x16x32_bf16 v[24:27], v[194:197], v[234:237], v[24:27]
	v_mfma_f32_16x16x32_bf16 v[20:23], v[202:205], v[226:229], v[20:23]
	v_mfma_f32_16x16x32_bf16 v[16:19], v[202:205], v[234:237], v[16:19]
	v_mfma_f32_16x16x32_bf16 v[12:15], v[210:213], v[226:229], v[12:15]
	v_mfma_f32_16x16x32_bf16 v[8:11], v[210:213], v[234:237], v[8:11]
	v_mfma_f32_16x16x32_bf16 v[4:7], v[218:221], v[226:229], v[4:7]
	v_mfma_f32_16x16x32_bf16 v[0:3], v[218:221], v[234:237], v[0:3]
	s_setprio 0
	s_barrier
	ds_read_b128 v[162:165], v140
	ds_read_b128 v[178:181], v140 offset:1024
	ds_read_b128 v[182:185], v140 offset:2048
	ds_read_b128 v[186:189], v140 offset:3072
	ds_read_b128 v[190:193], v135 offset:32768
	ds_read_b128 v[194:197], v135 offset:33792
	ds_read_b128 v[198:201], v156 offset:32768
	ds_read_b128 v[202:205], v156 offset:33792
	ds_read_b128 v[206:209], v157 offset:32768
	ds_read_b128 v[210:213], v157 offset:33792
	ds_read_b128 v[214:217], v158 offset:32768
	ds_read_b128 v[218:221], v158 offset:33792
	s_add_u32 m0, s32, 0x4000
	s_add_u32 s98, s14, 0x40100
	s_addc_u32 s99, s15, 0
	global_load_lds_dwordx4 v253, s[98:99]
	s_add_u32 m0, s32, 0x6000
	s_nop 0
	global_load_lds_dwordx4 v252, s[98:99]
	s_waitcnt lgkmcnt(8)
	s_barrier
; #define LDA(dst, b, h)                                                                                    \
;   _Pragma("unroll") for (int m = 0; m < 4; ++m) _Pragma("unroll") for (int k = 0; k < 2; ++k)             \
;       dst[m][k] = *reinterpret_cast<const bf16x8*>((char*)SA(b, h) + lds_byte(wr * 64 + m * 16 + fr, k * 32 + fq * 8))
; #define LDB(dst, b, h)                                                                                    \
;   _Pragma("unroll") for (int n = 0; n < 2; ++n) _Pragma("unroll") for (int k = 0; k < 2; ++k)             \
;       dst[n][k] = *reinterpret_cast<const bf16x8*>((char*)SB(b, h) + lds_byte(wc * 32 + n * 16 + fr, k * 32 + fq * 8))
; #define WAIT_V(n) asm volatile("s_waitcnt vmcnt(" #n ")" ::: "memory")
; #define WAIT_L(n) asm volatile("s_waitcnt lgkmcnt(" #n ")" ::: "memory")
; #define BAR __builtin_amdgcn_s_barrier()
; #define SCHED __builtin_amdgcn_sched_barrier(0)
; template <int EPI> ...
;     ...
;     WAIT_L(8); BAR; WAIT_L(0); MMA(0, 0, At, B0); BAR; SCHED;
;     LDB(B1, 1, 1); STAGE(SB(1, 0), Bt, bcol, t + 3);
;     BAR; WAIT_L(0); MMA(0, 1, At, B1); BAR;
;     LDA(At, 1, 1); STAGE(SA(1, 0), A, brow, t + 3);
;     BAR; WAIT_L(0); MMA(1, 0, At, B0); BAR; SCHED;
;     STAGE(SB(1, 1), Bt, bcol + HALF, t + 3);
;     WAIT_V(6); BAR; MMA(1, 1, At, B1); BAR;
;   }
	s_waitcnt lgkmcnt(0)
	s_setprio 1
	s_waitcnt lgkmcnt(0)
	v_mfma_f32_16x16x32_bf16 v[124:127], v[190:193], v[162:165], v[124:127]
	v_mfma_f32_16x16x32_bf16 v[120:123], v[190:193], v[182:185], v[120:123]
	v_mfma_f32_16x16x32_bf16 v[116:119], v[198:201], v[162:165], v[116:119]
	v_mfma_f32_16x16x32_bf16 v[112:115], v[198:201], v[182:185], v[112:115]
	v_mfma_f32_16x16x32_bf16 v[108:111], v[206:209], v[162:165], v[108:111]
	v_mfma_f32_16x16x32_bf16 v[104:107], v[206:209], v[182:185], v[104:107]
	v_mfma_f32_16x16x32_bf16 v[100:103], v[214:217], v[162:165], v[100:103]
	v_mfma_f32_16x16x32_bf16 v[96:99], v[214:217], v[182:185], v[96:99]
	v_mfma_f32_16x16x32_bf16 v[124:127], v[194:197], v[178:181], v[124:127]
	v_mfma_f32_16x16x32_bf16 v[120:123], v[194:197], v[186:189], v[120:123]
	v_mfma_f32_16x16x32_bf16 v[116:119], v[202:205], v[178:181], v[116:119]
	v_mfma_f32_16x16x32_bf16 v[112:115], v[202:205], v[186:189], v[112:115]
	v_mfma_f32_16x16x32_bf16 v[108:111], v[210:213], v[178:181], v[108:111]
	v_mfma_f32_16x16x32_bf16 v[104:107], v[210:213], v[186:189], v[104:107]
	v_mfma_f32_16x16x32_bf16 v[100:103], v[218:221], v[178:181], v[100:103]
	v_mfma_f32_16x16x32_bf16 v[96:99], v[218:221], v[186:189], v[96:99]
	s_setprio 0
	s_barrier
	ds_read_b128 v[222:225], v137
	ds_read_b128 v[226:229], v137 offset:1024
	ds_read_b128 v[230:233], v137 offset:2048
	ds_read_b128 v[234:237], v137 offset:3072
	s_add_u32 m0, s32, 0x18000
	s_add_u32 s98, s34, 0x180
	s_addc_u32 s99, s35, 0
	global_load_lds_dwordx4 v253, s[98:99]
	s_add_u32 m0, s32, 0x1a000
	s_nop 0
	global_load_lds_dwordx4 v252, s[98:99]
	s_barrier
	s_waitcnt lgkmcnt(0)
	s_setprio 1
	s_waitcnt lgkmcnt(0)
	v_mfma_f32_16x16x32_bf16 v[92:95], v[190:193], v[222:225], v[92:95]
	v_mfma_f32_16x16x32_bf16 v[88:91], v[190:193], v[230:233], v[88:91]
	v_mfma_f32_16x16x32_bf16 v[84:87], v[198:201], v[222:225], v[84:87]
	v_mfma_f32_16x16x32_bf16 v[80:83], v[198:201], v[230:233], v[80:83]
	v_mfma_f32_16x16x32_bf16 v[76:79], v[206:209], v[222:225], v[76:79]
	v_mfma_f32_16x16x32_bf16 v[72:75], v[206:209], v[230:233], v[72:75]
	v_mfma_f32_16x16x32_bf16 v[68:71], v[214:217], v[222:225], v[68:71]
	v_mfma_f32_16x16x32_bf16 v[64:67], v[214:217], v[230:233], v[64:67]
	v_mfma_f32_16x16x32_bf16 v[92:95], v[194:197], v[226:229], v[92:95]
	v_mfma_f32_16x16x32_bf16 v[88:91], v[194:197], v[234:237], v[88:91]
	v_mfma_f32_16x16x32_bf16 v[84:87], v[202:205], v[226:229], v[84:87]
	v_mfma_f32_16x16x32_bf16 v[80:83], v[202:205], v[234:237], v[80:83]
	v_mfma_f32_16x16x32_bf16 v[76:79], v[210:213], v[226:229], v[76:79]
	v_mfma_f32_16x16x32_bf16 v[72:75], v[210:213], v[234:237], v[72:75]
	v_mfma_f32_16x16x32_bf16 v[68:71], v[218:221], v[226:229], v[68:71]
	v_mfma_f32_16x16x32_bf16 v[64:67], v[218:221], v[234:237], v[64:67]
	s_setprio 0
	s_barrier
	ds_read_b128 v[190:193], v135 offset:49152
	ds_read_b128 v[194:197], v135 offset:50176
	ds_read_b128 v[198:201], v156 offset:49152
	ds_read_b128 v[202:205], v156 offset:50176
	ds_read_b128 v[206:209], v157 offset:49152
	ds_read_b128 v[210:213], v157 offset:50176
	ds_read_b128 v[214:217], v158 offset:49152
	ds_read_b128 v[218:221], v158 offset:50176
	s_add_u32 m0, s32, 0x8000
	s_add_u32 s98, s14, 0x180
	s_addc_u32 s99, s15, 0
	global_load_lds_dwordx4 v253, s[98:99]
	s_nop 0
	s_add_u32 m0, s32, 0xa000
	s_nop 0
	global_load_lds_dwordx4 v252, s[98:99]
	s_barrier
	s_waitcnt lgkmcnt(0)
	s_setprio 1
	s_waitcnt lgkmcnt(0)
	v_mfma_f32_16x16x32_bf16 v[60:63], v[190:193], v[162:165], v[60:63]
	v_mfma_f32_16x16x32_bf16 v[56:59], v[190:193], v[182:185], v[56:59]
	v_mfma_f32_16x16x32_bf16 v[52:55], v[198:201], v[162:165], v[52:55]
	v_mfma_f32_16x16x32_bf16 v[48:51], v[198:201], v[182:185], v[48:51]
	v_mfma_f32_16x16x32_bf16 v[44:47], v[206:209], v[162:165], v[44:47]
	v_mfma_f32_16x16x32_bf16 v[40:43], v[206:209], v[182:185], v[40:43]
	v_mfma_f32_16x16x32_bf16 v[36:39], v[214:217], v[162:165], v[36:39]
	v_mfma_f32_16x16x32_bf16 v[32:35], v[214:217], v[182:185], v[32:35]
	v_mfma_f32_16x16x32_bf16 v[60:63], v[194:197], v[178:181], v[60:63]
	v_mfma_f32_16x16x32_bf16 v[56:59], v[194:197], v[186:189], v[56:59]
	v_mfma_f32_16x16x32_bf16 v[52:55], v[202:205], v[178:181], v[52:55]
	v_mfma_f32_16x16x32_bf16 v[48:51], v[202:205], v[186:189], v[48:51]
	v_mfma_f32_16x16x32_bf16 v[44:47], v[210:213], v[178:181], v[44:47]
	v_mfma_f32_16x16x32_bf16 v[40:43], v[210:213], v[186:189], v[40:43]
	v_mfma_f32_16x16x32_bf16 v[36:39], v[218:221], v[178:181], v[36:39]
	v_mfma_f32_16x16x32_bf16 v[32:35], v[218:221], v[186:189], v[32:35]
	s_setprio 0
	s_barrier
	s_add_u32 m0, s32, 0x1c000
	s_add_u32 s98, s34, 0x40180
	s_addc_u32 s99, s35, 0
	global_load_lds_dwordx4 v253, s[98:99]
	s_add_u32 m0, s32, 0x1e000
	s_nop 0
	global_load_lds_dwordx4 v252, s[98:99]
	s_waitcnt vmcnt(6)
	s_barrier
	s_setprio 1
	v_mfma_f32_16x16x32_bf16 v[28:31], v[190:193], v[222:225], v[28:31]
	v_mfma_f32_16x16x32_bf16 v[24:27], v[190:193], v[230:233], v[24:27]
	v_mfma_f32_16x16x32_bf16 v[20:23], v[198:201], v[222:225], v[20:23]
	v_mfma_f32_16x16x32_bf16 v[16:19], v[198:201], v[230:233], v[16:19]
	v_mfma_f32_16x16x32_bf16 v[12:15], v[206:209], v[222:225], v[12:15]
	v_mfma_f32_16x16x32_bf16 v[8:11], v[206:209], v[230:233], v[8:11]
	v_mfma_f32_16x16x32_bf16 v[4:7], v[214:217], v[222:225], v[4:7]
	v_mfma_f32_16x16x32_bf16 v[0:3], v[214:217], v[230:233], v[0:3]
	v_mfma_f32_16x16x32_bf16 v[28:31], v[194:197], v[226:229], v[28:31]
	v_mfma_f32_16x16x32_bf16 v[24:27], v[194:197], v[234:237], v[24:27]
	v_mfma_f32_16x16x32_bf16 v[20:23], v[202:205], v[226:229], v[20:23]
	v_mfma_f32_16x16x32_bf16 v[16:19], v[202:205], v[234:237], v[16:19]
	v_mfma_f32_16x16x32_bf16 v[12:15], v[210:213], v[226:229], v[12:15]
	v_mfma_f32_16x16x32_bf16 v[8:11], v[210:213], v[234:237], v[8:11]
	v_mfma_f32_16x16x32_bf16 v[4:7], v[218:221], v[226:229], v[4:7]
	v_mfma_f32_16x16x32_bf16 v[0:3], v[218:221], v[234:237], v[0:3]
	s_setprio 0
	s_add_i32 s67, s67, 2
	s_add_u32 s12, s12, 0x100
	s_addc_u32 s13, s13, 0
	s_cmp_lt_u32 s67, 12
	s_barrier
; #define LDA(dst, b, h)                                                                                    \
;   _Pragma("unroll") for (int m = 0; m < 4; ++m) _Pragma("unroll") for (int k = 0; k < 2; ++k)             \
;       dst[m][k] = *reinterpret_cast<const bf16x8*>((char*)SA(b, h) + lds_byte(wr * 64 + m * 16 + fr, k * 32 + fq * 8))
; #define LDB(dst, b, h)                                                                                    \
;   _Pragma("unroll") for (int n = 0; n < 2; ++n) _Pragma("unroll") for (int k = 0; k < 2; ++k)             \
;       dst[n][k] = *reinterpret_cast<const bf16x8*>((char*)SB(b, h) + lds_byte(wc * 32 + n * 16 + fr, k * 32 + fq * 8))
; #define WAIT_V(n) asm volatile("s_waitcnt vmcnt(" #n ")" ::: "memory")
; #define WAIT_L(n) asm volatile("s_waitcnt lgkmcnt(" #n ")" ::: "memory")
; #define BAR __builtin_amdgcn_s_barrier()
; template <int EPI> ...
;     ...
;   }
;   {
;     LDB(B0, 0, 0); LDA(At, 0, 0); STAGE(SA(1, 1), A, brow + HALF, nt - 1);
;     BAR; WAIT_L(0); MMA(0, 0, At, B0); BAR;
;     LDB(B1, 0, 1); BAR; WAIT_L(0); MMA(0, 1, At, B1); BAR;
;     LDA(At, 0, 1); WAIT_V(4); BAR; WAIT_L(0); MMA(1, 0, At, B0); MMA(1, 1, At, B1); BAR;
;   }
;   {
;     LDB(B0, 1, 0); LDA(At, 1, 0); WAIT_V(2); BAR; WAIT_L(0); MMA(0, 0, At, B0); BAR;
	s_cbranch_scc1 .LBB0_416
	ds_read_b128 v[142:145], v155
	ds_read_b128 v[162:165], v155 offset:1024
	ds_read_b128 v[178:181], v155 offset:2048
	ds_read_b128 v[182:185], v155 offset:3072
	ds_read_b128 v[186:189], v135
	ds_read_b128 v[190:193], v135 offset:1024
	ds_read_b128 v[194:197], v156
	ds_read_b128 v[198:201], v156 offset:1024
	ds_read_b128 v[202:205], v157
	ds_read_b128 v[206:209], v157 offset:1024
	ds_read_b128 v[210:213], v158
	ds_read_b128 v[214:217], v158 offset:1024
	v_mov_b32_e32 v129, v149
	v_lshl_add_u64 v[128:129], v[128:129], 1, s[10:11]
	s_mov_b64 s[8:9], 0x780
	v_readfirstlane_b32 s6, v160
	v_lshl_add_u64 v[128:129], v[128:129], 0, s[8:9]
	s_mov_b32 m0, s6
	v_mov_b32_e32 v131, v149
	global_load_lds_dwordx4 v[128:129], off
	v_readfirstlane_b32 s6, v159
	v_lshl_add_u64 v[128:129], v[130:131], 1, s[10:11]
	v_lshl_add_u64 v[128:129], v[128:129], 0, s[8:9]
	s_mov_b32 m0, s6
	s_nop 0
	global_load_lds_dwordx4 v[128:129], off
	s_barrier
	s_waitcnt lgkmcnt(0)
	s_setprio 1
	s_waitcnt lgkmcnt(0)
	v_mfma_f32_16x16x32_bf16 v[124:127], v[186:189], v[142:145], v[124:127]
	v_mfma_f32_16x16x32_bf16 v[120:123], v[186:189], v[178:181], v[120:123]
	v_mfma_f32_16x16x32_bf16 v[116:119], v[194:197], v[142:145], v[116:119]
	v_mfma_f32_16x16x32_bf16 v[112:115], v[194:197], v[178:181], v[112:115]
	v_mfma_f32_16x16x32_bf16 v[108:111], v[202:205], v[142:145], v[108:111]
	v_mfma_f32_16x16x32_bf16 v[104:107], v[202:205], v[178:181], v[104:107]
	v_mfma_f32_16x16x32_bf16 v[96:99], v[210:213], v[178:181], v[96:99]
	v_mfma_f32_16x16x32_bf16 v[124:127], v[190:193], v[162:165], v[124:127]
	v_mfma_f32_16x16x32_bf16 v[120:123], v[190:193], v[182:185], v[120:123]
	v_mfma_f32_16x16x32_bf16 v[116:119], v[198:201], v[162:165], v[116:119]
	v_mfma_f32_16x16x32_bf16 v[112:115], v[198:201], v[182:185], v[112:115]
	v_mfma_f32_16x16x32_bf16 v[108:111], v[206:209], v[162:165], v[108:111]
	v_mfma_f32_16x16x32_bf16 v[104:107], v[206:209], v[182:185], v[104:107]
	v_mfma_f32_16x16x32_bf16 v[100:103], v[210:213], v[142:145], v[100:103]
	v_mfma_f32_16x16x32_bf16 v[96:99], v[214:217], v[182:185], v[96:99]
	v_mfma_f32_16x16x32_bf16 v[128:131], v[214:217], v[162:165], v[100:103]
	s_setprio 0
	s_barrier
	s_nop 3
	ds_read_b128 v[100:103], v152
	ds_read_b128 v[218:221], v152 offset:1024
	ds_read_b128 v[222:225], v152 offset:2048
	ds_read_b128 v[152:155], v152 offset:3072
	s_barrier
	s_waitcnt lgkmcnt(0)
	s_setprio 1
	s_waitcnt lgkmcnt(0)
	v_mfma_f32_16x16x32_bf16 v[88:91], v[186:189], v[222:225], v[88:91]
	v_mfma_f32_16x16x32_bf16 v[92:95], v[186:189], v[100:103], v[92:95]
	v_mfma_f32_16x16x32_bf16 v[88:91], v[190:193], v[152:155], v[88:91]
	v_mfma_f32_16x16x32_bf16 v[84:87], v[194:197], v[100:103], v[84:87]
	v_mfma_f32_16x16x32_bf16 v[80:83], v[194:197], v[222:225], v[80:83]
	v_mfma_f32_16x16x32_bf16 v[76:79], v[202:205], v[100:103], v[76:79]
	v_mfma_f32_16x16x32_bf16 v[72:75], v[202:205], v[222:225], v[72:75]
	v_mfma_f32_16x16x32_bf16 v[68:71], v[210:213], v[100:103], v[68:71]
	v_mfma_f32_16x16x32_bf16 v[64:67], v[210:213], v[222:225], v[64:67]
	v_mfma_f32_16x16x32_bf16 v[226:229], v[190:193], v[218:221], v[92:95]
	v_mfma_f32_16x16x32_bf16 v[186:189], v[198:201], v[218:221], v[84:87]
	v_mfma_f32_16x16x32_bf16 v[190:193], v[198:201], v[152:155], v[80:83]
	v_mfma_f32_16x16x32_bf16 v[194:197], v[206:209], v[218:221], v[76:79]
	v_mfma_f32_16x16x32_bf16 v[198:201], v[206:209], v[152:155], v[72:75]
	v_mfma_f32_16x16x32_bf16 v[202:205], v[214:217], v[218:221], v[68:71]
	v_mfma_f32_16x16x32_bf16 v[206:209], v[214:217], v[152:155], v[64:67]
	s_setprio 0
	s_barrier
	s_nop 0
	ds_read_b128 v[64:67], v135 offset:16384
	ds_read_b128 v[68:71], v135 offset:17408
	ds_read_b128 v[72:75], v156 offset:16384
	ds_read_b128 v[76:79], v156 offset:17408
	ds_read_b128 v[80:83], v157 offset:16384
	ds_read_b128 v[84:87], v157 offset:17408
	ds_read_b128 v[92:95], v158 offset:16384
	ds_read_b128 v[210:213], v158 offset:17408
	s_waitcnt vmcnt(4)
	s_barrier
	s_waitcnt lgkmcnt(0)
	s_setprio 1
	s_waitcnt lgkmcnt(0)
	v_mfma_f32_16x16x32_bf16 v[60:63], v[64:67], v[142:145], v[60:63]
	v_mfma_f32_16x16x32_bf16 v[56:59], v[64:67], v[178:181], v[56:59]
	v_mfma_f32_16x16x32_bf16 v[52:55], v[72:75], v[142:145], v[52:55]
	v_mfma_f32_16x16x32_bf16 v[48:51], v[72:75], v[178:181], v[48:51]
	v_mfma_f32_16x16x32_bf16 v[44:47], v[80:83], v[142:145], v[44:47]
	v_mfma_f32_16x16x32_bf16 v[40:43], v[80:83], v[178:181], v[40:43]
	v_mfma_f32_16x16x32_bf16 v[36:39], v[92:95], v[142:145], v[36:39]
	v_mfma_f32_16x16x32_bf16 v[32:35], v[92:95], v[178:181], v[32:35]
	v_mfma_f32_16x16x32_bf16 v[60:63], v[68:71], v[162:165], v[60:63]
	v_mfma_f32_16x16x32_bf16 v[56:59], v[68:71], v[182:185], v[56:59]
	v_mfma_f32_16x16x32_bf16 v[52:55], v[76:79], v[162:165], v[52:55]
	v_mfma_f32_16x16x32_bf16 v[48:51], v[76:79], v[182:185], v[48:51]
	v_mfma_f32_16x16x32_bf16 v[44:47], v[84:87], v[162:165], v[44:47]
	v_mfma_f32_16x16x32_bf16 v[40:43], v[84:87], v[182:185], v[40:43]
	v_mfma_f32_16x16x32_bf16 v[36:39], v[210:213], v[162:165], v[36:39]
	v_mfma_f32_16x16x32_bf16 v[32:35], v[210:213], v[182:185], v[32:35]
	s_setprio 0
	s_setprio 1
	v_mfma_f32_16x16x32_bf16 v[28:31], v[64:67], v[100:103], v[28:31]
	v_mfma_f32_16x16x32_bf16 v[24:27], v[64:67], v[222:225], v[24:27]
	v_mfma_f32_16x16x32_bf16 v[20:23], v[72:75], v[100:103], v[20:23]
	v_mfma_f32_16x16x32_bf16 v[16:19], v[72:75], v[222:225], v[16:19]
	v_mfma_f32_16x16x32_bf16 v[12:15], v[80:83], v[100:103], v[12:15]
	v_mfma_f32_16x16x32_bf16 v[8:11], v[80:83], v[222:225], v[8:11]
	v_mfma_f32_16x16x32_bf16 v[4:7], v[92:95], v[100:103], v[4:7]
	v_mfma_f32_16x16x32_bf16 v[0:3], v[92:95], v[222:225], v[0:3]
	v_mfma_f32_16x16x32_bf16 v[142:145], v[68:71], v[218:221], v[28:31]
	v_mfma_f32_16x16x32_bf16 v[160:163], v[68:71], v[152:155], v[24:27]
	v_mfma_f32_16x16x32_bf16 v[164:167], v[76:79], v[218:221], v[20:23]
	v_mfma_f32_16x16x32_bf16 v[178:181], v[76:79], v[152:155], v[16:19]
	v_mfma_f32_16x16x32_bf16 v[182:185], v[84:87], v[218:221], v[12:15]
	v_mfma_f32_16x16x32_bf16 v[214:217], v[84:87], v[152:155], v[8:11]
	v_mfma_f32_16x16x32_bf16 v[218:221], v[210:213], v[218:221], v[4:7]
	v_mfma_f32_16x16x32_bf16 v[152:155], v[210:213], v[152:155], v[0:3]
	s_setprio 0
	s_barrier
; #define LDA(dst, b, h)                                                                                    \
;   _Pragma("unroll") for (int m = 0; m < 4; ++m) _Pragma("unroll") for (int k = 0; k < 2; ++k)             \
;       dst[m][k] = *reinterpret_cast<const bf16x8*>((char*)SA(b, h) + lds_byte(wr * 64 + m * 16 + fr, k * 32 + fq * 8))
; #define LDB(dst, b, h)                                                                                    \
;   _Pragma("unroll") for (int n = 0; n < 2; ++n) _Pragma("unroll") for (int k = 0; k < 2; ++k)             \
;       dst[n][k] = *reinterpret_cast<const bf16x8*>((char*)SB(b, h) + lds_byte(wc * 32 + n * 16 + fr, k * 32 + fq * 8))
; #define WAIT_V(n) asm volatile("s_waitcnt vmcnt(" #n ")" ::: "memory")
; #define WAIT_L(n) asm volatile("s_waitcnt lgkmcnt(" #n ")" ::: "memory")
; #define BAR __builtin_amdgcn_s_barrier()
; template <int EPI> ...
;     ...
;     LDB(B0, 1, 0); LDA(At, 1, 0); WAIT_V(2); BAR; WAIT_L(0); MMA(0, 0, At, B0); BAR;
;     LDB(B1, 1, 1); WAIT_V(0); BAR; WAIT_L(0); MMA(0, 1, At, B1); BAR;
;     LDA(At, 1, 1); BAR; WAIT_L(0); MMA(1, 0, At, B0); MMA(1, 1, At, B1); BAR;
;   }
;   if (wr == 0) BAR;
;   if (has_next) ISSUE_PRO(nm0, nn0);
	s_nop 0
	ds_read_b128 v[0:3], v140
	ds_read_b128 v[4:7], v140 offset:1024
	ds_read_b128 v[210:213], v140 offset:2048
	ds_read_b128 v[138:141], v140 offset:3072
	ds_read_b128 v[8:11], v135 offset:32768
	ds_read_b128 v[12:15], v135 offset:33792
	ds_read_b128 v[16:19], v156 offset:32768
	ds_read_b128 v[20:23], v156 offset:33792
	ds_read_b128 v[24:27], v157 offset:32768
	ds_read_b128 v[28:31], v157 offset:33792
	ds_read_b128 v[222:225], v158 offset:32768
	ds_read_b128 v[230:233], v158 offset:33792
	s_waitcnt vmcnt(2)
	s_barrier
	s_waitcnt lgkmcnt(0)
	s_setprio 1
	s_waitcnt lgkmcnt(0)
	v_mfma_f32_16x16x32_bf16 v[64:67], v[8:11], v[0:3], v[124:127]
	v_mfma_f32_16x16x32_bf16 v[92:95], v[12:15], v[4:7], v[64:67]
	v_mfma_f32_16x16x32_bf16 v[64:67], v[8:11], v[210:213], v[120:123]
	v_mfma_f32_16x16x32_bf16 v[100:103], v[12:15], v[138:141], v[64:67]
	v_mfma_f32_16x16x32_bf16 v[64:67], v[16:19], v[0:3], v[116:119]
	v_mfma_f32_16x16x32_bf16 v[80:83], v[20:23], v[4:7], v[64:67]
	v_mfma_f32_16x16x32_bf16 v[64:67], v[16:19], v[210:213], v[112:115]
	v_mfma_f32_16x16x32_bf16 v[84:87], v[20:23], v[138:141], v[64:67]
	v_mfma_f32_16x16x32_bf16 v[64:67], v[24:27], v[0:3], v[108:111]
	v_mfma_f32_16x16x32_bf16 v[72:75], v[28:31], v[4:7], v[64:67]
	v_mfma_f32_16x16x32_bf16 v[64:67], v[24:27], v[210:213], v[104:107]
	v_mfma_f32_16x16x32_bf16 v[76:79], v[28:31], v[138:141], v[64:67]
	v_mfma_f32_16x16x32_bf16 v[64:67], v[222:225], v[0:3], v[128:131]
	v_mfma_f32_16x16x32_bf16 v[68:71], v[222:225], v[210:213], v[96:99]
	v_mfma_f32_16x16x32_bf16 v[64:67], v[230:233], v[4:7], v[64:67]
	v_mfma_f32_16x16x32_bf16 v[68:71], v[230:233], v[138:141], v[68:71]
	s_setprio 0
	s_barrier
	ds_read_b128 v[128:131], v137
	ds_read_b128 v[234:237], v137 offset:1024
	ds_read_b128 v[238:241], v137 offset:2048
	ds_read_b128 v[242:245], v137 offset:3072
	s_waitcnt vmcnt(0)
	s_barrier
	s_waitcnt lgkmcnt(0)
	s_setprio 1
	s_waitcnt lgkmcnt(0)
	v_mfma_f32_16x16x32_bf16 v[96:99], v[8:11], v[128:131], v[226:229]
	v_mfma_f32_16x16x32_bf16 v[8:11], v[8:11], v[238:241], v[88:91]
	v_mfma_f32_16x16x32_bf16 v[124:127], v[12:15], v[242:245], v[8:11]
	v_mfma_f32_16x16x32_bf16 v[8:11], v[16:19], v[128:131], v[186:189]
	v_mfma_f32_16x16x32_bf16 v[112:115], v[20:23], v[234:237], v[8:11]
	v_mfma_f32_16x16x32_bf16 v[8:11], v[16:19], v[238:241], v[190:193]
	v_mfma_f32_16x16x32_bf16 v[116:119], v[20:23], v[242:245], v[8:11]
	v_mfma_f32_16x16x32_bf16 v[8:11], v[24:27], v[128:131], v[194:197]
	v_mfma_f32_16x16x32_bf16 v[104:107], v[28:31], v[234:237], v[8:11]
	v_mfma_f32_16x16x32_bf16 v[8:11], v[24:27], v[238:241], v[198:201]
	v_mfma_f32_16x16x32_bf16 v[108:111], v[28:31], v[242:245], v[8:11]
	v_mfma_f32_16x16x32_bf16 v[8:11], v[222:225], v[128:131], v[202:205]
	v_mfma_f32_16x16x32_bf16 v[88:91], v[230:233], v[234:237], v[8:11]
	v_mfma_f32_16x16x32_bf16 v[8:11], v[222:225], v[238:241], v[206:209]
	v_mfma_f32_16x16x32_bf16 v[120:123], v[12:15], v[234:237], v[96:99]
	v_mfma_f32_16x16x32_bf16 v[96:99], v[230:233], v[242:245], v[8:11]
	s_setprio 0
	s_barrier
	ds_read_b128 v[186:189], v135 offset:49152
	ds_read_b128 v[134:137], v135 offset:50176
	ds_read_b128 v[190:193], v156 offset:49152
	ds_read_b128 v[194:197], v156 offset:50176
	ds_read_b128 v[198:201], v157 offset:49152
	ds_read_b128 v[202:205], v157 offset:50176
	ds_read_b128 v[206:209], v158 offset:49152
	ds_read_b128 v[156:159], v158 offset:50176
	s_barrier
	s_waitcnt lgkmcnt(0)
	s_setprio 1
	s_waitcnt lgkmcnt(0)
	v_mfma_f32_16x16x32_bf16 v[8:11], v[186:189], v[0:3], v[60:63]
	v_mfma_f32_16x16x32_bf16 v[24:27], v[134:137], v[4:7], v[8:11]
	v_mfma_f32_16x16x32_bf16 v[8:11], v[186:189], v[210:213], v[56:59]
	v_mfma_f32_16x16x32_bf16 v[28:31], v[134:137], v[138:141], v[8:11]
	v_mfma_f32_16x16x32_bf16 v[8:11], v[190:193], v[0:3], v[52:55]
	v_mfma_f32_16x16x32_bf16 v[16:19], v[194:197], v[4:7], v[8:11]
	v_mfma_f32_16x16x32_bf16 v[8:11], v[190:193], v[210:213], v[48:51]
	v_mfma_f32_16x16x32_bf16 v[20:23], v[194:197], v[138:141], v[8:11]
	v_mfma_f32_16x16x32_bf16 v[8:11], v[198:201], v[0:3], v[44:47]
	v_mfma_f32_16x16x32_bf16 v[0:3], v[206:209], v[0:3], v[36:39]
	v_mfma_f32_16x16x32_bf16 v[8:11], v[202:205], v[4:7], v[8:11]
	v_mfma_f32_16x16x32_bf16 v[12:15], v[198:201], v[210:213], v[40:43]
	v_mfma_f32_16x16x32_bf16 v[0:3], v[156:159], v[4:7], v[0:3]
	v_mfma_f32_16x16x32_bf16 v[4:7], v[206:209], v[210:213], v[32:35]
	v_mfma_f32_16x16x32_bf16 v[12:15], v[202:205], v[138:141], v[12:15]
	v_mfma_f32_16x16x32_bf16 v[4:7], v[156:159], v[138:141], v[4:7]
	s_setprio 0
	s_setprio 1
	v_mfma_f32_16x16x32_bf16 v[32:35], v[186:189], v[128:131], v[142:145]
	v_mfma_f32_16x16x32_bf16 v[56:59], v[134:137], v[234:237], v[32:35]
	v_mfma_f32_16x16x32_bf16 v[32:35], v[186:189], v[238:241], v[160:163]
	v_mfma_f32_16x16x32_bf16 v[60:63], v[134:137], v[242:245], v[32:35]
	v_mfma_f32_16x16x32_bf16 v[32:35], v[190:193], v[128:131], v[164:167]
	v_mfma_f32_16x16x32_bf16 v[48:51], v[194:197], v[234:237], v[32:35]
	v_mfma_f32_16x16x32_bf16 v[32:35], v[190:193], v[238:241], v[178:181]
	v_mfma_f32_16x16x32_bf16 v[52:55], v[194:197], v[242:245], v[32:35]
	v_mfma_f32_16x16x32_bf16 v[32:35], v[198:201], v[128:131], v[182:185]
	v_mfma_f32_16x16x32_bf16 v[40:43], v[202:205], v[234:237], v[32:35]
	v_mfma_f32_16x16x32_bf16 v[32:35], v[198:201], v[238:241], v[214:217]
	v_mfma_f32_16x16x32_bf16 v[44:47], v[202:205], v[242:245], v[32:35]
	v_mfma_f32_16x16x32_bf16 v[32:35], v[206:209], v[128:131], v[218:221]
	v_mfma_f32_16x16x32_bf16 v[36:39], v[206:209], v[238:241], v[152:155]
	v_mfma_f32_16x16x32_bf16 v[32:35], v[156:159], v[234:237], v[32:35]
	v_mfma_f32_16x16x32_bf16 v[36:39], v[156:159], v[242:245], v[36:39]
	s_setprio 0
	s_cmpk_gt_u32 s62, 0xff
	s_barrier
	s_cbranch_scc1 .LBB0_419
	s_barrier

; DEVI f32x4 ozero() { float z = 0.f; asm volatile("" : "+v"(z)); return f32x4{z, z, z, z}; }
; #define LDA(dst, b, h)                                                                                    \
;   _Pragma("unroll") for (int m = 0; m < 4; ++m) _Pragma("unroll") for (int k = 0; k < 2; ++k)             \
;       dst[m][k] = *reinterpret_cast<const bf16x8*>((char*)SA(b, h) + lds_byte(wr * 64 + m * 16 + fr, k * 32 + fq * 8))
; #define LDB(dst, b, h)                                                                                    \
;   _Pragma("unroll") for (int n = 0; n < 2; ++n) _Pragma("unroll") for (int k = 0; k < 2; ++k)             \
;       dst[n][k] = *reinterpret_cast<const bf16x8*>((char*)SB(b, h) + lds_byte(wc * 32 + n * 16 + fr, k * 32 + fq * 8))
; #define WAIT_V(n) asm volatile("s_waitcnt vmcnt(" #n ")" ::: "memory")
; #define WAIT_L(n) asm volatile("s_waitcnt lgkmcnt(" #n ")" ::: "memory")
; #define BAR __builtin_amdgcn_s_barrier()
; #define SCHED __builtin_amdgcn_sched_barrier(0)
; template <int EPI> ...
;     ...
;   const int brow = m0, bcol = n0;
;   const int wid = __builtin_amdgcn_readfirstlane(tid >> 6), lane = tid & 63, wr = wid >> 2, wc = wid & 3, fr = lane & 15, fq = lane >> 4;
;   f32x4 acc[2][2][4][2];
;   {
;     const f32x4 zq = ozero();
; #pragma unroll
;     for (int a_ = 0; a_ < 2; ++a_)
; #pragma unroll
;       for (int b_ = 0; b_ < 2; ++b_)
; #pragma unroll
;         for (int m = 0; m < 4; ++m) { acc[a_][b_][m][0] = zq; acc[a_][b_][m][1] = zq; }
;   }
;   bf16x8 At[4][2], B0[2][2], B1[2][2];
;   const int nt = K / BK;
;     ...
;   if (first) {
;     WAIT_V(0);
;     ISSUE_PRO(brow, bcol);
;   }
;   if (wr == 1) BAR;
;   WAIT_V(10); BAR;
;   WAIT_V(6); BAR;
;   for (int t = 0; t < nt - 2; t += 2) {
;     LDB(B0, 0, 0); SCHED; LDA(At, 0, 0); STAGE(SA(1, 1), A, brow + HALF, t + 1);
;     WAIT_L(8); BAR; WAIT_L(0); MMA(0, 0, At, B0); BAR; SCHED;
.LBB0_1015:
	v_and_b32_e32 v133, 15, v132
	v_and_b32_e32 v1, 48, v132
	v_lshlrev_b32_e32 v2, 6, v133
	v_lshlrev_b32_e32 v4, 2, v132
	v_or_b32_e32 v3, v2, v1
	v_and_b32_e32 v4, 32, v4
	s_mov_b32 s20, 0x10000
	v_bitop3_b32 v5, v3, s20, v4 bitop3:0xde
	s_mov_b32 s20, 0x14000
	s_ashr_i32 s35, s34, 6
	v_bitop3_b32 v6, v3, s20, v4 bitop3:0xde
	s_mov_b32 s20, 0x18000
	s_and_b32 s9, s35, 3
	s_waitcnt vmcnt(10)
	s_barrier
	s_waitcnt vmcnt(6)
	v_bitop3_b32 v7, v3, s20, v4 bitop3:0xde
	s_mov_b32 s20, 0x1c000
	v_lshlrev_b32_e32 v8, 6, v132
	s_lshl_b32 s23, s9, 12
	v_bitop3_b32 v2, v2, v4, v1 bitop3:0x36
	s_lshl_b32 s62, s22, 6
	v_bitop3_b32 v3, v3, s20, v4 bitop3:0xde
	s_lshl_b32 s22, s22, 13
	v_and_b32_e32 v8, 0x3c0, v8
	v_bitop3_b32 v154, v8, v4, v1 bitop3:0x36
	s_or_b32 s63, s22, 0x800
	s_or_b32 s69, s22, 0x1000
	s_or_b32 s70, s22, 0x1800
	s_mov_b32 s71, -2
	s_mov_b64 s[20:21], 0
	v_add_u32_e32 v155, s23, v5
	v_add_u32_e32 v135, s22, v2
	v_add_u32_e32 v152, s23, v6
	v_add_u32_e32 v140, s23, v7
	v_add_u32_e32 v137, s23, v3
	v_mov_b32_e32 v1, v0
	v_mov_b32_e32 v2, v0
	v_mov_b32_e32 v3, v0
	v_mov_b32_e32 v4, v0
	v_mov_b32_e32 v5, v0
	v_mov_b32_e32 v6, v0
	v_mov_b32_e32 v7, v0
	v_mov_b32_e32 v8, v0
	v_mov_b32_e32 v9, v0
	v_mov_b32_e32 v10, v0
	v_mov_b32_e32 v11, v0
	v_mov_b32_e32 v12, v0
	v_mov_b32_e32 v13, v0
	v_mov_b32_e32 v14, v0
	v_mov_b32_e32 v15, v0
	v_mov_b32_e32 v16, v0
	v_mov_b32_e32 v17, v0
	v_mov_b32_e32 v18, v0
	v_mov_b32_e32 v19, v0
	v_mov_b32_e32 v20, v0
	v_mov_b32_e32 v21, v0
	v_mov_b32_e32 v22, v0
	v_mov_b32_e32 v23, v0
	v_mov_b32_e32 v24, v0
	v_mov_b32_e32 v25, v0
	v_mov_b32_e32 v26, v0
	v_mov_b32_e32 v27, v0
	v_mov_b32_e32 v28, v0
	v_mov_b32_e32 v29, v0
	v_mov_b32_e32 v30, v0
	v_mov_b32_e32 v31, v0
	v_mov_b32_e32 v32, v0
	v_mov_b32_e32 v33, v0
	v_mov_b32_e32 v34, v0
	v_mov_b32_e32 v35, v0
	v_mov_b32_e32 v36, v0
	v_mov_b32_e32 v37, v0
	v_mov_b32_e32 v38, v0
	v_mov_b32_e32 v39, v0
	v_mov_b32_e32 v40, v0
	v_mov_b32_e32 v41, v0
	v_mov_b32_e32 v42, v0
	v_mov_b32_e32 v43, v0
	v_mov_b32_e32 v44, v0
	v_mov_b32_e32 v45, v0
	v_mov_b32_e32 v46, v0
	v_mov_b32_e32 v47, v0
	v_mov_b32_e32 v48, v0
	v_mov_b32_e32 v49, v0
	v_mov_b32_e32 v50, v0
	v_mov_b32_e32 v51, v0
	v_mov_b32_e32 v52, v0
	v_mov_b32_e32 v53, v0
	v_mov_b32_e32 v54, v0
	v_mov_b32_e32 v55, v0
	v_mov_b32_e32 v56, v0
	v_mov_b32_e32 v57, v0
	v_mov_b32_e32 v58, v0
	v_mov_b32_e32 v59, v0
	v_mov_b32_e32 v60, v0
	v_mov_b32_e32 v61, v0
	v_mov_b32_e32 v62, v0
	v_mov_b32_e32 v63, v0
	v_mov_b32_e32 v64, v0
	v_mov_b32_e32 v65, v0
	v_mov_b32_e32 v66, v0
	v_mov_b32_e32 v67, v0
	v_mov_b32_e32 v68, v0
	v_mov_b32_e32 v69, v0
	v_mov_b32_e32 v70, v0
	v_mov_b32_e32 v71, v0
	v_mov_b32_e32 v72, v0
	v_mov_b32_e32 v73, v0
	v_mov_b32_e32 v74, v0
	v_mov_b32_e32 v75, v0
	v_mov_b32_e32 v76, v0
	v_mov_b32_e32 v77, v0
	v_mov_b32_e32 v78, v0
	v_mov_b32_e32 v79, v0
	v_mov_b32_e32 v80, v0
	v_mov_b32_e32 v81, v0
	v_mov_b32_e32 v82, v0
	v_mov_b32_e32 v83, v0
	v_mov_b32_e32 v84, v0
	v_mov_b32_e32 v85, v0
	v_mov_b32_e32 v86, v0
	v_mov_b32_e32 v87, v0
	v_mov_b32_e32 v88, v0
	v_mov_b32_e32 v89, v0
	v_mov_b32_e32 v90, v0
	v_mov_b32_e32 v91, v0
	v_mov_b32_e32 v92, v0
	v_mov_b32_e32 v93, v0
	v_mov_b32_e32 v94, v0
	v_mov_b32_e32 v95, v0
	v_mov_b32_e32 v96, v0
	v_mov_b32_e32 v97, v0
	v_mov_b32_e32 v98, v0
	v_mov_b32_e32 v99, v0
	v_mov_b32_e32 v100, v0
	v_mov_b32_e32 v101, v0
	v_mov_b32_e32 v102, v0
	v_mov_b32_e32 v103, v0
	v_mov_b32_e32 v104, v0
	v_mov_b32_e32 v105, v0
	v_mov_b32_e32 v106, v0
	v_mov_b32_e32 v107, v0
	v_mov_b32_e32 v108, v0
	v_mov_b32_e32 v109, v0
	v_mov_b32_e32 v110, v0
	v_mov_b32_e32 v111, v0
	v_mov_b32_e32 v112, v0
	v_mov_b32_e32 v113, v0
	v_mov_b32_e32 v114, v0
	v_mov_b32_e32 v115, v0
	v_mov_b32_e32 v116, v0
	v_mov_b32_e32 v117, v0
	v_mov_b32_e32 v118, v0
	v_mov_b32_e32 v119, v0
	v_mov_b32_e32 v120, v0
	v_mov_b32_e32 v121, v0
	v_mov_b32_e32 v122, v0
	v_mov_b32_e32 v123, v0
	v_mov_b32_e32 v124, v0
	v_mov_b32_e32 v125, v0
	v_mov_b32_e32 v126, v0
	v_mov_b32_e32 v127, v0
	s_barrier
	v_lshlrev_b32_e32 v253, 1, v128
	v_lshlrev_b32_e32 v252, 1, v130
	v_readfirstlane_b32 s32, v129
.LBB0_1016:
	ds_read_b128 v[162:165], v155
	ds_read_b128 v[174:177], v155 offset:1024
	ds_read_b128 v[178:181], v155 offset:2048
	ds_read_b128 v[182:185], v155 offset:3072
	s_add_u32 s22, s14, s20
	v_add_u32_e32 v156, s63, v154
	v_add_u32_e32 v157, s69, v154
	v_add_u32_e32 v158, s70, v154
	s_addc_u32 s23, s15, s21
	ds_read_b128 v[186:189], v135
	ds_read_b128 v[190:193], v135 offset:1024
	ds_read_b128 v[194:197], v156
	ds_read_b128 v[198:201], v156 offset:1024
	ds_read_b128 v[202:205], v157
	ds_read_b128 v[206:209], v157 offset:1024
	ds_read_b128 v[210:213], v158
	ds_read_b128 v[214:217], v158 offset:1024
	v_add_u32_e32 v159, 0xe000, v129
	v_add_u32_e32 v160, 0xc000, v129
	s_add_u32 m0, s32, 0xc000
	s_add_u32 s98, s22, 0x40080
	s_addc_u32 s99, s23, 0
	global_load_lds_dwordx4 v253, s[98:99]
	s_add_u32 m0, s32, 0xe000
	s_nop 0
	global_load_lds_dwordx4 v252, s[98:99]
	s_waitcnt lgkmcnt(8)
	s_barrier
	s_waitcnt lgkmcnt(0)
	s_setprio 1
	s_waitcnt lgkmcnt(0)
	v_mfma_f32_16x16x32_bf16 v[124:127], v[186:189], v[162:165], v[124:127]
	v_mfma_f32_16x16x32_bf16 v[120:123], v[186:189], v[178:181], v[120:123]
	v_mfma_f32_16x16x32_bf16 v[116:119], v[194:197], v[162:165], v[116:119]
	v_mfma_f32_16x16x32_bf16 v[112:115], v[194:197], v[178:181], v[112:115]
	v_mfma_f32_16x16x32_bf16 v[108:111], v[202:205], v[162:165], v[108:111]
	v_mfma_f32_16x16x32_bf16 v[104:107], v[202:205], v[178:181], v[104:107]
	v_mfma_f32_16x16x32_bf16 v[100:103], v[210:213], v[162:165], v[100:103]
	v_mfma_f32_16x16x32_bf16 v[96:99], v[210:213], v[178:181], v[96:99]
	v_mfma_f32_16x16x32_bf16 v[124:127], v[190:193], v[174:177], v[124:127]
	v_mfma_f32_16x16x32_bf16 v[120:123], v[190:193], v[182:185], v[120:123]
	v_mfma_f32_16x16x32_bf16 v[116:119], v[198:201], v[174:177], v[116:119]
	v_mfma_f32_16x16x32_bf16 v[112:115], v[198:201], v[182:185], v[112:115]
	v_mfma_f32_16x16x32_bf16 v[108:111], v[206:209], v[174:177], v[108:111]
	v_mfma_f32_16x16x32_bf16 v[104:107], v[206:209], v[182:185], v[104:107]
	v_mfma_f32_16x16x32_bf16 v[100:103], v[214:217], v[174:177], v[100:103]
	v_mfma_f32_16x16x32_bf16 v[96:99], v[214:217], v[182:185], v[96:99]
	s_setprio 0
	s_barrier
; #define LDA(dst, b, h)                                                                                    \
;   _Pragma("unroll") for (int m = 0; m < 4; ++m) _Pragma("unroll") for (int k = 0; k < 2; ++k)             \
;       dst[m][k] = *reinterpret_cast<const bf16x8*>((char*)SA(b, h) + lds_byte(wr * 64 + m * 16 + fr, k * 32 + fq * 8))
; #define LDB(dst, b, h)                                                                                    \
;   _Pragma("unroll") for (int n = 0; n < 2; ++n) _Pragma("unroll") for (int k = 0; k < 2; ++k)             \
;       dst[n][k] = *reinterpret_cast<const bf16x8*>((char*)SB(b, h) + lds_byte(wc * 32 + n * 16 + fr, k * 32 + fq * 8))
; #define WAIT_V(n) asm volatile("s_waitcnt vmcnt(" #n ")" ::: "memory")
; #define WAIT_L(n) asm volatile("s_waitcnt lgkmcnt(" #n ")" ::: "memory")
; #define BAR __builtin_amdgcn_s_barrier()
; #define SCHED __builtin_amdgcn_sched_barrier(0)
; template <int EPI> ...
;     ...
;     LDB(B1, 0, 1); STAGE(SB(0, 0), Bt, bcol, t + 2);
;     BAR; WAIT_L(0); MMA(0, 1, At, B1); BAR;
;     LDA(At, 0, 1); STAGE(SA(0, 0), A, brow, t + 2);
;     BAR; WAIT_L(0); MMA(1, 0, At, B0); BAR; SCHED;
;     STAGE(SB(0, 1), Bt, bcol + HALF, t + 2);
;     WAIT_V(6); BAR; MMA(1, 1, At, B1); BAR;
;     LDB(B0, 1, 0); SCHED; LDA(At, 1, 0); STAGE(SA(0, 1), A, brow + HALF, t + 2);
;     WAIT_L(8); BAR; WAIT_L(0); MMA(0, 0, At, B0); BAR; SCHED;
	s_add_u32 s30, s12, s20
	s_addc_u32 s31, s13, s21
	ds_read_b128 v[218:221], v152
	ds_read_b128 v[222:225], v152 offset:1024
	ds_read_b128 v[226:229], v152 offset:2048
	ds_read_b128 v[230:233], v152 offset:3072
	s_add_u32 m0, s32, 0x10000
	s_add_u32 s98, s30, 0x100
	s_addc_u32 s99, s31, 0
	global_load_lds_dwordx4 v253, s[98:99]
	s_add_u32 m0, s32, 0x12000
	s_nop 0
	global_load_lds_dwordx4 v252, s[98:99]
	s_barrier
	s_waitcnt lgkmcnt(0)
	s_setprio 1
	s_waitcnt lgkmcnt(0)
	v_mfma_f32_16x16x32_bf16 v[92:95], v[186:189], v[218:221], v[92:95]
	v_mfma_f32_16x16x32_bf16 v[88:91], v[186:189], v[226:229], v[88:91]
	v_mfma_f32_16x16x32_bf16 v[84:87], v[194:197], v[218:221], v[84:87]
	v_mfma_f32_16x16x32_bf16 v[80:83], v[194:197], v[226:229], v[80:83]
	v_mfma_f32_16x16x32_bf16 v[76:79], v[202:205], v[218:221], v[76:79]
	v_mfma_f32_16x16x32_bf16 v[72:75], v[202:205], v[226:229], v[72:75]
	v_mfma_f32_16x16x32_bf16 v[68:71], v[210:213], v[218:221], v[68:71]
	v_mfma_f32_16x16x32_bf16 v[64:67], v[210:213], v[226:229], v[64:67]
	v_mfma_f32_16x16x32_bf16 v[92:95], v[190:193], v[222:225], v[92:95]
	v_mfma_f32_16x16x32_bf16 v[88:91], v[190:193], v[230:233], v[88:91]
	v_mfma_f32_16x16x32_bf16 v[84:87], v[198:201], v[222:225], v[84:87]
	v_mfma_f32_16x16x32_bf16 v[80:83], v[198:201], v[230:233], v[80:83]
	v_mfma_f32_16x16x32_bf16 v[76:79], v[206:209], v[222:225], v[76:79]
	v_mfma_f32_16x16x32_bf16 v[72:75], v[206:209], v[230:233], v[72:75]
	v_mfma_f32_16x16x32_bf16 v[68:71], v[214:217], v[222:225], v[68:71]
	v_mfma_f32_16x16x32_bf16 v[64:67], v[214:217], v[230:233], v[64:67]
	s_setprio 0
	s_barrier
	ds_read_b128 v[186:189], v135 offset:16384
	ds_read_b128 v[190:193], v135 offset:17408
	ds_read_b128 v[194:197], v156 offset:16384
	ds_read_b128 v[198:201], v156 offset:17408
	ds_read_b128 v[202:205], v157 offset:16384
	ds_read_b128 v[206:209], v157 offset:17408
	ds_read_b128 v[210:213], v158 offset:16384
	ds_read_b128 v[214:217], v158 offset:17408
	s_mov_b32 m0, s32
	s_add_u32 s98, s22, 0x100
	s_addc_u32 s99, s23, 0
	global_load_lds_dwordx4 v253, s[98:99]
	s_add_u32 m0, s32, 0x2000
	s_nop 0
	global_load_lds_dwordx4 v252, s[98:99]
	s_barrier
	s_waitcnt lgkmcnt(0)
	s_setprio 1
	s_waitcnt lgkmcnt(0)
	v_mfma_f32_16x16x32_bf16 v[60:63], v[186:189], v[162:165], v[60:63]
	v_mfma_f32_16x16x32_bf16 v[56:59], v[186:189], v[178:181], v[56:59]
	v_mfma_f32_16x16x32_bf16 v[52:55], v[194:197], v[162:165], v[52:55]
	v_mfma_f32_16x16x32_bf16 v[48:51], v[194:197], v[178:181], v[48:51]
	v_mfma_f32_16x16x32_bf16 v[44:47], v[202:205], v[162:165], v[44:47]
	v_mfma_f32_16x16x32_bf16 v[40:43], v[202:205], v[178:181], v[40:43]
	v_mfma_f32_16x16x32_bf16 v[36:39], v[210:213], v[162:165], v[36:39]
	v_mfma_f32_16x16x32_bf16 v[32:35], v[210:213], v[178:181], v[32:35]
	v_mfma_f32_16x16x32_bf16 v[60:63], v[190:193], v[174:177], v[60:63]
	v_mfma_f32_16x16x32_bf16 v[56:59], v[190:193], v[182:185], v[56:59]
	v_mfma_f32_16x16x32_bf16 v[52:55], v[198:201], v[174:177], v[52:55]
	v_mfma_f32_16x16x32_bf16 v[48:51], v[198:201], v[182:185], v[48:51]
	v_mfma_f32_16x16x32_bf16 v[44:47], v[206:209], v[174:177], v[44:47]
	v_mfma_f32_16x16x32_bf16 v[40:43], v[206:209], v[182:185], v[40:43]
	v_mfma_f32_16x16x32_bf16 v[36:39], v[214:217], v[174:177], v[36:39]
	v_mfma_f32_16x16x32_bf16 v[32:35], v[214:217], v[182:185], v[32:35]
	s_setprio 0
	s_barrier
	s_add_u32 m0, s32, 0x14000
	s_add_u32 s98, s30, 0x40100
	s_addc_u32 s99, s31, 0
	global_load_lds_dwordx4 v253, s[98:99]
	s_add_u32 m0, s32, 0x16000
	s_nop 0
	global_load_lds_dwordx4 v252, s[98:99]
	s_waitcnt vmcnt(6)
	s_barrier
	s_setprio 1
	v_mfma_f32_16x16x32_bf16 v[28:31], v[186:189], v[218:221], v[28:31]
	v_mfma_f32_16x16x32_bf16 v[24:27], v[186:189], v[226:229], v[24:27]
	v_mfma_f32_16x16x32_bf16 v[20:23], v[194:197], v[218:221], v[20:23]
	v_mfma_f32_16x16x32_bf16 v[16:19], v[194:197], v[226:229], v[16:19]
	v_mfma_f32_16x16x32_bf16 v[12:15], v[202:205], v[218:221], v[12:15]
	v_mfma_f32_16x16x32_bf16 v[8:11], v[202:205], v[226:229], v[8:11]
	v_mfma_f32_16x16x32_bf16 v[4:7], v[210:213], v[218:221], v[4:7]
	v_mfma_f32_16x16x32_bf16 v[0:3], v[210:213], v[226:229], v[0:3]
	v_mfma_f32_16x16x32_bf16 v[28:31], v[190:193], v[222:225], v[28:31]
	v_mfma_f32_16x16x32_bf16 v[24:27], v[190:193], v[230:233], v[24:27]
	v_mfma_f32_16x16x32_bf16 v[20:23], v[198:201], v[222:225], v[20:23]
	v_mfma_f32_16x16x32_bf16 v[16:19], v[198:201], v[230:233], v[16:19]
	v_mfma_f32_16x16x32_bf16 v[12:15], v[206:209], v[222:225], v[12:15]
	v_mfma_f32_16x16x32_bf16 v[8:11], v[206:209], v[230:233], v[8:11]
	v_mfma_f32_16x16x32_bf16 v[4:7], v[214:217], v[222:225], v[4:7]
	v_mfma_f32_16x16x32_bf16 v[0:3], v[214:217], v[230:233], v[0:3]
	s_setprio 0
	s_barrier
	ds_read_b128 v[162:165], v140
	ds_read_b128 v[174:177], v140 offset:1024
	ds_read_b128 v[178:181], v140 offset:2048
	ds_read_b128 v[182:185], v140 offset:3072
	ds_read_b128 v[186:189], v135 offset:32768
	ds_read_b128 v[190:193], v135 offset:33792
	ds_read_b128 v[194:197], v156 offset:32768
	ds_read_b128 v[198:201], v156 offset:33792
	ds_read_b128 v[202:205], v157 offset:32768
	ds_read_b128 v[206:209], v157 offset:33792
	ds_read_b128 v[210:213], v158 offset:32768
	ds_read_b128 v[214:217], v158 offset:33792
	s_add_u32 m0, s32, 0x4000
	s_add_u32 s98, s22, 0x40100
	s_addc_u32 s99, s23, 0
	global_load_lds_dwordx4 v253, s[98:99]
	s_add_u32 m0, s32, 0x6000
	s_nop 0
	global_load_lds_dwordx4 v252, s[98:99]
	s_waitcnt lgkmcnt(8)
	s_barrier
; #define LDA(dst, b, h)                                                                                    \
;   _Pragma("unroll") for (int m = 0; m < 4; ++m) _Pragma("unroll") for (int k = 0; k < 2; ++k)             \
;       dst[m][k] = *reinterpret_cast<const bf16x8*>((char*)SA(b, h) + lds_byte(wr * 64 + m * 16 + fr, k * 32 + fq * 8))
; #define LDB(dst, b, h)                                                                                    \
;   _Pragma("unroll") for (int n = 0; n < 2; ++n) _Pragma("unroll") for (int k = 0; k < 2; ++k)             \
;       dst[n][k] = *reinterpret_cast<const bf16x8*>((char*)SB(b, h) + lds_byte(wc * 32 + n * 16 + fr, k * 32 + fq * 8))
; #define WAIT_V(n) asm volatile("s_waitcnt vmcnt(" #n ")" ::: "memory")
; #define WAIT_L(n) asm volatile("s_waitcnt lgkmcnt(" #n ")" ::: "memory")
; #define BAR __builtin_amdgcn_s_barrier()
; #define SCHED __builtin_amdgcn_sched_barrier(0)
; template <int EPI> ...
;     ...
;     WAIT_L(8); BAR; WAIT_L(0); MMA(0, 0, At, B0); BAR; SCHED;
;     LDB(B1, 1, 1); STAGE(SB(1, 0), Bt, bcol, t + 3);
;     BAR; WAIT_L(0); MMA(0, 1, At, B1); BAR;
;     LDA(At, 1, 1); STAGE(SA(1, 0), A, brow, t + 3);
;     BAR; WAIT_L(0); MMA(1, 0, At, B0); BAR; SCHED;
;     STAGE(SB(1, 1), Bt, bcol + HALF, t + 3);
;     WAIT_V(6); BAR; MMA(1, 1, At, B1); BAR;
;   }
	s_waitcnt lgkmcnt(0)
	s_setprio 1
	s_waitcnt lgkmcnt(0)
	v_mfma_f32_16x16x32_bf16 v[124:127], v[186:189], v[162:165], v[124:127]
	v_mfma_f32_16x16x32_bf16 v[120:123], v[186:189], v[178:181], v[120:123]
	v_mfma_f32_16x16x32_bf16 v[116:119], v[194:197], v[162:165], v[116:119]
	v_mfma_f32_16x16x32_bf16 v[112:115], v[194:197], v[178:181], v[112:115]
	v_mfma_f32_16x16x32_bf16 v[108:111], v[202:205], v[162:165], v[108:111]
	v_mfma_f32_16x16x32_bf16 v[104:107], v[202:205], v[178:181], v[104:107]
	v_mfma_f32_16x16x32_bf16 v[100:103], v[210:213], v[162:165], v[100:103]
	v_mfma_f32_16x16x32_bf16 v[96:99], v[210:213], v[178:181], v[96:99]
	v_mfma_f32_16x16x32_bf16 v[124:127], v[190:193], v[174:177], v[124:127]
	v_mfma_f32_16x16x32_bf16 v[120:123], v[190:193], v[182:185], v[120:123]
	v_mfma_f32_16x16x32_bf16 v[116:119], v[198:201], v[174:177], v[116:119]
	v_mfma_f32_16x16x32_bf16 v[112:115], v[198:201], v[182:185], v[112:115]
	v_mfma_f32_16x16x32_bf16 v[108:111], v[206:209], v[174:177], v[108:111]
	v_mfma_f32_16x16x32_bf16 v[104:107], v[206:209], v[182:185], v[104:107]
	v_mfma_f32_16x16x32_bf16 v[100:103], v[214:217], v[174:177], v[100:103]
	v_mfma_f32_16x16x32_bf16 v[96:99], v[214:217], v[182:185], v[96:99]
	s_setprio 0
	s_barrier
	ds_read_b128 v[218:221], v137
	ds_read_b128 v[222:225], v137 offset:1024
	ds_read_b128 v[226:229], v137 offset:2048
	ds_read_b128 v[230:233], v137 offset:3072
	s_add_u32 m0, s32, 0x18000
	s_add_u32 s98, s30, 0x180
	s_addc_u32 s99, s31, 0
	global_load_lds_dwordx4 v253, s[98:99]
	s_add_u32 m0, s32, 0x1a000
	s_nop 0
	global_load_lds_dwordx4 v252, s[98:99]
	s_barrier
	s_waitcnt lgkmcnt(0)
	s_setprio 1
	s_waitcnt lgkmcnt(0)
	v_mfma_f32_16x16x32_bf16 v[92:95], v[186:189], v[218:221], v[92:95]
	v_mfma_f32_16x16x32_bf16 v[88:91], v[186:189], v[226:229], v[88:91]
	v_mfma_f32_16x16x32_bf16 v[84:87], v[194:197], v[218:221], v[84:87]
	v_mfma_f32_16x16x32_bf16 v[80:83], v[194:197], v[226:229], v[80:83]
	v_mfma_f32_16x16x32_bf16 v[76:79], v[202:205], v[218:221], v[76:79]
	v_mfma_f32_16x16x32_bf16 v[72:75], v[202:205], v[226:229], v[72:75]
	v_mfma_f32_16x16x32_bf16 v[68:71], v[210:213], v[218:221], v[68:71]
	v_mfma_f32_16x16x32_bf16 v[64:67], v[210:213], v[226:229], v[64:67]
	v_mfma_f32_16x16x32_bf16 v[92:95], v[190:193], v[222:225], v[92:95]
	v_mfma_f32_16x16x32_bf16 v[88:91], v[190:193], v[230:233], v[88:91]
	v_mfma_f32_16x16x32_bf16 v[84:87], v[198:201], v[222:225], v[84:87]
	v_mfma_f32_16x16x32_bf16 v[80:83], v[198:201], v[230:233], v[80:83]
	v_mfma_f32_16x16x32_bf16 v[76:79], v[206:209], v[222:225], v[76:79]
	v_mfma_f32_16x16x32_bf16 v[72:75], v[206:209], v[230:233], v[72:75]
	v_mfma_f32_16x16x32_bf16 v[68:71], v[214:217], v[222:225], v[68:71]
	v_mfma_f32_16x16x32_bf16 v[64:67], v[214:217], v[230:233], v[64:67]
	s_setprio 0
	s_barrier
	ds_read_b128 v[186:189], v135 offset:49152
	ds_read_b128 v[190:193], v135 offset:50176
	ds_read_b128 v[194:197], v156 offset:49152
	ds_read_b128 v[198:201], v156 offset:50176
	ds_read_b128 v[202:205], v157 offset:49152
	ds_read_b128 v[206:209], v157 offset:50176
	ds_read_b128 v[210:213], v158 offset:49152
	ds_read_b128 v[214:217], v158 offset:50176
	s_add_u32 m0, s32, 0x8000
	s_add_u32 s98, s22, 0x180
	s_addc_u32 s99, s23, 0
	global_load_lds_dwordx4 v253, s[98:99]
	s_nop 0
	s_add_u32 m0, s32, 0xa000
	s_nop 0
	global_load_lds_dwordx4 v252, s[98:99]
	s_barrier
	s_waitcnt lgkmcnt(0)
	s_setprio 1
	s_waitcnt lgkmcnt(0)
	v_mfma_f32_16x16x32_bf16 v[60:63], v[186:189], v[162:165], v[60:63]
	v_mfma_f32_16x16x32_bf16 v[56:59], v[186:189], v[178:181], v[56:59]
	v_mfma_f32_16x16x32_bf16 v[52:55], v[194:197], v[162:165], v[52:55]
	v_mfma_f32_16x16x32_bf16 v[48:51], v[194:197], v[178:181], v[48:51]
	v_mfma_f32_16x16x32_bf16 v[44:47], v[202:205], v[162:165], v[44:47]
	v_mfma_f32_16x16x32_bf16 v[40:43], v[202:205], v[178:181], v[40:43]
	v_mfma_f32_16x16x32_bf16 v[36:39], v[210:213], v[162:165], v[36:39]
	v_mfma_f32_16x16x32_bf16 v[32:35], v[210:213], v[178:181], v[32:35]
	v_mfma_f32_16x16x32_bf16 v[60:63], v[190:193], v[174:177], v[60:63]
	v_mfma_f32_16x16x32_bf16 v[56:59], v[190:193], v[182:185], v[56:59]
	v_mfma_f32_16x16x32_bf16 v[52:55], v[198:201], v[174:177], v[52:55]
	v_mfma_f32_16x16x32_bf16 v[48:51], v[198:201], v[182:185], v[48:51]
	v_mfma_f32_16x16x32_bf16 v[44:47], v[206:209], v[174:177], v[44:47]
	v_mfma_f32_16x16x32_bf16 v[40:43], v[206:209], v[182:185], v[40:43]
	v_mfma_f32_16x16x32_bf16 v[36:39], v[214:217], v[174:177], v[36:39]
	v_mfma_f32_16x16x32_bf16 v[32:35], v[214:217], v[182:185], v[32:35]
	s_setprio 0
	s_barrier
	s_add_u32 m0, s32, 0x1c000
	s_add_u32 s98, s30, 0x40180
	s_addc_u32 s99, s31, 0
	global_load_lds_dwordx4 v253, s[98:99]
	s_add_u32 m0, s32, 0x1e000
	s_nop 0
	global_load_lds_dwordx4 v252, s[98:99]
	s_waitcnt vmcnt(6)
	s_barrier
	s_setprio 1
	v_mfma_f32_16x16x32_bf16 v[28:31], v[186:189], v[218:221], v[28:31]
	v_mfma_f32_16x16x32_bf16 v[24:27], v[186:189], v[226:229], v[24:27]
	v_mfma_f32_16x16x32_bf16 v[20:23], v[194:197], v[218:221], v[20:23]
	v_mfma_f32_16x16x32_bf16 v[16:19], v[194:197], v[226:229], v[16:19]
	v_mfma_f32_16x16x32_bf16 v[12:15], v[202:205], v[218:221], v[12:15]
	v_mfma_f32_16x16x32_bf16 v[8:11], v[202:205], v[226:229], v[8:11]
	v_mfma_f32_16x16x32_bf16 v[4:7], v[210:213], v[218:221], v[4:7]
	v_mfma_f32_16x16x32_bf16 v[0:3], v[210:213], v[226:229], v[0:3]
	v_mfma_f32_16x16x32_bf16 v[28:31], v[190:193], v[222:225], v[28:31]
	v_mfma_f32_16x16x32_bf16 v[24:27], v[190:193], v[230:233], v[24:27]
	v_mfma_f32_16x16x32_bf16 v[20:23], v[198:201], v[222:225], v[20:23]
	v_mfma_f32_16x16x32_bf16 v[16:19], v[198:201], v[230:233], v[16:19]
	v_mfma_f32_16x16x32_bf16 v[12:15], v[206:209], v[222:225], v[12:15]
	v_mfma_f32_16x16x32_bf16 v[8:11], v[206:209], v[230:233], v[8:11]
	v_mfma_f32_16x16x32_bf16 v[4:7], v[214:217], v[222:225], v[4:7]
	v_mfma_f32_16x16x32_bf16 v[0:3], v[214:217], v[230:233], v[0:3]
	s_setprio 0
	s_add_i32 s71, s71, 2
	s_add_u32 s20, s20, 0x100
	s_addc_u32 s21, s21, 0
	s_cmp_lt_u32 s71, 12
	s_barrier
; #define LDA(dst, b, h)                                                                                    \
;   _Pragma("unroll") for (int m = 0; m < 4; ++m) _Pragma("unroll") for (int k = 0; k < 2; ++k)             \
;       dst[m][k] = *reinterpret_cast<const bf16x8*>((char*)SA(b, h) + lds_byte(wr * 64 + m * 16 + fr, k * 32 + fq * 8))
; #define LDB(dst, b, h)                                                                                    \
;   _Pragma("unroll") for (int n = 0; n < 2; ++n) _Pragma("unroll") for (int k = 0; k < 2; ++k)             \
;       dst[n][k] = *reinterpret_cast<const bf16x8*>((char*)SB(b, h) + lds_byte(wc * 32 + n * 16 + fr, k * 32 + fq * 8))
; #define WAIT_V(n) asm volatile("s_waitcnt vmcnt(" #n ")" ::: "memory")
; #define WAIT_L(n) asm volatile("s_waitcnt lgkmcnt(" #n ")" ::: "memory")
; #define BAR __builtin_amdgcn_s_barrier()
; template <int EPI> ...
;     ...
;   }
;   {
;     LDB(B0, 0, 0); LDA(At, 0, 0); STAGE(SA(1, 1), A, brow + HALF, nt - 1);
;     BAR; WAIT_L(0); MMA(0, 0, At, B0); BAR;
;     LDB(B1, 0, 1); BAR; WAIT_L(0); MMA(0, 1, At, B1); BAR;
;     LDA(At, 0, 1); WAIT_V(4); BAR; WAIT_L(0); MMA(1, 0, At, B0); MMA(1, 1, At, B1); BAR;
	s_cbranch_scc1 .LBB0_1016
	ds_read_b128 v[142:145], v155
	ds_read_b128 v[162:165], v155 offset:1024
	ds_read_b128 v[174:177], v155 offset:2048
	ds_read_b128 v[178:181], v155 offset:3072
	ds_read_b128 v[182:185], v135
	ds_read_b128 v[186:189], v135 offset:1024
	ds_read_b128 v[190:193], v156
	ds_read_b128 v[194:197], v156 offset:1024
	ds_read_b128 v[198:201], v157
	ds_read_b128 v[202:205], v157 offset:1024
	ds_read_b128 v[206:209], v158
	ds_read_b128 v[210:213], v158 offset:1024
	v_mov_b32_e32 v129, v149
	v_lshl_add_u64 v[128:129], v[128:129], 1, s[18:19]
	s_mov_b64 s[14:15], 0x780
	v_readfirstlane_b32 s12, v160
	v_lshl_add_u64 v[128:129], v[128:129], 0, s[14:15]
	s_mov_b32 m0, s12
	v_mov_b32_e32 v131, v149
	global_load_lds_dwordx4 v[128:129], off
	v_readfirstlane_b32 s12, v159
	v_lshl_add_u64 v[128:129], v[130:131], 1, s[18:19]
	v_lshl_add_u64 v[128:129], v[128:129], 0, s[14:15]
	s_mov_b32 m0, s12
	s_nop 0
	global_load_lds_dwordx4 v[128:129], off
	s_barrier
	s_waitcnt lgkmcnt(0)
	s_setprio 1
	s_waitcnt lgkmcnt(0)
	v_mfma_f32_16x16x32_bf16 v[124:127], v[182:185], v[142:145], v[124:127]
	v_mfma_f32_16x16x32_bf16 v[120:123], v[182:185], v[174:177], v[120:123]
	v_mfma_f32_16x16x32_bf16 v[116:119], v[190:193], v[142:145], v[116:119]
	v_mfma_f32_16x16x32_bf16 v[112:115], v[190:193], v[174:177], v[112:115]
	v_mfma_f32_16x16x32_bf16 v[108:111], v[198:201], v[142:145], v[108:111]
	v_mfma_f32_16x16x32_bf16 v[104:107], v[198:201], v[174:177], v[104:107]
	v_mfma_f32_16x16x32_bf16 v[96:99], v[206:209], v[174:177], v[96:99]
	v_mfma_f32_16x16x32_bf16 v[124:127], v[186:189], v[162:165], v[124:127]
	v_mfma_f32_16x16x32_bf16 v[120:123], v[186:189], v[178:181], v[120:123]
	v_mfma_f32_16x16x32_bf16 v[116:119], v[194:197], v[162:165], v[116:119]
	v_mfma_f32_16x16x32_bf16 v[112:115], v[194:197], v[178:181], v[112:115]
	v_mfma_f32_16x16x32_bf16 v[108:111], v[202:205], v[162:165], v[108:111]
	v_mfma_f32_16x16x32_bf16 v[104:107], v[202:205], v[178:181], v[104:107]
	v_mfma_f32_16x16x32_bf16 v[100:103], v[206:209], v[142:145], v[100:103]
	v_mfma_f32_16x16x32_bf16 v[96:99], v[210:213], v[178:181], v[96:99]
	v_mfma_f32_16x16x32_bf16 v[128:131], v[210:213], v[162:165], v[100:103]
	s_setprio 0
	s_barrier
	s_nop 3
	ds_read_b128 v[100:103], v152
	ds_read_b128 v[214:217], v152 offset:1024
	ds_read_b128 v[218:221], v152 offset:2048
	ds_read_b128 v[152:155], v152 offset:3072
	s_barrier
	s_waitcnt lgkmcnt(0)
	s_setprio 1
	s_waitcnt lgkmcnt(0)
	v_mfma_f32_16x16x32_bf16 v[88:91], v[182:185], v[218:221], v[88:91]
	v_mfma_f32_16x16x32_bf16 v[92:95], v[182:185], v[100:103], v[92:95]
	v_mfma_f32_16x16x32_bf16 v[88:91], v[186:189], v[152:155], v[88:91]
	v_mfma_f32_16x16x32_bf16 v[84:87], v[190:193], v[100:103], v[84:87]
	v_mfma_f32_16x16x32_bf16 v[80:83], v[190:193], v[218:221], v[80:83]
	v_mfma_f32_16x16x32_bf16 v[76:79], v[198:201], v[100:103], v[76:79]
	v_mfma_f32_16x16x32_bf16 v[72:75], v[198:201], v[218:221], v[72:75]
	v_mfma_f32_16x16x32_bf16 v[68:71], v[206:209], v[100:103], v[68:71]
	v_mfma_f32_16x16x32_bf16 v[64:67], v[206:209], v[218:221], v[64:67]
	v_mfma_f32_16x16x32_bf16 v[222:225], v[186:189], v[214:217], v[92:95]
	v_mfma_f32_16x16x32_bf16 v[182:185], v[194:197], v[214:217], v[84:87]
	v_mfma_f32_16x16x32_bf16 v[186:189], v[194:197], v[152:155], v[80:83]
	v_mfma_f32_16x16x32_bf16 v[190:193], v[202:205], v[214:217], v[76:79]
	v_mfma_f32_16x16x32_bf16 v[194:197], v[202:205], v[152:155], v[72:75]
	v_mfma_f32_16x16x32_bf16 v[198:201], v[210:213], v[214:217], v[68:71]
	v_mfma_f32_16x16x32_bf16 v[202:205], v[210:213], v[152:155], v[64:67]
	s_setprio 0
	s_barrier
	s_nop 0
	ds_read_b128 v[64:67], v135 offset:16384
	ds_read_b128 v[68:71], v135 offset:17408
	ds_read_b128 v[72:75], v156 offset:16384
	ds_read_b128 v[76:79], v156 offset:17408
	ds_read_b128 v[80:83], v157 offset:16384
	ds_read_b128 v[84:87], v157 offset:17408
	ds_read_b128 v[92:95], v158 offset:16384
	ds_read_b128 v[206:209], v158 offset:17408
	s_waitcnt vmcnt(4)
	s_barrier
	s_waitcnt lgkmcnt(0)
	s_setprio 1
	s_waitcnt lgkmcnt(0)
	v_mfma_f32_16x16x32_bf16 v[60:63], v[64:67], v[142:145], v[60:63]
	v_mfma_f32_16x16x32_bf16 v[56:59], v[64:67], v[174:177], v[56:59]
	v_mfma_f32_16x16x32_bf16 v[52:55], v[72:75], v[142:145], v[52:55]
	v_mfma_f32_16x16x32_bf16 v[48:51], v[72:75], v[174:177], v[48:51]
	v_mfma_f32_16x16x32_bf16 v[44:47], v[80:83], v[142:145], v[44:47]
	v_mfma_f32_16x16x32_bf16 v[40:43], v[80:83], v[174:177], v[40:43]
	v_mfma_f32_16x16x32_bf16 v[36:39], v[92:95], v[142:145], v[36:39]
	v_mfma_f32_16x16x32_bf16 v[32:35], v[92:95], v[174:177], v[32:35]
	v_mfma_f32_16x16x32_bf16 v[60:63], v[68:71], v[162:165], v[60:63]
	v_mfma_f32_16x16x32_bf16 v[56:59], v[68:71], v[178:181], v[56:59]
	v_mfma_f32_16x16x32_bf16 v[52:55], v[76:79], v[162:165], v[52:55]
	v_mfma_f32_16x16x32_bf16 v[48:51], v[76:79], v[178:181], v[48:51]
	v_mfma_f32_16x16x32_bf16 v[44:47], v[84:87], v[162:165], v[44:47]
	v_mfma_f32_16x16x32_bf16 v[40:43], v[84:87], v[178:181], v[40:43]
	v_mfma_f32_16x16x32_bf16 v[36:39], v[206:209], v[162:165], v[36:39]
	v_mfma_f32_16x16x32_bf16 v[32:35], v[206:209], v[178:181], v[32:35]
	s_setprio 0
	s_setprio 1
	v_mfma_f32_16x16x32_bf16 v[28:31], v[64:67], v[100:103], v[28:31]
	v_mfma_f32_16x16x32_bf16 v[24:27], v[64:67], v[218:221], v[24:27]
	v_mfma_f32_16x16x32_bf16 v[20:23], v[72:75], v[100:103], v[20:23]
	v_mfma_f32_16x16x32_bf16 v[16:19], v[72:75], v[218:221], v[16:19]
	v_mfma_f32_16x16x32_bf16 v[12:15], v[80:83], v[100:103], v[12:15]
	v_mfma_f32_16x16x32_bf16 v[8:11], v[80:83], v[218:221], v[8:11]
	v_mfma_f32_16x16x32_bf16 v[4:7], v[92:95], v[100:103], v[4:7]
	v_mfma_f32_16x16x32_bf16 v[0:3], v[92:95], v[218:221], v[0:3]
	v_mfma_f32_16x16x32_bf16 v[142:145], v[68:71], v[214:217], v[28:31]
	v_mfma_f32_16x16x32_bf16 v[160:163], v[68:71], v[152:155], v[24:27]
	v_mfma_f32_16x16x32_bf16 v[164:167], v[76:79], v[214:217], v[20:23]
	v_mfma_f32_16x16x32_bf16 v[174:177], v[76:79], v[152:155], v[16:19]
	v_mfma_f32_16x16x32_bf16 v[178:181], v[84:87], v[214:217], v[12:15]
	v_mfma_f32_16x16x32_bf16 v[210:213], v[84:87], v[152:155], v[8:11]
	v_mfma_f32_16x16x32_bf16 v[214:217], v[206:209], v[214:217], v[4:7]
	v_mfma_f32_16x16x32_bf16 v[152:155], v[206:209], v[152:155], v[0:3]
	s_setprio 0
	s_barrier
; #define LDA(dst, b, h)                                                                                    \
;   _Pragma("unroll") for (int m = 0; m < 4; ++m) _Pragma("unroll") for (int k = 0; k < 2; ++k)             \
;       dst[m][k] = *reinterpret_cast<const bf16x8*>((char*)SA(b, h) + lds_byte(wr * 64 + m * 16 + fr, k * 32 + fq * 8))
; #define LDB(dst, b, h)                                                                                    \
;   _Pragma("unroll") for (int n = 0; n < 2; ++n) _Pragma("unroll") for (int k = 0; k < 2; ++k)             \
;       dst[n][k] = *reinterpret_cast<const bf16x8*>((char*)SB(b, h) + lds_byte(wc * 32 + n * 16 + fr, k * 32 + fq * 8))
; #define WAIT_V(n) asm volatile("s_waitcnt vmcnt(" #n ")" ::: "memory")
; #define WAIT_L(n) asm volatile("s_waitcnt lgkmcnt(" #n ")" ::: "memory")
; #define BAR __builtin_amdgcn_s_barrier()
; template <int EPI> ...
;     ...
;     LDA(At, 0, 1); WAIT_V(4); BAR; WAIT_L(0); MMA(1, 0, At, B0); MMA(1, 1, At, B1); BAR;
;   }
;   {
;     LDB(B0, 1, 0); LDA(At, 1, 0); WAIT_V(2); BAR; WAIT_L(0); MMA(0, 0, At, B0); BAR;
;     LDB(B1, 1, 1); WAIT_V(0); BAR; WAIT_L(0); MMA(0, 1, At, B1); BAR;
;     LDA(At, 1, 1); BAR; WAIT_L(0); MMA(1, 0, At, B0); MMA(1, 1, At, B1); BAR;
;   }
;   if (wr == 0) BAR;
;   if (has_next) ISSUE_PRO(nm0, nn0);
	s_nop 0
	ds_read_b128 v[0:3], v140
	ds_read_b128 v[4:7], v140 offset:1024
	ds_read_b128 v[206:209], v140 offset:2048
	ds_read_b128 v[138:141], v140 offset:3072
	ds_read_b128 v[8:11], v135 offset:32768
	ds_read_b128 v[12:15], v135 offset:33792
	ds_read_b128 v[16:19], v156 offset:32768
	ds_read_b128 v[20:23], v156 offset:33792
	ds_read_b128 v[24:27], v157 offset:32768
	ds_read_b128 v[28:31], v157 offset:33792
	ds_read_b128 v[218:221], v158 offset:32768
	ds_read_b128 v[226:229], v158 offset:33792
	s_waitcnt vmcnt(2)
	s_barrier
	s_waitcnt lgkmcnt(0)
	s_setprio 1
	s_waitcnt lgkmcnt(0)
	v_mfma_f32_16x16x32_bf16 v[64:67], v[8:11], v[0:3], v[124:127]
	v_mfma_f32_16x16x32_bf16 v[92:95], v[12:15], v[4:7], v[64:67]
	v_mfma_f32_16x16x32_bf16 v[64:67], v[8:11], v[206:209], v[120:123]
	v_mfma_f32_16x16x32_bf16 v[100:103], v[12:15], v[138:141], v[64:67]
	v_mfma_f32_16x16x32_bf16 v[64:67], v[16:19], v[0:3], v[116:119]
	v_mfma_f32_16x16x32_bf16 v[80:83], v[20:23], v[4:7], v[64:67]
	v_mfma_f32_16x16x32_bf16 v[64:67], v[16:19], v[206:209], v[112:115]
	v_mfma_f32_16x16x32_bf16 v[84:87], v[20:23], v[138:141], v[64:67]
	v_mfma_f32_16x16x32_bf16 v[64:67], v[24:27], v[0:3], v[108:111]
	v_mfma_f32_16x16x32_bf16 v[72:75], v[28:31], v[4:7], v[64:67]
	v_mfma_f32_16x16x32_bf16 v[64:67], v[24:27], v[206:209], v[104:107]
	v_mfma_f32_16x16x32_bf16 v[76:79], v[28:31], v[138:141], v[64:67]
	v_mfma_f32_16x16x32_bf16 v[64:67], v[218:221], v[0:3], v[128:131]
	v_mfma_f32_16x16x32_bf16 v[68:71], v[218:221], v[206:209], v[96:99]
	v_mfma_f32_16x16x32_bf16 v[64:67], v[226:229], v[4:7], v[64:67]
	v_mfma_f32_16x16x32_bf16 v[68:71], v[226:229], v[138:141], v[68:71]
	s_setprio 0
	s_barrier
	ds_read_b128 v[128:131], v137
	ds_read_b128 v[230:233], v137 offset:1024
	ds_read_b128 v[234:237], v137 offset:2048
	ds_read_b128 v[238:241], v137 offset:3072
	s_waitcnt vmcnt(0)
	s_barrier
	s_waitcnt lgkmcnt(0)
	s_setprio 1
	s_waitcnt lgkmcnt(0)
	v_mfma_f32_16x16x32_bf16 v[96:99], v[8:11], v[128:131], v[222:225]
	v_mfma_f32_16x16x32_bf16 v[8:11], v[8:11], v[234:237], v[88:91]
	v_mfma_f32_16x16x32_bf16 v[124:127], v[12:15], v[238:241], v[8:11]
	v_mfma_f32_16x16x32_bf16 v[8:11], v[16:19], v[128:131], v[182:185]
	v_mfma_f32_16x16x32_bf16 v[112:115], v[20:23], v[230:233], v[8:11]
	v_mfma_f32_16x16x32_bf16 v[8:11], v[16:19], v[234:237], v[186:189]
	v_mfma_f32_16x16x32_bf16 v[116:119], v[20:23], v[238:241], v[8:11]
	v_mfma_f32_16x16x32_bf16 v[8:11], v[24:27], v[128:131], v[190:193]
	v_mfma_f32_16x16x32_bf16 v[104:107], v[28:31], v[230:233], v[8:11]
	v_mfma_f32_16x16x32_bf16 v[8:11], v[24:27], v[234:237], v[194:197]
	v_mfma_f32_16x16x32_bf16 v[108:111], v[28:31], v[238:241], v[8:11]
	v_mfma_f32_16x16x32_bf16 v[8:11], v[218:221], v[128:131], v[198:201]
	v_mfma_f32_16x16x32_bf16 v[88:91], v[226:229], v[230:233], v[8:11]
	v_mfma_f32_16x16x32_bf16 v[8:11], v[218:221], v[234:237], v[202:205]
	v_mfma_f32_16x16x32_bf16 v[120:123], v[12:15], v[230:233], v[96:99]
	v_mfma_f32_16x16x32_bf16 v[96:99], v[226:229], v[238:241], v[8:11]
	s_setprio 0
	s_barrier
	ds_read_b128 v[182:185], v135 offset:49152
	ds_read_b128 v[134:137], v135 offset:50176
	ds_read_b128 v[186:189], v156 offset:49152
	ds_read_b128 v[190:193], v156 offset:50176
	ds_read_b128 v[194:197], v157 offset:49152
	ds_read_b128 v[198:201], v157 offset:50176
	ds_read_b128 v[202:205], v158 offset:49152
	ds_read_b128 v[156:159], v158 offset:50176
	s_barrier
	s_waitcnt lgkmcnt(0)
	s_setprio 1
	s_waitcnt lgkmcnt(0)
	v_mfma_f32_16x16x32_bf16 v[8:11], v[182:185], v[0:3], v[60:63]
	v_mfma_f32_16x16x32_bf16 v[24:27], v[134:137], v[4:7], v[8:11]
	v_mfma_f32_16x16x32_bf16 v[8:11], v[182:185], v[206:209], v[56:59]
	v_mfma_f32_16x16x32_bf16 v[28:31], v[134:137], v[138:141], v[8:11]
	v_mfma_f32_16x16x32_bf16 v[8:11], v[186:189], v[0:3], v[52:55]
	v_mfma_f32_16x16x32_bf16 v[16:19], v[190:193], v[4:7], v[8:11]
	v_mfma_f32_16x16x32_bf16 v[8:11], v[186:189], v[206:209], v[48:51]
	v_mfma_f32_16x16x32_bf16 v[20:23], v[190:193], v[138:141], v[8:11]
	v_mfma_f32_16x16x32_bf16 v[8:11], v[194:197], v[0:3], v[44:47]
	v_mfma_f32_16x16x32_bf16 v[0:3], v[202:205], v[0:3], v[36:39]
	v_mfma_f32_16x16x32_bf16 v[8:11], v[198:201], v[4:7], v[8:11]
	v_mfma_f32_16x16x32_bf16 v[12:15], v[194:197], v[206:209], v[40:43]
	v_mfma_f32_16x16x32_bf16 v[0:3], v[156:159], v[4:7], v[0:3]
	v_mfma_f32_16x16x32_bf16 v[4:7], v[202:205], v[206:209], v[32:35]
	v_mfma_f32_16x16x32_bf16 v[12:15], v[198:201], v[138:141], v[12:15]
	v_mfma_f32_16x16x32_bf16 v[4:7], v[156:159], v[138:141], v[4:7]
	s_setprio 0
	s_setprio 1
	v_mfma_f32_16x16x32_bf16 v[32:35], v[182:185], v[128:131], v[142:145]
	v_mfma_f32_16x16x32_bf16 v[56:59], v[134:137], v[230:233], v[32:35]
	v_mfma_f32_16x16x32_bf16 v[32:35], v[182:185], v[234:237], v[160:163]
	v_mfma_f32_16x16x32_bf16 v[60:63], v[134:137], v[238:241], v[32:35]
	v_mfma_f32_16x16x32_bf16 v[32:35], v[186:189], v[128:131], v[164:167]
	v_mfma_f32_16x16x32_bf16 v[48:51], v[190:193], v[230:233], v[32:35]
	v_mfma_f32_16x16x32_bf16 v[32:35], v[186:189], v[234:237], v[174:177]
	v_mfma_f32_16x16x32_bf16 v[52:55], v[190:193], v[238:241], v[32:35]
	v_mfma_f32_16x16x32_bf16 v[32:35], v[194:197], v[128:131], v[178:181]
	v_mfma_f32_16x16x32_bf16 v[40:43], v[198:201], v[230:233], v[32:35]
	v_mfma_f32_16x16x32_bf16 v[32:35], v[194:197], v[234:237], v[210:213]
	v_mfma_f32_16x16x32_bf16 v[44:47], v[198:201], v[238:241], v[32:35]
	v_mfma_f32_16x16x32_bf16 v[32:35], v[202:205], v[128:131], v[214:217]
	v_mfma_f32_16x16x32_bf16 v[36:39], v[202:205], v[234:237], v[152:155]
	v_mfma_f32_16x16x32_bf16 v[32:35], v[156:159], v[230:233], v[32:35]
	v_mfma_f32_16x16x32_bf16 v[36:39], v[156:159], v[238:241], v[36:39]
	s_setprio 0
	s_cmpk_gt_u32 s34, 0xff
	s_barrier
	s_cbranch_scc1 .LBB0_1019
	s_barrier

; DEVI f32x4 ozero() { float z = 0.f; asm volatile("" : "+v"(z)); return f32x4{z, z, z, z}; }
; #define LDA(dst, b, h)                                                                                    \
;   _Pragma("unroll") for (int m = 0; m < 4; ++m) _Pragma("unroll") for (int k = 0; k < 2; ++k)             \
;       dst[m][k] = *reinterpret_cast<const bf16x8*>((char*)SA(b, h) + lds_byte(wr * 64 + m * 16 + fr, k * 32 + fq * 8))
; #define LDB(dst, b, h)                                                                                    \
;   _Pragma("unroll") for (int n = 0; n < 2; ++n) _Pragma("unroll") for (int k = 0; k < 2; ++k)             \
;       dst[n][k] = *reinterpret_cast<const bf16x8*>((char*)SB(b, h) + lds_byte(wc * 32 + n * 16 + fr, k * 32 + fq * 8))
; #define WAIT_V(n) asm volatile("s_waitcnt vmcnt(" #n ")" ::: "memory")
; #define WAIT_L(n) asm volatile("s_waitcnt lgkmcnt(" #n ")" ::: "memory")
; #define BAR __builtin_amdgcn_s_barrier()
; #define SCHED __builtin_amdgcn_sched_barrier(0)
; template <int EPI> ...
;     ...
;   const int brow = m0, bcol = n0;
;   const int wid = __builtin_amdgcn_readfirstlane(tid >> 6), lane = tid & 63, wr = wid >> 2, wc = wid & 3, fr = lane & 15, fq = lane >> 4;
;   f32x4 acc[2][2][4][2];
;   {
;     const f32x4 zq = ozero();
; #pragma unroll
;     for (int a_ = 0; a_ < 2; ++a_)
; #pragma unroll
;       for (int b_ = 0; b_ < 2; ++b_)
; #pragma unroll
;         for (int m = 0; m < 4; ++m) { acc[a_][b_][m][0] = zq; acc[a_][b_][m][1] = zq; }
;   }
;   bf16x8 At[4][2], B0[2][2], B1[2][2];
;   const int nt = K / BK;
;     ...
;   if (first) {
;     WAIT_V(0);
;     ISSUE_PRO(brow, bcol);
;   }
;   if (wr == 1) BAR;
;   WAIT_V(10); BAR;
;   WAIT_V(6); BAR;
;   for (int t = 0; t < nt - 2; t += 2) {
;     LDB(B0, 0, 0); SCHED; LDA(At, 0, 0); STAGE(SA(1, 1), A, brow + HALF, t + 1);
;     WAIT_L(8); BAR; WAIT_L(0); MMA(0, 0, At, B0); BAR; SCHED;
.LBB0_1665:
	v_and_b32_e32 v133, 15, v132
	v_and_b32_e32 v1, 48, v132
	v_lshlrev_b32_e32 v2, 6, v133
	v_lshlrev_b32_e32 v4, 2, v132
	v_or_b32_e32 v3, v2, v1
	v_and_b32_e32 v4, 32, v4
	s_mov_b32 s18, 0x10000
	v_bitop3_b32 v5, v3, s18, v4 bitop3:0xde
	s_mov_b32 s18, 0x14000
	s_ashr_i32 s31, s30, 6
	v_bitop3_b32 v6, v3, s18, v4 bitop3:0xde
	s_mov_b32 s18, 0x18000
	s_and_b32 s9, s31, 3
	s_waitcnt vmcnt(10)
	s_barrier
	s_waitcnt vmcnt(6)
	v_bitop3_b32 v7, v3, s18, v4 bitop3:0xde
	s_mov_b32 s18, 0x1c000
	v_lshlrev_b32_e32 v8, 6, v132
	s_lshl_b32 s21, s9, 12
	v_bitop3_b32 v2, v2, v4, v1 bitop3:0x36
	s_lshl_b32 s34, s20, 6
	v_bitop3_b32 v3, v3, s18, v4 bitop3:0xde
	s_lshl_b32 s20, s20, 13
	v_and_b32_e32 v8, 0x3c0, v8
	v_bitop3_b32 v154, v8, v4, v1 bitop3:0x36
	s_or_b32 s35, s20, 0x800
	s_or_b32 s67, s20, 0x1000
	s_or_b32 s68, s20, 0x1800
	s_mov_b32 s69, -2
	s_mov_b64 s[18:19], 0
	v_add_u32_e32 v155, s21, v5
	v_add_u32_e32 v135, s20, v2
	v_add_u32_e32 v152, s21, v6
	v_add_u32_e32 v140, s21, v7
	v_add_u32_e32 v137, s21, v3
	v_mov_b32_e32 v1, v0
	v_mov_b32_e32 v2, v0
	v_mov_b32_e32 v3, v0
	v_mov_b32_e32 v4, v0
	v_mov_b32_e32 v5, v0
	v_mov_b32_e32 v6, v0
	v_mov_b32_e32 v7, v0
	v_mov_b32_e32 v8, v0
	v_mov_b32_e32 v9, v0
	v_mov_b32_e32 v10, v0
	v_mov_b32_e32 v11, v0
	v_mov_b32_e32 v12, v0
	v_mov_b32_e32 v13, v0
	v_mov_b32_e32 v14, v0
	v_mov_b32_e32 v15, v0
	v_mov_b32_e32 v16, v0
	v_mov_b32_e32 v17, v0
	v_mov_b32_e32 v18, v0
	v_mov_b32_e32 v19, v0
	v_mov_b32_e32 v20, v0
	v_mov_b32_e32 v21, v0
	v_mov_b32_e32 v22, v0
	v_mov_b32_e32 v23, v0
	v_mov_b32_e32 v24, v0
	v_mov_b32_e32 v25, v0
	v_mov_b32_e32 v26, v0
	v_mov_b32_e32 v27, v0
	v_mov_b32_e32 v28, v0
	v_mov_b32_e32 v29, v0
	v_mov_b32_e32 v30, v0
	v_mov_b32_e32 v31, v0
	v_mov_b32_e32 v32, v0
	v_mov_b32_e32 v33, v0
	v_mov_b32_e32 v34, v0
	v_mov_b32_e32 v35, v0
	v_mov_b32_e32 v36, v0
	v_mov_b32_e32 v37, v0
	v_mov_b32_e32 v38, v0
	v_mov_b32_e32 v39, v0
	v_mov_b32_e32 v40, v0
	v_mov_b32_e32 v41, v0
	v_mov_b32_e32 v42, v0
	v_mov_b32_e32 v43, v0
	v_mov_b32_e32 v44, v0
	v_mov_b32_e32 v45, v0
	v_mov_b32_e32 v46, v0
	v_mov_b32_e32 v47, v0
	v_mov_b32_e32 v48, v0
	v_mov_b32_e32 v49, v0
	v_mov_b32_e32 v50, v0
	v_mov_b32_e32 v51, v0
	v_mov_b32_e32 v52, v0
	v_mov_b32_e32 v53, v0
	v_mov_b32_e32 v54, v0
	v_mov_b32_e32 v55, v0
	v_mov_b32_e32 v56, v0
	v_mov_b32_e32 v57, v0
	v_mov_b32_e32 v58, v0
	v_mov_b32_e32 v59, v0
	v_mov_b32_e32 v60, v0
	v_mov_b32_e32 v61, v0
	v_mov_b32_e32 v62, v0
	v_mov_b32_e32 v63, v0
	v_mov_b32_e32 v64, v0
	v_mov_b32_e32 v65, v0
	v_mov_b32_e32 v66, v0
	v_mov_b32_e32 v67, v0
	v_mov_b32_e32 v68, v0
	v_mov_b32_e32 v69, v0
	v_mov_b32_e32 v70, v0
	v_mov_b32_e32 v71, v0
	v_mov_b32_e32 v72, v0
	v_mov_b32_e32 v73, v0
	v_mov_b32_e32 v74, v0
	v_mov_b32_e32 v75, v0
	v_mov_b32_e32 v76, v0
	v_mov_b32_e32 v77, v0
	v_mov_b32_e32 v78, v0
	v_mov_b32_e32 v79, v0
	v_mov_b32_e32 v80, v0
	v_mov_b32_e32 v81, v0
	v_mov_b32_e32 v82, v0
	v_mov_b32_e32 v83, v0
	v_mov_b32_e32 v84, v0
	v_mov_b32_e32 v85, v0
	v_mov_b32_e32 v86, v0
	v_mov_b32_e32 v87, v0
	v_mov_b32_e32 v88, v0
	v_mov_b32_e32 v89, v0
	v_mov_b32_e32 v90, v0
	v_mov_b32_e32 v91, v0
	v_mov_b32_e32 v92, v0
	v_mov_b32_e32 v93, v0
	v_mov_b32_e32 v94, v0
	v_mov_b32_e32 v95, v0
	v_mov_b32_e32 v96, v0
	v_mov_b32_e32 v97, v0
	v_mov_b32_e32 v98, v0
	v_mov_b32_e32 v99, v0
	v_mov_b32_e32 v100, v0
	v_mov_b32_e32 v101, v0
	v_mov_b32_e32 v102, v0
	v_mov_b32_e32 v103, v0
	v_mov_b32_e32 v104, v0
	v_mov_b32_e32 v105, v0
	v_mov_b32_e32 v106, v0
	v_mov_b32_e32 v107, v0
	v_mov_b32_e32 v108, v0
	v_mov_b32_e32 v109, v0
	v_mov_b32_e32 v110, v0
	v_mov_b32_e32 v111, v0
	v_mov_b32_e32 v112, v0
	v_mov_b32_e32 v113, v0
	v_mov_b32_e32 v114, v0
	v_mov_b32_e32 v115, v0
	v_mov_b32_e32 v116, v0
	v_mov_b32_e32 v117, v0
	v_mov_b32_e32 v118, v0
	v_mov_b32_e32 v119, v0
	v_mov_b32_e32 v120, v0
	v_mov_b32_e32 v121, v0
	v_mov_b32_e32 v122, v0
	v_mov_b32_e32 v123, v0
	v_mov_b32_e32 v124, v0
	v_mov_b32_e32 v125, v0
	v_mov_b32_e32 v126, v0
	v_mov_b32_e32 v127, v0
	s_barrier
	v_lshlrev_b32_e32 v253, 1, v128
	v_lshlrev_b32_e32 v252, 1, v130
	v_readfirstlane_b32 s32, v129
.LBB0_1666:
	ds_read_b128 v[162:165], v155
	ds_read_b128 v[178:181], v155 offset:1024
	ds_read_b128 v[182:185], v155 offset:2048
	ds_read_b128 v[186:189], v155 offset:3072
	s_add_u32 s20, s14, s18
	v_add_u32_e32 v156, s35, v154
	v_add_u32_e32 v157, s67, v154
	v_add_u32_e32 v158, s68, v154
	s_addc_u32 s21, s15, s19
	ds_read_b128 v[190:193], v135
	ds_read_b128 v[194:197], v135 offset:1024
	ds_read_b128 v[198:201], v156
	ds_read_b128 v[202:205], v156 offset:1024
	ds_read_b128 v[206:209], v157
	ds_read_b128 v[210:213], v157 offset:1024
	ds_read_b128 v[214:217], v158
	ds_read_b128 v[218:221], v158 offset:1024
	v_add_u32_e32 v159, 0xe000, v129
	v_add_u32_e32 v160, 0xc000, v129
	s_add_u32 m0, s32, 0xc000
	s_add_u32 s98, s20, 0x40080
	s_addc_u32 s99, s21, 0
	global_load_lds_dwordx4 v253, s[98:99]
	s_add_u32 m0, s32, 0xe000
	s_nop 0
	global_load_lds_dwordx4 v252, s[98:99]
	s_waitcnt lgkmcnt(8)
	s_barrier
	s_waitcnt lgkmcnt(0)
	s_setprio 1
	s_waitcnt lgkmcnt(0)
	v_mfma_f32_16x16x32_bf16 v[124:127], v[190:193], v[162:165], v[124:127]
	v_mfma_f32_16x16x32_bf16 v[120:123], v[190:193], v[182:185], v[120:123]
	v_mfma_f32_16x16x32_bf16 v[116:119], v[198:201], v[162:165], v[116:119]
	v_mfma_f32_16x16x32_bf16 v[112:115], v[198:201], v[182:185], v[112:115]
	v_mfma_f32_16x16x32_bf16 v[108:111], v[206:209], v[162:165], v[108:111]
	v_mfma_f32_16x16x32_bf16 v[104:107], v[206:209], v[182:185], v[104:107]
	v_mfma_f32_16x16x32_bf16 v[100:103], v[214:217], v[162:165], v[100:103]
	v_mfma_f32_16x16x32_bf16 v[96:99], v[214:217], v[182:185], v[96:99]
	v_mfma_f32_16x16x32_bf16 v[124:127], v[194:197], v[178:181], v[124:127]
	v_mfma_f32_16x16x32_bf16 v[120:123], v[194:197], v[186:189], v[120:123]
	v_mfma_f32_16x16x32_bf16 v[116:119], v[202:205], v[178:181], v[116:119]
	v_mfma_f32_16x16x32_bf16 v[112:115], v[202:205], v[186:189], v[112:115]
	v_mfma_f32_16x16x32_bf16 v[108:111], v[210:213], v[178:181], v[108:111]
	v_mfma_f32_16x16x32_bf16 v[104:107], v[210:213], v[186:189], v[104:107]
	v_mfma_f32_16x16x32_bf16 v[100:103], v[218:221], v[178:181], v[100:103]
	v_mfma_f32_16x16x32_bf16 v[96:99], v[218:221], v[186:189], v[96:99]
	s_setprio 0
	s_barrier
; #define LDA(dst, b, h)                                                                                    \
;   _Pragma("unroll") for (int m = 0; m < 4; ++m) _Pragma("unroll") for (int k = 0; k < 2; ++k)             \
;       dst[m][k] = *reinterpret_cast<const bf16x8*>((char*)SA(b, h) + lds_byte(wr * 64 + m * 16 + fr, k * 32 + fq * 8))
; #define LDB(dst, b, h)                                                                                    \
;   _Pragma("unroll") for (int n = 0; n < 2; ++n) _Pragma("unroll") for (int k = 0; k < 2; ++k)             \
;       dst[n][k] = *reinterpret_cast<const bf16x8*>((char*)SB(b, h) + lds_byte(wc * 32 + n * 16 + fr, k * 32 + fq * 8))
; #define WAIT_V(n) asm volatile("s_waitcnt vmcnt(" #n ")" ::: "memory")
; #define WAIT_L(n) asm volatile("s_waitcnt lgkmcnt(" #n ")" ::: "memory")
; #define BAR __builtin_amdgcn_s_barrier()
; #define SCHED __builtin_amdgcn_sched_barrier(0)
; template <int EPI> ...
;     ...
;     LDB(B1, 0, 1); STAGE(SB(0, 0), Bt, bcol, t + 2);
;     BAR; WAIT_L(0); MMA(0, 1, At, B1); BAR;
;     LDA(At, 0, 1); STAGE(SA(0, 0), A, brow, t + 2);
;     BAR; WAIT_L(0); MMA(1, 0, At, B0); BAR; SCHED;
;     STAGE(SB(0, 1), Bt, bcol + HALF, t + 2);
;     WAIT_V(6); BAR; MMA(1, 1, At, B1); BAR;
;     LDB(B0, 1, 0); SCHED; LDA(At, 1, 0); STAGE(SA(0, 1), A, brow + HALF, t + 2);
;     WAIT_L(8); BAR; WAIT_L(0); MMA(0, 0, At, B0); BAR; SCHED;
;     LDB(B1, 1, 1); STAGE(SB(1, 0), Bt, bcol, t + 3);
	s_add_u32 s22, s12, s18
	s_addc_u32 s23, s13, s19
	ds_read_b128 v[222:225], v152
	ds_read_b128 v[226:229], v152 offset:1024
	ds_read_b128 v[230:233], v152 offset:2048
	ds_read_b128 v[234:237], v152 offset:3072
	s_add_u32 m0, s32, 0x10000
	s_add_u32 s98, s22, 0x100
	s_addc_u32 s99, s23, 0
	global_load_lds_dwordx4 v253, s[98:99]
	s_add_u32 m0, s32, 0x12000
	s_nop 0
	global_load_lds_dwordx4 v252, s[98:99]
	s_barrier
	s_waitcnt lgkmcnt(0)
	s_setprio 1
	s_waitcnt lgkmcnt(0)
	v_mfma_f32_16x16x32_bf16 v[92:95], v[190:193], v[222:225], v[92:95]
	v_mfma_f32_16x16x32_bf16 v[88:91], v[190:193], v[230:233], v[88:91]
	v_mfma_f32_16x16x32_bf16 v[84:87], v[198:201], v[222:225], v[84:87]
	v_mfma_f32_16x16x32_bf16 v[80:83], v[198:201], v[230:233], v[80:83]
	v_mfma_f32_16x16x32_bf16 v[76:79], v[206:209], v[222:225], v[76:79]
	v_mfma_f32_16x16x32_bf16 v[72:75], v[206:209], v[230:233], v[72:75]
	v_mfma_f32_16x16x32_bf16 v[68:71], v[214:217], v[222:225], v[68:71]
	v_mfma_f32_16x16x32_bf16 v[64:67], v[214:217], v[230:233], v[64:67]
	v_mfma_f32_16x16x32_bf16 v[92:95], v[194:197], v[226:229], v[92:95]
	v_mfma_f32_16x16x32_bf16 v[88:91], v[194:197], v[234:237], v[88:91]
	v_mfma_f32_16x16x32_bf16 v[84:87], v[202:205], v[226:229], v[84:87]
	v_mfma_f32_16x16x32_bf16 v[80:83], v[202:205], v[234:237], v[80:83]
	v_mfma_f32_16x16x32_bf16 v[76:79], v[210:213], v[226:229], v[76:79]
	v_mfma_f32_16x16x32_bf16 v[72:75], v[210:213], v[234:237], v[72:75]
	v_mfma_f32_16x16x32_bf16 v[68:71], v[218:221], v[226:229], v[68:71]
	v_mfma_f32_16x16x32_bf16 v[64:67], v[218:221], v[234:237], v[64:67]
	s_setprio 0
	s_barrier
	ds_read_b128 v[190:193], v135 offset:16384
	ds_read_b128 v[194:197], v135 offset:17408
	ds_read_b128 v[198:201], v156 offset:16384
	ds_read_b128 v[202:205], v156 offset:17408
	ds_read_b128 v[206:209], v157 offset:16384
	ds_read_b128 v[210:213], v157 offset:17408
	ds_read_b128 v[214:217], v158 offset:16384
	ds_read_b128 v[218:221], v158 offset:17408
	s_mov_b32 m0, s32
	s_add_u32 s98, s20, 0x100
	s_addc_u32 s99, s21, 0
	global_load_lds_dwordx4 v253, s[98:99]
	s_add_u32 m0, s32, 0x2000
	s_nop 0
	global_load_lds_dwordx4 v252, s[98:99]
	s_barrier
	s_waitcnt lgkmcnt(0)
	s_setprio 1
	s_waitcnt lgkmcnt(0)
	v_mfma_f32_16x16x32_bf16 v[60:63], v[190:193], v[162:165], v[60:63]
	v_mfma_f32_16x16x32_bf16 v[56:59], v[190:193], v[182:185], v[56:59]
	v_mfma_f32_16x16x32_bf16 v[52:55], v[198:201], v[162:165], v[52:55]
	v_mfma_f32_16x16x32_bf16 v[48:51], v[198:201], v[182:185], v[48:51]
	v_mfma_f32_16x16x32_bf16 v[44:47], v[206:209], v[162:165], v[44:47]
	v_mfma_f32_16x16x32_bf16 v[40:43], v[206:209], v[182:185], v[40:43]
	v_mfma_f32_16x16x32_bf16 v[36:39], v[214:217], v[162:165], v[36:39]
	v_mfma_f32_16x16x32_bf16 v[32:35], v[214:217], v[182:185], v[32:35]
	v_mfma_f32_16x16x32_bf16 v[60:63], v[194:197], v[178:181], v[60:63]
	v_mfma_f32_16x16x32_bf16 v[56:59], v[194:197], v[186:189], v[56:59]
	v_mfma_f32_16x16x32_bf16 v[52:55], v[202:205], v[178:181], v[52:55]
	v_mfma_f32_16x16x32_bf16 v[48:51], v[202:205], v[186:189], v[48:51]
	v_mfma_f32_16x16x32_bf16 v[44:47], v[210:213], v[178:181], v[44:47]
	v_mfma_f32_16x16x32_bf16 v[40:43], v[210:213], v[186:189], v[40:43]
	v_mfma_f32_16x16x32_bf16 v[36:39], v[218:221], v[178:181], v[36:39]
	v_mfma_f32_16x16x32_bf16 v[32:35], v[218:221], v[186:189], v[32:35]
	s_setprio 0
	s_barrier
	s_add_u32 m0, s32, 0x14000
	s_add_u32 s98, s22, 0x40100
	s_addc_u32 s99, s23, 0
	global_load_lds_dwordx4 v253, s[98:99]
	s_add_u32 m0, s32, 0x16000
	s_nop 0
	global_load_lds_dwordx4 v252, s[98:99]
	s_waitcnt vmcnt(6)
	s_barrier
	s_setprio 1
	v_mfma_f32_16x16x32_bf16 v[28:31], v[190:193], v[222:225], v[28:31]
	v_mfma_f32_16x16x32_bf16 v[24:27], v[190:193], v[230:233], v[24:27]
	v_mfma_f32_16x16x32_bf16 v[20:23], v[198:201], v[222:225], v[20:23]
	v_mfma_f32_16x16x32_bf16 v[16:19], v[198:201], v[230:233], v[16:19]
	v_mfma_f32_16x16x32_bf16 v[12:15], v[206:209], v[222:225], v[12:15]
	v_mfma_f32_16x16x32_bf16 v[8:11], v[206:209], v[230:233], v[8:11]
	v_mfma_f32_16x16x32_bf16 v[4:7], v[214:217], v[222:225], v[4:7]
	v_mfma_f32_16x16x32_bf16 v[0:3], v[214:217], v[230:233], v[0:3]
	v_mfma_f32_16x16x32_bf16 v[28:31], v[194:197], v[226:229], v[28:31]
	v_mfma_f32_16x16x32_bf16 v[24:27], v[194:197], v[234:237], v[24:27]
	v_mfma_f32_16x16x32_bf16 v[20:23], v[202:205], v[226:229], v[20:23]
	v_mfma_f32_16x16x32_bf16 v[16:19], v[202:205], v[234:237], v[16:19]
	v_mfma_f32_16x16x32_bf16 v[12:15], v[210:213], v[226:229], v[12:15]
	v_mfma_f32_16x16x32_bf16 v[8:11], v[210:213], v[234:237], v[8:11]
	v_mfma_f32_16x16x32_bf16 v[4:7], v[218:221], v[226:229], v[4:7]
	v_mfma_f32_16x16x32_bf16 v[0:3], v[218:221], v[234:237], v[0:3]
	s_setprio 0
	s_barrier
	ds_read_b128 v[162:165], v140
	ds_read_b128 v[178:181], v140 offset:1024
	ds_read_b128 v[182:185], v140 offset:2048
	ds_read_b128 v[186:189], v140 offset:3072
	ds_read_b128 v[190:193], v135 offset:32768
	ds_read_b128 v[194:197], v135 offset:33792
	ds_read_b128 v[198:201], v156 offset:32768
	ds_read_b128 v[202:205], v156 offset:33792
	ds_read_b128 v[206:209], v157 offset:32768
	ds_read_b128 v[210:213], v157 offset:33792
	ds_read_b128 v[214:217], v158 offset:32768
	ds_read_b128 v[218:221], v158 offset:33792
	s_add_u32 m0, s32, 0x4000
	s_add_u32 s98, s20, 0x40100
	s_addc_u32 s99, s21, 0
	global_load_lds_dwordx4 v253, s[98:99]
	s_add_u32 m0, s32, 0x6000
	s_nop 0
	global_load_lds_dwordx4 v252, s[98:99]
	s_waitcnt lgkmcnt(8)
	s_barrier
; #define LDA(dst, b, h)                                                                                    \
;   _Pragma("unroll") for (int m = 0; m < 4; ++m) _Pragma("unroll") for (int k = 0; k < 2; ++k)             \
;       dst[m][k] = *reinterpret_cast<const bf16x8*>((char*)SA(b, h) + lds_byte(wr * 64 + m * 16 + fr, k * 32 + fq * 8))
; #define LDB(dst, b, h)                                                                                    \
;   _Pragma("unroll") for (int n = 0; n < 2; ++n) _Pragma("unroll") for (int k = 0; k < 2; ++k)             \
;       dst[n][k] = *reinterpret_cast<const bf16x8*>((char*)SB(b, h) + lds_byte(wc * 32 + n * 16 + fr, k * 32 + fq * 8))
; #define WAIT_V(n) asm volatile("s_waitcnt vmcnt(" #n ")" ::: "memory")
; #define WAIT_L(n) asm volatile("s_waitcnt lgkmcnt(" #n ")" ::: "memory")
; #define BAR __builtin_amdgcn_s_barrier()
; #define SCHED __builtin_amdgcn_sched_barrier(0)
; template <int EPI> ...
;     ...
;     LDB(B1, 1, 1); STAGE(SB(1, 0), Bt, bcol, t + 3);
;     BAR; WAIT_L(0); MMA(0, 1, At, B1); BAR;
;     LDA(At, 1, 1); STAGE(SA(1, 0), A, brow, t + 3);
;     BAR; WAIT_L(0); MMA(1, 0, At, B0); BAR; SCHED;
;     STAGE(SB(1, 1), Bt, bcol + HALF, t + 3);
;     WAIT_V(6); BAR; MMA(1, 1, At, B1); BAR;
;   }
	s_waitcnt lgkmcnt(0)
	s_setprio 1
	s_waitcnt lgkmcnt(0)
	v_mfma_f32_16x16x32_bf16 v[124:127], v[190:193], v[162:165], v[124:127]
	v_mfma_f32_16x16x32_bf16 v[120:123], v[190:193], v[182:185], v[120:123]
	v_mfma_f32_16x16x32_bf16 v[116:119], v[198:201], v[162:165], v[116:119]
	v_mfma_f32_16x16x32_bf16 v[112:115], v[198:201], v[182:185], v[112:115]
	v_mfma_f32_16x16x32_bf16 v[108:111], v[206:209], v[162:165], v[108:111]
	v_mfma_f32_16x16x32_bf16 v[104:107], v[206:209], v[182:185], v[104:107]
	v_mfma_f32_16x16x32_bf16 v[100:103], v[214:217], v[162:165], v[100:103]
	v_mfma_f32_16x16x32_bf16 v[96:99], v[214:217], v[182:185], v[96:99]
	v_mfma_f32_16x16x32_bf16 v[124:127], v[194:197], v[178:181], v[124:127]
	v_mfma_f32_16x16x32_bf16 v[120:123], v[194:197], v[186:189], v[120:123]
	v_mfma_f32_16x16x32_bf16 v[116:119], v[202:205], v[178:181], v[116:119]
	v_mfma_f32_16x16x32_bf16 v[112:115], v[202:205], v[186:189], v[112:115]
	v_mfma_f32_16x16x32_bf16 v[108:111], v[210:213], v[178:181], v[108:111]
	v_mfma_f32_16x16x32_bf16 v[104:107], v[210:213], v[186:189], v[104:107]
	v_mfma_f32_16x16x32_bf16 v[100:103], v[218:221], v[178:181], v[100:103]
	v_mfma_f32_16x16x32_bf16 v[96:99], v[218:221], v[186:189], v[96:99]
	s_setprio 0
	s_barrier
	ds_read_b128 v[222:225], v137
	ds_read_b128 v[226:229], v137 offset:1024
	ds_read_b128 v[230:233], v137 offset:2048
	ds_read_b128 v[234:237], v137 offset:3072
	s_add_u32 m0, s32, 0x18000
	s_add_u32 s98, s22, 0x180
	s_addc_u32 s99, s23, 0
	global_load_lds_dwordx4 v253, s[98:99]
	s_add_u32 m0, s32, 0x1a000
	s_nop 0
	global_load_lds_dwordx4 v252, s[98:99]
	s_barrier
	s_waitcnt lgkmcnt(0)
	s_setprio 1
	s_waitcnt lgkmcnt(0)
	v_mfma_f32_16x16x32_bf16 v[92:95], v[190:193], v[222:225], v[92:95]
	v_mfma_f32_16x16x32_bf16 v[88:91], v[190:193], v[230:233], v[88:91]
	v_mfma_f32_16x16x32_bf16 v[84:87], v[198:201], v[222:225], v[84:87]
	v_mfma_f32_16x16x32_bf16 v[80:83], v[198:201], v[230:233], v[80:83]
	v_mfma_f32_16x16x32_bf16 v[76:79], v[206:209], v[222:225], v[76:79]
	v_mfma_f32_16x16x32_bf16 v[72:75], v[206:209], v[230:233], v[72:75]
	v_mfma_f32_16x16x32_bf16 v[68:71], v[214:217], v[222:225], v[68:71]
	v_mfma_f32_16x16x32_bf16 v[64:67], v[214:217], v[230:233], v[64:67]
	v_mfma_f32_16x16x32_bf16 v[92:95], v[194:197], v[226:229], v[92:95]
	v_mfma_f32_16x16x32_bf16 v[88:91], v[194:197], v[234:237], v[88:91]
	v_mfma_f32_16x16x32_bf16 v[84:87], v[202:205], v[226:229], v[84:87]
	v_mfma_f32_16x16x32_bf16 v[80:83], v[202:205], v[234:237], v[80:83]
	v_mfma_f32_16x16x32_bf16 v[76:79], v[210:213], v[226:229], v[76:79]
	v_mfma_f32_16x16x32_bf16 v[72:75], v[210:213], v[234:237], v[72:75]
	v_mfma_f32_16x16x32_bf16 v[68:71], v[218:221], v[226:229], v[68:71]
	v_mfma_f32_16x16x32_bf16 v[64:67], v[218:221], v[234:237], v[64:67]
	s_setprio 0
	s_barrier
	ds_read_b128 v[190:193], v135 offset:49152
	ds_read_b128 v[194:197], v135 offset:50176
	ds_read_b128 v[198:201], v156 offset:49152
	ds_read_b128 v[202:205], v156 offset:50176
	ds_read_b128 v[206:209], v157 offset:49152
	ds_read_b128 v[210:213], v157 offset:50176
	ds_read_b128 v[214:217], v158 offset:49152
	ds_read_b128 v[218:221], v158 offset:50176
	s_add_u32 m0, s32, 0x8000
	s_add_u32 s98, s20, 0x180
	s_addc_u32 s99, s21, 0
	global_load_lds_dwordx4 v253, s[98:99]
	s_nop 0
	s_add_u32 m0, s32, 0xa000
	s_nop 0
	global_load_lds_dwordx4 v252, s[98:99]
	s_barrier
	s_waitcnt lgkmcnt(0)
	s_setprio 1
	s_waitcnt lgkmcnt(0)
	v_mfma_f32_16x16x32_bf16 v[60:63], v[190:193], v[162:165], v[60:63]
	v_mfma_f32_16x16x32_bf16 v[56:59], v[190:193], v[182:185], v[56:59]
	v_mfma_f32_16x16x32_bf16 v[52:55], v[198:201], v[162:165], v[52:55]
	v_mfma_f32_16x16x32_bf16 v[48:51], v[198:201], v[182:185], v[48:51]
	v_mfma_f32_16x16x32_bf16 v[44:47], v[206:209], v[162:165], v[44:47]
	v_mfma_f32_16x16x32_bf16 v[40:43], v[206:209], v[182:185], v[40:43]
	v_mfma_f32_16x16x32_bf16 v[36:39], v[214:217], v[162:165], v[36:39]
	v_mfma_f32_16x16x32_bf16 v[32:35], v[214:217], v[182:185], v[32:35]
	v_mfma_f32_16x16x32_bf16 v[60:63], v[194:197], v[178:181], v[60:63]
	v_mfma_f32_16x16x32_bf16 v[56:59], v[194:197], v[186:189], v[56:59]
	v_mfma_f32_16x16x32_bf16 v[52:55], v[202:205], v[178:181], v[52:55]
	v_mfma_f32_16x16x32_bf16 v[48:51], v[202:205], v[186:189], v[48:51]
	v_mfma_f32_16x16x32_bf16 v[44:47], v[210:213], v[178:181], v[44:47]
	v_mfma_f32_16x16x32_bf16 v[40:43], v[210:213], v[186:189], v[40:43]
	v_mfma_f32_16x16x32_bf16 v[36:39], v[218:221], v[178:181], v[36:39]
	v_mfma_f32_16x16x32_bf16 v[32:35], v[218:221], v[186:189], v[32:35]
	s_setprio 0
	s_barrier
	s_add_u32 m0, s32, 0x1c000
	s_add_u32 s98, s22, 0x40180
	s_addc_u32 s99, s23, 0
	global_load_lds_dwordx4 v253, s[98:99]
	s_add_u32 m0, s32, 0x1e000
	s_nop 0
	global_load_lds_dwordx4 v252, s[98:99]
	s_waitcnt vmcnt(6)
	s_barrier
	s_setprio 1
	v_mfma_f32_16x16x32_bf16 v[28:31], v[190:193], v[222:225], v[28:31]
	v_mfma_f32_16x16x32_bf16 v[24:27], v[190:193], v[230:233], v[24:27]
	v_mfma_f32_16x16x32_bf16 v[20:23], v[198:201], v[222:225], v[20:23]
	v_mfma_f32_16x16x32_bf16 v[16:19], v[198:201], v[230:233], v[16:19]
	v_mfma_f32_16x16x32_bf16 v[12:15], v[206:209], v[222:225], v[12:15]
	v_mfma_f32_16x16x32_bf16 v[8:11], v[206:209], v[230:233], v[8:11]
	v_mfma_f32_16x16x32_bf16 v[4:7], v[214:217], v[222:225], v[4:7]
	v_mfma_f32_16x16x32_bf16 v[0:3], v[214:217], v[230:233], v[0:3]
	v_mfma_f32_16x16x32_bf16 v[28:31], v[194:197], v[226:229], v[28:31]
	v_mfma_f32_16x16x32_bf16 v[24:27], v[194:197], v[234:237], v[24:27]
	v_mfma_f32_16x16x32_bf16 v[20:23], v[202:205], v[226:229], v[20:23]
	v_mfma_f32_16x16x32_bf16 v[16:19], v[202:205], v[234:237], v[16:19]
	v_mfma_f32_16x16x32_bf16 v[12:15], v[210:213], v[226:229], v[12:15]
	v_mfma_f32_16x16x32_bf16 v[8:11], v[210:213], v[234:237], v[8:11]
	v_mfma_f32_16x16x32_bf16 v[4:7], v[218:221], v[226:229], v[4:7]
	v_mfma_f32_16x16x32_bf16 v[0:3], v[218:221], v[234:237], v[0:3]
	s_setprio 0
	s_add_i32 s69, s69, 2
	s_add_u32 s18, s18, 0x100
	s_addc_u32 s19, s19, 0
	s_cmp_lt_u32 s69, 12
	s_barrier
; #define LDA(dst, b, h)                                                                                    \
;   _Pragma("unroll") for (int m = 0; m < 4; ++m) _Pragma("unroll") for (int k = 0; k < 2; ++k)             \
;       dst[m][k] = *reinterpret_cast<const bf16x8*>((char*)SA(b, h) + lds_byte(wr * 64 + m * 16 + fr, k * 32 + fq * 8))
; #define LDB(dst, b, h)                                                                                    \
;   _Pragma("unroll") for (int n = 0; n < 2; ++n) _Pragma("unroll") for (int k = 0; k < 2; ++k)             \
;       dst[n][k] = *reinterpret_cast<const bf16x8*>((char*)SB(b, h) + lds_byte(wc * 32 + n * 16 + fr, k * 32 + fq * 8))
; #define WAIT_V(n) asm volatile("s_waitcnt vmcnt(" #n ")" ::: "memory")
; #define WAIT_L(n) asm volatile("s_waitcnt lgkmcnt(" #n ")" ::: "memory")
; #define BAR __builtin_amdgcn_s_barrier()
; template <int EPI> ...
;     ...
;   }
;   {
;     LDB(B0, 0, 0); LDA(At, 0, 0); STAGE(SA(1, 1), A, brow + HALF, nt - 1);
;     BAR; WAIT_L(0); MMA(0, 0, At, B0); BAR;
;     LDB(B1, 0, 1); BAR; WAIT_L(0); MMA(0, 1, At, B1); BAR;
;     LDA(At, 0, 1); WAIT_V(4); BAR; WAIT_L(0); MMA(1, 0, At, B0); MMA(1, 1, At, B1); BAR;
	s_cbranch_scc1 .LBB0_1666
	ds_read_b128 v[142:145], v155
	ds_read_b128 v[162:165], v155 offset:1024
	ds_read_b128 v[178:181], v155 offset:2048
	ds_read_b128 v[182:185], v155 offset:3072
	ds_read_b128 v[186:189], v135
	ds_read_b128 v[190:193], v135 offset:1024
	ds_read_b128 v[194:197], v156
	ds_read_b128 v[198:201], v156 offset:1024
	ds_read_b128 v[202:205], v157
	ds_read_b128 v[206:209], v157 offset:1024
	ds_read_b128 v[210:213], v158
	ds_read_b128 v[214:217], v158 offset:1024
	v_mov_b32_e32 v129, v149
	v_lshl_add_u64 v[128:129], v[128:129], 1, s[16:17]
	s_mov_b64 s[14:15], 0x780
	v_readfirstlane_b32 s12, v160
	v_lshl_add_u64 v[128:129], v[128:129], 0, s[14:15]
	s_mov_b32 m0, s12
	v_mov_b32_e32 v131, v149
	global_load_lds_dwordx4 v[128:129], off
	v_readfirstlane_b32 s12, v159
	v_lshl_add_u64 v[128:129], v[130:131], 1, s[16:17]
	v_lshl_add_u64 v[128:129], v[128:129], 0, s[14:15]
	s_mov_b32 m0, s12
	s_nop 0
	global_load_lds_dwordx4 v[128:129], off
	s_barrier
	s_waitcnt lgkmcnt(0)
	s_setprio 1
	s_waitcnt lgkmcnt(0)
	v_mfma_f32_16x16x32_bf16 v[124:127], v[186:189], v[142:145], v[124:127]
	v_mfma_f32_16x16x32_bf16 v[120:123], v[186:189], v[178:181], v[120:123]
	v_mfma_f32_16x16x32_bf16 v[116:119], v[194:197], v[142:145], v[116:119]
	v_mfma_f32_16x16x32_bf16 v[112:115], v[194:197], v[178:181], v[112:115]
	v_mfma_f32_16x16x32_bf16 v[108:111], v[202:205], v[142:145], v[108:111]
	v_mfma_f32_16x16x32_bf16 v[104:107], v[202:205], v[178:181], v[104:107]
	v_mfma_f32_16x16x32_bf16 v[96:99], v[210:213], v[178:181], v[96:99]
	v_mfma_f32_16x16x32_bf16 v[124:127], v[190:193], v[162:165], v[124:127]
	v_mfma_f32_16x16x32_bf16 v[120:123], v[190:193], v[182:185], v[120:123]
	v_mfma_f32_16x16x32_bf16 v[116:119], v[198:201], v[162:165], v[116:119]
	v_mfma_f32_16x16x32_bf16 v[112:115], v[198:201], v[182:185], v[112:115]
	v_mfma_f32_16x16x32_bf16 v[108:111], v[206:209], v[162:165], v[108:111]
	v_mfma_f32_16x16x32_bf16 v[104:107], v[206:209], v[182:185], v[104:107]
	v_mfma_f32_16x16x32_bf16 v[100:103], v[210:213], v[142:145], v[100:103]
	v_mfma_f32_16x16x32_bf16 v[96:99], v[214:217], v[182:185], v[96:99]
	v_mfma_f32_16x16x32_bf16 v[128:131], v[214:217], v[162:165], v[100:103]
	s_setprio 0
	s_barrier
	s_nop 3
	ds_read_b128 v[100:103], v152
	ds_read_b128 v[218:221], v152 offset:1024
	ds_read_b128 v[222:225], v152 offset:2048
	ds_read_b128 v[152:155], v152 offset:3072
	s_barrier
	s_waitcnt lgkmcnt(0)
	s_setprio 1
	s_waitcnt lgkmcnt(0)
	v_mfma_f32_16x16x32_bf16 v[88:91], v[186:189], v[222:225], v[88:91]
	v_mfma_f32_16x16x32_bf16 v[92:95], v[186:189], v[100:103], v[92:95]
	v_mfma_f32_16x16x32_bf16 v[88:91], v[190:193], v[152:155], v[88:91]
	v_mfma_f32_16x16x32_bf16 v[84:87], v[194:197], v[100:103], v[84:87]
	v_mfma_f32_16x16x32_bf16 v[80:83], v[194:197], v[222:225], v[80:83]
	v_mfma_f32_16x16x32_bf16 v[76:79], v[202:205], v[100:103], v[76:79]
	v_mfma_f32_16x16x32_bf16 v[72:75], v[202:205], v[222:225], v[72:75]
	v_mfma_f32_16x16x32_bf16 v[68:71], v[210:213], v[100:103], v[68:71]
	v_mfma_f32_16x16x32_bf16 v[64:67], v[210:213], v[222:225], v[64:67]
	v_mfma_f32_16x16x32_bf16 v[226:229], v[190:193], v[218:221], v[92:95]
	v_mfma_f32_16x16x32_bf16 v[186:189], v[198:201], v[218:221], v[84:87]
	v_mfma_f32_16x16x32_bf16 v[190:193], v[198:201], v[152:155], v[80:83]
	v_mfma_f32_16x16x32_bf16 v[194:197], v[206:209], v[218:221], v[76:79]
	v_mfma_f32_16x16x32_bf16 v[198:201], v[206:209], v[152:155], v[72:75]
	v_mfma_f32_16x16x32_bf16 v[202:205], v[214:217], v[218:221], v[68:71]
	v_mfma_f32_16x16x32_bf16 v[206:209], v[214:217], v[152:155], v[64:67]
	s_setprio 0
	s_barrier
	s_nop 0
	ds_read_b128 v[64:67], v135 offset:16384
	ds_read_b128 v[68:71], v135 offset:17408
	ds_read_b128 v[72:75], v156 offset:16384
	ds_read_b128 v[76:79], v156 offset:17408
	ds_read_b128 v[80:83], v157 offset:16384
	ds_read_b128 v[84:87], v157 offset:17408
	ds_read_b128 v[92:95], v158 offset:16384
	ds_read_b128 v[210:213], v158 offset:17408
	s_waitcnt vmcnt(4)
	s_barrier
	s_waitcnt lgkmcnt(0)
	s_setprio 1
	s_waitcnt lgkmcnt(0)
	v_mfma_f32_16x16x32_bf16 v[60:63], v[64:67], v[142:145], v[60:63]
	v_mfma_f32_16x16x32_bf16 v[56:59], v[64:67], v[178:181], v[56:59]
	v_mfma_f32_16x16x32_bf16 v[52:55], v[72:75], v[142:145], v[52:55]
	v_mfma_f32_16x16x32_bf16 v[48:51], v[72:75], v[178:181], v[48:51]
	v_mfma_f32_16x16x32_bf16 v[44:47], v[80:83], v[142:145], v[44:47]
	v_mfma_f32_16x16x32_bf16 v[40:43], v[80:83], v[178:181], v[40:43]
	v_mfma_f32_16x16x32_bf16 v[36:39], v[92:95], v[142:145], v[36:39]
	v_mfma_f32_16x16x32_bf16 v[32:35], v[92:95], v[178:181], v[32:35]
	v_mfma_f32_16x16x32_bf16 v[60:63], v[68:71], v[162:165], v[60:63]
	v_mfma_f32_16x16x32_bf16 v[56:59], v[68:71], v[182:185], v[56:59]
	v_mfma_f32_16x16x32_bf16 v[52:55], v[76:79], v[162:165], v[52:55]
	v_mfma_f32_16x16x32_bf16 v[48:51], v[76:79], v[182:185], v[48:51]
	v_mfma_f32_16x16x32_bf16 v[44:47], v[84:87], v[162:165], v[44:47]
	v_mfma_f32_16x16x32_bf16 v[40:43], v[84:87], v[182:185], v[40:43]
	v_mfma_f32_16x16x32_bf16 v[36:39], v[210:213], v[162:165], v[36:39]
	v_mfma_f32_16x16x32_bf16 v[32:35], v[210:213], v[182:185], v[32:35]
	s_setprio 0
	s_setprio 1
	v_mfma_f32_16x16x32_bf16 v[28:31], v[64:67], v[100:103], v[28:31]
	v_mfma_f32_16x16x32_bf16 v[24:27], v[64:67], v[222:225], v[24:27]
	v_mfma_f32_16x16x32_bf16 v[20:23], v[72:75], v[100:103], v[20:23]
	v_mfma_f32_16x16x32_bf16 v[16:19], v[72:75], v[222:225], v[16:19]
	v_mfma_f32_16x16x32_bf16 v[12:15], v[80:83], v[100:103], v[12:15]
	v_mfma_f32_16x16x32_bf16 v[8:11], v[80:83], v[222:225], v[8:11]
	v_mfma_f32_16x16x32_bf16 v[4:7], v[92:95], v[100:103], v[4:7]
	v_mfma_f32_16x16x32_bf16 v[0:3], v[92:95], v[222:225], v[0:3]
	v_mfma_f32_16x16x32_bf16 v[142:145], v[68:71], v[218:221], v[28:31]
	v_mfma_f32_16x16x32_bf16 v[160:163], v[68:71], v[152:155], v[24:27]
	v_mfma_f32_16x16x32_bf16 v[164:167], v[76:79], v[218:221], v[20:23]
	v_mfma_f32_16x16x32_bf16 v[178:181], v[76:79], v[152:155], v[16:19]
	v_mfma_f32_16x16x32_bf16 v[182:185], v[84:87], v[218:221], v[12:15]
	v_mfma_f32_16x16x32_bf16 v[214:217], v[84:87], v[152:155], v[8:11]
	v_mfma_f32_16x16x32_bf16 v[218:221], v[210:213], v[218:221], v[4:7]
	v_mfma_f32_16x16x32_bf16 v[152:155], v[210:213], v[152:155], v[0:3]
	s_setprio 0
	s_barrier
; #define LDA(dst, b, h)                                                                                    \
;   _Pragma("unroll") for (int m = 0; m < 4; ++m) _Pragma("unroll") for (int k = 0; k < 2; ++k)             \
;       dst[m][k] = *reinterpret_cast<const bf16x8*>((char*)SA(b, h) + lds_byte(wr * 64 + m * 16 + fr, k * 32 + fq * 8))
; #define LDB(dst, b, h)                                                                                    \
;   _Pragma("unroll") for (int n = 0; n < 2; ++n) _Pragma("unroll") for (int k = 0; k < 2; ++k)             \
;       dst[n][k] = *reinterpret_cast<const bf16x8*>((char*)SB(b, h) + lds_byte(wc * 32 + n * 16 + fr, k * 32 + fq * 8))
; #define WAIT_V(n) asm volatile("s_waitcnt vmcnt(" #n ")" ::: "memory")
; #define WAIT_L(n) asm volatile("s_waitcnt lgkmcnt(" #n ")" ::: "memory")
; #define BAR __builtin_amdgcn_s_barrier()
; template <int EPI> ...
;     ...
;     LDA(At, 0, 1); WAIT_V(4); BAR; WAIT_L(0); MMA(1, 0, At, B0); MMA(1, 1, At, B1); BAR;
;   }
;   {
;     LDB(B0, 1, 0); LDA(At, 1, 0); WAIT_V(2); BAR; WAIT_L(0); MMA(0, 0, At, B0); BAR;
;     LDB(B1, 1, 1); WAIT_V(0); BAR; WAIT_L(0); MMA(0, 1, At, B1); BAR;
;     LDA(At, 1, 1); BAR; WAIT_L(0); MMA(1, 0, At, B0); MMA(1, 1, At, B1); BAR;
;   }
;   if (wr == 0) BAR;
;   if (has_next) ISSUE_PRO(nm0, nn0);
	s_nop 0
	ds_read_b128 v[0:3], v140
	ds_read_b128 v[4:7], v140 offset:1024
	ds_read_b128 v[210:213], v140 offset:2048
	ds_read_b128 v[138:141], v140 offset:3072
	ds_read_b128 v[8:11], v135 offset:32768
	ds_read_b128 v[12:15], v135 offset:33792
	ds_read_b128 v[16:19], v156 offset:32768
	ds_read_b128 v[20:23], v156 offset:33792
	ds_read_b128 v[24:27], v157 offset:32768
	ds_read_b128 v[28:31], v157 offset:33792
	ds_read_b128 v[222:225], v158 offset:32768
	ds_read_b128 v[230:233], v158 offset:33792
	s_waitcnt vmcnt(2)
	s_barrier
	s_waitcnt lgkmcnt(0)
	s_setprio 1
	s_waitcnt lgkmcnt(0)
	v_mfma_f32_16x16x32_bf16 v[64:67], v[8:11], v[0:3], v[124:127]
	v_mfma_f32_16x16x32_bf16 v[92:95], v[12:15], v[4:7], v[64:67]
	v_mfma_f32_16x16x32_bf16 v[64:67], v[8:11], v[210:213], v[120:123]
	v_mfma_f32_16x16x32_bf16 v[100:103], v[12:15], v[138:141], v[64:67]
	v_mfma_f32_16x16x32_bf16 v[64:67], v[16:19], v[0:3], v[116:119]
	v_mfma_f32_16x16x32_bf16 v[80:83], v[20:23], v[4:7], v[64:67]
	v_mfma_f32_16x16x32_bf16 v[64:67], v[16:19], v[210:213], v[112:115]
	v_mfma_f32_16x16x32_bf16 v[84:87], v[20:23], v[138:141], v[64:67]
	v_mfma_f32_16x16x32_bf16 v[64:67], v[24:27], v[0:3], v[108:111]
	v_mfma_f32_16x16x32_bf16 v[72:75], v[28:31], v[4:7], v[64:67]
	v_mfma_f32_16x16x32_bf16 v[64:67], v[24:27], v[210:213], v[104:107]
	v_mfma_f32_16x16x32_bf16 v[76:79], v[28:31], v[138:141], v[64:67]
	v_mfma_f32_16x16x32_bf16 v[64:67], v[222:225], v[0:3], v[128:131]
	v_mfma_f32_16x16x32_bf16 v[68:71], v[222:225], v[210:213], v[96:99]
	v_mfma_f32_16x16x32_bf16 v[64:67], v[230:233], v[4:7], v[64:67]
	v_mfma_f32_16x16x32_bf16 v[68:71], v[230:233], v[138:141], v[68:71]
	s_setprio 0
	s_barrier
	ds_read_b128 v[128:131], v137
	ds_read_b128 v[234:237], v137 offset:1024
	ds_read_b128 v[238:241], v137 offset:2048
	ds_read_b128 v[242:245], v137 offset:3072
	s_waitcnt vmcnt(0)
	s_barrier
	s_waitcnt lgkmcnt(0)
	s_setprio 1
	s_waitcnt lgkmcnt(0)
	v_mfma_f32_16x16x32_bf16 v[96:99], v[8:11], v[128:131], v[226:229]
	v_mfma_f32_16x16x32_bf16 v[8:11], v[8:11], v[238:241], v[88:91]
	v_mfma_f32_16x16x32_bf16 v[124:127], v[12:15], v[242:245], v[8:11]
	v_mfma_f32_16x16x32_bf16 v[8:11], v[16:19], v[128:131], v[186:189]
	v_mfma_f32_16x16x32_bf16 v[112:115], v[20:23], v[234:237], v[8:11]
	v_mfma_f32_16x16x32_bf16 v[8:11], v[16:19], v[238:241], v[190:193]
	v_mfma_f32_16x16x32_bf16 v[116:119], v[20:23], v[242:245], v[8:11]
	v_mfma_f32_16x16x32_bf16 v[8:11], v[24:27], v[128:131], v[194:197]
	v_mfma_f32_16x16x32_bf16 v[104:107], v[28:31], v[234:237], v[8:11]
	v_mfma_f32_16x16x32_bf16 v[8:11], v[24:27], v[238:241], v[198:201]
	v_mfma_f32_16x16x32_bf16 v[108:111], v[28:31], v[242:245], v[8:11]
	v_mfma_f32_16x16x32_bf16 v[8:11], v[222:225], v[128:131], v[202:205]
	v_mfma_f32_16x16x32_bf16 v[88:91], v[230:233], v[234:237], v[8:11]
	v_mfma_f32_16x16x32_bf16 v[8:11], v[222:225], v[238:241], v[206:209]
	v_mfma_f32_16x16x32_bf16 v[120:123], v[12:15], v[234:237], v[96:99]
	v_mfma_f32_16x16x32_bf16 v[96:99], v[230:233], v[242:245], v[8:11]
	s_setprio 0
	s_barrier
	ds_read_b128 v[186:189], v135 offset:49152
	ds_read_b128 v[134:137], v135 offset:50176
	ds_read_b128 v[190:193], v156 offset:49152
	ds_read_b128 v[194:197], v156 offset:50176
	ds_read_b128 v[198:201], v157 offset:49152
	ds_read_b128 v[202:205], v157 offset:50176
	ds_read_b128 v[206:209], v158 offset:49152
	ds_read_b128 v[156:159], v158 offset:50176
	s_barrier
	s_waitcnt lgkmcnt(0)
	s_setprio 1
	s_waitcnt lgkmcnt(0)
	v_mfma_f32_16x16x32_bf16 v[8:11], v[186:189], v[0:3], v[60:63]
	v_mfma_f32_16x16x32_bf16 v[24:27], v[134:137], v[4:7], v[8:11]
	v_mfma_f32_16x16x32_bf16 v[8:11], v[186:189], v[210:213], v[56:59]
	v_mfma_f32_16x16x32_bf16 v[28:31], v[134:137], v[138:141], v[8:11]
	v_mfma_f32_16x16x32_bf16 v[8:11], v[190:193], v[0:3], v[52:55]
	v_mfma_f32_16x16x32_bf16 v[16:19], v[194:197], v[4:7], v[8:11]
	v_mfma_f32_16x16x32_bf16 v[8:11], v[190:193], v[210:213], v[48:51]
	v_mfma_f32_16x16x32_bf16 v[20:23], v[194:197], v[138:141], v[8:11]
	v_mfma_f32_16x16x32_bf16 v[8:11], v[198:201], v[0:3], v[44:47]
	v_mfma_f32_16x16x32_bf16 v[0:3], v[206:209], v[0:3], v[36:39]
	v_mfma_f32_16x16x32_bf16 v[8:11], v[202:205], v[4:7], v[8:11]
	v_mfma_f32_16x16x32_bf16 v[12:15], v[198:201], v[210:213], v[40:43]
	v_mfma_f32_16x16x32_bf16 v[0:3], v[156:159], v[4:7], v[0:3]
	v_mfma_f32_16x16x32_bf16 v[4:7], v[206:209], v[210:213], v[32:35]
	v_mfma_f32_16x16x32_bf16 v[12:15], v[202:205], v[138:141], v[12:15]
	v_mfma_f32_16x16x32_bf16 v[4:7], v[156:159], v[138:141], v[4:7]
	s_setprio 0
	s_setprio 1
	v_mfma_f32_16x16x32_bf16 v[32:35], v[186:189], v[128:131], v[142:145]
	v_mfma_f32_16x16x32_bf16 v[56:59], v[134:137], v[234:237], v[32:35]
	v_mfma_f32_16x16x32_bf16 v[32:35], v[186:189], v[238:241], v[160:163]
	v_mfma_f32_16x16x32_bf16 v[60:63], v[134:137], v[242:245], v[32:35]
	v_mfma_f32_16x16x32_bf16 v[32:35], v[190:193], v[128:131], v[164:167]
	v_mfma_f32_16x16x32_bf16 v[48:51], v[194:197], v[234:237], v[32:35]
	v_mfma_f32_16x16x32_bf16 v[32:35], v[190:193], v[238:241], v[178:181]
	v_mfma_f32_16x16x32_bf16 v[52:55], v[194:197], v[242:245], v[32:35]
	v_mfma_f32_16x16x32_bf16 v[32:35], v[198:201], v[128:131], v[182:185]
	v_mfma_f32_16x16x32_bf16 v[40:43], v[202:205], v[234:237], v[32:35]
	v_mfma_f32_16x16x32_bf16 v[32:35], v[198:201], v[238:241], v[214:217]
	v_mfma_f32_16x16x32_bf16 v[44:47], v[202:205], v[242:245], v[32:35]
	v_mfma_f32_16x16x32_bf16 v[32:35], v[206:209], v[128:131], v[218:221]
	v_mfma_f32_16x16x32_bf16 v[36:39], v[206:209], v[238:241], v[152:155]
	v_mfma_f32_16x16x32_bf16 v[32:35], v[156:159], v[234:237], v[32:35]
	v_mfma_f32_16x16x32_bf16 v[36:39], v[156:159], v[242:245], v[36:39]
	s_setprio 0
	s_cmpk_gt_u32 s30, 0xff
	s_barrier
	s_cbranch_scc1 .LBB0_1669
	s_barrier

; DEVI f32x4 ozero() { float z = 0.f; asm volatile("" : "+v"(z)); return f32x4{z, z, z, z}; }
; #define LDA(dst, b, h)                                                                                    \
;   _Pragma("unroll") for (int m = 0; m < 4; ++m) _Pragma("unroll") for (int k = 0; k < 2; ++k)             \
;       dst[m][k] = *reinterpret_cast<const bf16x8*>((char*)SA(b, h) + lds_byte(wr * 64 + m * 16 + fr, k * 32 + fq * 8))
; #define LDB(dst, b, h)                                                                                    \
;   _Pragma("unroll") for (int n = 0; n < 2; ++n) _Pragma("unroll") for (int k = 0; k < 2; ++k)             \
;       dst[n][k] = *reinterpret_cast<const bf16x8*>((char*)SB(b, h) + lds_byte(wc * 32 + n * 16 + fr, k * 32 + fq * 8))
; #define WAIT_V(n) asm volatile("s_waitcnt vmcnt(" #n ")" ::: "memory")
; #define WAIT_L(n) asm volatile("s_waitcnt lgkmcnt(" #n ")" ::: "memory")
; #define BAR __builtin_amdgcn_s_barrier()
; #define SCHED __builtin_amdgcn_sched_barrier(0)
; template <int EPI> ...
;     ...
;   const int brow = m0, bcol = n0;
;   const int wid = __builtin_amdgcn_readfirstlane(tid >> 6), lane = tid & 63, wr = wid >> 2, wc = wid & 3, fr = lane & 15, fq = lane >> 4;
;   f32x4 acc[2][2][4][2];
;   {
;     const f32x4 zq = ozero();
; #pragma unroll
;     for (int a_ = 0; a_ < 2; ++a_)
; #pragma unroll
;       for (int b_ = 0; b_ < 2; ++b_)
; #pragma unroll
;         for (int m = 0; m < 4; ++m) { acc[a_][b_][m][0] = zq; acc[a_][b_][m][1] = zq; }
;   }
;   bf16x8 At[4][2], B0[2][2], B1[2][2];
;   const int nt = K / BK;
;     ...
;   if (first) {
;     WAIT_V(0);
;     ISSUE_PRO(brow, bcol);
;   }
;   if (wr == 1) BAR;
;   WAIT_V(10); BAR;
;   WAIT_V(6); BAR;
;   for (int t = 0; t < nt - 2; t += 2) {
;     LDB(B0, 0, 0); SCHED; LDA(At, 0, 0); STAGE(SA(1, 1), A, brow + HALF, t + 1);
;     WAIT_L(8); BAR; WAIT_L(0); MMA(0, 0, At, B0); BAR; SCHED;
.LBB0_1753:
	v_and_b32_e32 v132, 15, v134
	v_and_b32_e32 v1, 48, v134
	v_lshlrev_b32_e32 v2, 6, v132
	v_lshlrev_b32_e32 v4, 2, v134
	v_or_b32_e32 v3, v2, v1
	v_and_b32_e32 v4, 32, v4
	s_mov_b32 s16, 0x10000
	v_bitop3_b32 v5, v3, s16, v4 bitop3:0xde
	s_mov_b32 s16, 0x14000
	s_ashr_i32 s9, s62, 6
	v_bitop3_b32 v6, v3, s16, v4 bitop3:0xde
	s_mov_b32 s16, 0x18000
	s_and_b32 s63, s9, 3
	s_waitcnt vmcnt(10)
	s_barrier
	s_waitcnt vmcnt(6)
	v_bitop3_b32 v7, v3, s16, v4 bitop3:0xde
	s_mov_b32 s16, 0x1c000
	v_lshlrev_b32_e32 v8, 6, v134
	s_lshl_b32 s19, s63, 12
	v_bitop3_b32 v2, v2, v4, v1 bitop3:0x36
	s_lshl_b32 s64, s18, 6
	v_bitop3_b32 v3, v3, s16, v4 bitop3:0xde
	s_lshl_b32 s18, s18, 13
	v_and_b32_e32 v8, 0x3c0, v8
	v_bitop3_b32 v154, v8, v4, v1 bitop3:0x36
	s_or_b32 s65, s18, 0x800
	s_or_b32 s66, s18, 0x1000
	s_or_b32 s67, s18, 0x1800
	s_mov_b32 s68, -2
	s_mov_b64 s[16:17], 0
	v_add_u32_e32 v155, s19, v5
	v_add_u32_e32 v135, s18, v2
	v_add_u32_e32 v152, s19, v6
	v_add_u32_e32 v140, s19, v7
	v_add_u32_e32 v137, s19, v3
	v_mov_b32_e32 v1, v0
	v_mov_b32_e32 v2, v0
	v_mov_b32_e32 v3, v0
	v_mov_b32_e32 v4, v0
	v_mov_b32_e32 v5, v0
	v_mov_b32_e32 v6, v0
	v_mov_b32_e32 v7, v0
	v_mov_b32_e32 v8, v0
	v_mov_b32_e32 v9, v0
	v_mov_b32_e32 v10, v0
	v_mov_b32_e32 v11, v0
	v_mov_b32_e32 v12, v0
	v_mov_b32_e32 v13, v0
	v_mov_b32_e32 v14, v0
	v_mov_b32_e32 v15, v0
	v_mov_b32_e32 v16, v0
	v_mov_b32_e32 v17, v0
	v_mov_b32_e32 v18, v0
	v_mov_b32_e32 v19, v0
	v_mov_b32_e32 v20, v0
	v_mov_b32_e32 v21, v0
	v_mov_b32_e32 v22, v0
	v_mov_b32_e32 v23, v0
	v_mov_b32_e32 v24, v0
	v_mov_b32_e32 v25, v0
	v_mov_b32_e32 v26, v0
	v_mov_b32_e32 v27, v0
	v_mov_b32_e32 v28, v0
	v_mov_b32_e32 v29, v0
	v_mov_b32_e32 v30, v0
	v_mov_b32_e32 v31, v0
	v_mov_b32_e32 v32, v0
	v_mov_b32_e32 v33, v0
	v_mov_b32_e32 v34, v0
	v_mov_b32_e32 v35, v0
	v_mov_b32_e32 v36, v0
	v_mov_b32_e32 v37, v0
	v_mov_b32_e32 v38, v0
	v_mov_b32_e32 v39, v0
	v_mov_b32_e32 v40, v0
	v_mov_b32_e32 v41, v0
	v_mov_b32_e32 v42, v0
	v_mov_b32_e32 v43, v0
	v_mov_b32_e32 v44, v0
	v_mov_b32_e32 v45, v0
	v_mov_b32_e32 v46, v0
	v_mov_b32_e32 v47, v0
	v_mov_b32_e32 v48, v0
	v_mov_b32_e32 v49, v0
	v_mov_b32_e32 v50, v0
	v_mov_b32_e32 v51, v0
	v_mov_b32_e32 v52, v0
	v_mov_b32_e32 v53, v0
	v_mov_b32_e32 v54, v0
	v_mov_b32_e32 v55, v0
	v_mov_b32_e32 v56, v0
	v_mov_b32_e32 v57, v0
	v_mov_b32_e32 v58, v0
	v_mov_b32_e32 v59, v0
	v_mov_b32_e32 v60, v0
	v_mov_b32_e32 v61, v0
	v_mov_b32_e32 v62, v0
	v_mov_b32_e32 v63, v0
	v_mov_b32_e32 v64, v0
	v_mov_b32_e32 v65, v0
	v_mov_b32_e32 v66, v0
	v_mov_b32_e32 v67, v0
	v_mov_b32_e32 v68, v0
	v_mov_b32_e32 v69, v0
	v_mov_b32_e32 v70, v0
	v_mov_b32_e32 v71, v0
	v_mov_b32_e32 v72, v0
	v_mov_b32_e32 v73, v0
	v_mov_b32_e32 v74, v0
	v_mov_b32_e32 v75, v0
	v_mov_b32_e32 v76, v0
	v_mov_b32_e32 v77, v0
	v_mov_b32_e32 v78, v0
	v_mov_b32_e32 v79, v0
	v_mov_b32_e32 v80, v0
	v_mov_b32_e32 v81, v0
	v_mov_b32_e32 v82, v0
	v_mov_b32_e32 v83, v0
	v_mov_b32_e32 v84, v0
	v_mov_b32_e32 v85, v0
	v_mov_b32_e32 v86, v0
	v_mov_b32_e32 v87, v0
	v_mov_b32_e32 v88, v0
	v_mov_b32_e32 v89, v0
	v_mov_b32_e32 v90, v0
	v_mov_b32_e32 v91, v0
	v_mov_b32_e32 v92, v0
	v_mov_b32_e32 v93, v0
	v_mov_b32_e32 v94, v0
	v_mov_b32_e32 v95, v0
	v_mov_b32_e32 v96, v0
	v_mov_b32_e32 v97, v0
	v_mov_b32_e32 v98, v0
	v_mov_b32_e32 v99, v0
	v_mov_b32_e32 v100, v0
	v_mov_b32_e32 v101, v0
	v_mov_b32_e32 v102, v0
	v_mov_b32_e32 v103, v0
	v_mov_b32_e32 v104, v0
	v_mov_b32_e32 v105, v0
	v_mov_b32_e32 v106, v0
	v_mov_b32_e32 v107, v0
	v_mov_b32_e32 v108, v0
	v_mov_b32_e32 v109, v0
	v_mov_b32_e32 v110, v0
	v_mov_b32_e32 v111, v0
	v_mov_b32_e32 v112, v0
	v_mov_b32_e32 v113, v0
	v_mov_b32_e32 v114, v0
	v_mov_b32_e32 v115, v0
	v_mov_b32_e32 v116, v0
	v_mov_b32_e32 v117, v0
	v_mov_b32_e32 v118, v0
	v_mov_b32_e32 v119, v0
	v_mov_b32_e32 v120, v0
	v_mov_b32_e32 v121, v0
	v_mov_b32_e32 v122, v0
	v_mov_b32_e32 v123, v0
	v_mov_b32_e32 v124, v0
	v_mov_b32_e32 v125, v0
	v_mov_b32_e32 v126, v0
	v_mov_b32_e32 v127, v0
	s_barrier
	v_lshlrev_b32_e32 v253, 1, v128
	v_lshlrev_b32_e32 v252, 1, v130
	v_readfirstlane_b32 s32, v133
.LBB0_1754:
	ds_read_b128 v[162:165], v155
	ds_read_b128 v[174:177], v155 offset:1024
	ds_read_b128 v[178:181], v155 offset:2048
	ds_read_b128 v[182:185], v155 offset:3072
	s_add_u32 s18, s12, s16
	v_add_u32_e32 v156, s65, v154
	v_add_u32_e32 v157, s66, v154
	v_add_u32_e32 v158, s67, v154
	s_addc_u32 s19, s13, s17
	ds_read_b128 v[186:189], v135
	ds_read_b128 v[190:193], v135 offset:1024
	ds_read_b128 v[194:197], v156
	ds_read_b128 v[198:201], v156 offset:1024
	ds_read_b128 v[202:205], v157
	ds_read_b128 v[206:209], v157 offset:1024
	ds_read_b128 v[210:213], v158
	ds_read_b128 v[214:217], v158 offset:1024
	v_add_u32_e32 v159, 0xe000, v133
	v_add_u32_e32 v160, 0xc000, v133
	s_add_u32 m0, s32, 0xc000
	s_add_u32 s98, s18, 0x40080
	s_addc_u32 s99, s19, 0
	global_load_lds_dwordx4 v253, s[98:99]
	s_add_u32 m0, s32, 0xe000
	s_nop 0
	global_load_lds_dwordx4 v252, s[98:99]
	s_waitcnt lgkmcnt(8)
	s_barrier
	s_waitcnt lgkmcnt(0)
	s_setprio 1
	s_waitcnt lgkmcnt(0)
	v_mfma_f32_16x16x32_bf16 v[124:127], v[186:189], v[162:165], v[124:127]
	v_mfma_f32_16x16x32_bf16 v[120:123], v[186:189], v[178:181], v[120:123]
	v_mfma_f32_16x16x32_bf16 v[116:119], v[194:197], v[162:165], v[116:119]
	v_mfma_f32_16x16x32_bf16 v[112:115], v[194:197], v[178:181], v[112:115]
	v_mfma_f32_16x16x32_bf16 v[108:111], v[202:205], v[162:165], v[108:111]
	v_mfma_f32_16x16x32_bf16 v[104:107], v[202:205], v[178:181], v[104:107]
	v_mfma_f32_16x16x32_bf16 v[100:103], v[210:213], v[162:165], v[100:103]
	v_mfma_f32_16x16x32_bf16 v[96:99], v[210:213], v[178:181], v[96:99]
	v_mfma_f32_16x16x32_bf16 v[124:127], v[190:193], v[174:177], v[124:127]
	v_mfma_f32_16x16x32_bf16 v[120:123], v[190:193], v[182:185], v[120:123]
	v_mfma_f32_16x16x32_bf16 v[116:119], v[198:201], v[174:177], v[116:119]
	v_mfma_f32_16x16x32_bf16 v[112:115], v[198:201], v[182:185], v[112:115]
	v_mfma_f32_16x16x32_bf16 v[108:111], v[206:209], v[174:177], v[108:111]
	v_mfma_f32_16x16x32_bf16 v[104:107], v[206:209], v[182:185], v[104:107]
	v_mfma_f32_16x16x32_bf16 v[100:103], v[214:217], v[174:177], v[100:103]
	v_mfma_f32_16x16x32_bf16 v[96:99], v[214:217], v[182:185], v[96:99]
	s_setprio 0
	s_barrier
; #define LDA(dst, b, h)                                                                                    \
;   _Pragma("unroll") for (int m = 0; m < 4; ++m) _Pragma("unroll") for (int k = 0; k < 2; ++k)             \
;       dst[m][k] = *reinterpret_cast<const bf16x8*>((char*)SA(b, h) + lds_byte(wr * 64 + m * 16 + fr, k * 32 + fq * 8))
; #define LDB(dst, b, h)                                                                                    \
;   _Pragma("unroll") for (int n = 0; n < 2; ++n) _Pragma("unroll") for (int k = 0; k < 2; ++k)             \
;       dst[n][k] = *reinterpret_cast<const bf16x8*>((char*)SB(b, h) + lds_byte(wc * 32 + n * 16 + fr, k * 32 + fq * 8))
; #define WAIT_V(n) asm volatile("s_waitcnt vmcnt(" #n ")" ::: "memory")
; #define WAIT_L(n) asm volatile("s_waitcnt lgkmcnt(" #n ")" ::: "memory")
; #define BAR __builtin_amdgcn_s_barrier()
; #define SCHED __builtin_amdgcn_sched_barrier(0)
; template <int EPI> ...
;     ...
;     LDB(B1, 0, 1); STAGE(SB(0, 0), Bt, bcol, t + 2);
;     BAR; WAIT_L(0); MMA(0, 1, At, B1); BAR;
;     LDA(At, 0, 1); STAGE(SA(0, 0), A, brow, t + 2);
;     BAR; WAIT_L(0); MMA(1, 0, At, B0); BAR; SCHED;
;     STAGE(SB(0, 1), Bt, bcol + HALF, t + 2);
;     WAIT_V(6); BAR; MMA(1, 1, At, B1); BAR;
;     LDB(B0, 1, 0); SCHED; LDA(At, 1, 0); STAGE(SA(0, 1), A, brow + HALF, t + 2);
;     WAIT_L(8); BAR; WAIT_L(0); MMA(0, 0, At, B0); BAR; SCHED;
;     LDB(B1, 1, 1); STAGE(SB(1, 0), Bt, bcol, t + 3);
	s_add_u32 s20, s10, s16
	s_addc_u32 s21, s11, s17
	ds_read_b128 v[218:221], v152
	ds_read_b128 v[222:225], v152 offset:1024
	ds_read_b128 v[226:229], v152 offset:2048
	ds_read_b128 v[230:233], v152 offset:3072
	s_add_u32 m0, s32, 0x10000
	s_add_u32 s98, s20, 0x100
	s_addc_u32 s99, s21, 0
	global_load_lds_dwordx4 v253, s[98:99]
	s_add_u32 m0, s32, 0x12000
	s_nop 0
	global_load_lds_dwordx4 v252, s[98:99]
	s_barrier
	s_waitcnt lgkmcnt(0)
	s_setprio 1
	s_waitcnt lgkmcnt(0)
	v_mfma_f32_16x16x32_bf16 v[92:95], v[186:189], v[218:221], v[92:95]
	v_mfma_f32_16x16x32_bf16 v[88:91], v[186:189], v[226:229], v[88:91]
	v_mfma_f32_16x16x32_bf16 v[84:87], v[194:197], v[218:221], v[84:87]
	v_mfma_f32_16x16x32_bf16 v[80:83], v[194:197], v[226:229], v[80:83]
	v_mfma_f32_16x16x32_bf16 v[76:79], v[202:205], v[218:221], v[76:79]
	v_mfma_f32_16x16x32_bf16 v[72:75], v[202:205], v[226:229], v[72:75]
	v_mfma_f32_16x16x32_bf16 v[68:71], v[210:213], v[218:221], v[68:71]
	v_mfma_f32_16x16x32_bf16 v[64:67], v[210:213], v[226:229], v[64:67]
	v_mfma_f32_16x16x32_bf16 v[92:95], v[190:193], v[222:225], v[92:95]
	v_mfma_f32_16x16x32_bf16 v[88:91], v[190:193], v[230:233], v[88:91]
	v_mfma_f32_16x16x32_bf16 v[84:87], v[198:201], v[222:225], v[84:87]
	v_mfma_f32_16x16x32_bf16 v[80:83], v[198:201], v[230:233], v[80:83]
	v_mfma_f32_16x16x32_bf16 v[76:79], v[206:209], v[222:225], v[76:79]
	v_mfma_f32_16x16x32_bf16 v[72:75], v[206:209], v[230:233], v[72:75]
	v_mfma_f32_16x16x32_bf16 v[68:71], v[214:217], v[222:225], v[68:71]
	v_mfma_f32_16x16x32_bf16 v[64:67], v[214:217], v[230:233], v[64:67]
	s_setprio 0
	s_barrier
	ds_read_b128 v[186:189], v135 offset:16384
	ds_read_b128 v[190:193], v135 offset:17408
	ds_read_b128 v[194:197], v156 offset:16384
	ds_read_b128 v[198:201], v156 offset:17408
	ds_read_b128 v[202:205], v157 offset:16384
	ds_read_b128 v[206:209], v157 offset:17408
	ds_read_b128 v[210:213], v158 offset:16384
	ds_read_b128 v[214:217], v158 offset:17408
	s_mov_b32 m0, s32
	s_add_u32 s98, s18, 0x100
	s_addc_u32 s99, s19, 0
	global_load_lds_dwordx4 v253, s[98:99]
	s_add_u32 m0, s32, 0x2000
	s_nop 0
	global_load_lds_dwordx4 v252, s[98:99]
	s_barrier
	s_waitcnt lgkmcnt(0)
	s_setprio 1
	s_waitcnt lgkmcnt(0)
	v_mfma_f32_16x16x32_bf16 v[60:63], v[186:189], v[162:165], v[60:63]
	v_mfma_f32_16x16x32_bf16 v[56:59], v[186:189], v[178:181], v[56:59]
	v_mfma_f32_16x16x32_bf16 v[52:55], v[194:197], v[162:165], v[52:55]
	v_mfma_f32_16x16x32_bf16 v[48:51], v[194:197], v[178:181], v[48:51]
	v_mfma_f32_16x16x32_bf16 v[44:47], v[202:205], v[162:165], v[44:47]
	v_mfma_f32_16x16x32_bf16 v[40:43], v[202:205], v[178:181], v[40:43]
	v_mfma_f32_16x16x32_bf16 v[36:39], v[210:213], v[162:165], v[36:39]
	v_mfma_f32_16x16x32_bf16 v[32:35], v[210:213], v[178:181], v[32:35]
	v_mfma_f32_16x16x32_bf16 v[60:63], v[190:193], v[174:177], v[60:63]
	v_mfma_f32_16x16x32_bf16 v[56:59], v[190:193], v[182:185], v[56:59]
	v_mfma_f32_16x16x32_bf16 v[52:55], v[198:201], v[174:177], v[52:55]
	v_mfma_f32_16x16x32_bf16 v[48:51], v[198:201], v[182:185], v[48:51]
	v_mfma_f32_16x16x32_bf16 v[44:47], v[206:209], v[174:177], v[44:47]
	v_mfma_f32_16x16x32_bf16 v[40:43], v[206:209], v[182:185], v[40:43]
	v_mfma_f32_16x16x32_bf16 v[36:39], v[214:217], v[174:177], v[36:39]
	v_mfma_f32_16x16x32_bf16 v[32:35], v[214:217], v[182:185], v[32:35]
	s_setprio 0
	s_barrier
	s_add_u32 m0, s32, 0x14000
	s_add_u32 s98, s20, 0x40100
	s_addc_u32 s99, s21, 0
	global_load_lds_dwordx4 v253, s[98:99]
	s_add_u32 m0, s32, 0x16000
	s_nop 0
	global_load_lds_dwordx4 v252, s[98:99]
	s_waitcnt vmcnt(6)
	s_barrier
	s_setprio 1
	v_mfma_f32_16x16x32_bf16 v[28:31], v[186:189], v[218:221], v[28:31]
	v_mfma_f32_16x16x32_bf16 v[24:27], v[186:189], v[226:229], v[24:27]
	v_mfma_f32_16x16x32_bf16 v[20:23], v[194:197], v[218:221], v[20:23]
	v_mfma_f32_16x16x32_bf16 v[16:19], v[194:197], v[226:229], v[16:19]
	v_mfma_f32_16x16x32_bf16 v[12:15], v[202:205], v[218:221], v[12:15]
	v_mfma_f32_16x16x32_bf16 v[8:11], v[202:205], v[226:229], v[8:11]
	v_mfma_f32_16x16x32_bf16 v[4:7], v[210:213], v[218:221], v[4:7]
	v_mfma_f32_16x16x32_bf16 v[0:3], v[210:213], v[226:229], v[0:3]
	v_mfma_f32_16x16x32_bf16 v[28:31], v[190:193], v[222:225], v[28:31]
	v_mfma_f32_16x16x32_bf16 v[24:27], v[190:193], v[230:233], v[24:27]
	v_mfma_f32_16x16x32_bf16 v[20:23], v[198:201], v[222:225], v[20:23]
	v_mfma_f32_16x16x32_bf16 v[16:19], v[198:201], v[230:233], v[16:19]
	v_mfma_f32_16x16x32_bf16 v[12:15], v[206:209], v[222:225], v[12:15]
	v_mfma_f32_16x16x32_bf16 v[8:11], v[206:209], v[230:233], v[8:11]
	v_mfma_f32_16x16x32_bf16 v[4:7], v[214:217], v[222:225], v[4:7]
	v_mfma_f32_16x16x32_bf16 v[0:3], v[214:217], v[230:233], v[0:3]
	s_setprio 0
	s_barrier
	ds_read_b128 v[162:165], v140
	ds_read_b128 v[174:177], v140 offset:1024
	ds_read_b128 v[178:181], v140 offset:2048
	ds_read_b128 v[182:185], v140 offset:3072
	ds_read_b128 v[186:189], v135 offset:32768
	ds_read_b128 v[190:193], v135 offset:33792
	ds_read_b128 v[194:197], v156 offset:32768
	ds_read_b128 v[198:201], v156 offset:33792
	ds_read_b128 v[202:205], v157 offset:32768
	ds_read_b128 v[206:209], v157 offset:33792
	ds_read_b128 v[210:213], v158 offset:32768
	ds_read_b128 v[214:217], v158 offset:33792
	s_add_u32 m0, s32, 0x4000
	s_add_u32 s98, s18, 0x40100
	s_addc_u32 s99, s19, 0
	global_load_lds_dwordx4 v253, s[98:99]
	s_add_u32 m0, s32, 0x6000
	s_nop 0
	global_load_lds_dwordx4 v252, s[98:99]
	s_waitcnt lgkmcnt(8)
	s_barrier
; #define LDA(dst, b, h)                                                                                    \
;   _Pragma("unroll") for (int m = 0; m < 4; ++m) _Pragma("unroll") for (int k = 0; k < 2; ++k)             \
;       dst[m][k] = *reinterpret_cast<const bf16x8*>((char*)SA(b, h) + lds_byte(wr * 64 + m * 16 + fr, k * 32 + fq * 8))
; #define LDB(dst, b, h)                                                                                    \
;   _Pragma("unroll") for (int n = 0; n < 2; ++n) _Pragma("unroll") for (int k = 0; k < 2; ++k)             \
;       dst[n][k] = *reinterpret_cast<const bf16x8*>((char*)SB(b, h) + lds_byte(wc * 32 + n * 16 + fr, k * 32 + fq * 8))
; #define WAIT_V(n) asm volatile("s_waitcnt vmcnt(" #n ")" ::: "memory")
; #define WAIT_L(n) asm volatile("s_waitcnt lgkmcnt(" #n ")" ::: "memory")
; #define BAR __builtin_amdgcn_s_barrier()
; #define SCHED __builtin_amdgcn_sched_barrier(0)
; template <int EPI> ...
;     ...
;     LDB(B1, 1, 1); STAGE(SB(1, 0), Bt, bcol, t + 3);
;     BAR; WAIT_L(0); MMA(0, 1, At, B1); BAR;
;     LDA(At, 1, 1); STAGE(SA(1, 0), A, brow, t + 3);
;     BAR; WAIT_L(0); MMA(1, 0, At, B0); BAR; SCHED;
;     STAGE(SB(1, 1), Bt, bcol + HALF, t + 3);
;     WAIT_V(6); BAR; MMA(1, 1, At, B1); BAR;
;   }
	s_waitcnt lgkmcnt(0)
	s_setprio 1
	s_waitcnt lgkmcnt(0)
	v_mfma_f32_16x16x32_bf16 v[124:127], v[186:189], v[162:165], v[124:127]
	v_mfma_f32_16x16x32_bf16 v[120:123], v[186:189], v[178:181], v[120:123]
	v_mfma_f32_16x16x32_bf16 v[116:119], v[194:197], v[162:165], v[116:119]
	v_mfma_f32_16x16x32_bf16 v[112:115], v[194:197], v[178:181], v[112:115]
	v_mfma_f32_16x16x32_bf16 v[108:111], v[202:205], v[162:165], v[108:111]
	v_mfma_f32_16x16x32_bf16 v[104:107], v[202:205], v[178:181], v[104:107]
	v_mfma_f32_16x16x32_bf16 v[100:103], v[210:213], v[162:165], v[100:103]
	v_mfma_f32_16x16x32_bf16 v[96:99], v[210:213], v[178:181], v[96:99]
	v_mfma_f32_16x16x32_bf16 v[124:127], v[190:193], v[174:177], v[124:127]
	v_mfma_f32_16x16x32_bf16 v[120:123], v[190:193], v[182:185], v[120:123]
	v_mfma_f32_16x16x32_bf16 v[116:119], v[198:201], v[174:177], v[116:119]
	v_mfma_f32_16x16x32_bf16 v[112:115], v[198:201], v[182:185], v[112:115]
	v_mfma_f32_16x16x32_bf16 v[108:111], v[206:209], v[174:177], v[108:111]
	v_mfma_f32_16x16x32_bf16 v[104:107], v[206:209], v[182:185], v[104:107]
	v_mfma_f32_16x16x32_bf16 v[100:103], v[214:217], v[174:177], v[100:103]
	v_mfma_f32_16x16x32_bf16 v[96:99], v[214:217], v[182:185], v[96:99]
	s_setprio 0
	s_barrier
	ds_read_b128 v[218:221], v137
	ds_read_b128 v[222:225], v137 offset:1024
	ds_read_b128 v[226:229], v137 offset:2048
	ds_read_b128 v[230:233], v137 offset:3072
	s_add_u32 m0, s32, 0x18000
	s_add_u32 s98, s20, 0x180
	s_addc_u32 s99, s21, 0
	global_load_lds_dwordx4 v253, s[98:99]
	s_add_u32 m0, s32, 0x1a000
	s_nop 0
	global_load_lds_dwordx4 v252, s[98:99]
	s_barrier
	s_waitcnt lgkmcnt(0)
	s_setprio 1
	s_waitcnt lgkmcnt(0)
	v_mfma_f32_16x16x32_bf16 v[92:95], v[186:189], v[218:221], v[92:95]
	v_mfma_f32_16x16x32_bf16 v[88:91], v[186:189], v[226:229], v[88:91]
	v_mfma_f32_16x16x32_bf16 v[84:87], v[194:197], v[218:221], v[84:87]
	v_mfma_f32_16x16x32_bf16 v[80:83], v[194:197], v[226:229], v[80:83]
	v_mfma_f32_16x16x32_bf16 v[76:79], v[202:205], v[218:221], v[76:79]
	v_mfma_f32_16x16x32_bf16 v[72:75], v[202:205], v[226:229], v[72:75]
	v_mfma_f32_16x16x32_bf16 v[68:71], v[210:213], v[218:221], v[68:71]
	v_mfma_f32_16x16x32_bf16 v[64:67], v[210:213], v[226:229], v[64:67]
	v_mfma_f32_16x16x32_bf16 v[92:95], v[190:193], v[222:225], v[92:95]
	v_mfma_f32_16x16x32_bf16 v[88:91], v[190:193], v[230:233], v[88:91]
	v_mfma_f32_16x16x32_bf16 v[84:87], v[198:201], v[222:225], v[84:87]
	v_mfma_f32_16x16x32_bf16 v[80:83], v[198:201], v[230:233], v[80:83]
	v_mfma_f32_16x16x32_bf16 v[76:79], v[206:209], v[222:225], v[76:79]
	v_mfma_f32_16x16x32_bf16 v[72:75], v[206:209], v[230:233], v[72:75]
	v_mfma_f32_16x16x32_bf16 v[68:71], v[214:217], v[222:225], v[68:71]
	v_mfma_f32_16x16x32_bf16 v[64:67], v[214:217], v[230:233], v[64:67]
	s_setprio 0
	s_barrier
	ds_read_b128 v[186:189], v135 offset:49152
	ds_read_b128 v[190:193], v135 offset:50176
	ds_read_b128 v[194:197], v156 offset:49152
	ds_read_b128 v[198:201], v156 offset:50176
	ds_read_b128 v[202:205], v157 offset:49152
	ds_read_b128 v[206:209], v157 offset:50176
	ds_read_b128 v[210:213], v158 offset:49152
	ds_read_b128 v[214:217], v158 offset:50176
	s_add_u32 m0, s32, 0x8000
	s_add_u32 s98, s18, 0x180
	s_addc_u32 s99, s19, 0
	global_load_lds_dwordx4 v253, s[98:99]
	s_nop 0
	s_add_u32 m0, s32, 0xa000
	s_nop 0
	global_load_lds_dwordx4 v252, s[98:99]
	s_barrier
	s_waitcnt lgkmcnt(0)
	s_setprio 1
	s_waitcnt lgkmcnt(0)
	v_mfma_f32_16x16x32_bf16 v[60:63], v[186:189], v[162:165], v[60:63]
	v_mfma_f32_16x16x32_bf16 v[56:59], v[186:189], v[178:181], v[56:59]
	v_mfma_f32_16x16x32_bf16 v[52:55], v[194:197], v[162:165], v[52:55]
	v_mfma_f32_16x16x32_bf16 v[48:51], v[194:197], v[178:181], v[48:51]
	v_mfma_f32_16x16x32_bf16 v[44:47], v[202:205], v[162:165], v[44:47]
	v_mfma_f32_16x16x32_bf16 v[40:43], v[202:205], v[178:181], v[40:43]
	v_mfma_f32_16x16x32_bf16 v[36:39], v[210:213], v[162:165], v[36:39]
	v_mfma_f32_16x16x32_bf16 v[32:35], v[210:213], v[178:181], v[32:35]
	v_mfma_f32_16x16x32_bf16 v[60:63], v[190:193], v[174:177], v[60:63]
	v_mfma_f32_16x16x32_bf16 v[56:59], v[190:193], v[182:185], v[56:59]
	v_mfma_f32_16x16x32_bf16 v[52:55], v[198:201], v[174:177], v[52:55]
	v_mfma_f32_16x16x32_bf16 v[48:51], v[198:201], v[182:185], v[48:51]
	v_mfma_f32_16x16x32_bf16 v[44:47], v[206:209], v[174:177], v[44:47]
	v_mfma_f32_16x16x32_bf16 v[40:43], v[206:209], v[182:185], v[40:43]
	v_mfma_f32_16x16x32_bf16 v[36:39], v[214:217], v[174:177], v[36:39]
	v_mfma_f32_16x16x32_bf16 v[32:35], v[214:217], v[182:185], v[32:35]
	s_setprio 0
	s_barrier
	s_add_u32 m0, s32, 0x1c000
	s_add_u32 s98, s20, 0x40180
	s_addc_u32 s99, s21, 0
	global_load_lds_dwordx4 v253, s[98:99]
	s_add_u32 m0, s32, 0x1e000
	s_nop 0
	global_load_lds_dwordx4 v252, s[98:99]
	s_waitcnt vmcnt(6)
	s_barrier
	s_setprio 1
	v_mfma_f32_16x16x32_bf16 v[28:31], v[186:189], v[218:221], v[28:31]
	v_mfma_f32_16x16x32_bf16 v[24:27], v[186:189], v[226:229], v[24:27]
	v_mfma_f32_16x16x32_bf16 v[20:23], v[194:197], v[218:221], v[20:23]
	v_mfma_f32_16x16x32_bf16 v[16:19], v[194:197], v[226:229], v[16:19]
	v_mfma_f32_16x16x32_bf16 v[12:15], v[202:205], v[218:221], v[12:15]
	v_mfma_f32_16x16x32_bf16 v[8:11], v[202:205], v[226:229], v[8:11]
	v_mfma_f32_16x16x32_bf16 v[4:7], v[210:213], v[218:221], v[4:7]
	v_mfma_f32_16x16x32_bf16 v[0:3], v[210:213], v[226:229], v[0:3]
	v_mfma_f32_16x16x32_bf16 v[28:31], v[190:193], v[222:225], v[28:31]
	v_mfma_f32_16x16x32_bf16 v[24:27], v[190:193], v[230:233], v[24:27]
	v_mfma_f32_16x16x32_bf16 v[20:23], v[198:201], v[222:225], v[20:23]
	v_mfma_f32_16x16x32_bf16 v[16:19], v[198:201], v[230:233], v[16:19]
	v_mfma_f32_16x16x32_bf16 v[12:15], v[206:209], v[222:225], v[12:15]
	v_mfma_f32_16x16x32_bf16 v[8:11], v[206:209], v[230:233], v[8:11]
	v_mfma_f32_16x16x32_bf16 v[4:7], v[214:217], v[222:225], v[4:7]
	v_mfma_f32_16x16x32_bf16 v[0:3], v[214:217], v[230:233], v[0:3]
	s_setprio 0
	s_add_i32 s68, s68, 2
	s_add_u32 s16, s16, 0x100
	s_addc_u32 s17, s17, 0
	s_cmp_lt_u32 s68, 12
	s_barrier
; #define LDA(dst, b, h)                                                                                    \
;   _Pragma("unroll") for (int m = 0; m < 4; ++m) _Pragma("unroll") for (int k = 0; k < 2; ++k)             \
;       dst[m][k] = *reinterpret_cast<const bf16x8*>((char*)SA(b, h) + lds_byte(wr * 64 + m * 16 + fr, k * 32 + fq * 8))
; #define LDB(dst, b, h)                                                                                    \
;   _Pragma("unroll") for (int n = 0; n < 2; ++n) _Pragma("unroll") for (int k = 0; k < 2; ++k)             \
;       dst[n][k] = *reinterpret_cast<const bf16x8*>((char*)SB(b, h) + lds_byte(wc * 32 + n * 16 + fr, k * 32 + fq * 8))
; #define WAIT_V(n) asm volatile("s_waitcnt vmcnt(" #n ")" ::: "memory")
; #define WAIT_L(n) asm volatile("s_waitcnt lgkmcnt(" #n ")" ::: "memory")
; #define BAR __builtin_amdgcn_s_barrier()
; template <int EPI> ...
;     ...
;   }
;   {
;     LDB(B0, 0, 0); LDA(At, 0, 0); STAGE(SA(1, 1), A, brow + HALF, nt - 1);
;     BAR; WAIT_L(0); MMA(0, 0, At, B0); BAR;
;     LDB(B1, 0, 1); BAR; WAIT_L(0); MMA(0, 1, At, B1); BAR;
;     LDA(At, 0, 1); WAIT_V(4); BAR; WAIT_L(0); MMA(1, 0, At, B0); MMA(1, 1, At, B1); BAR;
	s_cbranch_scc1 .LBB0_1754
	ds_read_b128 v[142:145], v155
	ds_read_b128 v[162:165], v155 offset:1024
	ds_read_b128 v[174:177], v155 offset:2048
	ds_read_b128 v[178:181], v155 offset:3072
	ds_read_b128 v[182:185], v135
	ds_read_b128 v[186:189], v135 offset:1024
	ds_read_b128 v[190:193], v156
	ds_read_b128 v[194:197], v156 offset:1024
	ds_read_b128 v[198:201], v157
	ds_read_b128 v[202:205], v157 offset:1024
	ds_read_b128 v[206:209], v158
	ds_read_b128 v[210:213], v158 offset:1024
	v_mov_b32_e32 v129, v149
	v_lshl_add_u64 v[128:129], v[128:129], 1, s[14:15]
	s_mov_b64 s[12:13], 0x780
	v_readfirstlane_b32 s10, v160
	v_lshl_add_u64 v[128:129], v[128:129], 0, s[12:13]
	s_mov_b32 m0, s10
	v_mov_b32_e32 v131, v149
	global_load_lds_dwordx4 v[128:129], off
	v_readfirstlane_b32 s10, v159
	v_lshl_add_u64 v[128:129], v[130:131], 1, s[14:15]
	v_lshl_add_u64 v[128:129], v[128:129], 0, s[12:13]
	s_mov_b32 m0, s10
	s_nop 0
	global_load_lds_dwordx4 v[128:129], off
	s_barrier
	s_waitcnt lgkmcnt(0)
	s_setprio 1
	s_waitcnt lgkmcnt(0)
	v_mfma_f32_16x16x32_bf16 v[124:127], v[182:185], v[142:145], v[124:127]
	v_mfma_f32_16x16x32_bf16 v[120:123], v[182:185], v[174:177], v[120:123]
	v_mfma_f32_16x16x32_bf16 v[116:119], v[190:193], v[142:145], v[116:119]
	v_mfma_f32_16x16x32_bf16 v[112:115], v[190:193], v[174:177], v[112:115]
	v_mfma_f32_16x16x32_bf16 v[108:111], v[198:201], v[142:145], v[108:111]
	v_mfma_f32_16x16x32_bf16 v[104:107], v[198:201], v[174:177], v[104:107]
	v_mfma_f32_16x16x32_bf16 v[96:99], v[206:209], v[174:177], v[96:99]
	v_mfma_f32_16x16x32_bf16 v[124:127], v[186:189], v[162:165], v[124:127]
	v_mfma_f32_16x16x32_bf16 v[120:123], v[186:189], v[178:181], v[120:123]
	v_mfma_f32_16x16x32_bf16 v[116:119], v[194:197], v[162:165], v[116:119]
	v_mfma_f32_16x16x32_bf16 v[112:115], v[194:197], v[178:181], v[112:115]
	v_mfma_f32_16x16x32_bf16 v[108:111], v[202:205], v[162:165], v[108:111]
	v_mfma_f32_16x16x32_bf16 v[104:107], v[202:205], v[178:181], v[104:107]
	v_mfma_f32_16x16x32_bf16 v[100:103], v[206:209], v[142:145], v[100:103]
	v_mfma_f32_16x16x32_bf16 v[96:99], v[210:213], v[178:181], v[96:99]
	v_mfma_f32_16x16x32_bf16 v[128:131], v[210:213], v[162:165], v[100:103]
	s_setprio 0
	s_barrier
	s_nop 3
	ds_read_b128 v[100:103], v152
	ds_read_b128 v[214:217], v152 offset:1024
	ds_read_b128 v[218:221], v152 offset:2048
	ds_read_b128 v[152:155], v152 offset:3072
	s_barrier
	s_waitcnt lgkmcnt(0)
	s_setprio 1
	s_waitcnt lgkmcnt(0)
	v_mfma_f32_16x16x32_bf16 v[88:91], v[182:185], v[218:221], v[88:91]
	v_mfma_f32_16x16x32_bf16 v[92:95], v[182:185], v[100:103], v[92:95]
	v_mfma_f32_16x16x32_bf16 v[88:91], v[186:189], v[152:155], v[88:91]
	v_mfma_f32_16x16x32_bf16 v[84:87], v[190:193], v[100:103], v[84:87]
	v_mfma_f32_16x16x32_bf16 v[80:83], v[190:193], v[218:221], v[80:83]
	v_mfma_f32_16x16x32_bf16 v[76:79], v[198:201], v[100:103], v[76:79]
	v_mfma_f32_16x16x32_bf16 v[72:75], v[198:201], v[218:221], v[72:75]
	v_mfma_f32_16x16x32_bf16 v[68:71], v[206:209], v[100:103], v[68:71]
	v_mfma_f32_16x16x32_bf16 v[64:67], v[206:209], v[218:221], v[64:67]
	v_mfma_f32_16x16x32_bf16 v[222:225], v[186:189], v[214:217], v[92:95]
	v_mfma_f32_16x16x32_bf16 v[182:185], v[194:197], v[214:217], v[84:87]
	v_mfma_f32_16x16x32_bf16 v[186:189], v[194:197], v[152:155], v[80:83]
	v_mfma_f32_16x16x32_bf16 v[190:193], v[202:205], v[214:217], v[76:79]
	v_mfma_f32_16x16x32_bf16 v[194:197], v[202:205], v[152:155], v[72:75]
	v_mfma_f32_16x16x32_bf16 v[198:201], v[210:213], v[214:217], v[68:71]
	v_mfma_f32_16x16x32_bf16 v[202:205], v[210:213], v[152:155], v[64:67]
	s_setprio 0
	s_barrier
	s_nop 0
	ds_read_b128 v[64:67], v135 offset:16384
	ds_read_b128 v[68:71], v135 offset:17408
	ds_read_b128 v[72:75], v156 offset:16384
	ds_read_b128 v[76:79], v156 offset:17408
	ds_read_b128 v[80:83], v157 offset:16384
	ds_read_b128 v[84:87], v157 offset:17408
	ds_read_b128 v[92:95], v158 offset:16384
	ds_read_b128 v[206:209], v158 offset:17408
	s_waitcnt vmcnt(4)
	s_barrier
	s_waitcnt lgkmcnt(0)
	s_setprio 1
	s_waitcnt lgkmcnt(0)
	v_mfma_f32_16x16x32_bf16 v[60:63], v[64:67], v[142:145], v[60:63]
	v_mfma_f32_16x16x32_bf16 v[56:59], v[64:67], v[174:177], v[56:59]
	v_mfma_f32_16x16x32_bf16 v[52:55], v[72:75], v[142:145], v[52:55]
	v_mfma_f32_16x16x32_bf16 v[48:51], v[72:75], v[174:177], v[48:51]
	v_mfma_f32_16x16x32_bf16 v[44:47], v[80:83], v[142:145], v[44:47]
	v_mfma_f32_16x16x32_bf16 v[40:43], v[80:83], v[174:177], v[40:43]
	v_mfma_f32_16x16x32_bf16 v[36:39], v[92:95], v[142:145], v[36:39]
	v_mfma_f32_16x16x32_bf16 v[32:35], v[92:95], v[174:177], v[32:35]
	v_mfma_f32_16x16x32_bf16 v[60:63], v[68:71], v[162:165], v[60:63]
	v_mfma_f32_16x16x32_bf16 v[56:59], v[68:71], v[178:181], v[56:59]
	v_mfma_f32_16x16x32_bf16 v[52:55], v[76:79], v[162:165], v[52:55]
	v_mfma_f32_16x16x32_bf16 v[48:51], v[76:79], v[178:181], v[48:51]
	v_mfma_f32_16x16x32_bf16 v[44:47], v[84:87], v[162:165], v[44:47]
	v_mfma_f32_16x16x32_bf16 v[40:43], v[84:87], v[178:181], v[40:43]
	v_mfma_f32_16x16x32_bf16 v[36:39], v[206:209], v[162:165], v[36:39]
	v_mfma_f32_16x16x32_bf16 v[32:35], v[206:209], v[178:181], v[32:35]
	s_setprio 0
	s_setprio 1
	v_mfma_f32_16x16x32_bf16 v[28:31], v[64:67], v[100:103], v[28:31]
	v_mfma_f32_16x16x32_bf16 v[24:27], v[64:67], v[218:221], v[24:27]
	v_mfma_f32_16x16x32_bf16 v[20:23], v[72:75], v[100:103], v[20:23]
	v_mfma_f32_16x16x32_bf16 v[16:19], v[72:75], v[218:221], v[16:19]
	v_mfma_f32_16x16x32_bf16 v[12:15], v[80:83], v[100:103], v[12:15]
	v_mfma_f32_16x16x32_bf16 v[8:11], v[80:83], v[218:221], v[8:11]
	v_mfma_f32_16x16x32_bf16 v[4:7], v[92:95], v[100:103], v[4:7]
	v_mfma_f32_16x16x32_bf16 v[0:3], v[92:95], v[218:221], v[0:3]
	v_mfma_f32_16x16x32_bf16 v[142:145], v[68:71], v[214:217], v[28:31]
	v_mfma_f32_16x16x32_bf16 v[160:163], v[68:71], v[152:155], v[24:27]
	v_mfma_f32_16x16x32_bf16 v[164:167], v[76:79], v[214:217], v[20:23]
	v_mfma_f32_16x16x32_bf16 v[174:177], v[76:79], v[152:155], v[16:19]
	v_mfma_f32_16x16x32_bf16 v[178:181], v[84:87], v[214:217], v[12:15]
	v_mfma_f32_16x16x32_bf16 v[210:213], v[84:87], v[152:155], v[8:11]
	v_mfma_f32_16x16x32_bf16 v[214:217], v[206:209], v[214:217], v[4:7]
	v_mfma_f32_16x16x32_bf16 v[152:155], v[206:209], v[152:155], v[0:3]
	s_setprio 0
	s_barrier
; #define LDA(dst, b, h)                                                                                    \
;   _Pragma("unroll") for (int m = 0; m < 4; ++m) _Pragma("unroll") for (int k = 0; k < 2; ++k)             \
;       dst[m][k] = *reinterpret_cast<const bf16x8*>((char*)SA(b, h) + lds_byte(wr * 64 + m * 16 + fr, k * 32 + fq * 8))
; #define LDB(dst, b, h)                                                                                    \
;   _Pragma("unroll") for (int n = 0; n < 2; ++n) _Pragma("unroll") for (int k = 0; k < 2; ++k)             \
;       dst[n][k] = *reinterpret_cast<const bf16x8*>((char*)SB(b, h) + lds_byte(wc * 32 + n * 16 + fr, k * 32 + fq * 8))
; #define WAIT_V(n) asm volatile("s_waitcnt vmcnt(" #n ")" ::: "memory")
; #define WAIT_L(n) asm volatile("s_waitcnt lgkmcnt(" #n ")" ::: "memory")
; #define BAR __builtin_amdgcn_s_barrier()
; template <int EPI> ...
;     ...
;     LDA(At, 0, 1); WAIT_V(4); BAR; WAIT_L(0); MMA(1, 0, At, B0); MMA(1, 1, At, B1); BAR;
;   }
;   {
;     LDB(B0, 1, 0); LDA(At, 1, 0); WAIT_V(2); BAR; WAIT_L(0); MMA(0, 0, At, B0); BAR;
;     LDB(B1, 1, 1); WAIT_V(0); BAR; WAIT_L(0); MMA(0, 1, At, B1); BAR;
;     LDA(At, 1, 1); BAR; WAIT_L(0); MMA(1, 0, At, B0); MMA(1, 1, At, B1); BAR;
;   }
;   if (wr == 0) BAR;
;   if (has_next) ISSUE_PRO(nm0, nn0);
	s_nop 0
	ds_read_b128 v[0:3], v140
	ds_read_b128 v[4:7], v140 offset:1024
	ds_read_b128 v[206:209], v140 offset:2048
	ds_read_b128 v[138:141], v140 offset:3072
	ds_read_b128 v[8:11], v135 offset:32768
	ds_read_b128 v[12:15], v135 offset:33792
	ds_read_b128 v[16:19], v156 offset:32768
	ds_read_b128 v[20:23], v156 offset:33792
	ds_read_b128 v[24:27], v157 offset:32768
	ds_read_b128 v[28:31], v157 offset:33792
	ds_read_b128 v[218:221], v158 offset:32768
	ds_read_b128 v[226:229], v158 offset:33792
	s_waitcnt vmcnt(2)
	s_barrier
	s_waitcnt lgkmcnt(0)
	s_setprio 1
	s_waitcnt lgkmcnt(0)
	v_mfma_f32_16x16x32_bf16 v[64:67], v[8:11], v[0:3], v[124:127]
	v_mfma_f32_16x16x32_bf16 v[92:95], v[12:15], v[4:7], v[64:67]
	v_mfma_f32_16x16x32_bf16 v[64:67], v[8:11], v[206:209], v[120:123]
	v_mfma_f32_16x16x32_bf16 v[100:103], v[12:15], v[138:141], v[64:67]
	v_mfma_f32_16x16x32_bf16 v[64:67], v[16:19], v[0:3], v[116:119]
	v_mfma_f32_16x16x32_bf16 v[80:83], v[20:23], v[4:7], v[64:67]
	v_mfma_f32_16x16x32_bf16 v[64:67], v[16:19], v[206:209], v[112:115]
	v_mfma_f32_16x16x32_bf16 v[84:87], v[20:23], v[138:141], v[64:67]
	v_mfma_f32_16x16x32_bf16 v[64:67], v[24:27], v[0:3], v[108:111]
	v_mfma_f32_16x16x32_bf16 v[72:75], v[28:31], v[4:7], v[64:67]
	v_mfma_f32_16x16x32_bf16 v[64:67], v[24:27], v[206:209], v[104:107]
	v_mfma_f32_16x16x32_bf16 v[76:79], v[28:31], v[138:141], v[64:67]
	v_mfma_f32_16x16x32_bf16 v[64:67], v[218:221], v[0:3], v[128:131]
	v_mfma_f32_16x16x32_bf16 v[68:71], v[218:221], v[206:209], v[96:99]
	v_mfma_f32_16x16x32_bf16 v[64:67], v[226:229], v[4:7], v[64:67]
	v_mfma_f32_16x16x32_bf16 v[68:71], v[226:229], v[138:141], v[68:71]
	s_setprio 0
	s_barrier
	ds_read_b128 v[128:131], v137
	ds_read_b128 v[230:233], v137 offset:1024
	ds_read_b128 v[234:237], v137 offset:2048
	ds_read_b128 v[238:241], v137 offset:3072
	s_waitcnt vmcnt(0)
	s_barrier
	s_waitcnt lgkmcnt(0)
	s_setprio 1
	s_waitcnt lgkmcnt(0)
	v_mfma_f32_16x16x32_bf16 v[96:99], v[8:11], v[128:131], v[222:225]
	v_mfma_f32_16x16x32_bf16 v[8:11], v[8:11], v[234:237], v[88:91]
	v_mfma_f32_16x16x32_bf16 v[124:127], v[12:15], v[238:241], v[8:11]
	v_mfma_f32_16x16x32_bf16 v[8:11], v[16:19], v[128:131], v[182:185]
	v_mfma_f32_16x16x32_bf16 v[112:115], v[20:23], v[230:233], v[8:11]
	v_mfma_f32_16x16x32_bf16 v[8:11], v[16:19], v[234:237], v[186:189]
	v_mfma_f32_16x16x32_bf16 v[116:119], v[20:23], v[238:241], v[8:11]
	v_mfma_f32_16x16x32_bf16 v[8:11], v[24:27], v[128:131], v[190:193]
	v_mfma_f32_16x16x32_bf16 v[104:107], v[28:31], v[230:233], v[8:11]
	v_mfma_f32_16x16x32_bf16 v[8:11], v[24:27], v[234:237], v[194:197]
	v_mfma_f32_16x16x32_bf16 v[108:111], v[28:31], v[238:241], v[8:11]
	v_mfma_f32_16x16x32_bf16 v[8:11], v[218:221], v[128:131], v[198:201]
	v_mfma_f32_16x16x32_bf16 v[88:91], v[226:229], v[230:233], v[8:11]
	v_mfma_f32_16x16x32_bf16 v[8:11], v[218:221], v[234:237], v[202:205]
	v_mfma_f32_16x16x32_bf16 v[120:123], v[12:15], v[230:233], v[96:99]
	v_mfma_f32_16x16x32_bf16 v[96:99], v[226:229], v[238:241], v[8:11]
	s_setprio 0
	s_barrier
	ds_read_b128 v[182:185], v135 offset:49152
	ds_read_b128 v[186:189], v135 offset:50176
	ds_read_b128 v[190:193], v156 offset:49152
	ds_read_b128 v[194:197], v156 offset:50176
	ds_read_b128 v[198:201], v157 offset:49152
	ds_read_b128 v[202:205], v157 offset:50176
	ds_read_b128 v[218:221], v158 offset:49152
	ds_read_b128 v[156:159], v158 offset:50176
	s_barrier
	s_waitcnt lgkmcnt(0)
	s_setprio 1
	s_waitcnt lgkmcnt(0)
	v_mfma_f32_16x16x32_bf16 v[8:11], v[182:185], v[0:3], v[60:63]
	v_mfma_f32_16x16x32_bf16 v[24:27], v[186:189], v[4:7], v[8:11]
	v_mfma_f32_16x16x32_bf16 v[8:11], v[182:185], v[206:209], v[56:59]
	v_mfma_f32_16x16x32_bf16 v[28:31], v[186:189], v[138:141], v[8:11]
	v_mfma_f32_16x16x32_bf16 v[8:11], v[190:193], v[0:3], v[52:55]
	v_mfma_f32_16x16x32_bf16 v[16:19], v[194:197], v[4:7], v[8:11]
	v_mfma_f32_16x16x32_bf16 v[8:11], v[190:193], v[206:209], v[48:51]
	v_mfma_f32_16x16x32_bf16 v[20:23], v[194:197], v[138:141], v[8:11]
	v_mfma_f32_16x16x32_bf16 v[8:11], v[198:201], v[0:3], v[44:47]
	v_mfma_f32_16x16x32_bf16 v[0:3], v[218:221], v[0:3], v[36:39]
	v_mfma_f32_16x16x32_bf16 v[8:11], v[202:205], v[4:7], v[8:11]
	v_mfma_f32_16x16x32_bf16 v[12:15], v[198:201], v[206:209], v[40:43]
	v_mfma_f32_16x16x32_bf16 v[0:3], v[156:159], v[4:7], v[0:3]
	v_mfma_f32_16x16x32_bf16 v[4:7], v[218:221], v[206:209], v[32:35]
	v_mfma_f32_16x16x32_bf16 v[12:15], v[202:205], v[138:141], v[12:15]
	v_mfma_f32_16x16x32_bf16 v[4:7], v[156:159], v[138:141], v[4:7]
	s_setprio 0
	s_setprio 1
	v_mfma_f32_16x16x32_bf16 v[32:35], v[182:185], v[128:131], v[142:145]
	v_mfma_f32_16x16x32_bf16 v[56:59], v[186:189], v[230:233], v[32:35]
	v_mfma_f32_16x16x32_bf16 v[32:35], v[182:185], v[234:237], v[160:163]
	v_mfma_f32_16x16x32_bf16 v[60:63], v[186:189], v[238:241], v[32:35]
	v_mfma_f32_16x16x32_bf16 v[32:35], v[190:193], v[128:131], v[164:167]
	v_mfma_f32_16x16x32_bf16 v[48:51], v[194:197], v[230:233], v[32:35]
	v_mfma_f32_16x16x32_bf16 v[32:35], v[190:193], v[234:237], v[174:177]
	v_mfma_f32_16x16x32_bf16 v[52:55], v[194:197], v[238:241], v[32:35]
	v_mfma_f32_16x16x32_bf16 v[32:35], v[198:201], v[128:131], v[178:181]
	v_mfma_f32_16x16x32_bf16 v[40:43], v[202:205], v[230:233], v[32:35]
	v_mfma_f32_16x16x32_bf16 v[32:35], v[198:201], v[234:237], v[210:213]
	v_mfma_f32_16x16x32_bf16 v[44:47], v[202:205], v[238:241], v[32:35]
	v_mfma_f32_16x16x32_bf16 v[32:35], v[218:221], v[128:131], v[214:217]
	v_mfma_f32_16x16x32_bf16 v[36:39], v[218:221], v[234:237], v[152:155]
	v_mfma_f32_16x16x32_bf16 v[32:35], v[156:159], v[230:233], v[32:35]
	v_mfma_f32_16x16x32_bf16 v[36:39], v[156:159], v[238:241], v[36:39]
	s_setprio 0
	s_cmpk_gt_u32 s62, 0xff
	s_barrier
	s_cbranch_scc1 .LBB0_1748
	s_barrier
	s_branch .LBB0_1748

; DEVI f32x4 ozero() { float z = 0.f; asm volatile("" : "+v"(z)); return f32x4{z, z, z, z}; }
; #define LDA(dst, b, h)                                                                                    \
;   _Pragma("unroll") for (int m = 0; m < 4; ++m) _Pragma("unroll") for (int k = 0; k < 2; ++k)             \
;       dst[m][k] = *reinterpret_cast<const bf16x8*>((char*)SA(b, h) + lds_byte(wr * 64 + m * 16 + fr, k * 32 + fq * 8))
; #define LDB(dst, b, h)                                                                                    \
;   _Pragma("unroll") for (int n = 0; n < 2; ++n) _Pragma("unroll") for (int k = 0; k < 2; ++k)             \
;       dst[n][k] = *reinterpret_cast<const bf16x8*>((char*)SB(b, h) + lds_byte(wc * 32 + n * 16 + fr, k * 32 + fq * 8))
; #define WAIT_V(n) asm volatile("s_waitcnt vmcnt(" #n ")" ::: "memory")
; #define WAIT_L(n) asm volatile("s_waitcnt lgkmcnt(" #n ")" ::: "memory")
; #define BAR __builtin_amdgcn_s_barrier()
; #define SCHED __builtin_amdgcn_sched_barrier(0)
; template <int EPI> ...
;     ...
;   const int brow = m0, bcol = n0;
;   const int wid = __builtin_amdgcn_readfirstlane(tid >> 6), lane = tid & 63, wr = wid >> 2, wc = wid & 3, fr = lane & 15, fq = lane >> 4;
;   f32x4 acc[2][2][4][2];
;   {
;     const f32x4 zq = ozero();
; #pragma unroll
;     for (int a_ = 0; a_ < 2; ++a_)
; #pragma unroll
;       for (int b_ = 0; b_ < 2; ++b_)
; #pragma unroll
;         for (int m = 0; m < 4; ++m) { acc[a_][b_][m][0] = zq; acc[a_][b_][m][1] = zq; }
;   }
;   bf16x8 At[4][2], B0[2][2], B1[2][2];
;   const int nt = K / BK;
;     ...
;   if (first) {
;     WAIT_V(0);
;     ISSUE_PRO(brow, bcol);
;   }
;   if (wr == 1) BAR;
;   WAIT_V(10); BAR;
;   WAIT_V(6); BAR;
;   for (int t = 0; t < nt - 2; t += 2) {
;     LDB(B0, 0, 0); SCHED; LDA(At, 0, 0); STAGE(SA(1, 1), A, brow + HALF, t + 1);
;     WAIT_L(8); BAR; WAIT_L(0); MMA(0, 0, At, B0); BAR; SCHED;
.LBB0_1778:
	v_and_b32_e32 v133, 15, v132
	v_and_b32_e32 v1, 48, v132
	v_lshlrev_b32_e32 v2, 6, v133
	v_lshlrev_b32_e32 v4, 2, v132
	v_or_b32_e32 v3, v2, v1
	v_and_b32_e32 v4, 32, v4
	s_mov_b32 s16, 0x10000
	v_bitop3_b32 v5, v3, s16, v4 bitop3:0xde
	s_mov_b32 s16, 0x14000
	s_ashr_i32 s34, s30, 6
	v_bitop3_b32 v6, v3, s16, v4 bitop3:0xde
	s_mov_b32 s16, 0x18000
	s_and_b32 s35, s34, 3
	s_waitcnt vmcnt(10)
	s_barrier
	s_waitcnt vmcnt(6)
	v_bitop3_b32 v7, v3, s16, v4 bitop3:0xde
	s_mov_b32 s16, 0x1c000
	v_lshlrev_b32_e32 v8, 6, v132
	s_lshl_b32 s19, s35, 12
	v_bitop3_b32 v2, v2, v4, v1 bitop3:0x36
	s_lshl_b32 s62, s18, 6
	v_bitop3_b32 v3, v3, s16, v4 bitop3:0xde
	s_lshl_b32 s18, s18, 13
	v_and_b32_e32 v8, 0x3c0, v8
	s_ashr_i32 s31, s23, 31
	v_bitop3_b32 v154, v8, v4, v1 bitop3:0x36
	s_or_b32 s63, s18, 0x800
	s_or_b32 s68, s18, 0x1000
	s_or_b32 s69, s18, 0x1800
	s_mov_b32 s70, -2
	s_mov_b64 s[16:17], 0
	v_add_u32_e32 v155, s19, v5
	v_add_u32_e32 v135, s18, v2
	v_add_u32_e32 v152, s19, v6
	v_add_u32_e32 v140, s19, v7
	v_add_u32_e32 v137, s19, v3
	v_mov_b32_e32 v1, v0
	v_mov_b32_e32 v2, v0
	v_mov_b32_e32 v3, v0
	v_mov_b32_e32 v4, v0
	v_mov_b32_e32 v5, v0
	v_mov_b32_e32 v6, v0
	v_mov_b32_e32 v7, v0
	v_mov_b32_e32 v8, v0
	v_mov_b32_e32 v9, v0
	v_mov_b32_e32 v10, v0
	v_mov_b32_e32 v11, v0
	v_mov_b32_e32 v12, v0
	v_mov_b32_e32 v13, v0
	v_mov_b32_e32 v14, v0
	v_mov_b32_e32 v15, v0
	v_mov_b32_e32 v16, v0
	v_mov_b32_e32 v17, v0
	v_mov_b32_e32 v18, v0
	v_mov_b32_e32 v19, v0
	v_mov_b32_e32 v20, v0
	v_mov_b32_e32 v21, v0
	v_mov_b32_e32 v22, v0
	v_mov_b32_e32 v23, v0
	v_mov_b32_e32 v24, v0
	v_mov_b32_e32 v25, v0
	v_mov_b32_e32 v26, v0
	v_mov_b32_e32 v27, v0
	v_mov_b32_e32 v28, v0
	v_mov_b32_e32 v29, v0
	v_mov_b32_e32 v30, v0
	v_mov_b32_e32 v31, v0
	v_mov_b32_e32 v32, v0
	v_mov_b32_e32 v33, v0
	v_mov_b32_e32 v34, v0
	v_mov_b32_e32 v35, v0
	v_mov_b32_e32 v36, v0
	v_mov_b32_e32 v37, v0
	v_mov_b32_e32 v38, v0
	v_mov_b32_e32 v39, v0
	v_mov_b32_e32 v40, v0
	v_mov_b32_e32 v41, v0
	v_mov_b32_e32 v42, v0
	v_mov_b32_e32 v43, v0
	v_mov_b32_e32 v44, v0
	v_mov_b32_e32 v45, v0
	v_mov_b32_e32 v46, v0
	v_mov_b32_e32 v47, v0
	v_mov_b32_e32 v48, v0
	v_mov_b32_e32 v49, v0
	v_mov_b32_e32 v50, v0
	v_mov_b32_e32 v51, v0
	v_mov_b32_e32 v52, v0
	v_mov_b32_e32 v53, v0
	v_mov_b32_e32 v54, v0
	v_mov_b32_e32 v55, v0
	v_mov_b32_e32 v56, v0
	v_mov_b32_e32 v57, v0
	v_mov_b32_e32 v58, v0
	v_mov_b32_e32 v59, v0
	v_mov_b32_e32 v60, v0
	v_mov_b32_e32 v61, v0
	v_mov_b32_e32 v62, v0
	v_mov_b32_e32 v63, v0
	v_mov_b32_e32 v64, v0
	v_mov_b32_e32 v65, v0
	v_mov_b32_e32 v66, v0
	v_mov_b32_e32 v67, v0
	v_mov_b32_e32 v68, v0
	v_mov_b32_e32 v69, v0
	v_mov_b32_e32 v70, v0
	v_mov_b32_e32 v71, v0
	v_mov_b32_e32 v72, v0
	v_mov_b32_e32 v73, v0
	v_mov_b32_e32 v74, v0
	v_mov_b32_e32 v75, v0
	v_mov_b32_e32 v76, v0
	v_mov_b32_e32 v77, v0
	v_mov_b32_e32 v78, v0
	v_mov_b32_e32 v79, v0
	v_mov_b32_e32 v80, v0
	v_mov_b32_e32 v81, v0
	v_mov_b32_e32 v82, v0
	v_mov_b32_e32 v83, v0
	v_mov_b32_e32 v84, v0
	v_mov_b32_e32 v85, v0
	v_mov_b32_e32 v86, v0
	v_mov_b32_e32 v87, v0
	v_mov_b32_e32 v88, v0
	v_mov_b32_e32 v89, v0
	v_mov_b32_e32 v90, v0
	v_mov_b32_e32 v91, v0
	v_mov_b32_e32 v92, v0
	v_mov_b32_e32 v93, v0
	v_mov_b32_e32 v94, v0
	v_mov_b32_e32 v95, v0
	v_mov_b32_e32 v96, v0
	v_mov_b32_e32 v97, v0
	v_mov_b32_e32 v98, v0
	v_mov_b32_e32 v99, v0
	v_mov_b32_e32 v100, v0
	v_mov_b32_e32 v101, v0
	v_mov_b32_e32 v102, v0
	v_mov_b32_e32 v103, v0
	v_mov_b32_e32 v104, v0
	v_mov_b32_e32 v105, v0
	v_mov_b32_e32 v106, v0
	v_mov_b32_e32 v107, v0
	v_mov_b32_e32 v108, v0
	v_mov_b32_e32 v109, v0
	v_mov_b32_e32 v110, v0
	v_mov_b32_e32 v111, v0
	v_mov_b32_e32 v112, v0
	v_mov_b32_e32 v113, v0
	v_mov_b32_e32 v114, v0
	v_mov_b32_e32 v115, v0
	v_mov_b32_e32 v116, v0
	v_mov_b32_e32 v117, v0
	v_mov_b32_e32 v118, v0
	v_mov_b32_e32 v119, v0
	v_mov_b32_e32 v120, v0
	v_mov_b32_e32 v121, v0
	v_mov_b32_e32 v122, v0
	v_mov_b32_e32 v123, v0
	v_mov_b32_e32 v124, v0
	v_mov_b32_e32 v125, v0
	v_mov_b32_e32 v126, v0
	v_mov_b32_e32 v127, v0
	s_barrier
	v_lshlrev_b32_e32 v253, 1, v128
	v_lshlrev_b32_e32 v252, 1, v130
	v_readfirstlane_b32 s32, v129
.LBB0_1779:
	ds_read_b128 v[162:165], v155
	ds_read_b128 v[174:177], v155 offset:1024
	ds_read_b128 v[178:181], v155 offset:2048
	ds_read_b128 v[182:185], v155 offset:3072
	s_add_u32 s18, s12, s16
	v_add_u32_e32 v156, s63, v154
	v_add_u32_e32 v157, s68, v154
	v_add_u32_e32 v158, s69, v154
	s_addc_u32 s19, s13, s17
	v_add_u32_e32 v159, 0xc000, v129
	ds_read_b128 v[186:189], v135
	ds_read_b128 v[190:193], v135 offset:1024
	ds_read_b128 v[194:197], v156
	ds_read_b128 v[198:201], v156 offset:1024
	ds_read_b128 v[202:205], v157
	ds_read_b128 v[206:209], v157 offset:1024
	ds_read_b128 v[210:213], v158
	ds_read_b128 v[214:217], v158 offset:1024
	s_add_u32 m0, s32, 0xc000
	s_add_u32 s98, s18, 0xb0080
	s_addc_u32 s99, s19, 0
	global_load_lds_dwordx4 v253, s[98:99]
	s_nop 0
	v_add_u32_e32 v160, 0xe000, v129
	s_nop 0
	s_add_u32 m0, s32, 0xe000
	s_nop 0
	global_load_lds_dwordx4 v252, s[98:99]
	s_waitcnt lgkmcnt(8)
	s_barrier
; #define LDA(dst, b, h)                                                                                    \
;   _Pragma("unroll") for (int m = 0; m < 4; ++m) _Pragma("unroll") for (int k = 0; k < 2; ++k)             \
;       dst[m][k] = *reinterpret_cast<const bf16x8*>((char*)SA(b, h) + lds_byte(wr * 64 + m * 16 + fr, k * 32 + fq * 8))
; #define LDB(dst, b, h)                                                                                    \
;   _Pragma("unroll") for (int n = 0; n < 2; ++n) _Pragma("unroll") for (int k = 0; k < 2; ++k)             \
;       dst[n][k] = *reinterpret_cast<const bf16x8*>((char*)SB(b, h) + lds_byte(wc * 32 + n * 16 + fr, k * 32 + fq * 8))
; #define WAIT_V(n) asm volatile("s_waitcnt vmcnt(" #n ")" ::: "memory")
; #define WAIT_L(n) asm volatile("s_waitcnt lgkmcnt(" #n ")" ::: "memory")
; #define BAR __builtin_amdgcn_s_barrier()
; #define SCHED __builtin_amdgcn_sched_barrier(0)
; template <int EPI> ...
;     ...
;     WAIT_L(8); BAR; WAIT_L(0); MMA(0, 0, At, B0); BAR; SCHED;
;     LDB(B1, 0, 1); STAGE(SB(0, 0), Bt, bcol, t + 2);
;     BAR; WAIT_L(0); MMA(0, 1, At, B1); BAR;
;     LDA(At, 0, 1); STAGE(SA(0, 0), A, brow, t + 2);
;     BAR; WAIT_L(0); MMA(1, 0, At, B0); BAR; SCHED;
;     STAGE(SB(0, 1), Bt, bcol + HALF, t + 2);
;     WAIT_V(6); BAR; MMA(1, 1, At, B1); BAR;
;     LDB(B0, 1, 0); SCHED; LDA(At, 1, 0); STAGE(SA(0, 1), A, brow + HALF, t + 2);
	s_waitcnt lgkmcnt(0)
	s_setprio 1
	s_waitcnt lgkmcnt(0)
	v_mfma_f32_16x16x32_bf16 v[124:127], v[186:189], v[162:165], v[124:127]
	v_mfma_f32_16x16x32_bf16 v[120:123], v[186:189], v[178:181], v[120:123]
	v_mfma_f32_16x16x32_bf16 v[116:119], v[194:197], v[162:165], v[116:119]
	v_mfma_f32_16x16x32_bf16 v[112:115], v[194:197], v[178:181], v[112:115]
	v_mfma_f32_16x16x32_bf16 v[108:111], v[202:205], v[162:165], v[108:111]
	v_mfma_f32_16x16x32_bf16 v[104:107], v[202:205], v[178:181], v[104:107]
	v_mfma_f32_16x16x32_bf16 v[100:103], v[210:213], v[162:165], v[100:103]
	v_mfma_f32_16x16x32_bf16 v[96:99], v[210:213], v[178:181], v[96:99]
	v_mfma_f32_16x16x32_bf16 v[124:127], v[190:193], v[174:177], v[124:127]
	v_mfma_f32_16x16x32_bf16 v[120:123], v[190:193], v[182:185], v[120:123]
	v_mfma_f32_16x16x32_bf16 v[116:119], v[198:201], v[174:177], v[116:119]
	v_mfma_f32_16x16x32_bf16 v[112:115], v[198:201], v[182:185], v[112:115]
	v_mfma_f32_16x16x32_bf16 v[108:111], v[206:209], v[174:177], v[108:111]
	v_mfma_f32_16x16x32_bf16 v[104:107], v[206:209], v[182:185], v[104:107]
	v_mfma_f32_16x16x32_bf16 v[100:103], v[214:217], v[174:177], v[100:103]
	v_mfma_f32_16x16x32_bf16 v[96:99], v[214:217], v[182:185], v[96:99]
	s_setprio 0
	s_barrier
	s_add_u32 s20, s10, s16
	s_addc_u32 s21, s11, s17
	ds_read_b128 v[218:221], v152
	ds_read_b128 v[222:225], v152 offset:1024
	ds_read_b128 v[226:229], v152 offset:2048
	ds_read_b128 v[230:233], v152 offset:3072
	s_add_u32 m0, s32, 0x10000
	s_add_u32 s98, s20, 0x100
	s_addc_u32 s99, s21, 0
	global_load_lds_dwordx4 v253, s[98:99]
	s_add_u32 m0, s32, 0x12000
	s_nop 0
	global_load_lds_dwordx4 v252, s[98:99]
	s_barrier
	s_waitcnt lgkmcnt(0)
	s_setprio 1
	s_waitcnt lgkmcnt(0)
	v_mfma_f32_16x16x32_bf16 v[92:95], v[186:189], v[218:221], v[92:95]
	v_mfma_f32_16x16x32_bf16 v[88:91], v[186:189], v[226:229], v[88:91]
	v_mfma_f32_16x16x32_bf16 v[84:87], v[194:197], v[218:221], v[84:87]
	v_mfma_f32_16x16x32_bf16 v[80:83], v[194:197], v[226:229], v[80:83]
	v_mfma_f32_16x16x32_bf16 v[76:79], v[202:205], v[218:221], v[76:79]
	v_mfma_f32_16x16x32_bf16 v[72:75], v[202:205], v[226:229], v[72:75]
	v_mfma_f32_16x16x32_bf16 v[68:71], v[210:213], v[218:221], v[68:71]
	v_mfma_f32_16x16x32_bf16 v[64:67], v[210:213], v[226:229], v[64:67]
	v_mfma_f32_16x16x32_bf16 v[92:95], v[190:193], v[222:225], v[92:95]
	v_mfma_f32_16x16x32_bf16 v[88:91], v[190:193], v[230:233], v[88:91]
	v_mfma_f32_16x16x32_bf16 v[84:87], v[198:201], v[222:225], v[84:87]
	v_mfma_f32_16x16x32_bf16 v[80:83], v[198:201], v[230:233], v[80:83]
	v_mfma_f32_16x16x32_bf16 v[76:79], v[206:209], v[222:225], v[76:79]
	v_mfma_f32_16x16x32_bf16 v[72:75], v[206:209], v[230:233], v[72:75]
	v_mfma_f32_16x16x32_bf16 v[68:71], v[214:217], v[222:225], v[68:71]
	v_mfma_f32_16x16x32_bf16 v[64:67], v[214:217], v[230:233], v[64:67]
	s_setprio 0
	s_barrier
	ds_read_b128 v[186:189], v135 offset:16384
	ds_read_b128 v[190:193], v135 offset:17408
	ds_read_b128 v[194:197], v156 offset:16384
	ds_read_b128 v[198:201], v156 offset:17408
	ds_read_b128 v[202:205], v157 offset:16384
	ds_read_b128 v[206:209], v157 offset:17408
	ds_read_b128 v[210:213], v158 offset:16384
	ds_read_b128 v[214:217], v158 offset:17408
	s_mov_b32 m0, s32
	s_add_u32 s98, s18, 0x100
	s_addc_u32 s99, s19, 0
	global_load_lds_dwordx4 v253, s[98:99]
	s_add_u32 m0, s32, 0x2000
	s_nop 0
	global_load_lds_dwordx4 v252, s[98:99]
	s_barrier
	s_waitcnt lgkmcnt(0)
	s_setprio 1
	s_waitcnt lgkmcnt(0)
	v_mfma_f32_16x16x32_bf16 v[60:63], v[186:189], v[162:165], v[60:63]
	v_mfma_f32_16x16x32_bf16 v[56:59], v[186:189], v[178:181], v[56:59]
	v_mfma_f32_16x16x32_bf16 v[52:55], v[194:197], v[162:165], v[52:55]
	v_mfma_f32_16x16x32_bf16 v[48:51], v[194:197], v[178:181], v[48:51]
	v_mfma_f32_16x16x32_bf16 v[44:47], v[202:205], v[162:165], v[44:47]
	v_mfma_f32_16x16x32_bf16 v[40:43], v[202:205], v[178:181], v[40:43]
	v_mfma_f32_16x16x32_bf16 v[36:39], v[210:213], v[162:165], v[36:39]
	v_mfma_f32_16x16x32_bf16 v[32:35], v[210:213], v[178:181], v[32:35]
	v_mfma_f32_16x16x32_bf16 v[60:63], v[190:193], v[174:177], v[60:63]
	v_mfma_f32_16x16x32_bf16 v[56:59], v[190:193], v[182:185], v[56:59]
	v_mfma_f32_16x16x32_bf16 v[52:55], v[198:201], v[174:177], v[52:55]
	v_mfma_f32_16x16x32_bf16 v[48:51], v[198:201], v[182:185], v[48:51]
	v_mfma_f32_16x16x32_bf16 v[44:47], v[206:209], v[174:177], v[44:47]
	v_mfma_f32_16x16x32_bf16 v[40:43], v[206:209], v[182:185], v[40:43]
	v_mfma_f32_16x16x32_bf16 v[36:39], v[214:217], v[174:177], v[36:39]
	v_mfma_f32_16x16x32_bf16 v[32:35], v[214:217], v[182:185], v[32:35]
	s_setprio 0
	s_barrier
	s_add_u32 m0, s32, 0x14000
	s_add_u32 s98, s20, 0xb0100
	s_addc_u32 s99, s21, 0
	global_load_lds_dwordx4 v253, s[98:99]
	s_add_u32 m0, s32, 0x16000
	s_nop 0
	global_load_lds_dwordx4 v252, s[98:99]
	s_waitcnt vmcnt(6)
	s_barrier
	s_setprio 1
	v_mfma_f32_16x16x32_bf16 v[28:31], v[186:189], v[218:221], v[28:31]
	v_mfma_f32_16x16x32_bf16 v[24:27], v[186:189], v[226:229], v[24:27]
	v_mfma_f32_16x16x32_bf16 v[20:23], v[194:197], v[218:221], v[20:23]
	v_mfma_f32_16x16x32_bf16 v[16:19], v[194:197], v[226:229], v[16:19]
	v_mfma_f32_16x16x32_bf16 v[12:15], v[202:205], v[218:221], v[12:15]
	v_mfma_f32_16x16x32_bf16 v[8:11], v[202:205], v[226:229], v[8:11]
	v_mfma_f32_16x16x32_bf16 v[4:7], v[210:213], v[218:221], v[4:7]
	v_mfma_f32_16x16x32_bf16 v[0:3], v[210:213], v[226:229], v[0:3]
	v_mfma_f32_16x16x32_bf16 v[28:31], v[190:193], v[222:225], v[28:31]
	v_mfma_f32_16x16x32_bf16 v[24:27], v[190:193], v[230:233], v[24:27]
	v_mfma_f32_16x16x32_bf16 v[20:23], v[198:201], v[222:225], v[20:23]
	v_mfma_f32_16x16x32_bf16 v[16:19], v[198:201], v[230:233], v[16:19]
	v_mfma_f32_16x16x32_bf16 v[12:15], v[206:209], v[222:225], v[12:15]
	v_mfma_f32_16x16x32_bf16 v[8:11], v[206:209], v[230:233], v[8:11]
	v_mfma_f32_16x16x32_bf16 v[4:7], v[214:217], v[222:225], v[4:7]
	v_mfma_f32_16x16x32_bf16 v[0:3], v[214:217], v[230:233], v[0:3]
	s_setprio 0
	s_barrier
; #define LDA(dst, b, h)                                                                                    \
;   _Pragma("unroll") for (int m = 0; m < 4; ++m) _Pragma("unroll") for (int k = 0; k < 2; ++k)             \
;       dst[m][k] = *reinterpret_cast<const bf16x8*>((char*)SA(b, h) + lds_byte(wr * 64 + m * 16 + fr, k * 32 + fq * 8))
; #define LDB(dst, b, h)                                                                                    \
;   _Pragma("unroll") for (int n = 0; n < 2; ++n) _Pragma("unroll") for (int k = 0; k < 2; ++k)             \
;       dst[n][k] = *reinterpret_cast<const bf16x8*>((char*)SB(b, h) + lds_byte(wc * 32 + n * 16 + fr, k * 32 + fq * 8))
; #define WAIT_V(n) asm volatile("s_waitcnt vmcnt(" #n ")" ::: "memory")
; #define WAIT_L(n) asm volatile("s_waitcnt lgkmcnt(" #n ")" ::: "memory")
; #define BAR __builtin_amdgcn_s_barrier()
; #define SCHED __builtin_amdgcn_sched_barrier(0)
; template <int EPI> ...
;     ...
;     LDB(B0, 1, 0); SCHED; LDA(At, 1, 0); STAGE(SA(0, 1), A, brow + HALF, t + 2);
;     WAIT_L(8); BAR; WAIT_L(0); MMA(0, 0, At, B0); BAR; SCHED;
;     LDB(B1, 1, 1); STAGE(SB(1, 0), Bt, bcol, t + 3);
;     BAR; WAIT_L(0); MMA(0, 1, At, B1); BAR;
;     LDA(At, 1, 1); STAGE(SA(1, 0), A, brow, t + 3);
;     BAR; WAIT_L(0); MMA(1, 0, At, B0); BAR; SCHED;
;     STAGE(SB(1, 1), Bt, bcol + HALF, t + 3);
;     WAIT_V(6); BAR; MMA(1, 1, At, B1); BAR;
	ds_read_b128 v[162:165], v140
	ds_read_b128 v[174:177], v140 offset:1024
	ds_read_b128 v[178:181], v140 offset:2048
	ds_read_b128 v[182:185], v140 offset:3072
	ds_read_b128 v[186:189], v135 offset:32768
	ds_read_b128 v[190:193], v135 offset:33792
	ds_read_b128 v[194:197], v156 offset:32768
	ds_read_b128 v[198:201], v156 offset:33792
	ds_read_b128 v[202:205], v157 offset:32768
	ds_read_b128 v[206:209], v157 offset:33792
	ds_read_b128 v[210:213], v158 offset:32768
	ds_read_b128 v[214:217], v158 offset:33792
	s_add_u32 m0, s32, 0x4000
	s_add_u32 s98, s18, 0xb0100
	s_addc_u32 s99, s19, 0
	global_load_lds_dwordx4 v253, s[98:99]
	s_add_u32 m0, s32, 0x6000
	s_nop 0
	global_load_lds_dwordx4 v252, s[98:99]
	s_waitcnt lgkmcnt(8)
	s_barrier
	s_waitcnt lgkmcnt(0)
	s_setprio 1
	s_waitcnt lgkmcnt(0)
	v_mfma_f32_16x16x32_bf16 v[124:127], v[186:189], v[162:165], v[124:127]
	v_mfma_f32_16x16x32_bf16 v[120:123], v[186:189], v[178:181], v[120:123]
	v_mfma_f32_16x16x32_bf16 v[116:119], v[194:197], v[162:165], v[116:119]
	v_mfma_f32_16x16x32_bf16 v[112:115], v[194:197], v[178:181], v[112:115]
	v_mfma_f32_16x16x32_bf16 v[108:111], v[202:205], v[162:165], v[108:111]
	v_mfma_f32_16x16x32_bf16 v[104:107], v[202:205], v[178:181], v[104:107]
	v_mfma_f32_16x16x32_bf16 v[100:103], v[210:213], v[162:165], v[100:103]
	v_mfma_f32_16x16x32_bf16 v[96:99], v[210:213], v[178:181], v[96:99]
	v_mfma_f32_16x16x32_bf16 v[124:127], v[190:193], v[174:177], v[124:127]
	v_mfma_f32_16x16x32_bf16 v[120:123], v[190:193], v[182:185], v[120:123]
	v_mfma_f32_16x16x32_bf16 v[116:119], v[198:201], v[174:177], v[116:119]
	v_mfma_f32_16x16x32_bf16 v[112:115], v[198:201], v[182:185], v[112:115]
	v_mfma_f32_16x16x32_bf16 v[108:111], v[206:209], v[174:177], v[108:111]
	v_mfma_f32_16x16x32_bf16 v[104:107], v[206:209], v[182:185], v[104:107]
	v_mfma_f32_16x16x32_bf16 v[100:103], v[214:217], v[174:177], v[100:103]
	v_mfma_f32_16x16x32_bf16 v[96:99], v[214:217], v[182:185], v[96:99]
	s_setprio 0
	s_barrier
	ds_read_b128 v[218:221], v137
	ds_read_b128 v[222:225], v137 offset:1024
	ds_read_b128 v[226:229], v137 offset:2048
	ds_read_b128 v[230:233], v137 offset:3072
	s_add_u32 m0, s32, 0x18000
	s_add_u32 s98, s20, 0x180
	s_addc_u32 s99, s21, 0
	global_load_lds_dwordx4 v253, s[98:99]
	s_add_u32 m0, s32, 0x1a000
	s_nop 0
	global_load_lds_dwordx4 v252, s[98:99]
	s_barrier
	s_waitcnt lgkmcnt(0)
	s_setprio 1
	s_waitcnt lgkmcnt(0)
	v_mfma_f32_16x16x32_bf16 v[92:95], v[186:189], v[218:221], v[92:95]
	v_mfma_f32_16x16x32_bf16 v[88:91], v[186:189], v[226:229], v[88:91]
	v_mfma_f32_16x16x32_bf16 v[84:87], v[194:197], v[218:221], v[84:87]
	v_mfma_f32_16x16x32_bf16 v[80:83], v[194:197], v[226:229], v[80:83]
	v_mfma_f32_16x16x32_bf16 v[76:79], v[202:205], v[218:221], v[76:79]
	v_mfma_f32_16x16x32_bf16 v[72:75], v[202:205], v[226:229], v[72:75]
	v_mfma_f32_16x16x32_bf16 v[68:71], v[210:213], v[218:221], v[68:71]
	v_mfma_f32_16x16x32_bf16 v[64:67], v[210:213], v[226:229], v[64:67]
	v_mfma_f32_16x16x32_bf16 v[92:95], v[190:193], v[222:225], v[92:95]
	v_mfma_f32_16x16x32_bf16 v[88:91], v[190:193], v[230:233], v[88:91]
	v_mfma_f32_16x16x32_bf16 v[84:87], v[198:201], v[222:225], v[84:87]
	v_mfma_f32_16x16x32_bf16 v[80:83], v[198:201], v[230:233], v[80:83]
	v_mfma_f32_16x16x32_bf16 v[76:79], v[206:209], v[222:225], v[76:79]
	v_mfma_f32_16x16x32_bf16 v[72:75], v[206:209], v[230:233], v[72:75]
	v_mfma_f32_16x16x32_bf16 v[68:71], v[214:217], v[222:225], v[68:71]
	v_mfma_f32_16x16x32_bf16 v[64:67], v[214:217], v[230:233], v[64:67]
	s_setprio 0
	s_barrier
	ds_read_b128 v[186:189], v135 offset:49152
	ds_read_b128 v[190:193], v135 offset:50176
	ds_read_b128 v[194:197], v156 offset:49152
	ds_read_b128 v[198:201], v156 offset:50176
	ds_read_b128 v[202:205], v157 offset:49152
	ds_read_b128 v[206:209], v157 offset:50176
	ds_read_b128 v[210:213], v158 offset:49152
	ds_read_b128 v[214:217], v158 offset:50176
	s_add_u32 m0, s32, 0x8000
	s_add_u32 s98, s18, 0x180
	s_addc_u32 s99, s19, 0
	global_load_lds_dwordx4 v253, s[98:99]
	s_nop 0
	s_add_u32 m0, s32, 0xa000
	s_nop 0
	global_load_lds_dwordx4 v252, s[98:99]
	s_barrier
	s_waitcnt lgkmcnt(0)
	s_setprio 1
	s_waitcnt lgkmcnt(0)
	v_mfma_f32_16x16x32_bf16 v[60:63], v[186:189], v[162:165], v[60:63]
	v_mfma_f32_16x16x32_bf16 v[56:59], v[186:189], v[178:181], v[56:59]
	v_mfma_f32_16x16x32_bf16 v[52:55], v[194:197], v[162:165], v[52:55]
	v_mfma_f32_16x16x32_bf16 v[48:51], v[194:197], v[178:181], v[48:51]
	v_mfma_f32_16x16x32_bf16 v[44:47], v[202:205], v[162:165], v[44:47]
	v_mfma_f32_16x16x32_bf16 v[40:43], v[202:205], v[178:181], v[40:43]
	v_mfma_f32_16x16x32_bf16 v[36:39], v[210:213], v[162:165], v[36:39]
	v_mfma_f32_16x16x32_bf16 v[32:35], v[210:213], v[178:181], v[32:35]
	v_mfma_f32_16x16x32_bf16 v[60:63], v[190:193], v[174:177], v[60:63]
	v_mfma_f32_16x16x32_bf16 v[56:59], v[190:193], v[182:185], v[56:59]
	v_mfma_f32_16x16x32_bf16 v[52:55], v[198:201], v[174:177], v[52:55]
	v_mfma_f32_16x16x32_bf16 v[48:51], v[198:201], v[182:185], v[48:51]
	v_mfma_f32_16x16x32_bf16 v[44:47], v[206:209], v[174:177], v[44:47]
	v_mfma_f32_16x16x32_bf16 v[40:43], v[206:209], v[182:185], v[40:43]
	v_mfma_f32_16x16x32_bf16 v[36:39], v[214:217], v[174:177], v[36:39]
	v_mfma_f32_16x16x32_bf16 v[32:35], v[214:217], v[182:185], v[32:35]
	s_setprio 0
	s_barrier
	s_add_u32 m0, s32, 0x1c000
	s_add_u32 s98, s20, 0xb0180
	s_addc_u32 s99, s21, 0
	global_load_lds_dwordx4 v253, s[98:99]
	s_add_u32 m0, s32, 0x1e000
	s_nop 0
	global_load_lds_dwordx4 v252, s[98:99]
	s_waitcnt vmcnt(6)
	s_barrier
; #define LDA(dst, b, h)                                                                                    \
;   _Pragma("unroll") for (int m = 0; m < 4; ++m) _Pragma("unroll") for (int k = 0; k < 2; ++k)             \
;       dst[m][k] = *reinterpret_cast<const bf16x8*>((char*)SA(b, h) + lds_byte(wr * 64 + m * 16 + fr, k * 32 + fq * 8))
; #define LDB(dst, b, h)                                                                                    \
;   _Pragma("unroll") for (int n = 0; n < 2; ++n) _Pragma("unroll") for (int k = 0; k < 2; ++k)             \
;       dst[n][k] = *reinterpret_cast<const bf16x8*>((char*)SB(b, h) + lds_byte(wc * 32 + n * 16 + fr, k * 32 + fq * 8))
; #define WAIT_V(n) asm volatile("s_waitcnt vmcnt(" #n ")" ::: "memory")
; #define WAIT_L(n) asm volatile("s_waitcnt lgkmcnt(" #n ")" ::: "memory")
; #define BAR __builtin_amdgcn_s_barrier()
; template <int EPI> ...
;     ...
;     WAIT_V(6); BAR; MMA(1, 1, At, B1); BAR;
;   }
;   {
;     LDB(B0, 0, 0); LDA(At, 0, 0); STAGE(SA(1, 1), A, brow + HALF, nt - 1);
;     BAR; WAIT_L(0); MMA(0, 0, At, B0); BAR;
;     LDB(B1, 0, 1); BAR; WAIT_L(0); MMA(0, 1, At, B1); BAR;
;     LDA(At, 0, 1); WAIT_V(4); BAR; WAIT_L(0); MMA(1, 0, At, B0); MMA(1, 1, At, B1); BAR;
;   }
;   {
;     LDB(B0, 1, 0); LDA(At, 1, 0); WAIT_V(2); BAR; WAIT_L(0); MMA(0, 0, At, B0); BAR;
	s_setprio 1
	v_mfma_f32_16x16x32_bf16 v[28:31], v[186:189], v[218:221], v[28:31]
	v_mfma_f32_16x16x32_bf16 v[24:27], v[186:189], v[226:229], v[24:27]
	v_mfma_f32_16x16x32_bf16 v[20:23], v[194:197], v[218:221], v[20:23]
	v_mfma_f32_16x16x32_bf16 v[16:19], v[194:197], v[226:229], v[16:19]
	v_mfma_f32_16x16x32_bf16 v[12:15], v[202:205], v[218:221], v[12:15]
	v_mfma_f32_16x16x32_bf16 v[8:11], v[202:205], v[226:229], v[8:11]
	v_mfma_f32_16x16x32_bf16 v[4:7], v[210:213], v[218:221], v[4:7]
	v_mfma_f32_16x16x32_bf16 v[0:3], v[210:213], v[226:229], v[0:3]
	v_mfma_f32_16x16x32_bf16 v[28:31], v[190:193], v[222:225], v[28:31]
	v_mfma_f32_16x16x32_bf16 v[24:27], v[190:193], v[230:233], v[24:27]
	v_mfma_f32_16x16x32_bf16 v[20:23], v[198:201], v[222:225], v[20:23]
	v_mfma_f32_16x16x32_bf16 v[16:19], v[198:201], v[230:233], v[16:19]
	v_mfma_f32_16x16x32_bf16 v[12:15], v[206:209], v[222:225], v[12:15]
	v_mfma_f32_16x16x32_bf16 v[8:11], v[206:209], v[230:233], v[8:11]
	v_mfma_f32_16x16x32_bf16 v[4:7], v[214:217], v[222:225], v[4:7]
	v_mfma_f32_16x16x32_bf16 v[0:3], v[214:217], v[230:233], v[0:3]
	s_setprio 0
	s_add_i32 s70, s70, 2
	s_add_u32 s16, s16, 0x100
	s_addc_u32 s17, s17, 0
	s_cmp_lt_u32 s70, 40
	s_barrier
	s_cbranch_scc1 .LBB0_1779
	s_add_u32 s10, s14, 0x1580
	ds_read_b128 v[142:145], v155
	ds_read_b128 v[162:165], v155 offset:1024
	ds_read_b128 v[174:177], v155 offset:2048
	ds_read_b128 v[178:181], v155 offset:3072
	ds_read_b128 v[182:185], v135
	ds_read_b128 v[186:189], v135 offset:1024
	ds_read_b128 v[190:193], v156
	ds_read_b128 v[194:197], v156 offset:1024
	ds_read_b128 v[198:201], v157
	ds_read_b128 v[202:205], v157 offset:1024
	ds_read_b128 v[206:209], v158
	ds_read_b128 v[210:213], v158 offset:1024
	s_addc_u32 s11, s15, 0
	v_mov_b32_e32 v129, v149
	v_readfirstlane_b32 s12, v159
	v_lshl_add_u64 v[128:129], v[128:129], 1, s[10:11]
	s_mov_b32 m0, s12
	v_mov_b32_e32 v131, v149
	global_load_lds_dwordx4 v[128:129], off
	s_nop 0
	v_lshl_add_u64 v[128:129], v[130:131], 1, s[10:11]
	v_readfirstlane_b32 s10, v160
	s_mov_b32 m0, s10
	s_nop 0
	global_load_lds_dwordx4 v[128:129], off
	s_barrier
	s_waitcnt lgkmcnt(0)
	s_setprio 1
	s_waitcnt lgkmcnt(0)
	v_mfma_f32_16x16x32_bf16 v[124:127], v[182:185], v[142:145], v[124:127]
	v_mfma_f32_16x16x32_bf16 v[120:123], v[182:185], v[174:177], v[120:123]
	v_mfma_f32_16x16x32_bf16 v[116:119], v[190:193], v[142:145], v[116:119]
	v_mfma_f32_16x16x32_bf16 v[112:115], v[190:193], v[174:177], v[112:115]
	v_mfma_f32_16x16x32_bf16 v[108:111], v[198:201], v[142:145], v[108:111]
	v_mfma_f32_16x16x32_bf16 v[104:107], v[198:201], v[174:177], v[104:107]
	v_mfma_f32_16x16x32_bf16 v[96:99], v[206:209], v[174:177], v[96:99]
	v_mfma_f32_16x16x32_bf16 v[124:127], v[186:189], v[162:165], v[124:127]
	v_mfma_f32_16x16x32_bf16 v[120:123], v[186:189], v[178:181], v[120:123]
	v_mfma_f32_16x16x32_bf16 v[116:119], v[194:197], v[162:165], v[116:119]
	v_mfma_f32_16x16x32_bf16 v[112:115], v[194:197], v[178:181], v[112:115]
	v_mfma_f32_16x16x32_bf16 v[108:111], v[202:205], v[162:165], v[108:111]
	v_mfma_f32_16x16x32_bf16 v[104:107], v[202:205], v[178:181], v[104:107]
	v_mfma_f32_16x16x32_bf16 v[100:103], v[206:209], v[142:145], v[100:103]
	v_mfma_f32_16x16x32_bf16 v[96:99], v[210:213], v[178:181], v[96:99]
	v_mfma_f32_16x16x32_bf16 v[128:131], v[210:213], v[162:165], v[100:103]
	s_setprio 0
	s_barrier
	s_nop 3
	ds_read_b128 v[100:103], v152
	ds_read_b128 v[214:217], v152 offset:1024
	ds_read_b128 v[218:221], v152 offset:2048
	ds_read_b128 v[152:155], v152 offset:3072
	s_barrier
	s_waitcnt lgkmcnt(0)
	s_setprio 1
	s_waitcnt lgkmcnt(0)
	v_mfma_f32_16x16x32_bf16 v[88:91], v[182:185], v[218:221], v[88:91]
	v_mfma_f32_16x16x32_bf16 v[92:95], v[182:185], v[100:103], v[92:95]
	v_mfma_f32_16x16x32_bf16 v[88:91], v[186:189], v[152:155], v[88:91]
	v_mfma_f32_16x16x32_bf16 v[84:87], v[190:193], v[100:103], v[84:87]
	v_mfma_f32_16x16x32_bf16 v[80:83], v[190:193], v[218:221], v[80:83]
	v_mfma_f32_16x16x32_bf16 v[76:79], v[198:201], v[100:103], v[76:79]
	v_mfma_f32_16x16x32_bf16 v[72:75], v[198:201], v[218:221], v[72:75]
	v_mfma_f32_16x16x32_bf16 v[68:71], v[206:209], v[100:103], v[68:71]
	v_mfma_f32_16x16x32_bf16 v[64:67], v[206:209], v[218:221], v[64:67]
	v_mfma_f32_16x16x32_bf16 v[222:225], v[186:189], v[214:217], v[92:95]
	v_mfma_f32_16x16x32_bf16 v[182:185], v[194:197], v[214:217], v[84:87]
	v_mfma_f32_16x16x32_bf16 v[186:189], v[194:197], v[152:155], v[80:83]
	v_mfma_f32_16x16x32_bf16 v[190:193], v[202:205], v[214:217], v[76:79]
	v_mfma_f32_16x16x32_bf16 v[194:197], v[202:205], v[152:155], v[72:75]
	v_mfma_f32_16x16x32_bf16 v[198:201], v[210:213], v[214:217], v[68:71]
	v_mfma_f32_16x16x32_bf16 v[202:205], v[210:213], v[152:155], v[64:67]
	s_setprio 0
	s_barrier
	s_nop 0
	ds_read_b128 v[64:67], v135 offset:16384
	ds_read_b128 v[68:71], v135 offset:17408
	ds_read_b128 v[72:75], v156 offset:16384
	ds_read_b128 v[76:79], v156 offset:17408
	ds_read_b128 v[80:83], v157 offset:16384
	ds_read_b128 v[84:87], v157 offset:17408
	ds_read_b128 v[92:95], v158 offset:16384
	ds_read_b128 v[206:209], v158 offset:17408
	s_waitcnt vmcnt(4)
	s_barrier
; #define LDA(dst, b, h)                                                                                    \
;   _Pragma("unroll") for (int m = 0; m < 4; ++m) _Pragma("unroll") for (int k = 0; k < 2; ++k)             \
;       dst[m][k] = *reinterpret_cast<const bf16x8*>((char*)SA(b, h) + lds_byte(wr * 64 + m * 16 + fr, k * 32 + fq * 8))
; #define LDB(dst, b, h)                                                                                    \
;   _Pragma("unroll") for (int n = 0; n < 2; ++n) _Pragma("unroll") for (int k = 0; k < 2; ++k)             \
;       dst[n][k] = *reinterpret_cast<const bf16x8*>((char*)SB(b, h) + lds_byte(wc * 32 + n * 16 + fr, k * 32 + fq * 8))
; #define WAIT_V(n) asm volatile("s_waitcnt vmcnt(" #n ")" ::: "memory")
; #define WAIT_L(n) asm volatile("s_waitcnt lgkmcnt(" #n ")" ::: "memory")
; #define BAR __builtin_amdgcn_s_barrier()
; template <int EPI> ...
;     ...
;     LDA(At, 0, 1); WAIT_V(4); BAR; WAIT_L(0); MMA(1, 0, At, B0); MMA(1, 1, At, B1); BAR;
;   }
;   {
;     LDB(B0, 1, 0); LDA(At, 1, 0); WAIT_V(2); BAR; WAIT_L(0); MMA(0, 0, At, B0); BAR;
	s_waitcnt lgkmcnt(0)
	s_setprio 1
	s_waitcnt lgkmcnt(0)
	v_mfma_f32_16x16x32_bf16 v[60:63], v[64:67], v[142:145], v[60:63]
	v_mfma_f32_16x16x32_bf16 v[56:59], v[64:67], v[174:177], v[56:59]
	v_mfma_f32_16x16x32_bf16 v[52:55], v[72:75], v[142:145], v[52:55]
	v_mfma_f32_16x16x32_bf16 v[48:51], v[72:75], v[174:177], v[48:51]
	v_mfma_f32_16x16x32_bf16 v[44:47], v[80:83], v[142:145], v[44:47]
	v_mfma_f32_16x16x32_bf16 v[40:43], v[80:83], v[174:177], v[40:43]
	v_mfma_f32_16x16x32_bf16 v[36:39], v[92:95], v[142:145], v[36:39]
	v_mfma_f32_16x16x32_bf16 v[32:35], v[92:95], v[174:177], v[32:35]
	v_mfma_f32_16x16x32_bf16 v[60:63], v[68:71], v[162:165], v[60:63]
	v_mfma_f32_16x16x32_bf16 v[56:59], v[68:71], v[178:181], v[56:59]
	v_mfma_f32_16x16x32_bf16 v[52:55], v[76:79], v[162:165], v[52:55]
	v_mfma_f32_16x16x32_bf16 v[48:51], v[76:79], v[178:181], v[48:51]
	v_mfma_f32_16x16x32_bf16 v[44:47], v[84:87], v[162:165], v[44:47]
	v_mfma_f32_16x16x32_bf16 v[40:43], v[84:87], v[178:181], v[40:43]
	v_mfma_f32_16x16x32_bf16 v[36:39], v[206:209], v[162:165], v[36:39]
	v_mfma_f32_16x16x32_bf16 v[32:35], v[206:209], v[178:181], v[32:35]
	s_setprio 0
	s_setprio 1
	v_mfma_f32_16x16x32_bf16 v[28:31], v[64:67], v[100:103], v[28:31]
	v_mfma_f32_16x16x32_bf16 v[24:27], v[64:67], v[218:221], v[24:27]
	v_mfma_f32_16x16x32_bf16 v[20:23], v[72:75], v[100:103], v[20:23]
	v_mfma_f32_16x16x32_bf16 v[16:19], v[72:75], v[218:221], v[16:19]
	v_mfma_f32_16x16x32_bf16 v[12:15], v[80:83], v[100:103], v[12:15]
	v_mfma_f32_16x16x32_bf16 v[8:11], v[80:83], v[218:221], v[8:11]
	v_mfma_f32_16x16x32_bf16 v[4:7], v[92:95], v[100:103], v[4:7]
	v_mfma_f32_16x16x32_bf16 v[0:3], v[92:95], v[218:221], v[0:3]
	v_mfma_f32_16x16x32_bf16 v[142:145], v[68:71], v[214:217], v[28:31]
	v_mfma_f32_16x16x32_bf16 v[160:163], v[68:71], v[152:155], v[24:27]
	v_mfma_f32_16x16x32_bf16 v[164:167], v[76:79], v[214:217], v[20:23]
	v_mfma_f32_16x16x32_bf16 v[174:177], v[76:79], v[152:155], v[16:19]
	v_mfma_f32_16x16x32_bf16 v[178:181], v[84:87], v[214:217], v[12:15]
	v_mfma_f32_16x16x32_bf16 v[210:213], v[84:87], v[152:155], v[8:11]
	v_mfma_f32_16x16x32_bf16 v[214:217], v[206:209], v[214:217], v[4:7]
	v_mfma_f32_16x16x32_bf16 v[152:155], v[206:209], v[152:155], v[0:3]
	s_setprio 0
	s_barrier
	s_nop 0
	ds_read_b128 v[0:3], v140
	ds_read_b128 v[4:7], v140 offset:1024
	ds_read_b128 v[206:209], v140 offset:2048
	ds_read_b128 v[138:141], v140 offset:3072
	ds_read_b128 v[8:11], v135 offset:32768
	ds_read_b128 v[12:15], v135 offset:33792
	ds_read_b128 v[16:19], v156 offset:32768
	ds_read_b128 v[20:23], v156 offset:33792
	ds_read_b128 v[24:27], v157 offset:32768
	ds_read_b128 v[28:31], v157 offset:33792
	ds_read_b128 v[218:221], v158 offset:32768
	ds_read_b128 v[226:229], v158 offset:33792
	s_waitcnt vmcnt(2)
	s_barrier
	s_waitcnt lgkmcnt(0)
	s_setprio 1
	s_waitcnt lgkmcnt(0)
	v_mfma_f32_16x16x32_bf16 v[64:67], v[8:11], v[0:3], v[124:127]
	v_mfma_f32_16x16x32_bf16 v[92:95], v[12:15], v[4:7], v[64:67]
	v_mfma_f32_16x16x32_bf16 v[64:67], v[8:11], v[206:209], v[120:123]
	v_mfma_f32_16x16x32_bf16 v[100:103], v[12:15], v[138:141], v[64:67]
	v_mfma_f32_16x16x32_bf16 v[64:67], v[16:19], v[0:3], v[116:119]
	v_mfma_f32_16x16x32_bf16 v[80:83], v[20:23], v[4:7], v[64:67]
	v_mfma_f32_16x16x32_bf16 v[64:67], v[16:19], v[206:209], v[112:115]
	v_mfma_f32_16x16x32_bf16 v[84:87], v[20:23], v[138:141], v[64:67]
	v_mfma_f32_16x16x32_bf16 v[64:67], v[24:27], v[0:3], v[108:111]
	v_mfma_f32_16x16x32_bf16 v[72:75], v[28:31], v[4:7], v[64:67]
	v_mfma_f32_16x16x32_bf16 v[64:67], v[24:27], v[206:209], v[104:107]
	v_mfma_f32_16x16x32_bf16 v[76:79], v[28:31], v[138:141], v[64:67]
	v_mfma_f32_16x16x32_bf16 v[64:67], v[218:221], v[0:3], v[128:131]
	v_mfma_f32_16x16x32_bf16 v[68:71], v[218:221], v[206:209], v[96:99]
	v_mfma_f32_16x16x32_bf16 v[64:67], v[226:229], v[4:7], v[64:67]
	v_mfma_f32_16x16x32_bf16 v[68:71], v[226:229], v[138:141], v[68:71]
	s_setprio 0
	s_barrier
; #define LDA(dst, b, h)                                                                                    \
;   _Pragma("unroll") for (int m = 0; m < 4; ++m) _Pragma("unroll") for (int k = 0; k < 2; ++k)             \
;       dst[m][k] = *reinterpret_cast<const bf16x8*>((char*)SA(b, h) + lds_byte(wr * 64 + m * 16 + fr, k * 32 + fq * 8))
; #define LDB(dst, b, h)                                                                                    \
;   _Pragma("unroll") for (int n = 0; n < 2; ++n) _Pragma("unroll") for (int k = 0; k < 2; ++k)             \
;       dst[n][k] = *reinterpret_cast<const bf16x8*>((char*)SB(b, h) + lds_byte(wc * 32 + n * 16 + fr, k * 32 + fq * 8))
; #define WAIT_V(n) asm volatile("s_waitcnt vmcnt(" #n ")" ::: "memory")
; #define WAIT_L(n) asm volatile("s_waitcnt lgkmcnt(" #n ")" ::: "memory")
; #define BAR __builtin_amdgcn_s_barrier()
; template <int EPI> ...
;     ...
;     LDB(B1, 1, 1); WAIT_V(0); BAR; WAIT_L(0); MMA(0, 1, At, B1); BAR;
;     LDA(At, 1, 1); BAR; WAIT_L(0); MMA(1, 0, At, B0); MMA(1, 1, At, B1); BAR;
;   }
;   if (wr == 0) BAR;
	ds_read_b128 v[128:131], v137
	ds_read_b128 v[230:233], v137 offset:1024
	ds_read_b128 v[234:237], v137 offset:2048
	ds_read_b128 v[238:241], v137 offset:3072
	s_waitcnt vmcnt(0)
	s_barrier
	s_waitcnt lgkmcnt(0)
	s_setprio 1
	s_waitcnt lgkmcnt(0)
	v_mfma_f32_16x16x32_bf16 v[96:99], v[8:11], v[128:131], v[222:225]
	v_mfma_f32_16x16x32_bf16 v[8:11], v[8:11], v[234:237], v[88:91]
	v_mfma_f32_16x16x32_bf16 v[124:127], v[12:15], v[238:241], v[8:11]
	v_mfma_f32_16x16x32_bf16 v[8:11], v[16:19], v[128:131], v[182:185]
	v_mfma_f32_16x16x32_bf16 v[112:115], v[20:23], v[230:233], v[8:11]
	v_mfma_f32_16x16x32_bf16 v[8:11], v[16:19], v[234:237], v[186:189]
	v_mfma_f32_16x16x32_bf16 v[116:119], v[20:23], v[238:241], v[8:11]
	v_mfma_f32_16x16x32_bf16 v[8:11], v[24:27], v[128:131], v[190:193]
	v_mfma_f32_16x16x32_bf16 v[104:107], v[28:31], v[230:233], v[8:11]
	v_mfma_f32_16x16x32_bf16 v[8:11], v[24:27], v[234:237], v[194:197]
	v_mfma_f32_16x16x32_bf16 v[108:111], v[28:31], v[238:241], v[8:11]
	v_mfma_f32_16x16x32_bf16 v[8:11], v[218:221], v[128:131], v[198:201]
	v_mfma_f32_16x16x32_bf16 v[88:91], v[226:229], v[230:233], v[8:11]
	v_mfma_f32_16x16x32_bf16 v[8:11], v[218:221], v[234:237], v[202:205]
	v_mfma_f32_16x16x32_bf16 v[120:123], v[12:15], v[230:233], v[96:99]
	v_mfma_f32_16x16x32_bf16 v[96:99], v[226:229], v[238:241], v[8:11]
	s_setprio 0
	s_barrier
	ds_read_b128 v[182:185], v135 offset:49152
	ds_read_b128 v[134:137], v135 offset:50176
	ds_read_b128 v[186:189], v156 offset:49152
	ds_read_b128 v[190:193], v156 offset:50176
	ds_read_b128 v[194:197], v157 offset:49152
	ds_read_b128 v[198:201], v157 offset:50176
	ds_read_b128 v[202:205], v158 offset:49152
	ds_read_b128 v[156:159], v158 offset:50176
	s_barrier
	s_waitcnt lgkmcnt(0)
	s_setprio 1
	s_waitcnt lgkmcnt(0)
	v_mfma_f32_16x16x32_bf16 v[8:11], v[182:185], v[0:3], v[60:63]
	v_mfma_f32_16x16x32_bf16 v[24:27], v[134:137], v[4:7], v[8:11]
	v_mfma_f32_16x16x32_bf16 v[8:11], v[182:185], v[206:209], v[56:59]
	v_mfma_f32_16x16x32_bf16 v[28:31], v[134:137], v[138:141], v[8:11]
	v_mfma_f32_16x16x32_bf16 v[8:11], v[186:189], v[0:3], v[52:55]
	v_mfma_f32_16x16x32_bf16 v[16:19], v[190:193], v[4:7], v[8:11]
	v_mfma_f32_16x16x32_bf16 v[8:11], v[186:189], v[206:209], v[48:51]
	v_mfma_f32_16x16x32_bf16 v[20:23], v[190:193], v[138:141], v[8:11]
	v_mfma_f32_16x16x32_bf16 v[8:11], v[194:197], v[0:3], v[44:47]
	v_mfma_f32_16x16x32_bf16 v[0:3], v[202:205], v[0:3], v[36:39]
	v_mfma_f32_16x16x32_bf16 v[8:11], v[198:201], v[4:7], v[8:11]
	v_mfma_f32_16x16x32_bf16 v[12:15], v[194:197], v[206:209], v[40:43]
	v_mfma_f32_16x16x32_bf16 v[0:3], v[156:159], v[4:7], v[0:3]
	v_mfma_f32_16x16x32_bf16 v[4:7], v[202:205], v[206:209], v[32:35]
	v_mfma_f32_16x16x32_bf16 v[12:15], v[198:201], v[138:141], v[12:15]
	v_mfma_f32_16x16x32_bf16 v[4:7], v[156:159], v[138:141], v[4:7]
	s_setprio 0
	s_setprio 1
	v_mfma_f32_16x16x32_bf16 v[32:35], v[182:185], v[128:131], v[142:145]
	v_mfma_f32_16x16x32_bf16 v[56:59], v[134:137], v[230:233], v[32:35]
	v_mfma_f32_16x16x32_bf16 v[32:35], v[182:185], v[234:237], v[160:163]
	v_mfma_f32_16x16x32_bf16 v[60:63], v[134:137], v[238:241], v[32:35]
	v_mfma_f32_16x16x32_bf16 v[32:35], v[186:189], v[128:131], v[164:167]
	v_mfma_f32_16x16x32_bf16 v[48:51], v[190:193], v[230:233], v[32:35]
	v_mfma_f32_16x16x32_bf16 v[32:35], v[186:189], v[234:237], v[174:177]
	v_mfma_f32_16x16x32_bf16 v[52:55], v[190:193], v[238:241], v[32:35]
	v_mfma_f32_16x16x32_bf16 v[32:35], v[194:197], v[128:131], v[178:181]
	v_mfma_f32_16x16x32_bf16 v[40:43], v[198:201], v[230:233], v[32:35]
	v_mfma_f32_16x16x32_bf16 v[32:35], v[194:197], v[234:237], v[210:213]
	v_mfma_f32_16x16x32_bf16 v[44:47], v[198:201], v[238:241], v[32:35]
	v_mfma_f32_16x16x32_bf16 v[32:35], v[202:205], v[128:131], v[214:217]
	v_mfma_f32_16x16x32_bf16 v[36:39], v[202:205], v[234:237], v[152:155]
	v_mfma_f32_16x16x32_bf16 v[32:35], v[156:159], v[230:233], v[32:35]
	v_mfma_f32_16x16x32_bf16 v[36:39], v[156:159], v[238:241], v[36:39]
	s_setprio 0
	s_cmpk_gt_u32 s30, 0xff
	s_barrier
	s_cbranch_scc1 .LBB0_1782
	s_barrier

; DEVI f32x4 ozero() { float z = 0.f; asm volatile("" : "+v"(z)); return f32x4{z, z, z, z}; }
; #define LDA(dst, b, h)                                                                                    \
;   _Pragma("unroll") for (int m = 0; m < 4; ++m) _Pragma("unroll") for (int k = 0; k < 2; ++k)             \
;       dst[m][k] = *reinterpret_cast<const bf16x8*>((char*)SA(b, h) + lds_byte(wr * 64 + m * 16 + fr, k * 32 + fq * 8))
; #define LDB(dst, b, h)                                                                                    \
;   _Pragma("unroll") for (int n = 0; n < 2; ++n) _Pragma("unroll") for (int k = 0; k < 2; ++k)             \
;       dst[n][k] = *reinterpret_cast<const bf16x8*>((char*)SB(b, h) + lds_byte(wc * 32 + n * 16 + fr, k * 32 + fq * 8))
; #define WAIT_V(n) asm volatile("s_waitcnt vmcnt(" #n ")" ::: "memory")
; #define WAIT_L(n) asm volatile("s_waitcnt lgkmcnt(" #n ")" ::: "memory")
; #define BAR __builtin_amdgcn_s_barrier()
; #define SCHED __builtin_amdgcn_sched_barrier(0)
; template <int EPI> ...
;     ...
;   const int brow = m0, bcol = n0;
;   const int wid = __builtin_amdgcn_readfirstlane(tid >> 6), lane = tid & 63, wr = wid >> 2, wc = wid & 3, fr = lane & 15, fq = lane >> 4;
;   f32x4 acc[2][2][4][2];
;   {
;     const f32x4 zq = ozero();
; #pragma unroll
;     for (int a_ = 0; a_ < 2; ++a_)
; #pragma unroll
;       for (int b_ = 0; b_ < 2; ++b_)
; #pragma unroll
;         for (int m = 0; m < 4; ++m) { acc[a_][b_][m][0] = zq; acc[a_][b_][m][1] = zq; }
;   }
;   bf16x8 At[4][2], B0[2][2], B1[2][2];
;   const int nt = K / BK;
;     ...
;   if (first) {
;     WAIT_V(0);
;     ISSUE_PRO(brow, bcol);
;   }
;   if (wr == 1) BAR;
;   WAIT_V(10); BAR;
;   WAIT_V(6); BAR;
;   for (int t = 0; t < nt - 2; t += 2) {
;     LDB(B0, 0, 0); SCHED; LDA(At, 0, 0); STAGE(SA(1, 1), A, brow + HALF, t + 1);
;     WAIT_L(8); BAR; WAIT_L(0); MMA(0, 0, At, B0); BAR; SCHED;
.LBB0_1882:
	v_and_b32_e32 v143, 15, v132
	v_and_b32_e32 v1, 48, v132
	v_lshlrev_b32_e32 v2, 6, v143
	v_lshlrev_b32_e32 v4, 2, v132
	v_or_b32_e32 v3, v2, v1
	v_and_b32_e32 v4, 32, v4
	s_mov_b32 s30, 0x10000
	v_bitop3_b32 v5, v3, s30, v4 bitop3:0xde
	s_mov_b32 s30, 0x14000
	s_ashr_i32 s5, s64, 6
	v_bitop3_b32 v6, v3, s30, v4 bitop3:0xde
	s_mov_b32 s30, 0x18000
	s_and_b32 s65, s5, 3
	s_waitcnt vmcnt(10)
	s_barrier
	s_waitcnt vmcnt(6)
	v_bitop3_b32 v7, v3, s30, v4 bitop3:0xde
	s_mov_b32 s30, 0x1c000
	v_lshlrev_b32_e32 v8, 6, v132
	s_lshl_b32 s35, s65, 12
	v_bitop3_b32 v2, v2, v4, v1 bitop3:0x36
	s_lshl_b32 s66, s34, 6
	v_bitop3_b32 v3, v3, s30, v4 bitop3:0xde
	s_lshl_b32 s34, s34, 13
	v_and_b32_e32 v8, 0x3c0, v8
	v_bitop3_b32 v154, v8, v4, v1 bitop3:0x36
	s_or_b32 s67, s34, 0x800
	s_or_b32 s68, s34, 0x1000
	s_or_b32 s69, s34, 0x1800
	s_mov_b32 s70, -2
	s_mov_b64 s[30:31], 0
	v_add_u32_e32 v155, s35, v5
	v_add_u32_e32 v134, s34, v2
	v_add_u32_e32 v152, s35, v6
	v_add_u32_e32 v139, s35, v7
	v_add_u32_e32 v136, s35, v3
	v_mov_b32_e32 v1, v0
	v_mov_b32_e32 v2, v0
	v_mov_b32_e32 v3, v0
	v_mov_b32_e32 v4, v0
	v_mov_b32_e32 v5, v0
	v_mov_b32_e32 v6, v0
	v_mov_b32_e32 v7, v0
	v_mov_b32_e32 v8, v0
	v_mov_b32_e32 v9, v0
	v_mov_b32_e32 v10, v0
	v_mov_b32_e32 v11, v0
	v_mov_b32_e32 v12, v0
	v_mov_b32_e32 v13, v0
	v_mov_b32_e32 v14, v0
	v_mov_b32_e32 v15, v0
	v_mov_b32_e32 v16, v0
	v_mov_b32_e32 v17, v0
	v_mov_b32_e32 v18, v0
	v_mov_b32_e32 v19, v0
	v_mov_b32_e32 v20, v0
	v_mov_b32_e32 v21, v0
	v_mov_b32_e32 v22, v0
	v_mov_b32_e32 v23, v0
	v_mov_b32_e32 v24, v0
	v_mov_b32_e32 v25, v0
	v_mov_b32_e32 v26, v0
	v_mov_b32_e32 v27, v0
	v_mov_b32_e32 v28, v0
	v_mov_b32_e32 v29, v0
	v_mov_b32_e32 v30, v0
	v_mov_b32_e32 v31, v0
	v_mov_b32_e32 v32, v0
	v_mov_b32_e32 v33, v0
	v_mov_b32_e32 v34, v0
	v_mov_b32_e32 v35, v0
	v_mov_b32_e32 v36, v0
	v_mov_b32_e32 v37, v0
	v_mov_b32_e32 v38, v0
	v_mov_b32_e32 v39, v0
	v_mov_b32_e32 v40, v0
	v_mov_b32_e32 v41, v0
	v_mov_b32_e32 v42, v0
	v_mov_b32_e32 v43, v0
	v_mov_b32_e32 v44, v0
	v_mov_b32_e32 v45, v0
	v_mov_b32_e32 v46, v0
	v_mov_b32_e32 v47, v0
	v_mov_b32_e32 v48, v0
	v_mov_b32_e32 v49, v0
	v_mov_b32_e32 v50, v0
	v_mov_b32_e32 v51, v0
	v_mov_b32_e32 v52, v0
	v_mov_b32_e32 v53, v0
	v_mov_b32_e32 v54, v0
	v_mov_b32_e32 v55, v0
	v_mov_b32_e32 v56, v0
	v_mov_b32_e32 v57, v0
	v_mov_b32_e32 v58, v0
	v_mov_b32_e32 v59, v0
	v_mov_b32_e32 v60, v0
	v_mov_b32_e32 v61, v0
	v_mov_b32_e32 v62, v0
	v_mov_b32_e32 v63, v0
	v_mov_b32_e32 v64, v0
	v_mov_b32_e32 v65, v0
	v_mov_b32_e32 v66, v0
	v_mov_b32_e32 v67, v0
	v_mov_b32_e32 v68, v0
	v_mov_b32_e32 v69, v0
	v_mov_b32_e32 v70, v0
	v_mov_b32_e32 v71, v0
	v_mov_b32_e32 v72, v0
	v_mov_b32_e32 v73, v0
	v_mov_b32_e32 v74, v0
	v_mov_b32_e32 v75, v0
	v_mov_b32_e32 v76, v0
	v_mov_b32_e32 v77, v0
	v_mov_b32_e32 v78, v0
	v_mov_b32_e32 v79, v0
	v_mov_b32_e32 v80, v0
	v_mov_b32_e32 v81, v0
	v_mov_b32_e32 v82, v0
	v_mov_b32_e32 v83, v0
	v_mov_b32_e32 v84, v0
	v_mov_b32_e32 v85, v0
	v_mov_b32_e32 v86, v0
	v_mov_b32_e32 v87, v0
	v_mov_b32_e32 v88, v0
	v_mov_b32_e32 v89, v0
	v_mov_b32_e32 v90, v0
	v_mov_b32_e32 v91, v0
	v_mov_b32_e32 v92, v0
	v_mov_b32_e32 v93, v0
	v_mov_b32_e32 v94, v0
	v_mov_b32_e32 v95, v0
	v_mov_b32_e32 v96, v0
	v_mov_b32_e32 v97, v0
	v_mov_b32_e32 v98, v0
	v_mov_b32_e32 v99, v0
	v_mov_b32_e32 v100, v0
	v_mov_b32_e32 v101, v0
	v_mov_b32_e32 v102, v0
	v_mov_b32_e32 v103, v0
	v_mov_b32_e32 v104, v0
	v_mov_b32_e32 v105, v0
	v_mov_b32_e32 v106, v0
	v_mov_b32_e32 v107, v0
	v_mov_b32_e32 v108, v0
	v_mov_b32_e32 v109, v0
	v_mov_b32_e32 v110, v0
	v_mov_b32_e32 v111, v0
	v_mov_b32_e32 v112, v0
	v_mov_b32_e32 v113, v0
	v_mov_b32_e32 v114, v0
	v_mov_b32_e32 v115, v0
	v_mov_b32_e32 v116, v0
	v_mov_b32_e32 v117, v0
	v_mov_b32_e32 v118, v0
	v_mov_b32_e32 v119, v0
	v_mov_b32_e32 v120, v0
	v_mov_b32_e32 v121, v0
	v_mov_b32_e32 v122, v0
	v_mov_b32_e32 v123, v0
	v_mov_b32_e32 v124, v0
	v_mov_b32_e32 v125, v0
	v_mov_b32_e32 v126, v0
	v_mov_b32_e32 v127, v0
	s_barrier
	v_lshlrev_b32_e32 v253, 1, v128
	v_lshlrev_b32_e32 v252, 1, v130
	v_readfirstlane_b32 s32, v129
.LBB0_1883:
	ds_read_b128 v[162:165], v155
	ds_read_b128 v[174:177], v155 offset:1024
	ds_read_b128 v[178:181], v155 offset:2048
	ds_read_b128 v[182:185], v155 offset:3072
	s_add_u32 s34, s20, s30
	v_add_u32_e32 v156, s67, v154
	v_add_u32_e32 v157, s68, v154
	v_add_u32_e32 v158, s69, v154
	s_addc_u32 s35, s21, s31
	ds_read_b128 v[186:189], v134
	ds_read_b128 v[190:193], v134 offset:1024
	ds_read_b128 v[194:197], v156
	ds_read_b128 v[198:201], v156 offset:1024
	ds_read_b128 v[202:205], v157
	ds_read_b128 v[206:209], v157 offset:1024
	ds_read_b128 v[210:213], v158
	ds_read_b128 v[214:217], v158 offset:1024
	v_add_u32_e32 v159, 0xe000, v129
	v_add_u32_e32 v160, 0xc000, v129
	s_add_u32 m0, s32, 0xc000
	s_add_u32 s98, s34, 0x40080
	s_addc_u32 s99, s35, 0
	global_load_lds_dwordx4 v253, s[98:99]
	s_add_u32 m0, s32, 0xe000
	s_nop 0
	global_load_lds_dwordx4 v252, s[98:99]
	s_waitcnt lgkmcnt(8)
	s_barrier
	s_waitcnt lgkmcnt(0)
	s_setprio 1
	s_waitcnt lgkmcnt(0)
	v_mfma_f32_16x16x32_bf16 v[124:127], v[186:189], v[162:165], v[124:127]
	v_mfma_f32_16x16x32_bf16 v[120:123], v[186:189], v[178:181], v[120:123]
	v_mfma_f32_16x16x32_bf16 v[116:119], v[194:197], v[162:165], v[116:119]
	v_mfma_f32_16x16x32_bf16 v[112:115], v[194:197], v[178:181], v[112:115]
	v_mfma_f32_16x16x32_bf16 v[108:111], v[202:205], v[162:165], v[108:111]
	v_mfma_f32_16x16x32_bf16 v[104:107], v[202:205], v[178:181], v[104:107]
	v_mfma_f32_16x16x32_bf16 v[100:103], v[210:213], v[162:165], v[100:103]
	v_mfma_f32_16x16x32_bf16 v[96:99], v[210:213], v[178:181], v[96:99]
	v_mfma_f32_16x16x32_bf16 v[124:127], v[190:193], v[174:177], v[124:127]
	v_mfma_f32_16x16x32_bf16 v[120:123], v[190:193], v[182:185], v[120:123]
	v_mfma_f32_16x16x32_bf16 v[116:119], v[198:201], v[174:177], v[116:119]
	v_mfma_f32_16x16x32_bf16 v[112:115], v[198:201], v[182:185], v[112:115]
	v_mfma_f32_16x16x32_bf16 v[108:111], v[206:209], v[174:177], v[108:111]
	v_mfma_f32_16x16x32_bf16 v[104:107], v[206:209], v[182:185], v[104:107]
	v_mfma_f32_16x16x32_bf16 v[100:103], v[214:217], v[174:177], v[100:103]
	v_mfma_f32_16x16x32_bf16 v[96:99], v[214:217], v[182:185], v[96:99]
	s_setprio 0
	s_barrier
; #define LDA(dst, b, h)                                                                                    \
;   _Pragma("unroll") for (int m = 0; m < 4; ++m) _Pragma("unroll") for (int k = 0; k < 2; ++k)             \
;       dst[m][k] = *reinterpret_cast<const bf16x8*>((char*)SA(b, h) + lds_byte(wr * 64 + m * 16 + fr, k * 32 + fq * 8))
; #define LDB(dst, b, h)                                                                                    \
;   _Pragma("unroll") for (int n = 0; n < 2; ++n) _Pragma("unroll") for (int k = 0; k < 2; ++k)             \
;       dst[n][k] = *reinterpret_cast<const bf16x8*>((char*)SB(b, h) + lds_byte(wc * 32 + n * 16 + fr, k * 32 + fq * 8))
; #define WAIT_V(n) asm volatile("s_waitcnt vmcnt(" #n ")" ::: "memory")
; #define WAIT_L(n) asm volatile("s_waitcnt lgkmcnt(" #n ")" ::: "memory")
; #define BAR __builtin_amdgcn_s_barrier()
; #define SCHED __builtin_amdgcn_sched_barrier(0)
; template <int EPI> ...
;     ...
;     LDB(B0, 0, 0); SCHED; LDA(At, 0, 0); STAGE(SA(1, 1), A, brow + HALF, t + 1);
;     WAIT_L(8); BAR; WAIT_L(0); MMA(0, 0, At, B0); BAR; SCHED;
;     LDB(B1, 0, 1); STAGE(SB(0, 0), Bt, bcol, t + 2);
;     BAR; WAIT_L(0); MMA(0, 1, At, B1); BAR;
;     LDA(At, 0, 1); STAGE(SA(0, 0), A, brow, t + 2);
;     BAR; WAIT_L(0); MMA(1, 0, At, B0); BAR; SCHED;
;     STAGE(SB(0, 1), Bt, bcol + HALF, t + 2);
;     WAIT_V(6); BAR; MMA(1, 1, At, B1); BAR;
;     LDB(B0, 1, 0); SCHED; LDA(At, 1, 0); STAGE(SA(0, 1), A, brow + HALF, t + 2);
;     WAIT_L(8); BAR; WAIT_L(0); MMA(0, 0, At, B0); BAR; SCHED;
;     LDB(B1, 1, 1); STAGE(SB(1, 0), Bt, bcol, t + 3);
;     BAR; WAIT_L(0); MMA(0, 1, At, B1); BAR;
;     LDA(At, 1, 1); STAGE(SA(1, 0), A, brow, t + 3);
;     BAR; WAIT_L(0); MMA(1, 0, At, B0); BAR; SCHED;
;     STAGE(SB(1, 1), Bt, bcol + HALF, t + 3);
;     WAIT_V(6); BAR; MMA(1, 1, At, B1); BAR;
	s_add_u32 s62, s18, s30
	s_addc_u32 s63, s19, s31
	ds_read_b128 v[218:221], v152
	ds_read_b128 v[222:225], v152 offset:1024
	ds_read_b128 v[226:229], v152 offset:2048
	ds_read_b128 v[230:233], v152 offset:3072
	s_add_u32 m0, s32, 0x10000
	s_add_u32 s98, s62, 0x100
	s_addc_u32 s99, s63, 0
	global_load_lds_dwordx4 v253, s[98:99]
	s_add_u32 m0, s32, 0x12000
	s_nop 0
	global_load_lds_dwordx4 v252, s[98:99]
	s_barrier
	s_waitcnt lgkmcnt(0)
	s_setprio 1
	s_waitcnt lgkmcnt(0)
	v_mfma_f32_16x16x32_bf16 v[92:95], v[186:189], v[218:221], v[92:95]
	v_mfma_f32_16x16x32_bf16 v[88:91], v[186:189], v[226:229], v[88:91]
	v_mfma_f32_16x16x32_bf16 v[84:87], v[194:197], v[218:221], v[84:87]
	v_mfma_f32_16x16x32_bf16 v[80:83], v[194:197], v[226:229], v[80:83]
	v_mfma_f32_16x16x32_bf16 v[76:79], v[202:205], v[218:221], v[76:79]
	v_mfma_f32_16x16x32_bf16 v[72:75], v[202:205], v[226:229], v[72:75]
	v_mfma_f32_16x16x32_bf16 v[68:71], v[210:213], v[218:221], v[68:71]
	v_mfma_f32_16x16x32_bf16 v[64:67], v[210:213], v[226:229], v[64:67]
	v_mfma_f32_16x16x32_bf16 v[92:95], v[190:193], v[222:225], v[92:95]
	v_mfma_f32_16x16x32_bf16 v[88:91], v[190:193], v[230:233], v[88:91]
	v_mfma_f32_16x16x32_bf16 v[84:87], v[198:201], v[222:225], v[84:87]
	v_mfma_f32_16x16x32_bf16 v[80:83], v[198:201], v[230:233], v[80:83]
	v_mfma_f32_16x16x32_bf16 v[76:79], v[206:209], v[222:225], v[76:79]
	v_mfma_f32_16x16x32_bf16 v[72:75], v[206:209], v[230:233], v[72:75]
	v_mfma_f32_16x16x32_bf16 v[68:71], v[214:217], v[222:225], v[68:71]
	v_mfma_f32_16x16x32_bf16 v[64:67], v[214:217], v[230:233], v[64:67]
	s_setprio 0
	s_barrier
	ds_read_b128 v[186:189], v134 offset:16384
	ds_read_b128 v[190:193], v134 offset:17408
	ds_read_b128 v[194:197], v156 offset:16384
	ds_read_b128 v[198:201], v156 offset:17408
	ds_read_b128 v[202:205], v157 offset:16384
	ds_read_b128 v[206:209], v157 offset:17408
	ds_read_b128 v[210:213], v158 offset:16384
	ds_read_b128 v[214:217], v158 offset:17408
	s_mov_b32 m0, s32
	s_add_u32 s98, s34, 0x100
	s_addc_u32 s99, s35, 0
	global_load_lds_dwordx4 v253, s[98:99]
	s_add_u32 m0, s32, 0x2000
	s_nop 0
	global_load_lds_dwordx4 v252, s[98:99]
	s_barrier
	s_waitcnt lgkmcnt(0)
	s_setprio 1
	s_waitcnt lgkmcnt(0)
	v_mfma_f32_16x16x32_bf16 v[60:63], v[186:189], v[162:165], v[60:63]
	v_mfma_f32_16x16x32_bf16 v[56:59], v[186:189], v[178:181], v[56:59]
	v_mfma_f32_16x16x32_bf16 v[52:55], v[194:197], v[162:165], v[52:55]
	v_mfma_f32_16x16x32_bf16 v[48:51], v[194:197], v[178:181], v[48:51]
	v_mfma_f32_16x16x32_bf16 v[44:47], v[202:205], v[162:165], v[44:47]
	v_mfma_f32_16x16x32_bf16 v[40:43], v[202:205], v[178:181], v[40:43]
	v_mfma_f32_16x16x32_bf16 v[36:39], v[210:213], v[162:165], v[36:39]
	v_mfma_f32_16x16x32_bf16 v[32:35], v[210:213], v[178:181], v[32:35]
	v_mfma_f32_16x16x32_bf16 v[60:63], v[190:193], v[174:177], v[60:63]
	v_mfma_f32_16x16x32_bf16 v[56:59], v[190:193], v[182:185], v[56:59]
	v_mfma_f32_16x16x32_bf16 v[52:55], v[198:201], v[174:177], v[52:55]
	v_mfma_f32_16x16x32_bf16 v[48:51], v[198:201], v[182:185], v[48:51]
	v_mfma_f32_16x16x32_bf16 v[44:47], v[206:209], v[174:177], v[44:47]
	v_mfma_f32_16x16x32_bf16 v[40:43], v[206:209], v[182:185], v[40:43]
	v_mfma_f32_16x16x32_bf16 v[36:39], v[214:217], v[174:177], v[36:39]
	v_mfma_f32_16x16x32_bf16 v[32:35], v[214:217], v[182:185], v[32:35]
	s_setprio 0
	s_barrier
	s_add_u32 m0, s32, 0x14000
	s_add_u32 s98, s62, 0x40100
	s_addc_u32 s99, s63, 0
	global_load_lds_dwordx4 v253, s[98:99]
	s_add_u32 m0, s32, 0x16000
	s_nop 0
	global_load_lds_dwordx4 v252, s[98:99]
	s_waitcnt vmcnt(6)
	s_barrier
	s_setprio 1
	v_mfma_f32_16x16x32_bf16 v[28:31], v[186:189], v[218:221], v[28:31]
	v_mfma_f32_16x16x32_bf16 v[24:27], v[186:189], v[226:229], v[24:27]
	v_mfma_f32_16x16x32_bf16 v[20:23], v[194:197], v[218:221], v[20:23]
	v_mfma_f32_16x16x32_bf16 v[16:19], v[194:197], v[226:229], v[16:19]
	v_mfma_f32_16x16x32_bf16 v[12:15], v[202:205], v[218:221], v[12:15]
	v_mfma_f32_16x16x32_bf16 v[8:11], v[202:205], v[226:229], v[8:11]
	v_mfma_f32_16x16x32_bf16 v[4:7], v[210:213], v[218:221], v[4:7]
	v_mfma_f32_16x16x32_bf16 v[0:3], v[210:213], v[226:229], v[0:3]
	v_mfma_f32_16x16x32_bf16 v[28:31], v[190:193], v[222:225], v[28:31]
	v_mfma_f32_16x16x32_bf16 v[24:27], v[190:193], v[230:233], v[24:27]
	v_mfma_f32_16x16x32_bf16 v[20:23], v[198:201], v[222:225], v[20:23]
	v_mfma_f32_16x16x32_bf16 v[16:19], v[198:201], v[230:233], v[16:19]
	v_mfma_f32_16x16x32_bf16 v[12:15], v[206:209], v[222:225], v[12:15]
	v_mfma_f32_16x16x32_bf16 v[8:11], v[206:209], v[230:233], v[8:11]
	v_mfma_f32_16x16x32_bf16 v[4:7], v[214:217], v[222:225], v[4:7]
	v_mfma_f32_16x16x32_bf16 v[0:3], v[214:217], v[230:233], v[0:3]
	s_setprio 0
	s_barrier
	ds_read_b128 v[162:165], v139
	ds_read_b128 v[174:177], v139 offset:1024
	ds_read_b128 v[178:181], v139 offset:2048
	ds_read_b128 v[182:185], v139 offset:3072
	ds_read_b128 v[186:189], v134 offset:32768
	ds_read_b128 v[190:193], v134 offset:33792
	ds_read_b128 v[194:197], v156 offset:32768
	ds_read_b128 v[198:201], v156 offset:33792
	ds_read_b128 v[202:205], v157 offset:32768
	ds_read_b128 v[206:209], v157 offset:33792
	ds_read_b128 v[210:213], v158 offset:32768
	ds_read_b128 v[214:217], v158 offset:33792
	s_add_u32 m0, s32, 0x4000
	s_add_u32 s98, s34, 0x40100
	s_addc_u32 s99, s35, 0
	global_load_lds_dwordx4 v253, s[98:99]
	s_add_u32 m0, s32, 0x6000
	s_nop 0
	global_load_lds_dwordx4 v252, s[98:99]
	s_waitcnt lgkmcnt(8)
	s_barrier
; #define LDA(dst, b, h)                                                                                    \
;   _Pragma("unroll") for (int m = 0; m < 4; ++m) _Pragma("unroll") for (int k = 0; k < 2; ++k)             \
;       dst[m][k] = *reinterpret_cast<const bf16x8*>((char*)SA(b, h) + lds_byte(wr * 64 + m * 16 + fr, k * 32 + fq * 8))
; #define LDB(dst, b, h)                                                                                    \
;   _Pragma("unroll") for (int n = 0; n < 2; ++n) _Pragma("unroll") for (int k = 0; k < 2; ++k)             \
;       dst[n][k] = *reinterpret_cast<const bf16x8*>((char*)SB(b, h) + lds_byte(wc * 32 + n * 16 + fr, k * 32 + fq * 8))
; #define WAIT_V(n) asm volatile("s_waitcnt vmcnt(" #n ")" ::: "memory")
; #define WAIT_L(n) asm volatile("s_waitcnt lgkmcnt(" #n ")" ::: "memory")
; #define BAR __builtin_amdgcn_s_barrier()
; #define SCHED __builtin_amdgcn_sched_barrier(0)
; template <int EPI> ...
;     ...
;     LDB(B0, 1, 0); SCHED; LDA(At, 1, 0); STAGE(SA(0, 1), A, brow + HALF, t + 2);
;     WAIT_L(8); BAR; WAIT_L(0); MMA(0, 0, At, B0); BAR; SCHED;
;     LDB(B1, 1, 1); STAGE(SB(1, 0), Bt, bcol, t + 3);
;     BAR; WAIT_L(0); MMA(0, 1, At, B1); BAR;
;     LDA(At, 1, 1); STAGE(SA(1, 0), A, brow, t + 3);
;     BAR; WAIT_L(0); MMA(1, 0, At, B0); BAR; SCHED;
;     STAGE(SB(1, 1), Bt, bcol + HALF, t + 3);
;     WAIT_V(6); BAR; MMA(1, 1, At, B1); BAR;
;   }
	s_waitcnt lgkmcnt(0)
	s_setprio 1
	s_waitcnt lgkmcnt(0)
	v_mfma_f32_16x16x32_bf16 v[124:127], v[186:189], v[162:165], v[124:127]
	v_mfma_f32_16x16x32_bf16 v[120:123], v[186:189], v[178:181], v[120:123]
	v_mfma_f32_16x16x32_bf16 v[116:119], v[194:197], v[162:165], v[116:119]
	v_mfma_f32_16x16x32_bf16 v[112:115], v[194:197], v[178:181], v[112:115]
	v_mfma_f32_16x16x32_bf16 v[108:111], v[202:205], v[162:165], v[108:111]
	v_mfma_f32_16x16x32_bf16 v[104:107], v[202:205], v[178:181], v[104:107]
	v_mfma_f32_16x16x32_bf16 v[100:103], v[210:213], v[162:165], v[100:103]
	v_mfma_f32_16x16x32_bf16 v[96:99], v[210:213], v[178:181], v[96:99]
	v_mfma_f32_16x16x32_bf16 v[124:127], v[190:193], v[174:177], v[124:127]
	v_mfma_f32_16x16x32_bf16 v[120:123], v[190:193], v[182:185], v[120:123]
	v_mfma_f32_16x16x32_bf16 v[116:119], v[198:201], v[174:177], v[116:119]
	v_mfma_f32_16x16x32_bf16 v[112:115], v[198:201], v[182:185], v[112:115]
	v_mfma_f32_16x16x32_bf16 v[108:111], v[206:209], v[174:177], v[108:111]
	v_mfma_f32_16x16x32_bf16 v[104:107], v[206:209], v[182:185], v[104:107]
	v_mfma_f32_16x16x32_bf16 v[100:103], v[214:217], v[174:177], v[100:103]
	v_mfma_f32_16x16x32_bf16 v[96:99], v[214:217], v[182:185], v[96:99]
	s_setprio 0
	s_barrier
	ds_read_b128 v[218:221], v136
	ds_read_b128 v[222:225], v136 offset:1024
	ds_read_b128 v[226:229], v136 offset:2048
	ds_read_b128 v[230:233], v136 offset:3072
	s_add_u32 m0, s32, 0x18000
	s_add_u32 s98, s62, 0x180
	s_addc_u32 s99, s63, 0
	global_load_lds_dwordx4 v253, s[98:99]
	s_add_u32 m0, s32, 0x1a000
	s_nop 0
	global_load_lds_dwordx4 v252, s[98:99]
	s_barrier
	s_waitcnt lgkmcnt(0)
	s_setprio 1
	s_waitcnt lgkmcnt(0)
	v_mfma_f32_16x16x32_bf16 v[92:95], v[186:189], v[218:221], v[92:95]
	v_mfma_f32_16x16x32_bf16 v[88:91], v[186:189], v[226:229], v[88:91]
	v_mfma_f32_16x16x32_bf16 v[84:87], v[194:197], v[218:221], v[84:87]
	v_mfma_f32_16x16x32_bf16 v[80:83], v[194:197], v[226:229], v[80:83]
	v_mfma_f32_16x16x32_bf16 v[76:79], v[202:205], v[218:221], v[76:79]
	v_mfma_f32_16x16x32_bf16 v[72:75], v[202:205], v[226:229], v[72:75]
	v_mfma_f32_16x16x32_bf16 v[68:71], v[210:213], v[218:221], v[68:71]
	v_mfma_f32_16x16x32_bf16 v[64:67], v[210:213], v[226:229], v[64:67]
	v_mfma_f32_16x16x32_bf16 v[92:95], v[190:193], v[222:225], v[92:95]
	v_mfma_f32_16x16x32_bf16 v[88:91], v[190:193], v[230:233], v[88:91]
	v_mfma_f32_16x16x32_bf16 v[84:87], v[198:201], v[222:225], v[84:87]
	v_mfma_f32_16x16x32_bf16 v[80:83], v[198:201], v[230:233], v[80:83]
	v_mfma_f32_16x16x32_bf16 v[76:79], v[206:209], v[222:225], v[76:79]
	v_mfma_f32_16x16x32_bf16 v[72:75], v[206:209], v[230:233], v[72:75]
	v_mfma_f32_16x16x32_bf16 v[68:71], v[214:217], v[222:225], v[68:71]
	v_mfma_f32_16x16x32_bf16 v[64:67], v[214:217], v[230:233], v[64:67]
	s_setprio 0
	s_barrier
	ds_read_b128 v[186:189], v134 offset:49152
	ds_read_b128 v[190:193], v134 offset:50176
	ds_read_b128 v[194:197], v156 offset:49152
	ds_read_b128 v[198:201], v156 offset:50176
	ds_read_b128 v[202:205], v157 offset:49152
	ds_read_b128 v[206:209], v157 offset:50176
	ds_read_b128 v[210:213], v158 offset:49152
	ds_read_b128 v[214:217], v158 offset:50176
	s_add_u32 m0, s32, 0x8000
	s_add_u32 s98, s34, 0x180
	s_addc_u32 s99, s35, 0
	global_load_lds_dwordx4 v253, s[98:99]
	s_nop 0
	s_add_u32 m0, s32, 0xa000
	s_nop 0
	global_load_lds_dwordx4 v252, s[98:99]
	s_barrier
	s_waitcnt lgkmcnt(0)
	s_setprio 1
	s_waitcnt lgkmcnt(0)
	v_mfma_f32_16x16x32_bf16 v[60:63], v[186:189], v[162:165], v[60:63]
	v_mfma_f32_16x16x32_bf16 v[56:59], v[186:189], v[178:181], v[56:59]
	v_mfma_f32_16x16x32_bf16 v[52:55], v[194:197], v[162:165], v[52:55]
	v_mfma_f32_16x16x32_bf16 v[48:51], v[194:197], v[178:181], v[48:51]
	v_mfma_f32_16x16x32_bf16 v[44:47], v[202:205], v[162:165], v[44:47]
	v_mfma_f32_16x16x32_bf16 v[40:43], v[202:205], v[178:181], v[40:43]
	v_mfma_f32_16x16x32_bf16 v[36:39], v[210:213], v[162:165], v[36:39]
	v_mfma_f32_16x16x32_bf16 v[32:35], v[210:213], v[178:181], v[32:35]
	v_mfma_f32_16x16x32_bf16 v[60:63], v[190:193], v[174:177], v[60:63]
	v_mfma_f32_16x16x32_bf16 v[56:59], v[190:193], v[182:185], v[56:59]
	v_mfma_f32_16x16x32_bf16 v[52:55], v[198:201], v[174:177], v[52:55]
	v_mfma_f32_16x16x32_bf16 v[48:51], v[198:201], v[182:185], v[48:51]
	v_mfma_f32_16x16x32_bf16 v[44:47], v[206:209], v[174:177], v[44:47]
	v_mfma_f32_16x16x32_bf16 v[40:43], v[206:209], v[182:185], v[40:43]
	v_mfma_f32_16x16x32_bf16 v[36:39], v[214:217], v[174:177], v[36:39]
	v_mfma_f32_16x16x32_bf16 v[32:35], v[214:217], v[182:185], v[32:35]
	s_setprio 0
	s_barrier
	s_add_u32 m0, s32, 0x1c000
	s_add_u32 s98, s62, 0x40180
	s_addc_u32 s99, s63, 0
	global_load_lds_dwordx4 v253, s[98:99]
	s_add_u32 m0, s32, 0x1e000
	s_nop 0
	global_load_lds_dwordx4 v252, s[98:99]
	s_waitcnt vmcnt(6)
	s_barrier
	s_setprio 1
	v_mfma_f32_16x16x32_bf16 v[28:31], v[186:189], v[218:221], v[28:31]
	v_mfma_f32_16x16x32_bf16 v[24:27], v[186:189], v[226:229], v[24:27]
	v_mfma_f32_16x16x32_bf16 v[20:23], v[194:197], v[218:221], v[20:23]
	v_mfma_f32_16x16x32_bf16 v[16:19], v[194:197], v[226:229], v[16:19]
	v_mfma_f32_16x16x32_bf16 v[12:15], v[202:205], v[218:221], v[12:15]
	v_mfma_f32_16x16x32_bf16 v[8:11], v[202:205], v[226:229], v[8:11]
	v_mfma_f32_16x16x32_bf16 v[4:7], v[210:213], v[218:221], v[4:7]
	v_mfma_f32_16x16x32_bf16 v[0:3], v[210:213], v[226:229], v[0:3]
	v_mfma_f32_16x16x32_bf16 v[28:31], v[190:193], v[222:225], v[28:31]
	v_mfma_f32_16x16x32_bf16 v[24:27], v[190:193], v[230:233], v[24:27]
	v_mfma_f32_16x16x32_bf16 v[20:23], v[198:201], v[222:225], v[20:23]
	v_mfma_f32_16x16x32_bf16 v[16:19], v[198:201], v[230:233], v[16:19]
	v_mfma_f32_16x16x32_bf16 v[12:15], v[206:209], v[222:225], v[12:15]
	v_mfma_f32_16x16x32_bf16 v[8:11], v[206:209], v[230:233], v[8:11]
	v_mfma_f32_16x16x32_bf16 v[4:7], v[214:217], v[222:225], v[4:7]
	v_mfma_f32_16x16x32_bf16 v[0:3], v[214:217], v[230:233], v[0:3]
	s_setprio 0
	s_add_i32 s70, s70, 2
	s_add_u32 s30, s30, 0x100
	s_addc_u32 s31, s31, 0
	s_cmp_lt_u32 s70, 12
	s_barrier
; #define LDA(dst, b, h)                                                                                    \
;   _Pragma("unroll") for (int m = 0; m < 4; ++m) _Pragma("unroll") for (int k = 0; k < 2; ++k)             \
;       dst[m][k] = *reinterpret_cast<const bf16x8*>((char*)SA(b, h) + lds_byte(wr * 64 + m * 16 + fr, k * 32 + fq * 8))
; #define LDB(dst, b, h)                                                                                    \
;   _Pragma("unroll") for (int n = 0; n < 2; ++n) _Pragma("unroll") for (int k = 0; k < 2; ++k)             \
;       dst[n][k] = *reinterpret_cast<const bf16x8*>((char*)SB(b, h) + lds_byte(wc * 32 + n * 16 + fr, k * 32 + fq * 8))
; #define WAIT_V(n) asm volatile("s_waitcnt vmcnt(" #n ")" ::: "memory")
; #define WAIT_L(n) asm volatile("s_waitcnt lgkmcnt(" #n ")" ::: "memory")
; #define BAR __builtin_amdgcn_s_barrier()
; template <int EPI> ...
;     ...
;   {
;     LDB(B0, 0, 0); LDA(At, 0, 0); STAGE(SA(1, 1), A, brow + HALF, nt - 1);
;     BAR; WAIT_L(0); MMA(0, 0, At, B0); BAR;
;     LDB(B1, 0, 1); BAR; WAIT_L(0); MMA(0, 1, At, B1); BAR;
;     LDA(At, 0, 1); WAIT_V(4); BAR; WAIT_L(0); MMA(1, 0, At, B0); MMA(1, 1, At, B1); BAR;
;   }
	s_cbranch_scc1 .LBB0_1883
	ds_read_b128 v[144:147], v155
	ds_read_b128 v[162:165], v155 offset:1024
	ds_read_b128 v[174:177], v155 offset:2048
	ds_read_b128 v[178:181], v155 offset:3072
	ds_read_b128 v[182:185], v134
	ds_read_b128 v[186:189], v134 offset:1024
	ds_read_b128 v[190:193], v156
	ds_read_b128 v[194:197], v156 offset:1024
	ds_read_b128 v[198:201], v157
	ds_read_b128 v[202:205], v157 offset:1024
	ds_read_b128 v[206:209], v158
	ds_read_b128 v[210:213], v158 offset:1024
	v_mov_b32_e32 v129, v149
	v_lshl_add_u64 v[128:129], v[128:129], 1, s[22:23]
	s_mov_b64 s[20:21], 0x780
	v_readfirstlane_b32 s18, v160
	v_lshl_add_u64 v[128:129], v[128:129], 0, s[20:21]
	s_mov_b32 m0, s18
	v_mov_b32_e32 v131, v149
	global_load_lds_dwordx4 v[128:129], off
	v_readfirstlane_b32 s18, v159
	v_lshl_add_u64 v[128:129], v[130:131], 1, s[22:23]
	v_lshl_add_u64 v[128:129], v[128:129], 0, s[20:21]
	s_mov_b32 m0, s18
	s_nop 0
	global_load_lds_dwordx4 v[128:129], off
	s_barrier
	s_waitcnt lgkmcnt(0)
	s_setprio 1
	s_waitcnt lgkmcnt(0)
	v_mfma_f32_16x16x32_bf16 v[124:127], v[182:185], v[144:147], v[124:127]
	v_mfma_f32_16x16x32_bf16 v[120:123], v[182:185], v[174:177], v[120:123]
	v_mfma_f32_16x16x32_bf16 v[116:119], v[190:193], v[144:147], v[116:119]
	v_mfma_f32_16x16x32_bf16 v[112:115], v[190:193], v[174:177], v[112:115]
	v_mfma_f32_16x16x32_bf16 v[108:111], v[198:201], v[144:147], v[108:111]
	v_mfma_f32_16x16x32_bf16 v[104:107], v[198:201], v[174:177], v[104:107]
	v_mfma_f32_16x16x32_bf16 v[96:99], v[206:209], v[174:177], v[96:99]
	v_mfma_f32_16x16x32_bf16 v[124:127], v[186:189], v[162:165], v[124:127]
	v_mfma_f32_16x16x32_bf16 v[120:123], v[186:189], v[178:181], v[120:123]
	v_mfma_f32_16x16x32_bf16 v[116:119], v[194:197], v[162:165], v[116:119]
	v_mfma_f32_16x16x32_bf16 v[112:115], v[194:197], v[178:181], v[112:115]
	v_mfma_f32_16x16x32_bf16 v[108:111], v[202:205], v[162:165], v[108:111]
	v_mfma_f32_16x16x32_bf16 v[104:107], v[202:205], v[178:181], v[104:107]
	v_mfma_f32_16x16x32_bf16 v[100:103], v[206:209], v[144:147], v[100:103]
	v_mfma_f32_16x16x32_bf16 v[96:99], v[210:213], v[178:181], v[96:99]
	v_mfma_f32_16x16x32_bf16 v[128:131], v[210:213], v[162:165], v[100:103]
	s_setprio 0
	s_barrier
	s_nop 3
	ds_read_b128 v[100:103], v152
	ds_read_b128 v[214:217], v152 offset:1024
	ds_read_b128 v[218:221], v152 offset:2048
	ds_read_b128 v[152:155], v152 offset:3072
	s_barrier
	s_waitcnt lgkmcnt(0)
	s_setprio 1
	s_waitcnt lgkmcnt(0)
	v_mfma_f32_16x16x32_bf16 v[88:91], v[182:185], v[218:221], v[88:91]
	v_mfma_f32_16x16x32_bf16 v[92:95], v[182:185], v[100:103], v[92:95]
	v_mfma_f32_16x16x32_bf16 v[88:91], v[186:189], v[152:155], v[88:91]
	v_mfma_f32_16x16x32_bf16 v[84:87], v[190:193], v[100:103], v[84:87]
	v_mfma_f32_16x16x32_bf16 v[80:83], v[190:193], v[218:221], v[80:83]
	v_mfma_f32_16x16x32_bf16 v[76:79], v[198:201], v[100:103], v[76:79]
	v_mfma_f32_16x16x32_bf16 v[72:75], v[198:201], v[218:221], v[72:75]
	v_mfma_f32_16x16x32_bf16 v[68:71], v[206:209], v[100:103], v[68:71]
	v_mfma_f32_16x16x32_bf16 v[64:67], v[206:209], v[218:221], v[64:67]
	v_mfma_f32_16x16x32_bf16 v[222:225], v[186:189], v[214:217], v[92:95]
	v_mfma_f32_16x16x32_bf16 v[182:185], v[194:197], v[214:217], v[84:87]
	v_mfma_f32_16x16x32_bf16 v[186:189], v[194:197], v[152:155], v[80:83]
	v_mfma_f32_16x16x32_bf16 v[190:193], v[202:205], v[214:217], v[76:79]
	v_mfma_f32_16x16x32_bf16 v[194:197], v[202:205], v[152:155], v[72:75]
	v_mfma_f32_16x16x32_bf16 v[198:201], v[210:213], v[214:217], v[68:71]
	v_mfma_f32_16x16x32_bf16 v[202:205], v[210:213], v[152:155], v[64:67]
	s_setprio 0
	s_barrier
	s_nop 0
	ds_read_b128 v[64:67], v134 offset:16384
	ds_read_b128 v[68:71], v134 offset:17408
	ds_read_b128 v[72:75], v156 offset:16384
	ds_read_b128 v[76:79], v156 offset:17408
	ds_read_b128 v[80:83], v157 offset:16384
	ds_read_b128 v[84:87], v157 offset:17408
	ds_read_b128 v[92:95], v158 offset:16384
	ds_read_b128 v[206:209], v158 offset:17408
	s_waitcnt vmcnt(4)
	s_barrier
	s_waitcnt lgkmcnt(0)
	s_setprio 1
	s_waitcnt lgkmcnt(0)
	v_mfma_f32_16x16x32_bf16 v[60:63], v[64:67], v[144:147], v[60:63]
	v_mfma_f32_16x16x32_bf16 v[56:59], v[64:67], v[174:177], v[56:59]
	v_mfma_f32_16x16x32_bf16 v[52:55], v[72:75], v[144:147], v[52:55]
	v_mfma_f32_16x16x32_bf16 v[48:51], v[72:75], v[174:177], v[48:51]
	v_mfma_f32_16x16x32_bf16 v[44:47], v[80:83], v[144:147], v[44:47]
	v_mfma_f32_16x16x32_bf16 v[40:43], v[80:83], v[174:177], v[40:43]
	v_mfma_f32_16x16x32_bf16 v[36:39], v[92:95], v[144:147], v[36:39]
	v_mfma_f32_16x16x32_bf16 v[32:35], v[92:95], v[174:177], v[32:35]
	v_mfma_f32_16x16x32_bf16 v[60:63], v[68:71], v[162:165], v[60:63]
	v_mfma_f32_16x16x32_bf16 v[56:59], v[68:71], v[178:181], v[56:59]
	v_mfma_f32_16x16x32_bf16 v[52:55], v[76:79], v[162:165], v[52:55]
	v_mfma_f32_16x16x32_bf16 v[48:51], v[76:79], v[178:181], v[48:51]
	v_mfma_f32_16x16x32_bf16 v[44:47], v[84:87], v[162:165], v[44:47]
	v_mfma_f32_16x16x32_bf16 v[40:43], v[84:87], v[178:181], v[40:43]
	v_mfma_f32_16x16x32_bf16 v[36:39], v[206:209], v[162:165], v[36:39]
	v_mfma_f32_16x16x32_bf16 v[32:35], v[206:209], v[178:181], v[32:35]
	s_setprio 0
	s_setprio 1
	v_mfma_f32_16x16x32_bf16 v[28:31], v[64:67], v[100:103], v[28:31]
	v_mfma_f32_16x16x32_bf16 v[24:27], v[64:67], v[218:221], v[24:27]
	v_mfma_f32_16x16x32_bf16 v[20:23], v[72:75], v[100:103], v[20:23]
	v_mfma_f32_16x16x32_bf16 v[16:19], v[72:75], v[218:221], v[16:19]
	v_mfma_f32_16x16x32_bf16 v[12:15], v[80:83], v[100:103], v[12:15]
	v_mfma_f32_16x16x32_bf16 v[8:11], v[80:83], v[218:221], v[8:11]
	v_mfma_f32_16x16x32_bf16 v[4:7], v[92:95], v[100:103], v[4:7]
	v_mfma_f32_16x16x32_bf16 v[0:3], v[92:95], v[218:221], v[0:3]
	v_mfma_f32_16x16x32_bf16 v[144:147], v[68:71], v[214:217], v[28:31]
	v_mfma_f32_16x16x32_bf16 v[160:163], v[68:71], v[152:155], v[24:27]
	v_mfma_f32_16x16x32_bf16 v[164:167], v[76:79], v[214:217], v[20:23]
	v_mfma_f32_16x16x32_bf16 v[174:177], v[76:79], v[152:155], v[16:19]
	v_mfma_f32_16x16x32_bf16 v[178:181], v[84:87], v[214:217], v[12:15]
	v_mfma_f32_16x16x32_bf16 v[210:213], v[84:87], v[152:155], v[8:11]
	v_mfma_f32_16x16x32_bf16 v[214:217], v[206:209], v[214:217], v[4:7]
	v_mfma_f32_16x16x32_bf16 v[152:155], v[206:209], v[152:155], v[0:3]
	s_setprio 0
	s_barrier
; #define LDA(dst, b, h)                                                                                    \
;   _Pragma("unroll") for (int m = 0; m < 4; ++m) _Pragma("unroll") for (int k = 0; k < 2; ++k)             \
;       dst[m][k] = *reinterpret_cast<const bf16x8*>((char*)SA(b, h) + lds_byte(wr * 64 + m * 16 + fr, k * 32 + fq * 8))
; #define LDB(dst, b, h)                                                                                    \
;   _Pragma("unroll") for (int n = 0; n < 2; ++n) _Pragma("unroll") for (int k = 0; k < 2; ++k)             \
;       dst[n][k] = *reinterpret_cast<const bf16x8*>((char*)SB(b, h) + lds_byte(wc * 32 + n * 16 + fr, k * 32 + fq * 8))
; #define WAIT_V(n) asm volatile("s_waitcnt vmcnt(" #n ")" ::: "memory")
; #define WAIT_L(n) asm volatile("s_waitcnt lgkmcnt(" #n ")" ::: "memory")
; #define BAR __builtin_amdgcn_s_barrier()
; template <int EPI> ...
;     ...
;   {
;     LDB(B0, 1, 0); LDA(At, 1, 0); WAIT_V(2); BAR; WAIT_L(0); MMA(0, 0, At, B0); BAR;
;     LDB(B1, 1, 1); WAIT_V(0); BAR; WAIT_L(0); MMA(0, 1, At, B1); BAR;
;     LDA(At, 1, 1); BAR; WAIT_L(0); MMA(1, 0, At, B0); MMA(1, 1, At, B1); BAR;
;   }
;   if (wr == 0) BAR;
	s_nop 0
	ds_read_b128 v[0:3], v139
	ds_read_b128 v[4:7], v139 offset:1024
	ds_read_b128 v[206:209], v139 offset:2048
	ds_read_b128 v[138:141], v139 offset:3072
	ds_read_b128 v[8:11], v134 offset:32768
	ds_read_b128 v[12:15], v134 offset:33792
	ds_read_b128 v[16:19], v156 offset:32768
	ds_read_b128 v[20:23], v156 offset:33792
	ds_read_b128 v[24:27], v157 offset:32768
	ds_read_b128 v[28:31], v157 offset:33792
	ds_read_b128 v[218:221], v158 offset:32768
	ds_read_b128 v[226:229], v158 offset:33792
	s_waitcnt vmcnt(2)
	s_barrier
	s_waitcnt lgkmcnt(0)
	s_setprio 1
	s_waitcnt lgkmcnt(0)
	v_mfma_f32_16x16x32_bf16 v[64:67], v[8:11], v[0:3], v[124:127]
	v_mfma_f32_16x16x32_bf16 v[92:95], v[12:15], v[4:7], v[64:67]
	v_mfma_f32_16x16x32_bf16 v[64:67], v[8:11], v[206:209], v[120:123]
	v_mfma_f32_16x16x32_bf16 v[100:103], v[12:15], v[138:141], v[64:67]
	v_mfma_f32_16x16x32_bf16 v[64:67], v[16:19], v[0:3], v[116:119]
	v_mfma_f32_16x16x32_bf16 v[80:83], v[20:23], v[4:7], v[64:67]
	v_mfma_f32_16x16x32_bf16 v[64:67], v[16:19], v[206:209], v[112:115]
	v_mfma_f32_16x16x32_bf16 v[84:87], v[20:23], v[138:141], v[64:67]
	v_mfma_f32_16x16x32_bf16 v[64:67], v[24:27], v[0:3], v[108:111]
	v_mfma_f32_16x16x32_bf16 v[72:75], v[28:31], v[4:7], v[64:67]
	v_mfma_f32_16x16x32_bf16 v[64:67], v[24:27], v[206:209], v[104:107]
	v_mfma_f32_16x16x32_bf16 v[76:79], v[28:31], v[138:141], v[64:67]
	v_mfma_f32_16x16x32_bf16 v[64:67], v[218:221], v[0:3], v[128:131]
	v_mfma_f32_16x16x32_bf16 v[68:71], v[218:221], v[206:209], v[96:99]
	v_mfma_f32_16x16x32_bf16 v[64:67], v[226:229], v[4:7], v[64:67]
	v_mfma_f32_16x16x32_bf16 v[68:71], v[226:229], v[138:141], v[68:71]
	s_setprio 0
	s_barrier
	ds_read_b128 v[128:131], v136
	ds_read_b128 v[230:233], v136 offset:1024
	ds_read_b128 v[234:237], v136 offset:2048
	ds_read_b128 v[238:241], v136 offset:3072
	s_waitcnt vmcnt(0)
	s_barrier
	s_waitcnt lgkmcnt(0)
	s_setprio 1
	s_waitcnt lgkmcnt(0)
	v_mfma_f32_16x16x32_bf16 v[96:99], v[8:11], v[128:131], v[222:225]
	v_mfma_f32_16x16x32_bf16 v[8:11], v[8:11], v[234:237], v[88:91]
	v_mfma_f32_16x16x32_bf16 v[124:127], v[12:15], v[238:241], v[8:11]
	v_mfma_f32_16x16x32_bf16 v[8:11], v[16:19], v[128:131], v[182:185]
	v_mfma_f32_16x16x32_bf16 v[112:115], v[20:23], v[230:233], v[8:11]
	v_mfma_f32_16x16x32_bf16 v[8:11], v[16:19], v[234:237], v[186:189]
	v_mfma_f32_16x16x32_bf16 v[116:119], v[20:23], v[238:241], v[8:11]
	v_mfma_f32_16x16x32_bf16 v[8:11], v[24:27], v[128:131], v[190:193]
	v_mfma_f32_16x16x32_bf16 v[104:107], v[28:31], v[230:233], v[8:11]
	v_mfma_f32_16x16x32_bf16 v[8:11], v[24:27], v[234:237], v[194:197]
	v_mfma_f32_16x16x32_bf16 v[108:111], v[28:31], v[238:241], v[8:11]
	v_mfma_f32_16x16x32_bf16 v[8:11], v[218:221], v[128:131], v[198:201]
	v_mfma_f32_16x16x32_bf16 v[88:91], v[226:229], v[230:233], v[8:11]
	v_mfma_f32_16x16x32_bf16 v[8:11], v[218:221], v[234:237], v[202:205]
	v_mfma_f32_16x16x32_bf16 v[120:123], v[12:15], v[230:233], v[96:99]
	v_mfma_f32_16x16x32_bf16 v[96:99], v[226:229], v[238:241], v[8:11]
	s_setprio 0
	s_barrier
	ds_read_b128 v[182:185], v134 offset:49152
	ds_read_b128 v[134:137], v134 offset:50176
	ds_read_b128 v[186:189], v156 offset:49152
	ds_read_b128 v[190:193], v156 offset:50176
	ds_read_b128 v[194:197], v157 offset:49152
	ds_read_b128 v[198:201], v157 offset:50176
	ds_read_b128 v[202:205], v158 offset:49152
	ds_read_b128 v[156:159], v158 offset:50176
	s_barrier
	s_waitcnt lgkmcnt(0)
	s_setprio 1
	s_waitcnt lgkmcnt(0)
	v_mfma_f32_16x16x32_bf16 v[8:11], v[182:185], v[0:3], v[60:63]
	v_mfma_f32_16x16x32_bf16 v[24:27], v[134:137], v[4:7], v[8:11]
	v_mfma_f32_16x16x32_bf16 v[8:11], v[182:185], v[206:209], v[56:59]
	v_mfma_f32_16x16x32_bf16 v[28:31], v[134:137], v[138:141], v[8:11]
	v_mfma_f32_16x16x32_bf16 v[8:11], v[186:189], v[0:3], v[52:55]
	v_mfma_f32_16x16x32_bf16 v[16:19], v[190:193], v[4:7], v[8:11]
	v_mfma_f32_16x16x32_bf16 v[8:11], v[186:189], v[206:209], v[48:51]
	v_mfma_f32_16x16x32_bf16 v[20:23], v[190:193], v[138:141], v[8:11]
	v_mfma_f32_16x16x32_bf16 v[8:11], v[194:197], v[0:3], v[44:47]
	v_mfma_f32_16x16x32_bf16 v[0:3], v[202:205], v[0:3], v[36:39]
	v_mfma_f32_16x16x32_bf16 v[8:11], v[198:201], v[4:7], v[8:11]
	v_mfma_f32_16x16x32_bf16 v[12:15], v[194:197], v[206:209], v[40:43]
	v_mfma_f32_16x16x32_bf16 v[0:3], v[156:159], v[4:7], v[0:3]
	v_mfma_f32_16x16x32_bf16 v[4:7], v[202:205], v[206:209], v[32:35]
	v_mfma_f32_16x16x32_bf16 v[12:15], v[198:201], v[138:141], v[12:15]
	v_mfma_f32_16x16x32_bf16 v[4:7], v[156:159], v[138:141], v[4:7]
	s_setprio 0
	s_setprio 1
	v_mfma_f32_16x16x32_bf16 v[32:35], v[182:185], v[128:131], v[144:147]
	v_mfma_f32_16x16x32_bf16 v[56:59], v[134:137], v[230:233], v[32:35]
	v_mfma_f32_16x16x32_bf16 v[32:35], v[182:185], v[234:237], v[160:163]
	v_mfma_f32_16x16x32_bf16 v[60:63], v[134:137], v[238:241], v[32:35]
	v_mfma_f32_16x16x32_bf16 v[32:35], v[186:189], v[128:131], v[164:167]
	v_mfma_f32_16x16x32_bf16 v[48:51], v[190:193], v[230:233], v[32:35]
	v_mfma_f32_16x16x32_bf16 v[32:35], v[186:189], v[234:237], v[174:177]
	v_mfma_f32_16x16x32_bf16 v[52:55], v[190:193], v[238:241], v[32:35]
	v_mfma_f32_16x16x32_bf16 v[32:35], v[194:197], v[128:131], v[178:181]
	v_mfma_f32_16x16x32_bf16 v[40:43], v[198:201], v[230:233], v[32:35]
	v_mfma_f32_16x16x32_bf16 v[32:35], v[194:197], v[234:237], v[210:213]
	v_mfma_f32_16x16x32_bf16 v[44:47], v[198:201], v[238:241], v[32:35]
	v_mfma_f32_16x16x32_bf16 v[32:35], v[202:205], v[128:131], v[214:217]
	v_mfma_f32_16x16x32_bf16 v[36:39], v[202:205], v[234:237], v[152:155]
	v_mfma_f32_16x16x32_bf16 v[32:35], v[156:159], v[230:233], v[32:35]
	v_mfma_f32_16x16x32_bf16 v[36:39], v[156:159], v[238:241], v[36:39]
	s_setprio 0
	s_cmpk_gt_u32 s64, 0xff
	s_barrier
	s_cbranch_scc1 .LBB0_1886
	s_barrier
